# scan LDS-read pipelining + f32 division as rcp+1 Newton step+div_fixup (faithful, <0.5000001 ulp) in epilogues
# speedup vs baseline: 1.0189x; 1.0189x over previous
; #define PG8_STAGE(bufoff, gbase, voff) do { _Pragma("unroll") for (int _i = 0; _i < 2; ++_i) \
;         __builtin_amdgcn_global_load_lds((const unsigned*)((const char*)(gbase) + (voff)[_i]), (LAS unsigned*)(lds + (bufoff) + ldsw + _i * 8192), 16, 0, 0); } while (0)
; #define PG8_LDA(dst, b, h) do { _Pragma("unroll") for (int m = 0; m < 4; ++m) _Pragma("unroll") for (int k = 0; k < 2; ++k) dst[m][k] = *(const LAS bf16x8*)(lds + PG8_SA(b, h) + aoff + m * 2048 + k * 1024); } while (0)
; #define PG8_LDB(dst, b, h) do { _Pragma("unroll") for (int n = 0; n < 2; ++n) _Pragma("unroll") for (int k = 0; k < 2; ++k) dst[n][k] = *(const LAS bf16x8*)(lds + PG8_SB(b, h) + boff + n * 2048 + k * 1024); } while (0)
; #define PG8_MMA(ai, bj, At, Bt) do { __builtin_amdgcn_s_setprio(1); _Pragma("unroll") for (int m = 0; m < 4; ++m) _Pragma("unroll") for (int n = 0; n < 2; ++n) _Pragma("unroll") for (int k = 0; k < 2; ++k) \
;         acc[ai][bj][m][n] = __builtin_amdgcn_mfma_f32_16x16x32_bf16(Bt[n][k], At[m][k], acc[ai][bj][m][n], 0, 0, 0); __builtin_amdgcn_s_setprio(0); } while (0)
; #define PG8_WAIT_L(n) asm volatile("s_waitcnt lgkmcnt(" #n ")" ::: "memory")
; #define PG8_BAR __builtin_amdgcn_s_barrier()
; #define PG8_SCHED __builtin_amdgcn_sched_barrier(0)
; template <class Epi, class Sched>
; DI void gemm_phase(LAS unsigned char* lds, const Gemm g, const Sched& S, const Epi& E) {
;     ...
;             PG8_LDB(B0, 0, 0); PG8_SCHED; PG8_LDA(At, 0, 0); PG8_STAGE(PG8_SA(1, 1), a1 + hstepA, voffA);
;             PG8_WAIT_L(8); PG8_BAR; PG8_WAIT_L(0); PG8_MMA(0, 0, At, B0); PG8_BAR; PG8_SCHED;
;             PG8_LDB(B1, 0, 1); PG8_STAGE(PG8_SB(0, 0), b2, voffB);
;             PG8_BAR; PG8_WAIT_L(0); PG8_MMA(0, 1, At, B1); PG8_BAR;
;             PG8_LDA(At, 0, 1); PG8_STAGE(PG8_SA(0, 0), a2, voffA);
;             PG8_BAR; PG8_WAIT_L(0); PG8_MMA(1, 0, At, B0); PG8_BAR; PG8_SCHED;
.LBB0_47:
	s_add_u32 s2, s20, 0xfff80080
	s_addc_u32 s3, s21, -1
	s_add_i32 s82, 0, 0x10000
	v_add_u32_e32 v145, s82, v143
	ds_read_b128 v[146:149], v145
	ds_read_b128 v[150:153], v145 offset:1024
	ds_read_b128 v[154:157], v145 offset:2048
	ds_read_b128 v[158:161], v145 offset:3072
	s_cmp_eq_u32 s65, 28
	s_cselect_b32 s39, s31, s3
	s_cselect_b32 s38, s59, s2
	s_cselect_b32 s3, s27, s64
	s_cselect_b32 s2, s60, s61
	v_lshl_add_u64 v[190:191], s[20:21], 0, v[138:139]
	s_add_i32 m0, s48, 0xc000
	ds_read_b128 v[162:165], v144
	ds_read_b128 v[166:169], v144 offset:1024
	ds_read_b128 v[170:173], v144 offset:2048
	ds_read_b128 v[174:177], v144 offset:3072
	ds_read_b128 v[178:181], v144 offset:4096
	ds_read_b128 v[182:185], v144 offset:5120
	ds_read_b128 v[186:189], v144 offset:6144
	ds_read_b128 v[202:205], v144 offset:7168
	global_load_lds_dwordx4 v[190:191], off
	v_lshl_add_u64 v[190:191], s[20:21], 0, v[140:141]
	s_add_i32 m0, s48, 0xe000
	s_nop 0
	global_load_lds_dwordx4 v[190:191], off
	s_waitcnt lgkmcnt(8)
	s_barrier
	s_waitcnt lgkmcnt(0)
	s_setprio 1
	s_waitcnt lgkmcnt(0)
	v_mfma_f32_16x16x32_bf16 v[128:131], v[146:149], v[162:165], v[128:131]
	v_mfma_f32_16x16x32_bf16 v[120:123], v[154:157], v[162:165], v[120:123]
	v_mfma_f32_16x16x32_bf16 v[112:115], v[146:149], v[170:173], v[112:115]
	v_mfma_f32_16x16x32_bf16 v[104:107], v[154:157], v[170:173], v[104:107]
	v_mfma_f32_16x16x32_bf16 v[96:99], v[146:149], v[178:181], v[96:99]
	v_mfma_f32_16x16x32_bf16 v[88:91], v[154:157], v[178:181], v[88:91]
	v_mfma_f32_16x16x32_bf16 v[80:83], v[146:149], v[186:189], v[80:83]
	v_mfma_f32_16x16x32_bf16 v[72:75], v[154:157], v[186:189], v[72:75]
	v_mfma_f32_16x16x32_bf16 v[128:131], v[150:153], v[166:169], v[128:131]
	v_mfma_f32_16x16x32_bf16 v[120:123], v[158:161], v[166:169], v[120:123]
	v_mfma_f32_16x16x32_bf16 v[112:115], v[150:153], v[174:177], v[112:115]
	v_mfma_f32_16x16x32_bf16 v[104:107], v[158:161], v[174:177], v[104:107]
	v_mfma_f32_16x16x32_bf16 v[96:99], v[150:153], v[182:185], v[96:99]
	v_mfma_f32_16x16x32_bf16 v[88:91], v[158:161], v[182:185], v[88:91]
	v_mfma_f32_16x16x32_bf16 v[80:83], v[150:153], v[202:205], v[80:83]
	v_mfma_f32_16x16x32_bf16 v[72:75], v[158:161], v[202:205], v[72:75]
	s_setprio 0
	s_barrier
	s_add_i32 s84, 0, 0x14000
	s_add_i32 s82, s82, s45
	v_add_u32_e32 v145, s84, v143
	v_lshl_add_u64 v[190:191], s[2:3], 0, v[134:135]
	s_mov_b32 m0, s82
	ds_read_b128 v[206:209], v145
	ds_read_b128 v[210:213], v145 offset:1024
	ds_read_b128 v[214:217], v145 offset:2048
	ds_read_b128 v[230:233], v145 offset:3072
	global_load_lds_dwordx4 v[190:191], off
	v_lshl_add_u64 v[234:235], s[2:3], 0, v[0:1]
	s_add_i32 m0, s82, 0x2000
	s_nop 0
	global_load_lds_dwordx4 v[234:235], off
	s_barrier
	s_waitcnt lgkmcnt(0)
	s_setprio 1
	s_waitcnt lgkmcnt(0)
	v_mfma_f32_16x16x32_bf16 v[124:127], v[206:209], v[162:165], v[124:127]
	v_mfma_f32_16x16x32_bf16 v[116:119], v[214:217], v[162:165], v[116:119]
	v_mfma_f32_16x16x32_bf16 v[108:111], v[206:209], v[170:173], v[108:111]
	v_mfma_f32_16x16x32_bf16 v[100:103], v[214:217], v[170:173], v[100:103]
	v_mfma_f32_16x16x32_bf16 v[92:95], v[206:209], v[178:181], v[92:95]
	v_mfma_f32_16x16x32_bf16 v[84:87], v[214:217], v[178:181], v[84:87]
	v_mfma_f32_16x16x32_bf16 v[76:79], v[206:209], v[186:189], v[76:79]
	v_mfma_f32_16x16x32_bf16 v[68:71], v[214:217], v[186:189], v[68:71]
	v_mfma_f32_16x16x32_bf16 v[124:127], v[210:213], v[166:169], v[124:127]
	v_mfma_f32_16x16x32_bf16 v[116:119], v[230:233], v[166:169], v[116:119]
	v_mfma_f32_16x16x32_bf16 v[108:111], v[210:213], v[174:177], v[108:111]
	v_mfma_f32_16x16x32_bf16 v[100:103], v[230:233], v[174:177], v[100:103]
	v_mfma_f32_16x16x32_bf16 v[92:95], v[210:213], v[182:185], v[92:95]
	v_mfma_f32_16x16x32_bf16 v[84:87], v[230:233], v[182:185], v[84:87]
	v_mfma_f32_16x16x32_bf16 v[76:79], v[210:213], v[202:205], v[76:79]
	v_mfma_f32_16x16x32_bf16 v[68:71], v[230:233], v[202:205], v[68:71]
	s_setprio 0
	s_mov_b32 m0, s48
	v_lshl_add_u64 v[236:237], s[38:39], 0, v[136:137]
	s_barrier
	ds_read_b128 v[162:165], v144 offset:16384
	ds_read_b128 v[166:169], v144 offset:17408
	ds_read_b128 v[170:173], v144 offset:18432
	ds_read_b128 v[174:177], v144 offset:19456
	ds_read_b128 v[178:181], v144 offset:20480
	ds_read_b128 v[182:185], v144 offset:21504
	ds_read_b128 v[186:189], v144 offset:22528
	ds_read_b128 v[202:205], v144 offset:23552
	global_load_lds_dwordx4 v[236:237], off
	v_lshl_add_u64 v[238:239], s[38:39], 0, v[132:133]
	s_mov_b32 m0, s49
	s_nop 0
	global_load_lds_dwordx4 v[238:239], off
	s_barrier
	s_waitcnt lgkmcnt(0)
	s_setprio 1
	s_waitcnt lgkmcnt(0)
	v_mfma_f32_16x16x32_bf16 v[64:67], v[146:149], v[162:165], v[64:67]
	v_mfma_f32_16x16x32_bf16 v[56:59], v[154:157], v[162:165], v[56:59]
	v_mfma_f32_16x16x32_bf16 v[48:51], v[146:149], v[170:173], v[48:51]
	v_mfma_f32_16x16x32_bf16 v[40:43], v[154:157], v[170:173], v[40:43]
	v_mfma_f32_16x16x32_bf16 v[32:35], v[146:149], v[178:181], v[32:35]
	v_mfma_f32_16x16x32_bf16 v[24:27], v[154:157], v[178:181], v[24:27]
	v_mfma_f32_16x16x32_bf16 v[16:19], v[146:149], v[186:189], v[16:19]
	v_mfma_f32_16x16x32_bf16 v[8:11], v[154:157], v[186:189], v[8:11]
	v_mfma_f32_16x16x32_bf16 v[64:67], v[150:153], v[166:169], v[64:67]
	v_mfma_f32_16x16x32_bf16 v[56:59], v[158:161], v[166:169], v[56:59]
	v_mfma_f32_16x16x32_bf16 v[48:51], v[150:153], v[174:177], v[48:51]
	v_mfma_f32_16x16x32_bf16 v[40:43], v[158:161], v[174:177], v[40:43]
	v_mfma_f32_16x16x32_bf16 v[32:35], v[150:153], v[182:185], v[32:35]
	v_mfma_f32_16x16x32_bf16 v[24:27], v[158:161], v[182:185], v[24:27]
	v_mfma_f32_16x16x32_bf16 v[16:19], v[150:153], v[202:205], v[16:19]
	v_mfma_f32_16x16x32_bf16 v[8:11], v[158:161], v[202:205], v[8:11]
	s_setprio 0
	s_barrier
; #define PG8_STAGE(bufoff, gbase, voff) do { _Pragma("unroll") for (int _i = 0; _i < 2; ++_i) \
;         __builtin_amdgcn_global_load_lds((const unsigned*)((const char*)(gbase) + (voff)[_i]), (LAS unsigned*)(lds + (bufoff) + ldsw + _i * 8192), 16, 0, 0); } while (0)
; #define PG8_LDA(dst, b, h) do { _Pragma("unroll") for (int m = 0; m < 4; ++m) _Pragma("unroll") for (int k = 0; k < 2; ++k) dst[m][k] = *(const LAS bf16x8*)(lds + PG8_SA(b, h) + aoff + m * 2048 + k * 1024); } while (0)
; #define PG8_LDB(dst, b, h) do { _Pragma("unroll") for (int n = 0; n < 2; ++n) _Pragma("unroll") for (int k = 0; k < 2; ++k) dst[n][k] = *(const LAS bf16x8*)(lds + PG8_SB(b, h) + boff + n * 2048 + k * 1024); } while (0)
; #define PG8_MMA(ai, bj, At, Bt) do { __builtin_amdgcn_s_setprio(1); _Pragma("unroll") for (int m = 0; m < 4; ++m) _Pragma("unroll") for (int n = 0; n < 2; ++n) _Pragma("unroll") for (int k = 0; k < 2; ++k) \
;         acc[ai][bj][m][n] = __builtin_amdgcn_mfma_f32_16x16x32_bf16(Bt[n][k], At[m][k], acc[ai][bj][m][n], 0, 0, 0); __builtin_amdgcn_s_setprio(0); } while (0)
; #define PG8_WAIT_V(n) asm volatile("s_waitcnt vmcnt(" #n ")" ::: "memory")
; #define PG8_WAIT_L(n) asm volatile("s_waitcnt lgkmcnt(" #n ")" ::: "memory")
; #define PG8_BAR __builtin_amdgcn_s_barrier()
; #define PG8_SCHED __builtin_amdgcn_sched_barrier(0)
; template <class Epi, class Sched>
; DI void gemm_phase(LAS unsigned char* lds, const Gemm g, const Sched& S, const Epi& E) {
;     ...
;             PG8_STAGE(PG8_SB(0, 1), b2 + hstepB, voffB);
;             PG8_WAIT_V(6); PG8_BAR; PG8_MMA(1, 1, At, B1); PG8_BAR;
;             PG8_LDB(B0, 1, 0); PG8_SCHED; PG8_LDA(At, 1, 0); PG8_STAGE(PG8_SA(0, 1), a2 + hstepA, voffA);
;             PG8_WAIT_L(8); PG8_BAR; PG8_WAIT_L(0); PG8_MMA(0, 0, At, B0); PG8_BAR; PG8_SCHED;
;             PG8_LDB(B1, 1, 1); PG8_STAGE(PG8_SB(1, 0), b3, voffB);
;             PG8_BAR; PG8_WAIT_L(0); PG8_MMA(0, 1, At, B1); PG8_BAR;
;             PG8_LDA(At, 1, 1); PG8_STAGE(PG8_SA(1, 0), a3, voffA);
;             PG8_BAR; PG8_WAIT_L(0); PG8_MMA(1, 0, At, B0); PG8_BAR; PG8_SCHED;
	s_add_u32 s82, s2, 0x80000
	s_addc_u32 s83, s3, 0
	s_add_i32 s84, s84, s45
	v_lshl_add_u64 v[146:147], s[82:83], 0, v[134:135]
	s_mov_b32 m0, s84
	s_nop 0
	global_load_lds_dwordx4 v[146:147], off
	v_lshl_add_u64 v[146:147], s[82:83], 0, v[0:1]
	s_add_i32 m0, s84, 0x2000
	s_nop 0
	global_load_lds_dwordx4 v[146:147], off
	s_waitcnt vmcnt(6)
	s_barrier
	s_setprio 1
	v_mfma_f32_16x16x32_bf16 v[60:63], v[206:209], v[162:165], v[60:63]
	v_mfma_f32_16x16x32_bf16 v[52:55], v[214:217], v[162:165], v[52:55]
	v_mfma_f32_16x16x32_bf16 v[44:47], v[206:209], v[170:173], v[44:47]
	v_mfma_f32_16x16x32_bf16 v[36:39], v[214:217], v[170:173], v[36:39]
	v_mfma_f32_16x16x32_bf16 v[28:31], v[206:209], v[178:181], v[28:31]
	v_mfma_f32_16x16x32_bf16 v[20:23], v[214:217], v[178:181], v[20:23]
	v_mfma_f32_16x16x32_bf16 v[12:15], v[206:209], v[186:189], v[12:15]
	v_mfma_f32_16x16x32_bf16 v[4:7], v[214:217], v[186:189], v[4:7]
	v_mfma_f32_16x16x32_bf16 v[60:63], v[210:213], v[166:169], v[60:63]
	v_mfma_f32_16x16x32_bf16 v[52:55], v[230:233], v[166:169], v[52:55]
	v_mfma_f32_16x16x32_bf16 v[44:47], v[210:213], v[174:177], v[44:47]
	v_mfma_f32_16x16x32_bf16 v[36:39], v[230:233], v[174:177], v[36:39]
	v_mfma_f32_16x16x32_bf16 v[28:31], v[210:213], v[182:185], v[28:31]
	v_mfma_f32_16x16x32_bf16 v[20:23], v[230:233], v[182:185], v[20:23]
	v_mfma_f32_16x16x32_bf16 v[12:15], v[210:213], v[202:205], v[12:15]
	v_mfma_f32_16x16x32_bf16 v[4:7], v[230:233], v[202:205], v[4:7]
	s_setprio 0
	s_add_i32 s82, 0, 0x18000
	v_add_u32_e32 v145, s82, v143
	s_barrier
	ds_read_b128 v[146:149], v145
	ds_read_b128 v[150:153], v145 offset:1024
	ds_read_b128 v[154:157], v145 offset:2048
	ds_read_b128 v[158:161], v145 offset:3072
	s_add_u32 s38, s38, 0x80000
	s_addc_u32 s39, s39, 0
	s_mov_b32 m0, s50
	v_lshl_add_u64 v[206:207], s[38:39], 0, v[136:137]
	ds_read_b128 v[162:165], v144 offset:32768
	ds_read_b128 v[166:169], v144 offset:33792
	ds_read_b128 v[170:173], v144 offset:34816
	ds_read_b128 v[174:177], v144 offset:35840
	ds_read_b128 v[178:181], v144 offset:36864
	ds_read_b128 v[182:185], v144 offset:37888
	ds_read_b128 v[186:189], v144 offset:38912
	ds_read_b128 v[202:205], v144 offset:39936
	global_load_lds_dwordx4 v[206:207], off
	v_lshl_add_u64 v[206:207], s[38:39], 0, v[132:133]
	s_mov_b32 m0, s51
	s_nop 0
	global_load_lds_dwordx4 v[206:207], off
	s_waitcnt lgkmcnt(8)
	s_barrier
	s_waitcnt lgkmcnt(0)
	s_setprio 1
	s_waitcnt lgkmcnt(0)
	v_mfma_f32_16x16x32_bf16 v[128:131], v[146:149], v[162:165], v[128:131]
	v_mfma_f32_16x16x32_bf16 v[120:123], v[154:157], v[162:165], v[120:123]
	v_mfma_f32_16x16x32_bf16 v[112:115], v[146:149], v[170:173], v[112:115]
	v_mfma_f32_16x16x32_bf16 v[104:107], v[154:157], v[170:173], v[104:107]
	v_mfma_f32_16x16x32_bf16 v[96:99], v[146:149], v[178:181], v[96:99]
	v_mfma_f32_16x16x32_bf16 v[88:91], v[154:157], v[178:181], v[88:91]
	v_mfma_f32_16x16x32_bf16 v[80:83], v[146:149], v[186:189], v[80:83]
	v_mfma_f32_16x16x32_bf16 v[72:75], v[154:157], v[186:189], v[72:75]
	v_mfma_f32_16x16x32_bf16 v[128:131], v[150:153], v[166:169], v[128:131]
	v_mfma_f32_16x16x32_bf16 v[120:123], v[158:161], v[166:169], v[120:123]
	v_mfma_f32_16x16x32_bf16 v[112:115], v[150:153], v[174:177], v[112:115]
	v_mfma_f32_16x16x32_bf16 v[104:107], v[158:161], v[174:177], v[104:107]
	v_mfma_f32_16x16x32_bf16 v[96:99], v[150:153], v[182:185], v[96:99]
	v_mfma_f32_16x16x32_bf16 v[88:91], v[158:161], v[182:185], v[88:91]
	v_mfma_f32_16x16x32_bf16 v[80:83], v[150:153], v[202:205], v[80:83]
	v_mfma_f32_16x16x32_bf16 v[72:75], v[158:161], v[202:205], v[72:75]
	s_setprio 0
	s_barrier
	s_add_i32 s38, 0, 0x1c000
	s_add_i32 s39, s82, s45
	v_add_u32_e32 v145, s38, v143
	v_lshl_add_u64 v[190:191], v[190:191], 0, s[78:79]
	s_mov_b32 m0, s39
	ds_read_b128 v[206:209], v145
	ds_read_b128 v[210:213], v145 offset:1024
	ds_read_b128 v[214:217], v145 offset:2048
	ds_read_b128 v[230:233], v145 offset:3072
	global_load_lds_dwordx4 v[190:191], off
	v_lshl_add_u64 v[190:191], v[234:235], 0, s[78:79]
	s_add_i32 m0, s39, 0x2000
	s_nop 0
	global_load_lds_dwordx4 v[190:191], off
	s_barrier
	s_waitcnt lgkmcnt(0)
	s_setprio 1
	s_waitcnt lgkmcnt(0)
	v_mfma_f32_16x16x32_bf16 v[124:127], v[206:209], v[162:165], v[124:127]
	v_mfma_f32_16x16x32_bf16 v[116:119], v[214:217], v[162:165], v[116:119]
	v_mfma_f32_16x16x32_bf16 v[108:111], v[206:209], v[170:173], v[108:111]
	v_mfma_f32_16x16x32_bf16 v[100:103], v[214:217], v[170:173], v[100:103]
	v_mfma_f32_16x16x32_bf16 v[92:95], v[206:209], v[178:181], v[92:95]
	v_mfma_f32_16x16x32_bf16 v[84:87], v[214:217], v[178:181], v[84:87]
	v_mfma_f32_16x16x32_bf16 v[76:79], v[206:209], v[186:189], v[76:79]
	v_mfma_f32_16x16x32_bf16 v[68:71], v[214:217], v[186:189], v[68:71]
	v_mfma_f32_16x16x32_bf16 v[124:127], v[210:213], v[166:169], v[124:127]
	v_mfma_f32_16x16x32_bf16 v[116:119], v[230:233], v[166:169], v[116:119]
	v_mfma_f32_16x16x32_bf16 v[108:111], v[210:213], v[174:177], v[108:111]
	v_mfma_f32_16x16x32_bf16 v[100:103], v[230:233], v[174:177], v[100:103]
	v_mfma_f32_16x16x32_bf16 v[92:95], v[210:213], v[182:185], v[92:95]
	v_mfma_f32_16x16x32_bf16 v[84:87], v[230:233], v[182:185], v[84:87]
	v_mfma_f32_16x16x32_bf16 v[76:79], v[210:213], v[202:205], v[76:79]
	v_mfma_f32_16x16x32_bf16 v[68:71], v[230:233], v[202:205], v[68:71]
	s_setprio 0
	s_mov_b32 m0, s52
	v_lshl_add_u64 v[190:191], v[236:237], 0, s[78:79]
	s_barrier
	ds_read_b128 v[162:165], v144 offset:49152
	ds_read_b128 v[166:169], v144 offset:50176
	ds_read_b128 v[170:173], v144 offset:51200
	ds_read_b128 v[174:177], v144 offset:52224
	ds_read_b128 v[178:181], v144 offset:53248
	ds_read_b128 v[182:185], v144 offset:54272
	ds_read_b128 v[186:189], v144 offset:55296
	ds_read_b128 v[202:205], v144 offset:56320
	global_load_lds_dwordx4 v[190:191], off
	v_lshl_add_u64 v[190:191], v[238:239], 0, s[78:79]
	s_mov_b32 m0, s53
	s_nop 0
	global_load_lds_dwordx4 v[190:191], off
	s_barrier
; DI u32x4 pack44(f32x4 a, f32x4 b) { u32x4 w; w.x = pk2(a[0], a[1]); w.y = pk2(a[2], a[3]); w.z = pk2(b[0], b[1]); w.w = pk2(b[2], b[3]); return w; }
; DI float siluf_(float x) { return x / (1.f + __expf(-x)); }
; #define PG8_STAGE(bufoff, gbase, voff) do { _Pragma("unroll") for (int _i = 0; _i < 2; ++_i) \
;         __builtin_amdgcn_global_load_lds((const unsigned*)((const char*)(gbase) + (voff)[_i]), (LAS unsigned*)(lds + (bufoff) + ldsw + _i * 8192), 16, 0, 0); } while (0)
; #define PG8_MMA(ai, bj, At, Bt) do { __builtin_amdgcn_s_setprio(1); _Pragma("unroll") for (int m = 0; m < 4; ++m) _Pragma("unroll") for (int n = 0; n < 2; ++n) _Pragma("unroll") for (int k = 0; k < 2; ++k) \
;         acc[ai][bj][m][n] = __builtin_amdgcn_mfma_f32_16x16x32_bf16(Bt[n][k], At[m][k], acc[ai][bj][m][n], 0, 0, 0); __builtin_amdgcn_s_setprio(0); } while (0)
; #define PG8_WAIT_V(n) asm volatile("s_waitcnt vmcnt(" #n ")" ::: "memory")
; #define PG8_WAIT_L(n) asm volatile("s_waitcnt lgkmcnt(" #n ")" ::: "memory")
; #define PG8_BAR __builtin_amdgcn_s_barrier()
; #define PG8_SCHED __builtin_amdgcn_sched_barrier(0)
; template <class Epi, class Sched>
; DI void gemm_phase(LAS unsigned char* lds, const Gemm g, const Sched& S, const Epi& E) {
;     ...
;             PG8_BAR; PG8_WAIT_L(0); PG8_MMA(1, 0, At, B0); PG8_BAR; PG8_SCHED;
;             PG8_STAGE(PG8_SB(1, 1), b3 + hstepB, voffB);
;             PG8_WAIT_V(6); PG8_BAR; PG8_MMA(1, 1, At, B1); PG8_BAR;
;     DI void operator()(const Acc& acc, const Unit& u, int wr, int wc, int fr, int fq) const {
;     ...
;         for (int ai = 0; ai < 2; ++ai)
; #pragma unroll
;             for (int m = 0; m < 4; ++m) { const int row = u.pm * 256 + ai * 128 + wr * 64 + m * 16 + fr;
;                 f32x4 g0 = acc[ai][0][m][0], g1 = acc[ai][0][m][1]; const f32x4 u0 = acc[ai][1][m][0], u1 = acc[ai][1][m][1];
;                 for (int j = 0; j < 4; ++j) { g0[j] = siluf_(g0[j]) * u0[j]; g1[j] = siluf_(g1[j]) * u1[j]; }
;                 *(u32x4*)(a + (size_t)row * FH + u.pn * 128 + wc * 32 + 8 * fq) = pack44(g0, g1); }
	s_waitcnt lgkmcnt(0)
	s_setprio 1
	s_waitcnt lgkmcnt(0)
	v_mfma_f32_16x16x32_bf16 v[64:67], v[146:149], v[162:165], v[64:67]
	v_mfma_f32_16x16x32_bf16 v[56:59], v[154:157], v[162:165], v[56:59]
	v_mfma_f32_16x16x32_bf16 v[48:51], v[146:149], v[170:173], v[48:51]
	v_mfma_f32_16x16x32_bf16 v[40:43], v[154:157], v[170:173], v[40:43]
	v_mfma_f32_16x16x32_bf16 v[32:35], v[146:149], v[178:181], v[32:35]
	v_mfma_f32_16x16x32_bf16 v[24:27], v[154:157], v[178:181], v[24:27]
	v_mfma_f32_16x16x32_bf16 v[16:19], v[146:149], v[186:189], v[16:19]
	v_mfma_f32_16x16x32_bf16 v[8:11], v[154:157], v[186:189], v[8:11]
	v_mfma_f32_16x16x32_bf16 v[64:67], v[150:153], v[166:169], v[64:67]
	v_mfma_f32_16x16x32_bf16 v[56:59], v[158:161], v[166:169], v[56:59]
	v_mfma_f32_16x16x32_bf16 v[48:51], v[150:153], v[174:177], v[48:51]
	v_mfma_f32_16x16x32_bf16 v[40:43], v[158:161], v[174:177], v[40:43]
	v_mfma_f32_16x16x32_bf16 v[32:35], v[150:153], v[182:185], v[32:35]
	v_mfma_f32_16x16x32_bf16 v[24:27], v[158:161], v[182:185], v[24:27]
	v_mfma_f32_16x16x32_bf16 v[16:19], v[150:153], v[202:205], v[16:19]
	v_mfma_f32_16x16x32_bf16 v[8:11], v[158:161], v[202:205], v[8:11]
	s_setprio 0
	s_barrier
	s_add_u32 s2, s2, 0x80080
	s_addc_u32 s3, s3, 0
	s_add_i32 s38, s38, s45
	v_lshl_add_u64 v[146:147], s[2:3], 0, v[134:135]
	s_mov_b32 m0, s38
	s_nop 0
	global_load_lds_dwordx4 v[146:147], off
	v_lshl_add_u64 v[146:147], s[2:3], 0, v[0:1]
	s_add_i32 m0, s38, 0x2000
	s_nop 0
	global_load_lds_dwordx4 v[146:147], off
	s_waitcnt vmcnt(6)
	s_barrier
	s_setprio 1
	v_mfma_f32_16x16x32_bf16 v[60:63], v[206:209], v[162:165], v[60:63]
	v_mfma_f32_16x16x32_bf16 v[52:55], v[214:217], v[162:165], v[52:55]
	v_mfma_f32_16x16x32_bf16 v[44:47], v[206:209], v[170:173], v[44:47]
	v_mfma_f32_16x16x32_bf16 v[36:39], v[214:217], v[170:173], v[36:39]
	v_mfma_f32_16x16x32_bf16 v[28:31], v[206:209], v[178:181], v[28:31]
	v_mfma_f32_16x16x32_bf16 v[20:23], v[214:217], v[178:181], v[20:23]
	v_mfma_f32_16x16x32_bf16 v[12:15], v[206:209], v[186:189], v[12:15]
	v_mfma_f32_16x16x32_bf16 v[4:7], v[214:217], v[186:189], v[4:7]
	v_mfma_f32_16x16x32_bf16 v[60:63], v[210:213], v[166:169], v[60:63]
	v_mfma_f32_16x16x32_bf16 v[52:55], v[230:233], v[166:169], v[52:55]
	v_mfma_f32_16x16x32_bf16 v[44:47], v[210:213], v[174:177], v[44:47]
	v_mfma_f32_16x16x32_bf16 v[36:39], v[230:233], v[174:177], v[36:39]
	v_mfma_f32_16x16x32_bf16 v[28:31], v[210:213], v[182:185], v[28:31]
	v_mfma_f32_16x16x32_bf16 v[20:23], v[230:233], v[182:185], v[20:23]
	v_mfma_f32_16x16x32_bf16 v[12:15], v[210:213], v[202:205], v[12:15]
	v_mfma_f32_16x16x32_bf16 v[4:7], v[230:233], v[202:205], v[4:7]
	s_setprio 0
	s_add_i32 s65, s65, 2
	s_add_u32 s20, s20, 0x100
	s_addc_u32 s21, s21, 0
	s_add_u32 s61, s61, 0x100
	s_addc_u32 s64, s64, 0
	s_cmp_gt_u32 s65, 29
	s_barrier
	s_cbranch_scc0 .LBB0_47
	v_mul_f32_e32 v147, 0xbfb8aa3b, v120
	v_mul_f32_e32 v146, 0xbfb8aa3b, v128
	v_exp_f32_e32 v148, v147
	v_mul_f32_e32 v147, 0xbfb8aa3b, v129
	v_exp_f32_e32 v146, v146
	v_exp_f32_e32 v147, v147
	s_lshl_b32 s2, s55, 7
	v_lshl_add_u32 v145, s58, 8, v142
	s_ashr_i32 s3, s2, 31
	v_pk_add_f32 v[146:147], v[146:147], 1.0 op_sel_hi:[1,0]
	s_movk_i32 s27, 0x2c00
	v_rcp_f32_e32 v150, v147
	s_nop 0
	s_lshl_b64 s[38:39], s[2:3], 1
	s_mov_b32 s55, s26
	s_mov_b32 s58, s30
	v_mul_f32_e32 v152, v129, v150
	v_fma_f32 v153, -v147, v152, v129
	v_fmac_f32_e32 v152, v153, v150
	v_div_fixup_f32 v129, v152, v147, v129
	v_rcp_f32_e32 v149, v146
	s_nop 0
	v_mul_f32_e32 v151, v128, v149
	v_fma_f32 v152, -v146, v151, v128
	v_fmac_f32_e32 v151, v152, v149
	v_div_fixup_f32 v128, v151, v146, v128
	v_pk_mul_f32 v[124:125], v[128:129], v[124:125]
	v_mul_f32_e32 v128, 0xbfb8aa3b, v121
	v_exp_f32_e32 v149, v128
	s_nop 0
	v_pk_add_f32 v[128:129], v[148:149], 1.0 op_sel_hi:[1,0]
	s_nop 0
	v_rcp_f32_e32 v147, v129
	s_nop 0
	v_mul_f32_e32 v149, v121, v147
	v_fma_f32 v150, -v129, v149, v121
	v_fmac_f32_e32 v149, v150, v147
	v_div_fixup_f32 v121, v149, v129, v121
	v_rcp_f32_e32 v146, v128
	s_nop 0
	v_mul_f32_e32 v148, v120, v146
	v_fma_f32 v149, -v128, v148, v120
	v_fmac_f32_e32 v148, v149, v146
	v_div_fixup_f32 v120, v148, v128, v120
	v_pk_mul_f32 v[116:117], v[120:121], v[116:117]
	v_mul_f32_e32 v121, 0xbfb8aa3b, v122
	v_mul_f32_e32 v120, 0xbfb8aa3b, v130
	v_exp_f32_e32 v128, v121
	v_mul_f32_e32 v121, 0xbfb8aa3b, v131
	v_exp_f32_e32 v120, v120
	v_exp_f32_e32 v121, v121
	s_nop 0
	v_pk_add_f32 v[120:121], v[120:121], 1.0 op_sel_hi:[1,0]
	s_nop 0
	v_rcp_f32_e32 v146, v121
	s_nop 0
	v_mul_f32_e32 v148, v131, v146
	v_fma_f32 v149, -v121, v148, v131
	v_fmac_f32_e32 v148, v149, v146
	v_div_fixup_f32 v121, v148, v121, v131
	v_rcp_f32_e32 v131, v120
	s_nop 0
	v_mul_f32_e32 v147, v130, v131
	v_fma_f32 v148, -v120, v147, v130
	v_fmac_f32_e32 v147, v148, v131
	v_div_fixup_f32 v120, v147, v120, v130
	v_pk_mul_f32 v[120:121], v[120:121], v[126:127]
	v_mul_f32_e32 v126, 0xbfb8aa3b, v123
	v_exp_f32_e32 v129, v126
	s_nop 0
	v_pk_add_f32 v[126:127], v[128:129], 1.0 op_sel_hi:[1,0]
	s_nop 0
	v_rcp_f32_e32 v129, v127
	s_nop 0
	v_mul_f32_e32 v131, v123, v129
	v_fma_f32 v146, -v127, v131, v123
	v_fmac_f32_e32 v131, v146, v129
	v_div_fixup_f32 v123, v131, v127, v123
	v_rcp_f32_e32 v128, v126
	s_nop 0
	v_mul_f32_e32 v130, v122, v128
	v_fma_f32 v131, -v126, v130, v122
	v_fmac_f32_e32 v130, v131, v128
	v_div_fixup_f32 v122, v130, v126, v122
	v_pk_mul_f32 v[122:123], v[122:123], v[118:119]
	v_cvt_pk_bf16_f32 v119, v120, v121
	v_cvt_pk_bf16_f32 v120, v116, v117
	v_mov_b64_e32 v[116:117], s[24:25]
	v_cvt_pk_bf16_f32 v121, v122, v123
	v_mad_i64_i32 v[122:123], s[20:21], v145, s27, v[116:117]
	v_lshl_add_u64 v[122:123], v[122:123], 0, s[38:39]
; DI u32x4 pack44(f32x4 a, f32x4 b) { u32x4 w; w.x = pk2(a[0], a[1]); w.y = pk2(a[2], a[3]); w.z = pk2(b[0], b[1]); w.w = pk2(b[2], b[3]); return w; }
; DI float siluf_(float x) { return x / (1.f + __expf(-x)); }
;     DI void operator()(const Acc& acc, const Unit& u, int wr, int wc, int fr, int fq) const {
;     ...
;         for (int ai = 0; ai < 2; ++ai)
; #pragma unroll
;             for (int m = 0; m < 4; ++m) { const int row = u.pm * 256 + ai * 128 + wr * 64 + m * 16 + fr;
;                 f32x4 g0 = acc[ai][0][m][0], g1 = acc[ai][0][m][1]; const f32x4 u0 = acc[ai][1][m][0], u1 = acc[ai][1][m][1];
;                 for (int j = 0; j < 4; ++j) { g0[j] = siluf_(g0[j]) * u0[j]; g1[j] = siluf_(g1[j]) * u1[j]; }
;                 *(u32x4*)(a + (size_t)row * FH + u.pn * 128 + wc * 32 + 8 * fq) = pack44(g0, g1); }
	v_lshl_add_u64 v[122:123], v[122:123], 0, s[56:57]
	v_cvt_pk_bf16_f32 v118, v124, v125
	v_lshl_add_u64 v[122:123], v[122:123], 0, v[2:3]
	global_store_dwordx4 v[122:123], v[118:121], off
	s_mov_b64 s[20:21], s[34:35]
	s_nop 0
	v_mul_f32_e32 v119, 0xbfb8aa3b, v104
	v_mul_f32_e32 v118, 0xbfb8aa3b, v112
	v_exp_f32_e32 v120, v119
	v_mul_f32_e32 v119, 0xbfb8aa3b, v113
	v_exp_f32_e32 v118, v118
	v_exp_f32_e32 v119, v119
	s_nop 0
	v_pk_add_f32 v[118:119], v[118:119], 1.0 op_sel_hi:[1,0]
	s_nop 0
	v_rcp_f32_e32 v122, v119
	s_nop 0
	v_mul_f32_e32 v124, v113, v122
	v_fma_f32 v125, -v119, v124, v113
	v_fmac_f32_e32 v124, v125, v122
	v_div_fixup_f32 v113, v124, v119, v113
	v_rcp_f32_e32 v121, v118
	s_nop 0
	v_mul_f32_e32 v123, v112, v121
	v_fma_f32 v124, -v118, v123, v112
	v_fmac_f32_e32 v123, v124, v121
	v_div_fixup_f32 v112, v123, v118, v112
	v_pk_mul_f32 v[108:109], v[112:113], v[108:109]
	v_mul_f32_e32 v112, 0xbfb8aa3b, v105
	v_exp_f32_e32 v121, v112
	s_nop 0
	v_pk_add_f32 v[112:113], v[120:121], 1.0 op_sel_hi:[1,0]
	s_nop 0
	v_rcp_f32_e32 v119, v113
	s_nop 0
	v_mul_f32_e32 v121, v105, v119
	v_fma_f32 v122, -v113, v121, v105
	v_fmac_f32_e32 v121, v122, v119
	v_div_fixup_f32 v105, v121, v113, v105
	v_rcp_f32_e32 v118, v112
	s_nop 0
	v_mul_f32_e32 v120, v104, v118
	v_fma_f32 v121, -v112, v120, v104
	v_fmac_f32_e32 v120, v121, v118
	v_div_fixup_f32 v104, v120, v112, v104
	v_pk_mul_f32 v[104:105], v[104:105], v[100:101]
	v_mul_f32_e32 v101, 0xbfb8aa3b, v106
	v_mul_f32_e32 v100, 0xbfb8aa3b, v114
	v_exp_f32_e32 v112, v101
	v_mul_f32_e32 v101, 0xbfb8aa3b, v115
	v_exp_f32_e32 v100, v100
	v_exp_f32_e32 v101, v101
	s_nop 0
	v_pk_add_f32 v[100:101], v[100:101], 1.0 op_sel_hi:[1,0]
	s_nop 0
	v_rcp_f32_e32 v118, v101
	s_nop 0
	v_mul_f32_e32 v120, v115, v118
	v_fma_f32 v121, -v101, v120, v115
	v_fmac_f32_e32 v120, v121, v118
	v_div_fixup_f32 v101, v120, v101, v115
	v_rcp_f32_e32 v115, v100
	s_nop 0
	v_mul_f32_e32 v119, v114, v115
	v_fma_f32 v120, -v100, v119, v114
	v_fmac_f32_e32 v119, v120, v115
	v_div_fixup_f32 v100, v119, v100, v114
	v_pk_mul_f32 v[110:111], v[100:101], v[110:111]
	v_mul_f32_e32 v100, 0xbfb8aa3b, v107
	v_exp_f32_e32 v113, v100
	s_nop 0
	v_pk_add_f32 v[100:101], v[112:113], 1.0 op_sel_hi:[1,0]
	s_nop 0
	v_rcp_f32_e32 v113, v101
	s_nop 0
	v_mul_f32_e32 v115, v107, v113
	v_fma_f32 v118, -v101, v115, v107
	v_fmac_f32_e32 v115, v118, v113
	v_div_fixup_f32 v101, v115, v101, v107
	v_rcp_f32_e32 v112, v100
	s_nop 0
	v_mul_f32_e32 v114, v106, v112
	v_fma_f32 v115, -v100, v114, v106
	v_fmac_f32_e32 v114, v115, v112
	v_div_fixup_f32 v100, v114, v100, v106
	v_or_b32_e32 v112, 16, v145
	v_pk_mul_f32 v[106:107], v[100:101], v[102:103]
	v_cvt_pk_bf16_f32 v102, v104, v105
	v_mad_i64_i32 v[104:105], s[2:3], v112, s27, v[116:117]
	v_lshl_add_u64 v[104:105], v[104:105], 0, s[38:39]
	v_lshl_add_u64 v[104:105], v[104:105], 0, s[56:57]
	v_cvt_pk_bf16_f32 v100, v108, v109
	v_cvt_pk_bf16_f32 v101, v110, v111
	v_cvt_pk_bf16_f32 v103, v106, v107
	v_lshl_add_u64 v[104:105], v[104:105], 0, v[2:3]
	global_store_dwordx4 v[104:105], v[100:103], off
	s_nop 1
	v_mul_f32_e32 v101, 0xbfb8aa3b, v88
	v_mul_f32_e32 v100, 0xbfb8aa3b, v96
	v_exp_f32_e32 v102, v101
	v_mul_f32_e32 v101, 0xbfb8aa3b, v97
	v_exp_f32_e32 v100, v100
	v_exp_f32_e32 v101, v101
	s_nop 0
	v_pk_add_f32 v[100:101], v[100:101], 1.0 op_sel_hi:[1,0]
	s_nop 0
	v_rcp_f32_e32 v104, v101
	s_nop 0
	v_mul_f32_e32 v106, v97, v104
	v_fma_f32 v107, -v101, v106, v97
	v_fmac_f32_e32 v106, v107, v104
	v_div_fixup_f32 v97, v106, v101, v97
	v_rcp_f32_e32 v103, v100
	s_nop 0
	v_mul_f32_e32 v105, v96, v103
	v_fma_f32 v106, -v100, v105, v96
	v_fmac_f32_e32 v105, v106, v103
	v_div_fixup_f32 v96, v105, v100, v96
	v_pk_mul_f32 v[92:93], v[96:97], v[92:93]
	v_mul_f32_e32 v96, 0xbfb8aa3b, v89
	v_exp_f32_e32 v103, v96
	s_nop 0
	v_pk_add_f32 v[96:97], v[102:103], 1.0 op_sel_hi:[1,0]
	s_nop 0
	v_rcp_f32_e32 v101, v97
	s_nop 0
	v_mul_f32_e32 v103, v89, v101
	v_fma_f32 v104, -v97, v103, v89
	v_fmac_f32_e32 v103, v104, v101
	v_div_fixup_f32 v89, v103, v97, v89
	v_rcp_f32_e32 v100, v96
	s_nop 0
	v_mul_f32_e32 v102, v88, v100
	v_fma_f32 v103, -v96, v102, v88
	v_fmac_f32_e32 v102, v103, v100
	v_div_fixup_f32 v88, v102, v96, v88
	v_pk_mul_f32 v[88:89], v[88:89], v[84:85]
	v_mul_f32_e32 v85, 0xbfb8aa3b, v90
	v_mul_f32_e32 v84, 0xbfb8aa3b, v98
	v_exp_f32_e32 v96, v85
	v_mul_f32_e32 v85, 0xbfb8aa3b, v99
	v_exp_f32_e32 v84, v84
	v_exp_f32_e32 v85, v85
	s_nop 0
	v_pk_add_f32 v[84:85], v[84:85], 1.0 op_sel_hi:[1,0]
	s_nop 0
	v_rcp_f32_e32 v100, v85
	s_nop 0
	v_mul_f32_e32 v102, v99, v100
	v_fma_f32 v103, -v85, v102, v99
	v_fmac_f32_e32 v102, v103, v100
	v_div_fixup_f32 v85, v102, v85, v99
	v_rcp_f32_e32 v99, v84
	s_nop 0
	v_mul_f32_e32 v101, v98, v99
	v_fma_f32 v102, -v84, v101, v98
	v_fmac_f32_e32 v101, v102, v99
	v_div_fixup_f32 v84, v101, v84, v98
	v_pk_mul_f32 v[94:95], v[84:85], v[94:95]
	v_mul_f32_e32 v84, 0xbfb8aa3b, v91
	v_exp_f32_e32 v97, v84
	s_nop 0
	v_pk_add_f32 v[84:85], v[96:97], 1.0 op_sel_hi:[1,0]
	s_nop 0
	v_rcp_f32_e32 v97, v85
	s_nop 0
	v_mul_f32_e32 v99, v91, v97
	v_fma_f32 v100, -v85, v99, v91
	v_fmac_f32_e32 v99, v100, v97
	v_div_fixup_f32 v85, v99, v85, v91
	v_rcp_f32_e32 v96, v84
	s_nop 0
	v_mul_f32_e32 v98, v90, v96
	v_fma_f32 v99, -v84, v98, v90
	v_fmac_f32_e32 v98, v99, v96
	v_div_fixup_f32 v84, v98, v84, v90
	v_or_b32_e32 v96, 32, v145
	v_pk_mul_f32 v[90:91], v[84:85], v[86:87]
	v_cvt_pk_bf16_f32 v86, v88, v89
	v_mad_i64_i32 v[88:89], s[2:3], v96, s27, v[116:117]
	v_lshl_add_u64 v[88:89], v[88:89], 0, s[38:39]
	v_lshl_add_u64 v[88:89], v[88:89], 0, s[56:57]
	v_cvt_pk_bf16_f32 v84, v92, v93
	v_cvt_pk_bf16_f32 v85, v94, v95
; DI u32x4 pack44(f32x4 a, f32x4 b) { u32x4 w; w.x = pk2(a[0], a[1]); w.y = pk2(a[2], a[3]); w.z = pk2(b[0], b[1]); w.w = pk2(b[2], b[3]); return w; }
; DI float siluf_(float x) { return x / (1.f + __expf(-x)); }
;     DI void operator()(const Acc& acc, const Unit& u, int wr, int wc, int fr, int fq) const {
;     ...
;         for (int ai = 0; ai < 2; ++ai)
; #pragma unroll
;             for (int m = 0; m < 4; ++m) { const int row = u.pm * 256 + ai * 128 + wr * 64 + m * 16 + fr;
;                 f32x4 g0 = acc[ai][0][m][0], g1 = acc[ai][0][m][1]; const f32x4 u0 = acc[ai][1][m][0], u1 = acc[ai][1][m][1];
;                 for (int j = 0; j < 4; ++j) { g0[j] = siluf_(g0[j]) * u0[j]; g1[j] = siluf_(g1[j]) * u1[j]; }
;                 *(u32x4*)(a + (size_t)row * FH + u.pn * 128 + wc * 32 + 8 * fq) = pack44(g0, g1); }
	v_cvt_pk_bf16_f32 v87, v90, v91
	v_lshl_add_u64 v[88:89], v[88:89], 0, v[2:3]
	global_store_dwordx4 v[88:89], v[84:87], off
	s_nop 1
	v_mul_f32_e32 v85, 0xbfb8aa3b, v72
	v_mul_f32_e32 v84, 0xbfb8aa3b, v80
	v_exp_f32_e32 v86, v85
	v_mul_f32_e32 v85, 0xbfb8aa3b, v81
	v_exp_f32_e32 v84, v84
	v_exp_f32_e32 v85, v85
	s_nop 0
	v_pk_add_f32 v[84:85], v[84:85], 1.0 op_sel_hi:[1,0]
	s_nop 0
	v_rcp_f32_e32 v88, v85
	s_nop 0
	v_mul_f32_e32 v90, v81, v88
	v_fma_f32 v91, -v85, v90, v81
	v_fmac_f32_e32 v90, v91, v88
	v_div_fixup_f32 v81, v90, v85, v81
	v_rcp_f32_e32 v87, v84
	s_nop 0
	v_mul_f32_e32 v89, v80, v87
	v_fma_f32 v90, -v84, v89, v80
	v_fmac_f32_e32 v89, v90, v87
	v_div_fixup_f32 v80, v89, v84, v80
	v_pk_mul_f32 v[76:77], v[80:81], v[76:77]
	v_mul_f32_e32 v80, 0xbfb8aa3b, v73
	v_exp_f32_e32 v87, v80
	s_nop 0
	v_pk_add_f32 v[80:81], v[86:87], 1.0 op_sel_hi:[1,0]
	s_nop 0
	v_rcp_f32_e32 v85, v81
	s_nop 0
	v_mul_f32_e32 v87, v73, v85
	v_fma_f32 v88, -v81, v87, v73
	v_fmac_f32_e32 v87, v88, v85
	v_div_fixup_f32 v73, v87, v81, v73
	v_rcp_f32_e32 v84, v80
	s_nop 0
	v_mul_f32_e32 v86, v72, v84
	v_fma_f32 v87, -v80, v86, v72
	v_fmac_f32_e32 v86, v87, v84
	v_div_fixup_f32 v72, v86, v80, v72
	v_pk_mul_f32 v[72:73], v[72:73], v[68:69]
	v_mul_f32_e32 v69, 0xbfb8aa3b, v74
	v_mul_f32_e32 v68, 0xbfb8aa3b, v82
	v_exp_f32_e32 v80, v69
	v_mul_f32_e32 v69, 0xbfb8aa3b, v83
	v_exp_f32_e32 v68, v68
	v_exp_f32_e32 v69, v69
	s_nop 0
	v_pk_add_f32 v[68:69], v[68:69], 1.0 op_sel_hi:[1,0]
	s_nop 0
	v_rcp_f32_e32 v84, v69
	s_nop 0
	v_mul_f32_e32 v86, v83, v84
	v_fma_f32 v87, -v69, v86, v83
	v_fmac_f32_e32 v86, v87, v84
	v_div_fixup_f32 v69, v86, v69, v83
	v_rcp_f32_e32 v83, v68
	s_nop 0
	v_mul_f32_e32 v85, v82, v83
	v_fma_f32 v86, -v68, v85, v82
	v_fmac_f32_e32 v85, v86, v83
	v_div_fixup_f32 v68, v85, v68, v82
	v_pk_mul_f32 v[78:79], v[68:69], v[78:79]
	v_mul_f32_e32 v68, 0xbfb8aa3b, v75
	v_exp_f32_e32 v81, v68
	s_nop 0
	v_pk_add_f32 v[68:69], v[80:81], 1.0 op_sel_hi:[1,0]
	s_nop 0
	v_rcp_f32_e32 v81, v69
	s_nop 0
	v_mul_f32_e32 v83, v75, v81
	v_fma_f32 v84, -v69, v83, v75
	v_fmac_f32_e32 v83, v84, v81
	v_div_fixup_f32 v69, v83, v69, v75
	v_rcp_f32_e32 v80, v68
	s_nop 0
	v_mul_f32_e32 v82, v74, v80
	v_fma_f32 v83, -v68, v82, v74
	v_fmac_f32_e32 v82, v83, v80
	v_div_fixup_f32 v68, v82, v68, v74
	v_or_b32_e32 v80, 48, v145
	v_pk_mul_f32 v[74:75], v[68:69], v[70:71]
	v_cvt_pk_bf16_f32 v70, v72, v73
	v_mad_i64_i32 v[72:73], s[2:3], v80, s27, v[116:117]
	v_lshl_add_u64 v[72:73], v[72:73], 0, s[38:39]
	v_lshl_add_u64 v[72:73], v[72:73], 0, s[56:57]
	v_cvt_pk_bf16_f32 v68, v76, v77
	v_cvt_pk_bf16_f32 v69, v78, v79
	v_cvt_pk_bf16_f32 v71, v74, v75
	v_lshl_add_u64 v[72:73], v[72:73], 0, v[2:3]
	global_store_dwordx4 v[72:73], v[68:71], off
	v_add_u32_e32 v72, 0x80, v145
	s_nop 0
	v_mul_f32_e32 v69, 0xbfb8aa3b, v56
	v_mul_f32_e32 v68, 0xbfb8aa3b, v64
	v_exp_f32_e32 v70, v69
	v_mul_f32_e32 v69, 0xbfb8aa3b, v65
	v_exp_f32_e32 v68, v68
	v_exp_f32_e32 v69, v69
	s_nop 0
	v_pk_add_f32 v[68:69], v[68:69], 1.0 op_sel_hi:[1,0]
	s_nop 0
	v_rcp_f32_e32 v73, v69
	s_nop 0
	v_mul_f32_e32 v75, v65, v73
	v_fma_f32 v76, -v69, v75, v65
	v_fmac_f32_e32 v75, v76, v73
	v_div_fixup_f32 v65, v75, v69, v65
	v_rcp_f32_e32 v71, v68
	s_nop 0
	v_mul_f32_e32 v74, v64, v71
	v_fma_f32 v75, -v68, v74, v64
	v_fmac_f32_e32 v74, v75, v71
	v_div_fixup_f32 v64, v74, v68, v64
	v_pk_mul_f32 v[60:61], v[64:65], v[60:61]
	v_mul_f32_e32 v64, 0xbfb8aa3b, v57
	v_exp_f32_e32 v71, v64
	s_nop 0
	v_pk_add_f32 v[64:65], v[70:71], 1.0 op_sel_hi:[1,0]
	s_nop 0
	v_rcp_f32_e32 v69, v65
	s_nop 0
	v_mul_f32_e32 v71, v57, v69
	v_fma_f32 v73, -v65, v71, v57
	v_fmac_f32_e32 v71, v73, v69
	v_div_fixup_f32 v57, v71, v65, v57
	v_rcp_f32_e32 v68, v64
	s_nop 0
	v_mul_f32_e32 v70, v56, v68
	v_fma_f32 v71, -v64, v70, v56
	v_fmac_f32_e32 v70, v71, v68
	v_div_fixup_f32 v56, v70, v64, v56
	v_pk_mul_f32 v[56:57], v[56:57], v[52:53]
	v_mul_f32_e32 v53, 0xbfb8aa3b, v58
	v_mul_f32_e32 v52, 0xbfb8aa3b, v66
	v_exp_f32_e32 v64, v53
	v_mul_f32_e32 v53, 0xbfb8aa3b, v67
	v_exp_f32_e32 v52, v52
	v_exp_f32_e32 v53, v53
	s_nop 0
	v_pk_add_f32 v[52:53], v[52:53], 1.0 op_sel_hi:[1,0]
	s_nop 0
	v_rcp_f32_e32 v68, v53
	s_nop 0
	v_mul_f32_e32 v70, v67, v68
	v_fma_f32 v71, -v53, v70, v67
	v_fmac_f32_e32 v70, v71, v68
	v_div_fixup_f32 v53, v70, v53, v67
	v_rcp_f32_e32 v67, v52
	s_nop 0
	v_mul_f32_e32 v69, v66, v67
	v_fma_f32 v70, -v52, v69, v66
	v_fmac_f32_e32 v69, v70, v67
	v_div_fixup_f32 v52, v69, v52, v66
	v_pk_mul_f32 v[62:63], v[52:53], v[62:63]
	v_mul_f32_e32 v52, 0xbfb8aa3b, v59
	v_exp_f32_e32 v65, v52
	s_nop 0
	v_pk_add_f32 v[52:53], v[64:65], 1.0 op_sel_hi:[1,0]
	s_nop 0
	v_rcp_f32_e32 v65, v53
	s_nop 0
	v_mul_f32_e32 v67, v59, v65
	v_fma_f32 v68, -v53, v67, v59
	v_fmac_f32_e32 v67, v68, v65
	v_div_fixup_f32 v53, v67, v53, v59
	v_rcp_f32_e32 v64, v52
	s_nop 0
	v_mul_f32_e32 v66, v58, v64
	v_fma_f32 v67, -v52, v66, v58
	v_fmac_f32_e32 v66, v67, v64
	v_div_fixup_f32 v52, v66, v52, v58
	v_pk_mul_f32 v[58:59], v[52:53], v[54:55]
	v_cvt_pk_bf16_f32 v54, v56, v57
	v_mad_i64_i32 v[56:57], s[2:3], v72, s27, v[116:117]
	v_lshl_add_u64 v[56:57], v[56:57], 0, s[38:39]
	v_lshl_add_u64 v[56:57], v[56:57], 0, s[56:57]
	v_cvt_pk_bf16_f32 v52, v60, v61
	v_cvt_pk_bf16_f32 v53, v62, v63
	v_cvt_pk_bf16_f32 v55, v58, v59
	v_lshl_add_u64 v[56:57], v[56:57], 0, v[2:3]
	global_store_dwordx4 v[56:57], v[52:55], off
	s_nop 1
	v_mul_f32_e32 v53, 0xbfb8aa3b, v40
	v_mul_f32_e32 v52, 0xbfb8aa3b, v48
	v_exp_f32_e32 v54, v53
	v_mul_f32_e32 v53, 0xbfb8aa3b, v49
	v_exp_f32_e32 v52, v52
	v_exp_f32_e32 v53, v53
	s_nop 0
	v_pk_add_f32 v[52:53], v[52:53], 1.0 op_sel_hi:[1,0]
	s_nop 0
; DI u32x4 pack44(f32x4 a, f32x4 b) { u32x4 w; w.x = pk2(a[0], a[1]); w.y = pk2(a[2], a[3]); w.z = pk2(b[0], b[1]); w.w = pk2(b[2], b[3]); return w; }
; DI float siluf_(float x) { return x / (1.f + __expf(-x)); }
;     DI void operator()(const Acc& acc, const Unit& u, int wr, int wc, int fr, int fq) const {
;     ...
;         for (int ai = 0; ai < 2; ++ai)
; #pragma unroll
;             for (int m = 0; m < 4; ++m) { const int row = u.pm * 256 + ai * 128 + wr * 64 + m * 16 + fr;
;                 f32x4 g0 = acc[ai][0][m][0], g1 = acc[ai][0][m][1]; const f32x4 u0 = acc[ai][1][m][0], u1 = acc[ai][1][m][1];
;                 for (int j = 0; j < 4; ++j) { g0[j] = siluf_(g0[j]) * u0[j]; g1[j] = siluf_(g1[j]) * u1[j]; }
;                 *(u32x4*)(a + (size_t)row * FH + u.pn * 128 + wc * 32 + 8 * fq) = pack44(g0, g1); }
	v_rcp_f32_e32 v56, v53
	s_nop 0
	v_mul_f32_e32 v58, v49, v56
	v_fma_f32 v59, -v53, v58, v49
	v_fmac_f32_e32 v58, v59, v56
	v_div_fixup_f32 v49, v58, v53, v49
	v_rcp_f32_e32 v55, v52
	s_nop 0
	v_mul_f32_e32 v57, v48, v55
	v_fma_f32 v58, -v52, v57, v48
	v_fmac_f32_e32 v57, v58, v55
	v_div_fixup_f32 v48, v57, v52, v48
	v_pk_mul_f32 v[44:45], v[48:49], v[44:45]
	v_mul_f32_e32 v48, 0xbfb8aa3b, v41
	v_exp_f32_e32 v55, v48
	s_nop 0
	v_pk_add_f32 v[48:49], v[54:55], 1.0 op_sel_hi:[1,0]
	s_nop 0
	v_rcp_f32_e32 v53, v49
	s_nop 0
	v_mul_f32_e32 v55, v41, v53
	v_fma_f32 v56, -v49, v55, v41
	v_fmac_f32_e32 v55, v56, v53
	v_div_fixup_f32 v41, v55, v49, v41
	v_rcp_f32_e32 v52, v48
	s_nop 0
	v_mul_f32_e32 v54, v40, v52
	v_fma_f32 v55, -v48, v54, v40
	v_fmac_f32_e32 v54, v55, v52
	v_div_fixup_f32 v40, v54, v48, v40
	v_pk_mul_f32 v[40:41], v[40:41], v[36:37]
	v_mul_f32_e32 v37, 0xbfb8aa3b, v42
	v_mul_f32_e32 v36, 0xbfb8aa3b, v50
	v_exp_f32_e32 v48, v37
	v_mul_f32_e32 v37, 0xbfb8aa3b, v51
	v_exp_f32_e32 v36, v36
	v_exp_f32_e32 v37, v37
	s_nop 0
	v_pk_add_f32 v[36:37], v[36:37], 1.0 op_sel_hi:[1,0]
	s_nop 0
	v_rcp_f32_e32 v52, v37
	s_nop 0
	v_mul_f32_e32 v54, v51, v52
	v_fma_f32 v55, -v37, v54, v51
	v_fmac_f32_e32 v54, v55, v52
	v_div_fixup_f32 v37, v54, v37, v51
	v_rcp_f32_e32 v51, v36
	s_nop 0
	v_mul_f32_e32 v53, v50, v51
	v_fma_f32 v54, -v36, v53, v50
	v_fmac_f32_e32 v53, v54, v51
	v_div_fixup_f32 v36, v53, v36, v50
	v_pk_mul_f32 v[46:47], v[36:37], v[46:47]
	v_mul_f32_e32 v36, 0xbfb8aa3b, v43
	v_exp_f32_e32 v49, v36
	s_nop 0
	v_pk_add_f32 v[36:37], v[48:49], 1.0 op_sel_hi:[1,0]
	s_nop 0
	v_rcp_f32_e32 v49, v37
	s_nop 0
	v_mul_f32_e32 v51, v43, v49
	v_fma_f32 v52, -v37, v51, v43
	v_fmac_f32_e32 v51, v52, v49
	v_div_fixup_f32 v37, v51, v37, v43
	v_rcp_f32_e32 v48, v36
	s_nop 0
	v_mul_f32_e32 v50, v42, v48
	v_fma_f32 v51, -v36, v50, v42
	v_fmac_f32_e32 v50, v51, v48
	v_div_fixup_f32 v36, v50, v36, v42
	v_add_u32_e32 v48, 0x90, v145
	v_pk_mul_f32 v[42:43], v[36:37], v[38:39]
	v_cvt_pk_bf16_f32 v38, v40, v41
	v_mad_i64_i32 v[40:41], s[2:3], v48, s27, v[116:117]
	v_lshl_add_u64 v[40:41], v[40:41], 0, s[38:39]
	v_lshl_add_u64 v[40:41], v[40:41], 0, s[56:57]
	v_cvt_pk_bf16_f32 v36, v44, v45
	v_cvt_pk_bf16_f32 v37, v46, v47
	v_cvt_pk_bf16_f32 v39, v42, v43
	v_lshl_add_u64 v[40:41], v[40:41], 0, v[2:3]
	global_store_dwordx4 v[40:41], v[36:39], off
	s_nop 1
	v_mul_f32_e32 v37, 0xbfb8aa3b, v24
	v_mul_f32_e32 v36, 0xbfb8aa3b, v32
	v_exp_f32_e32 v38, v37
	v_mul_f32_e32 v37, 0xbfb8aa3b, v33
	v_exp_f32_e32 v36, v36
	v_exp_f32_e32 v37, v37
	s_nop 0
	v_pk_add_f32 v[36:37], v[36:37], 1.0 op_sel_hi:[1,0]
	s_nop 0
	v_rcp_f32_e32 v40, v37
	s_nop 0
	v_mul_f32_e32 v42, v33, v40
	v_fma_f32 v43, -v37, v42, v33
	v_fmac_f32_e32 v42, v43, v40
	v_div_fixup_f32 v33, v42, v37, v33
	v_rcp_f32_e32 v39, v36
	s_nop 0
	v_mul_f32_e32 v41, v32, v39
	v_fma_f32 v42, -v36, v41, v32
	v_fmac_f32_e32 v41, v42, v39
	v_div_fixup_f32 v32, v41, v36, v32
	v_pk_mul_f32 v[28:29], v[32:33], v[28:29]
	v_mul_f32_e32 v32, 0xbfb8aa3b, v25
	v_exp_f32_e32 v39, v32
	s_nop 0
	v_pk_add_f32 v[32:33], v[38:39], 1.0 op_sel_hi:[1,0]
	s_nop 0
	v_rcp_f32_e32 v37, v33
	s_nop 0
	v_mul_f32_e32 v39, v25, v37
	v_fma_f32 v40, -v33, v39, v25
	v_fmac_f32_e32 v39, v40, v37
	v_div_fixup_f32 v25, v39, v33, v25
	v_rcp_f32_e32 v36, v32
	s_nop 0
	v_mul_f32_e32 v38, v24, v36
	v_fma_f32 v39, -v32, v38, v24
	v_fmac_f32_e32 v38, v39, v36
	v_div_fixup_f32 v24, v38, v32, v24
	v_pk_mul_f32 v[24:25], v[24:25], v[20:21]
	v_mul_f32_e32 v21, 0xbfb8aa3b, v26
	v_mul_f32_e32 v20, 0xbfb8aa3b, v34
	v_exp_f32_e32 v32, v21
	v_mul_f32_e32 v21, 0xbfb8aa3b, v35
	v_exp_f32_e32 v20, v20
	v_exp_f32_e32 v21, v21
	s_nop 0
	v_pk_add_f32 v[20:21], v[20:21], 1.0 op_sel_hi:[1,0]
	s_nop 0
	v_rcp_f32_e32 v36, v21
	s_nop 0
	v_mul_f32_e32 v38, v35, v36
	v_fma_f32 v39, -v21, v38, v35
	v_fmac_f32_e32 v38, v39, v36
; DI u32x4 pack44(f32x4 a, f32x4 b) { u32x4 w; w.x = pk2(a[0], a[1]); w.y = pk2(a[2], a[3]); w.z = pk2(b[0], b[1]); w.w = pk2(b[2], b[3]); return w; }
; DI float siluf_(float x) { return x / (1.f + __expf(-x)); }
; #define PG8_WAIT_V(n) asm volatile("s_waitcnt vmcnt(" #n ")" ::: "memory")
; #define PG8_BAR __builtin_amdgcn_s_barrier()
; template <class Epi, class Sched>
; DI void gemm_phase(LAS unsigned char* lds, const Gemm g, const Sched& S, const Epi& E) {
;     ...
;         if (!has_next) break;
; #pragma unroll
;         for (int a = 0; a < 2; ++a)
; #pragma unroll
;             for (int b = 0; b < 2; ++b)
; #pragma unroll
;                 for (int m = 0; m < 4; ++m)
; #pragma unroll
;                     for (int n = 0; n < 2; ++n) acc[a][b][m][n] = (f32x4){0.f, 0.f, 0.f, 0.f};
;         cur = nxt; cA = nA; cB = nB; ++ui;
;     }
;     PG8_WAIT_V(0);
;     if (wr == 0) PG8_BAR;
;     PG8_BAR;
;     DI void operator()(const Acc& acc, const Unit& u, int wr, int wc, int fr, int fq) const {
;     ...
;         for (int ai = 0; ai < 2; ++ai)
; #pragma unroll
;             for (int m = 0; m < 4; ++m) { const int row = u.pm * 256 + ai * 128 + wr * 64 + m * 16 + fr;
;                 f32x4 g0 = acc[ai][0][m][0], g1 = acc[ai][0][m][1]; const f32x4 u0 = acc[ai][1][m][0], u1 = acc[ai][1][m][1];
;                 for (int j = 0; j < 4; ++j) { g0[j] = siluf_(g0[j]) * u0[j]; g1[j] = siluf_(g1[j]) * u1[j]; }
;                 *(u32x4*)(a + (size_t)row * FH + u.pn * 128 + wc * 32 + 8 * fq) = pack44(g0, g1); }
	v_div_fixup_f32 v21, v38, v21, v35
	v_rcp_f32_e32 v35, v20
	s_nop 0
	v_mul_f32_e32 v37, v34, v35
	v_fma_f32 v38, -v20, v37, v34
	v_fmac_f32_e32 v37, v38, v35
	v_div_fixup_f32 v20, v37, v20, v34
	v_pk_mul_f32 v[30:31], v[20:21], v[30:31]
	v_mul_f32_e32 v20, 0xbfb8aa3b, v27
	v_exp_f32_e32 v33, v20
	s_nop 0
	v_pk_add_f32 v[20:21], v[32:33], 1.0 op_sel_hi:[1,0]
	s_nop 0
	v_rcp_f32_e32 v33, v21
	s_nop 0
	v_mul_f32_e32 v35, v27, v33
	v_fma_f32 v36, -v21, v35, v27
	v_fmac_f32_e32 v35, v36, v33
	v_div_fixup_f32 v21, v35, v21, v27
	v_rcp_f32_e32 v32, v20
	s_nop 0
	v_mul_f32_e32 v34, v26, v32
	v_fma_f32 v35, -v20, v34, v26
	v_fmac_f32_e32 v34, v35, v32
	v_div_fixup_f32 v20, v34, v20, v26
	v_add_u32_e32 v32, 0xa0, v145
	v_pk_mul_f32 v[26:27], v[20:21], v[22:23]
	v_cvt_pk_bf16_f32 v22, v24, v25
	v_mad_i64_i32 v[24:25], s[2:3], v32, s27, v[116:117]
	v_lshl_add_u64 v[24:25], v[24:25], 0, s[38:39]
	v_lshl_add_u64 v[24:25], v[24:25], 0, s[56:57]
	v_cvt_pk_bf16_f32 v20, v28, v29
	v_cvt_pk_bf16_f32 v21, v30, v31
	v_cvt_pk_bf16_f32 v23, v26, v27
	v_lshl_add_u64 v[24:25], v[24:25], 0, v[2:3]
	global_store_dwordx4 v[24:25], v[20:23], off
	s_nop 1
	v_mul_f32_e32 v21, 0xbfb8aa3b, v8
	v_mul_f32_e32 v20, 0xbfb8aa3b, v16
	v_exp_f32_e32 v22, v21
	v_mul_f32_e32 v21, 0xbfb8aa3b, v17
	v_exp_f32_e32 v20, v20
	v_exp_f32_e32 v21, v21
	s_nop 0
	v_pk_add_f32 v[20:21], v[20:21], 1.0 op_sel_hi:[1,0]
	s_nop 0
	v_rcp_f32_e32 v24, v21
	s_nop 0
	v_mul_f32_e32 v26, v17, v24
	v_fma_f32 v27, -v21, v26, v17
	v_fmac_f32_e32 v26, v27, v24
	v_div_fixup_f32 v17, v26, v21, v17
	v_rcp_f32_e32 v23, v20
	s_nop 0
	v_mul_f32_e32 v25, v16, v23
	v_fma_f32 v26, -v20, v25, v16
	v_fmac_f32_e32 v25, v26, v23
	v_div_fixup_f32 v16, v25, v20, v16
	v_pk_mul_f32 v[12:13], v[16:17], v[12:13]
	v_mul_f32_e32 v16, 0xbfb8aa3b, v9
	v_exp_f32_e32 v23, v16
	s_nop 0
	v_pk_add_f32 v[16:17], v[22:23], 1.0 op_sel_hi:[1,0]
	s_nop 0
	v_rcp_f32_e32 v21, v17
	s_nop 0
	v_mul_f32_e32 v23, v9, v21
	v_fma_f32 v24, -v17, v23, v9
	v_fmac_f32_e32 v23, v24, v21
	v_div_fixup_f32 v9, v23, v17, v9
	v_rcp_f32_e32 v20, v16
	s_nop 0
	v_mul_f32_e32 v22, v8, v20
	v_fma_f32 v23, -v16, v22, v8
	v_fmac_f32_e32 v22, v23, v20
	v_div_fixup_f32 v8, v22, v16, v8
	v_pk_mul_f32 v[8:9], v[8:9], v[4:5]
	v_mul_f32_e32 v5, 0xbfb8aa3b, v10
	v_mul_f32_e32 v4, 0xbfb8aa3b, v18
	v_exp_f32_e32 v16, v5
	v_mul_f32_e32 v5, 0xbfb8aa3b, v19
	v_exp_f32_e32 v4, v4
	v_exp_f32_e32 v5, v5
	s_nop 0
	v_pk_add_f32 v[4:5], v[4:5], 1.0 op_sel_hi:[1,0]
	s_nop 0
	v_rcp_f32_e32 v20, v5
	s_nop 0
	v_mul_f32_e32 v22, v19, v20
	v_fma_f32 v23, -v5, v22, v19
	v_fmac_f32_e32 v22, v23, v20
	v_div_fixup_f32 v5, v22, v5, v19
	v_rcp_f32_e32 v19, v4
	s_nop 0
	v_mul_f32_e32 v21, v18, v19
	v_fma_f32 v22, -v4, v21, v18
	v_fmac_f32_e32 v21, v22, v19
	v_div_fixup_f32 v4, v21, v4, v18
	v_pk_mul_f32 v[14:15], v[4:5], v[14:15]
	v_mul_f32_e32 v4, 0xbfb8aa3b, v11
	v_exp_f32_e32 v17, v4
	s_nop 0
	v_pk_add_f32 v[4:5], v[16:17], 1.0 op_sel_hi:[1,0]
	s_nop 0
	v_rcp_f32_e32 v17, v5
	s_nop 0
	v_mul_f32_e32 v19, v11, v17
	v_fma_f32 v20, -v5, v19, v11
	v_fmac_f32_e32 v19, v20, v17
	v_div_fixup_f32 v5, v19, v5, v11
	v_rcp_f32_e32 v16, v4
	s_nop 0
	v_mul_f32_e32 v18, v10, v16
	v_fma_f32 v19, -v4, v18, v10
	v_fmac_f32_e32 v18, v19, v16
	v_div_fixup_f32 v4, v18, v4, v10
	v_add_u32_e32 v16, 0xb0, v145
	v_pk_mul_f32 v[10:11], v[4:5], v[6:7]
	v_cvt_pk_bf16_f32 v6, v8, v9
	v_mad_i64_i32 v[8:9], s[2:3], v16, s27, v[116:117]
	v_lshl_add_u64 v[8:9], v[8:9], 0, s[38:39]
	v_lshl_add_u64 v[8:9], v[8:9], 0, s[56:57]
	v_cvt_pk_bf16_f32 v4, v12, v13
	v_cvt_pk_bf16_f32 v5, v14, v15
	v_cvt_pk_bf16_f32 v7, v10, v11
	v_lshl_add_u64 v[8:9], v[8:9], 0, v[2:3]
	s_and_b64 vcc, exec, s[22:23]
	s_mov_b64 s[2:3], s[36:37]
	global_store_dwordx4 v[8:9], v[4:7], off
	s_cbranch_vccz .LBB0_44
	s_waitcnt vmcnt(0)
	s_cmpk_gt_u32 s42, 0xff
	s_cbranch_scc1 .LBB0_51
	s_barrier

; DI int TID() { int t = __builtin_amdgcn_workitem_id_x(); asm volatile("" : "+v"(t)); return t; }
; DI void unpack8(u32x4 w, float* f) { f[0] = bflo(w.x); f[1] = bfhi(w.x); f[2] = bflo(w.y); f[3] = bfhi(w.y); f[4] = bflo(w.z); f[5] = bfhi(w.z); f[6] = bflo(w.w); f[7] = bfhi(w.w); }
; DI u32x4 pack8(const float* f) { u32x4 w; w.x = pk2(f[0], f[1]); w.y = pk2(f[2], f[3]); w.z = pk2(f[4], f[5]); w.w = pk2(f[6], f[7]); return w; }
; DI float siluf_(float x) { return x / (1.f + __expf(-x)); }
; DI void phase_normgate(PP p, int l, int nblk, int bid) {
;     ...
;     for (int grp0 = bid * 128 + (TID() >> 4); grp0 < L * 8; grp0 += nblk * 128) {
;         u32x4 ov[4], zv[4];
; #pragma unroll
;         for (int q = 0; q < 4; ++q) { const int grp = grp0 + 32 * q; const size_t base = (size_t)(grp >> 3) * 1024 + (grp & 7) * 128 + o8 * 8;
;             ov[q] = *(const u32x4*)(obf + base); zv[q] = *(const u32x4*)(z + base); }
; #pragma unroll
;         for (int q = 0; q < 4; ++q) { const int grp = grp0 + 32 * q; const size_t base = (size_t)(grp >> 3) * 1024 + (grp & 7) * 128 + o8 * 8;
;             float o[8], zz[8]; unpack8(ov[q], o); unpack8(zv[q], zz);
;             float ss = 0.f;
; #pragma unroll
;             for (int i = 0; i < 8; ++i) ss += o[i] * o[i];
;             ss += __shfl_xor(ss, 1); ss += __shfl_xor(ss, 2); ss += __shfl_xor(ss, 4); ss += __shfl_xor(ss, 8);
;             const float sc = rsqrtf(ss * (1.f / 128.f) + 1e-6f);
; #pragma unroll
;             for (int i = 0; i < 4; ++i) { o[i] = o[i] * sc * w0[i] * siluf_(zz[i]); o[4 + i] = o[4 + i] * sc * w1[i] * siluf_(zz[4 + i]); }
;             *(u32x4*)(obf + base) = pack8(o); }
.LBB0_98:
	v_and_b32_e32 v2, 0x380, v74
	v_ashrrev_i32_e32 v12, 3, v69
	v_or_b32_e32 v14, v2, v68
	v_ashrrev_i32_e32 v13, 31, v12
	v_lshlrev_b32_e32 v16, 1, v14
	v_lshlrev_b64 v[52:53], 11, v[12:13]
	v_or_b32_e32 v12, v52, v16
	v_mov_b32_e32 v13, v53
	v_lshl_add_u64 v[14:15], s[26:27], 0, v[12:13]
	v_lshl_add_u64 v[12:13], s[30:31], 0, v[12:13]
	global_load_dwordx4 v[36:39], v[14:15], off
	global_load_dwordx4 v[40:43], v[12:13], off
	v_lshlrev_b32_e32 v2, 1, v2
	v_lshl_add_u64 v[46:47], v[0:1], 0, v[2:3]
	v_add_u32_e32 v12, 32, v69
	v_ashrrev_i32_e32 v12, 3, v12
	v_ashrrev_i32_e32 v13, 31, v12
	v_lshlrev_b64 v[50:51], 11, v[12:13]
	v_or_b32_e32 v12, v50, v16
	v_mov_b32_e32 v13, v51
	v_lshl_add_u64 v[14:15], s[26:27], 0, v[12:13]
	v_lshl_add_u64 v[12:13], s[30:31], 0, v[12:13]
	global_load_dwordx4 v[28:31], v[14:15], off
	global_load_dwordx4 v[32:35], v[12:13], off
	v_add_u32_e32 v12, 64, v69
	v_ashrrev_i32_e32 v12, 3, v12
	v_ashrrev_i32_e32 v13, 31, v12
	v_lshlrev_b64 v[48:49], 11, v[12:13]
	v_or_b32_e32 v12, v48, v16
	v_mov_b32_e32 v13, v49
	v_lshl_add_u64 v[14:15], s[26:27], 0, v[12:13]
	v_lshl_add_u64 v[12:13], s[30:31], 0, v[12:13]
	global_load_dwordx4 v[20:23], v[14:15], off
	global_load_dwordx4 v[24:27], v[12:13], off
	v_add_u32_e32 v12, 0x60, v69
	v_ashrrev_i32_e32 v12, 3, v12
	v_ashrrev_i32_e32 v13, 31, v12
	v_lshlrev_b64 v[44:45], 11, v[12:13]
	v_or_b32_e32 v16, v44, v16
	v_mov_b32_e32 v17, v45
	v_lshl_add_u64 v[12:13], s[26:27], 0, v[16:17]
	v_lshl_add_u64 v[16:17], s[30:31], 0, v[16:17]
	v_lshl_add_u64 v[52:53], v[46:47], 0, v[52:53]
	global_load_dwordx4 v[12:15], v[12:13], off
	v_lshl_add_u64 v[48:49], v[46:47], 0, v[48:49]
	global_load_dwordx4 v[16:19], v[16:17], off
	v_add_u32_e32 v69, s20, v69
	v_add_u32_e32 v74, s21, v74
	s_waitcnt vmcnt(0)
	v_lshlrev_b32_e32 v54, 16, v39
	v_lshlrev_b32_e32 v2, 16, v43
	v_and_b32_e32 v75, 0xffff0000, v43
	v_lshlrev_b32_e32 v43, 16, v42
	v_and_b32_e32 v42, 0xffff0000, v42
	v_and_b32_e32 v55, 0xffff0000, v39
	v_lshlrev_b32_e32 v56, 16, v38
	v_and_b32_e32 v57, 0xffff0000, v38
	v_mul_f32_e32 v38, 0xbfb8aa3b, v43
	v_mul_f32_e32 v39, 0xbfb8aa3b, v42
	v_exp_f32_e32 v38, v38
	v_exp_f32_e32 v39, v39
	v_pk_mul_f32 v[60:61], v[56:57], v[56:57]
	v_and_b32_e32 v82, 0xffff0000, v34
	v_and_b32_e32 v94, 0xffff0000, v35
	v_pk_add_f32 v[38:39], v[38:39], 1.0 op_sel_hi:[1,0]
	v_pk_mul_f32 v[58:59], v[54:55], v[54:55]
	v_rcp_f32_e32 v63, v39
	s_nop 0
	v_mul_f32_e32 v65, v42, v63
	v_fma_f32 v66, -v39, v65, v42
	v_fmac_f32_e32 v65, v66, v63
	v_div_fixup_f32 v39, v65, v39, v42
	v_rcp_f32_e32 v62, v38
	s_nop 0
	v_mul_f32_e32 v64, v43, v62
	v_fma_f32 v65, -v38, v64, v43
	v_fmac_f32_e32 v64, v65, v62
	v_div_fixup_f32 v38, v64, v38, v43
	v_mul_f32_e32 v42, 0xbfb8aa3b, v2
	v_exp_f32_e32 v76, v42
	v_lshlrev_b32_e32 v42, 16, v37
	v_and_b32_e32 v43, 0xffff0000, v37
	v_lshlrev_b32_e32 v37, 16, v41
	v_and_b32_e32 v41, 0xffff0000, v41
	v_mul_f32_e32 v62, 0xbfb8aa3b, v37
	v_mul_f32_e32 v63, 0xbfb8aa3b, v41
	v_exp_f32_e32 v62, v62
	v_exp_f32_e32 v63, v63
	v_pk_mul_f32 v[66:67], v[42:43], v[42:43]
	v_pk_add_f32 v[62:63], v[62:63], 1.0 op_sel_hi:[1,0]
	s_nop 0
	v_rcp_f32_e32 v65, v63
	s_nop 0
	v_mul_f32_e32 v78, v41, v65
	v_fma_f32 v79, -v63, v78, v41
	v_fmac_f32_e32 v78, v79, v65
	v_div_fixup_f32 v63, v78, v63, v41
	v_rcp_f32_e32 v64, v62
	s_nop 0
	v_mul_f32_e32 v77, v37, v64
	v_fma_f32 v78, -v62, v77, v37
	v_fmac_f32_e32 v77, v78, v64
	v_div_fixup_f32 v62, v77, v62, v37
	v_lshlrev_b32_e32 v41, 16, v40
	v_and_b32_e32 v40, 0xffff0000, v40
	v_lshlrev_b32_e32 v64, 16, v36
	v_and_b32_e32 v65, 0xffff0000, v36
	v_mul_f32_e32 v36, 0xbfb8aa3b, v41
	v_mul_f32_e32 v37, 0xbfb8aa3b, v40
	v_exp_f32_e32 v36, v36
	v_exp_f32_e32 v37, v37
	s_nop 0
	v_pk_add_f32 v[36:37], v[36:37], 1.0 op_sel_hi:[1,0]
	s_nop 0
	v_rcp_f32_e32 v78, v37
	s_nop 0
	v_mul_f32_e32 v80, v40, v78
	v_fma_f32 v81, -v37, v80, v40
	v_fmac_f32_e32 v80, v81, v78
	v_div_fixup_f32 v37, v80, v37, v40
	v_rcp_f32_e32 v77, v36
	s_nop 0
	v_and_b32_e32 v81, 0xffff0000, v30
	v_mul_f32_e32 v79, v41, v77
	v_fma_f32 v80, -v36, v79, v41
	v_fmac_f32_e32 v79, v80, v77
	v_div_fixup_f32 v36, v79, v36, v41
	v_mul_f32_e32 v40, 0xbfb8aa3b, v75
	v_exp_f32_e32 v77, v40
	s_nop 0
	v_pk_add_f32 v[40:41], v[76:77], 1.0 op_sel_hi:[1,0]
	s_nop 0
	v_rcp_f32_e32 v77, v41
	s_nop 0
	v_mul_f32_e32 v79, v75, v77
	v_fma_f32 v80, -v41, v79, v75
	v_fmac_f32_e32 v79, v80, v77
	v_div_fixup_f32 v41, v79, v41, v75
	v_rcp_f32_e32 v76, v40
	s_nop 0
	v_lshlrev_b32_e32 v80, 16, v30
	v_mul_f32_e32 v78, v2, v76
	v_fma_f32 v79, -v40, v78, v2
	v_fmac_f32_e32 v78, v79, v76
	v_div_fixup_f32 v40, v78, v40, v2
	v_lshlrev_b32_e32 v2, 16, v34
	v_lshlrev_b32_e32 v75, 16, v35
	v_mul_f32_e32 v34, 0xbfb8aa3b, v2
	v_mul_f32_e32 v35, 0xbfb8aa3b, v82
	v_exp_f32_e32 v34, v34
	v_exp_f32_e32 v35, v35
	v_lshlrev_b32_e32 v76, 16, v31
	v_and_b32_e32 v77, 0xffff0000, v31
	v_pk_mul_f32 v[30:31], v[80:81], v[80:81]
	v_pk_add_f32 v[34:35], v[34:35], 1.0 op_sel_hi:[1,0]
	v_pk_mul_f32 v[78:79], v[76:77], v[76:77]
	v_rcp_f32_e32 v84, v35
	s_nop 0
	v_mul_f32_e32 v86, v82, v84
	v_fma_f32 v87, -v35, v86, v82
	v_fmac_f32_e32 v86, v87, v84
	v_div_fixup_f32 v35, v86, v35, v82
	v_rcp_f32_e32 v83, v34
	s_nop 0
	v_mul_f32_e32 v85, v2, v83
	v_fma_f32 v86, -v34, v85, v2
	v_fmac_f32_e32 v85, v86, v83
	v_div_fixup_f32 v34, v85, v34, v2
	v_mul_f32_e32 v2, 0xbfb8aa3b, v75
	v_exp_f32_e32 v82, v2
	v_lshlrev_b32_e32 v2, 16, v33
	v_lshlrev_b32_e32 v84, 16, v29
	v_and_b32_e32 v85, 0xffff0000, v29
	v_and_b32_e32 v29, 0xffff0000, v33
	v_mul_f32_e32 v33, 0xbfb8aa3b, v2
	v_exp_f32_e32 v88, v33
	v_mul_f32_e32 v33, 0xbfb8aa3b, v29
	v_exp_f32_e32 v89, v33
; DI void unpack8(u32x4 w, float* f) { f[0] = bflo(w.x); f[1] = bfhi(w.x); f[2] = bflo(w.y); f[3] = bfhi(w.y); f[4] = bflo(w.z); f[5] = bfhi(w.z); f[6] = bflo(w.w); f[7] = bfhi(w.w); }
; DI u32x4 pack8(const float* f) { u32x4 w; w.x = pk2(f[0], f[1]); w.y = pk2(f[2], f[3]); w.z = pk2(f[4], f[5]); w.w = pk2(f[6], f[7]); return w; }
; DI float siluf_(float x) { return x / (1.f + __expf(-x)); }
; DI void phase_normgate(PP p, int l, int nblk, int bid) {
;     ...
;         for (int q = 0; q < 4; ++q) { const int grp = grp0 + 32 * q; const size_t base = (size_t)(grp >> 3) * 1024 + (grp & 7) * 128 + o8 * 8;
;             float o[8], zz[8]; unpack8(ov[q], o); unpack8(zv[q], zz);
;             float ss = 0.f;
; #pragma unroll
;             for (int i = 0; i < 8; ++i) ss += o[i] * o[i];
;             ss += __shfl_xor(ss, 1); ss += __shfl_xor(ss, 2); ss += __shfl_xor(ss, 4); ss += __shfl_xor(ss, 8);
;             const float sc = rsqrtf(ss * (1.f / 128.f) + 1e-6f);
; #pragma unroll
;             for (int i = 0; i < 4; ++i) { o[i] = o[i] * sc * w0[i] * siluf_(zz[i]); o[4 + i] = o[4 + i] * sc * w1[i] * siluf_(zz[4 + i]); }
;             *(u32x4*)(obf + base) = pack8(o); }
	v_pk_mul_f32 v[86:87], v[84:85], v[84:85]
	v_pk_add_f32 v[88:89], v[88:89], 1.0 op_sel_hi:[1,0]
	s_nop 0
	v_rcp_f32_e32 v83, v89
	s_nop 0
	v_mul_f32_e32 v91, v29, v83
	v_fma_f32 v92, -v89, v91, v29
	v_fmac_f32_e32 v91, v92, v83
	v_div_fixup_f32 v89, v91, v89, v29
	v_rcp_f32_e32 v33, v88
	s_nop 0
	v_mul_f32_e32 v90, v2, v33
	v_fma_f32 v91, -v88, v90, v2
	v_fmac_f32_e32 v90, v91, v33
	v_div_fixup_f32 v88, v90, v88, v2
	v_lshlrev_b32_e32 v2, 16, v32
	v_and_b32_e32 v32, 0xffff0000, v32
	v_lshlrev_b32_e32 v90, 16, v28
	v_and_b32_e32 v91, 0xffff0000, v28
	v_mul_f32_e32 v28, 0xbfb8aa3b, v2
	v_mul_f32_e32 v29, 0xbfb8aa3b, v32
	v_exp_f32_e32 v28, v28
	v_exp_f32_e32 v29, v29
	s_nop 0
	v_pk_add_f32 v[28:29], v[28:29], 1.0 op_sel_hi:[1,0]
	s_nop 0
	v_rcp_f32_e32 v83, v29
	s_nop 0
	v_mul_f32_e32 v93, v32, v83
	v_fma_f32 v95, -v29, v93, v32
	v_fmac_f32_e32 v93, v95, v83
	v_div_fixup_f32 v93, v93, v29, v32
	v_div_scale_f32 v29, s[2:3], v28, v28, v2
	v_rcp_f32_e32 v32, v29
	s_mov_b32 s2, 0x358637bd
	v_fma_f32 v33, -v29, v32, 1.0
	v_fmac_f32_e32 v32, v33, v32
	v_div_scale_f32 v33, vcc, v2, v28, v2
	v_mul_f32_e32 v83, v33, v32
	v_fma_f32 v92, -v29, v83, v33
	v_fmac_f32_e32 v83, v92, v32
	v_fma_f32 v29, -v29, v83, v33
	v_div_fmas_f32 v29, v29, v32, v83
	v_mov_b32_e32 v32, v91
	v_mov_b32_e32 v33, v65
	v_div_fixup_f32 v92, v29, v28, v2
	v_mov_b32_e32 v28, v90
	v_mov_b32_e32 v29, v64
	v_pk_mul_f32 v[32:33], v[32:33], v[32:33]
	s_nop 0
	v_pk_fma_f32 v[28:29], v[28:29], v[28:29], v[32:33]
	v_mov_b32_e32 v32, v86
	v_mov_b32_e32 v33, v66
	v_pk_add_f32 v[28:29], v[32:33], v[28:29]
	v_mov_b32_e32 v66, v87
	v_pk_add_f32 v[28:29], v[66:67], v[28:29]
	v_mov_b32_e32 v32, v30
	v_mov_b32_e32 v33, v60
	v_pk_add_f32 v[28:29], v[32:33], v[28:29]
	v_mov_b32_e32 v60, v31
	v_pk_add_f32 v[28:29], v[60:61], v[28:29]
	v_mov_b32_e32 v30, v78
	v_mov_b32_e32 v31, v58
	v_pk_add_f32 v[28:29], v[30:31], v[28:29]
	v_mov_b32_e32 v58, v79
	v_pk_add_f32 v[28:29], v[58:59], v[28:29]
	ds_bpermute_b32 v31, v70, v29
	ds_bpermute_b32 v30, v70, v28
	v_mov_b64_e32 v[32:33], s[2:3]
	s_waitcnt lgkmcnt(0)
	v_pk_add_f32 v[28:29], v[28:29], v[30:31]
	ds_bpermute_b32 v31, v71, v29
	ds_bpermute_b32 v30, v71, v28
	s_waitcnt lgkmcnt(0)
	v_pk_add_f32 v[28:29], v[28:29], v[30:31]
	ds_bpermute_b32 v31, v72, v29
	ds_bpermute_b32 v30, v72, v28
	s_waitcnt lgkmcnt(0)
	v_pk_add_f32 v[28:29], v[28:29], v[30:31]
	ds_bpermute_b32 v31, v73, v29
	ds_bpermute_b32 v30, v73, v28
	s_waitcnt lgkmcnt(0)
	v_pk_add_f32 v[28:29], v[28:29], v[30:31]
	s_nop 0
	v_pk_fma_f32 v[58:59], v[28:29], s[36:37], v[32:33] op_sel_hi:[1,0,0]
	s_nop 0
	v_mul_f32_e32 v2, 0x4b800000, v59
	v_cmp_gt_f32_e64 s[22:23], s10, v59
	v_cmp_gt_f32_e32 vcc, s10, v58
	s_nop 0
	v_cndmask_b32_e64 v2, v59, v2, s[22:23]
	v_rsq_f32_e32 v2, v2
	s_nop 0
	v_mul_f32_e32 v28, 0x45800000, v2
	v_cndmask_b32_e64 v2, v2, v28, s[22:23]
	v_pk_mul_f32 v[28:29], v[2:3], v[64:65] op_sel_hi:[0,1]
	v_pk_mul_f32 v[30:31], v[2:3], v[56:57] op_sel_hi:[0,1]
	v_pk_mul_f32 v[28:29], v[8:9], v[28:29]
	v_pk_mul_f32 v[30:31], v[4:5], v[30:31]
	v_pk_mul_f32 v[28:29], v[36:37], v[28:29]
	v_pk_mul_f32 v[30:31], v[38:39], v[30:31]
	v_pk_mul_f32 v[36:37], v[2:3], v[42:43] op_sel_hi:[0,1]
	v_pk_mul_f32 v[38:39], v[2:3], v[54:55] op_sel_hi:[0,1]
	v_mul_f32_e32 v2, 0x4b800000, v58
	v_cndmask_b32_e32 v2, v58, v2, vcc
	v_rsq_f32_e32 v2, v2
	v_pk_mul_f32 v[36:37], v[10:11], v[36:37]
	v_pk_mul_f32 v[38:39], v[6:7], v[38:39]
	v_pk_mul_f32 v[36:37], v[62:63], v[36:37]
	v_pk_mul_f32 v[38:39], v[40:41], v[38:39]
	v_cvt_pk_bf16_f32 v28, v28, v29
	v_cvt_pk_bf16_f32 v29, v36, v37
	v_cvt_pk_bf16_f32 v30, v30, v31
	v_cvt_pk_bf16_f32 v31, v38, v39
	global_store_dwordx4 v[52:53], v[28:31], off
	v_and_b32_e32 v52, 0xffff0000, v27
	s_nop 0
	v_mul_f32_e32 v28, 0x45800000, v2
	v_cndmask_b32_e32 v2, v2, v28, vcc
	v_pk_mul_f32 v[30:31], v[2:3], v[80:81] op_sel_hi:[0,1]
	v_pk_mul_f32 v[30:31], v[4:5], v[30:31]
	v_pk_mul_f32 v[28:29], v[2:3], v[90:91] op_sel_hi:[0,1]
	v_pk_mul_f32 v[30:31], v[34:35], v[30:31]
	v_pk_mul_f32 v[34:35], v[2:3], v[84:85] op_sel_hi:[0,1]
	v_pk_mul_f32 v[36:37], v[2:3], v[76:77] op_sel_hi:[0,1]
	v_mul_f32_e32 v2, 0xbfb8aa3b, v94
	v_exp_f32_e32 v83, v2
	v_pk_mul_f32 v[28:29], v[8:9], v[28:29]
	v_pk_mul_f32 v[34:35], v[10:11], v[34:35]
	v_pk_mul_f32 v[36:37], v[6:7], v[36:37]
	v_pk_add_f32 v[38:39], v[82:83], 1.0 op_sel_hi:[1,0]
	v_pk_mul_f32 v[28:29], v[92:93], v[28:29]
	v_rcp_f32_e32 v40, v39
	s_nop 0
	v_pk_mul_f32 v[34:35], v[88:89], v[34:35]
	v_cvt_pk_bf16_f32 v28, v28, v29
	v_cvt_pk_bf16_f32 v29, v34, v35
	v_mul_f32_e32 v42, v94, v40
	v_fma_f32 v43, -v39, v42, v94
	v_fmac_f32_e32 v42, v43, v40
	v_div_fixup_f32 v39, v42, v39, v94
	v_rcp_f32_e32 v40, v38
	s_nop 0
	v_cvt_pk_bf16_f32 v30, v30, v31
	v_lshl_add_u64 v[34:35], v[46:47], 0, v[50:51]
	v_and_b32_e32 v76, 0xffff0000, v19
	v_mul_f32_e32 v42, v75, v40
	v_fma_f32 v43, -v38, v42, v75
	v_fmac_f32_e32 v42, v43, v40
	v_div_fixup_f32 v38, v42, v38, v75
	v_pk_mul_f32 v[36:37], v[38:39], v[36:37]
	v_lshlrev_b32_e32 v2, 16, v27
	v_cvt_pk_bf16_f32 v31, v36, v37
	v_lshlrev_b32_e32 v36, 16, v26
	v_and_b32_e32 v37, 0xffff0000, v26
	global_store_dwordx4 v[34:35], v[28:31], off
	v_lshlrev_b32_e32 v75, 16, v19
	s_nop 0
	v_lshlrev_b32_e32 v28, 16, v23
	v_and_b32_e32 v29, 0xffff0000, v23
	v_lshlrev_b32_e32 v30, 16, v22
	v_and_b32_e32 v31, 0xffff0000, v22
	v_mul_f32_e32 v22, 0xbfb8aa3b, v36
	v_mul_f32_e32 v23, 0xbfb8aa3b, v37
	v_exp_f32_e32 v22, v22
	v_exp_f32_e32 v23, v23
	v_pk_mul_f32 v[26:27], v[30:31], v[30:31]
	v_pk_mul_f32 v[34:35], v[28:29], v[28:29]
	v_pk_add_f32 v[22:23], v[22:23], 1.0 op_sel_hi:[1,0]
	s_nop 0
	v_rcp_f32_e32 v39, v23
	s_nop 0
; DI void unpack8(u32x4 w, float* f) { f[0] = bflo(w.x); f[1] = bfhi(w.x); f[2] = bflo(w.y); f[3] = bfhi(w.y); f[4] = bflo(w.z); f[5] = bfhi(w.z); f[6] = bflo(w.w); f[7] = bfhi(w.w); }
; DI u32x4 pack8(const float* f) { u32x4 w; w.x = pk2(f[0], f[1]); w.y = pk2(f[2], f[3]); w.z = pk2(f[4], f[5]); w.w = pk2(f[6], f[7]); return w; }
; DI float siluf_(float x) { return x / (1.f + __expf(-x)); }
; DI void phase_normgate(PP p, int l, int nblk, int bid) {
;     ...
;         for (int q = 0; q < 4; ++q) { const int grp = grp0 + 32 * q; const size_t base = (size_t)(grp >> 3) * 1024 + (grp & 7) * 128 + o8 * 8;
;             float o[8], zz[8]; unpack8(ov[q], o); unpack8(zv[q], zz);
;             float ss = 0.f;
; #pragma unroll
;             for (int i = 0; i < 8; ++i) ss += o[i] * o[i];
;             ss += __shfl_xor(ss, 1); ss += __shfl_xor(ss, 2); ss += __shfl_xor(ss, 4); ss += __shfl_xor(ss, 8);
;             const float sc = rsqrtf(ss * (1.f / 128.f) + 1e-6f);
; #pragma unroll
;             for (int i = 0; i < 4; ++i) { o[i] = o[i] * sc * w0[i] * siluf_(zz[i]); o[4 + i] = o[4 + i] * sc * w1[i] * siluf_(zz[4 + i]); }
;             *(u32x4*)(obf + base) = pack8(o); }
	v_mul_f32_e32 v41, v37, v39
	v_fma_f32 v42, -v23, v41, v37
	v_fmac_f32_e32 v41, v42, v39
	v_div_fixup_f32 v23, v41, v23, v37
	v_rcp_f32_e32 v38, v22
	s_nop 0
	v_mul_f32_e32 v40, v36, v38
	v_fma_f32 v41, -v22, v40, v36
	v_fmac_f32_e32 v40, v41, v38
	v_div_fixup_f32 v22, v40, v22, v36
	v_mul_f32_e32 v36, 0xbfb8aa3b, v2
	v_exp_f32_e32 v50, v36
	v_lshlrev_b32_e32 v36, 16, v21
	v_and_b32_e32 v37, 0xffff0000, v21
	v_lshlrev_b32_e32 v21, 16, v25
	v_and_b32_e32 v25, 0xffff0000, v25
	v_mul_f32_e32 v38, 0xbfb8aa3b, v21
	v_mul_f32_e32 v39, 0xbfb8aa3b, v25
	v_exp_f32_e32 v38, v38
	v_exp_f32_e32 v39, v39
	v_pk_mul_f32 v[42:43], v[36:37], v[36:37]
	v_pk_add_f32 v[38:39], v[38:39], 1.0 op_sel_hi:[1,0]
	s_nop 0
	v_rcp_f32_e32 v41, v39
	s_nop 0
	v_mul_f32_e32 v53, v25, v41
	v_fma_f32 v54, -v39, v53, v25
	v_fmac_f32_e32 v53, v54, v41
	v_div_fixup_f32 v39, v53, v39, v25
	v_rcp_f32_e32 v40, v38
	s_nop 0
	v_mul_f32_e32 v51, v21, v40
	v_fma_f32 v53, -v38, v51, v21
	v_fmac_f32_e32 v51, v53, v40
	v_div_fixup_f32 v38, v51, v38, v21
	v_lshlrev_b32_e32 v25, 16, v24
	v_and_b32_e32 v24, 0xffff0000, v24
	v_lshlrev_b32_e32 v40, 16, v20
	v_and_b32_e32 v41, 0xffff0000, v20
	v_mul_f32_e32 v20, 0xbfb8aa3b, v25
	v_mul_f32_e32 v21, 0xbfb8aa3b, v24
	v_exp_f32_e32 v20, v20
	v_exp_f32_e32 v21, v21
	s_nop 0
	v_pk_add_f32 v[20:21], v[20:21], 1.0 op_sel_hi:[1,0]
	s_nop 0
	v_rcp_f32_e32 v53, v21
	s_nop 0
	v_mul_f32_e32 v55, v24, v53
	v_fma_f32 v56, -v21, v55, v24
	v_fmac_f32_e32 v55, v56, v53
	v_div_fixup_f32 v21, v55, v21, v24
	v_rcp_f32_e32 v51, v20
	s_nop 0
	v_and_b32_e32 v56, 0xffff0000, v18
	v_mul_f32_e32 v19, 0xbfb8aa3b, v56
	v_exp_f32_e32 v19, v19
	v_mul_f32_e32 v54, v25, v51
	v_fma_f32 v55, -v20, v54, v25
	v_fmac_f32_e32 v54, v55, v51
	v_div_fixup_f32 v20, v54, v20, v25
	v_mul_f32_e32 v24, 0xbfb8aa3b, v52
	v_exp_f32_e32 v51, v24
	s_nop 0
	v_pk_add_f32 v[24:25], v[50:51], 1.0 op_sel_hi:[1,0]
	s_nop 0
	v_rcp_f32_e32 v51, v25
	s_nop 0
	v_mul_f32_e32 v54, v52, v51
	v_fma_f32 v55, -v25, v54, v52
	v_fmac_f32_e32 v54, v55, v51
	v_div_fixup_f32 v25, v54, v25, v52
	v_rcp_f32_e32 v51, v24
	s_nop 0
	v_and_b32_e32 v55, 0xffff0000, v14
	v_mul_f32_e32 v53, v2, v51
	v_fma_f32 v54, -v24, v53, v2
	v_fmac_f32_e32 v53, v54, v51
	v_div_fixup_f32 v24, v53, v24, v2
	v_lshlrev_b32_e32 v2, 16, v18
	v_mul_f32_e32 v18, 0xbfb8aa3b, v2
	v_exp_f32_e32 v18, v18
	v_lshlrev_b32_e32 v54, 16, v14
	v_lshlrev_b32_e32 v50, 16, v15
	v_and_b32_e32 v51, 0xffff0000, v15
	v_pk_add_f32 v[18:19], v[18:19], 1.0 op_sel_hi:[1,0]
	v_pk_mul_f32 v[14:15], v[54:55], v[54:55]
	v_rcp_f32_e32 v58, v19
	s_nop 0
	v_pk_mul_f32 v[52:53], v[50:51], v[50:51]
	v_mul_f32_e32 v60, v56, v58
	v_fma_f32 v61, -v19, v60, v56
	v_fmac_f32_e32 v60, v61, v58
	v_div_fixup_f32 v19, v60, v19, v56
	v_rcp_f32_e32 v57, v18
	s_nop 0
	v_mul_f32_e32 v59, v2, v57
	v_fma_f32 v60, -v18, v59, v2
	v_fmac_f32_e32 v59, v60, v57
	v_div_fixup_f32 v18, v59, v18, v2
	v_mul_f32_e32 v2, 0xbfb8aa3b, v75
	v_exp_f32_e32 v56, v2
	v_lshlrev_b32_e32 v2, 16, v17
	v_lshlrev_b32_e32 v58, 16, v13
	v_and_b32_e32 v59, 0xffff0000, v13
	v_and_b32_e32 v13, 0xffff0000, v17
	v_mul_f32_e32 v17, 0xbfb8aa3b, v2
	v_exp_f32_e32 v62, v17
	v_mul_f32_e32 v17, 0xbfb8aa3b, v13
	v_exp_f32_e32 v63, v17
	v_pk_mul_f32 v[60:61], v[58:59], v[58:59]
	v_pk_add_f32 v[62:63], v[62:63], 1.0 op_sel_hi:[1,0]
	s_nop 0
	v_rcp_f32_e32 v57, v63
	s_nop 0
	v_mul_f32_e32 v65, v13, v57
	v_fma_f32 v66, -v63, v65, v13
	v_fmac_f32_e32 v65, v66, v57
	v_div_fixup_f32 v63, v65, v63, v13
	v_rcp_f32_e32 v17, v62
	s_nop 0
	v_mul_f32_e32 v64, v2, v17
	v_fma_f32 v65, -v62, v64, v2
	v_fmac_f32_e32 v64, v65, v17
	v_div_fixup_f32 v62, v64, v62, v2
	v_lshlrev_b32_e32 v2, 16, v16
	v_and_b32_e32 v16, 0xffff0000, v16
	v_lshlrev_b32_e32 v64, 16, v12
	v_and_b32_e32 v65, 0xffff0000, v12
	v_mul_f32_e32 v12, 0xbfb8aa3b, v2
	v_mul_f32_e32 v13, 0xbfb8aa3b, v16
	v_exp_f32_e32 v12, v12
	v_exp_f32_e32 v13, v13
	s_nop 0
	v_pk_add_f32 v[12:13], v[12:13], 1.0 op_sel_hi:[1,0]
	s_nop 0
	v_rcp_f32_e32 v57, v13
	s_nop 0
	v_mul_f32_e32 v67, v16, v57
	v_fma_f32 v77, -v13, v67, v16
	v_fmac_f32_e32 v67, v77, v57
	v_div_fixup_f32 v17, v67, v13, v16
	v_div_scale_f32 v13, s[2:3], v12, v12, v2
	v_rcp_f32_e32 v16, v13
	s_nop 0
	v_fma_f32 v57, -v13, v16, 1.0
	v_fmac_f32_e32 v16, v57, v16
	v_div_scale_f32 v57, vcc, v2, v12, v2
	v_mul_f32_e32 v66, v57, v16
	v_fma_f32 v67, -v13, v66, v57
	v_fmac_f32_e32 v66, v67, v16
	v_fma_f32 v13, -v13, v66, v57
	v_div_fmas_f32 v13, v13, v16, v66
	v_mov_b32_e32 v66, v65
	v_mov_b32_e32 v67, v41
	v_div_fixup_f32 v16, v13, v12, v2
	v_mov_b32_e32 v12, v64
	v_mov_b32_e32 v13, v40
	v_pk_mul_f32 v[66:67], v[66:67], v[66:67]
	s_nop 0
	v_pk_fma_f32 v[12:13], v[12:13], v[12:13], v[66:67]
	v_mov_b32_e32 v66, v60
	v_mov_b32_e32 v67, v42
	v_pk_add_f32 v[12:13], v[66:67], v[12:13]
	v_mov_b32_e32 v42, v61
	v_pk_add_f32 v[12:13], v[42:43], v[12:13]
	v_mov_b32_e32 v42, v14
	v_mov_b32_e32 v43, v26
	v_pk_add_f32 v[12:13], v[42:43], v[12:13]
	v_mov_b32_e32 v26, v15
	v_pk_add_f32 v[12:13], v[26:27], v[12:13]
	v_mov_b32_e32 v14, v52
	v_mov_b32_e32 v15, v34
	v_pk_add_f32 v[12:13], v[14:15], v[12:13]
	v_mov_b32_e32 v34, v53
	v_pk_add_f32 v[12:13], v[34:35], v[12:13]
	ds_bpermute_b32 v15, v70, v13
	ds_bpermute_b32 v14, v70, v12
	s_waitcnt lgkmcnt(0)
; DI int TID() { int t = __builtin_amdgcn_workitem_id_x(); asm volatile("" : "+v"(t)); return t; }
; DI void unpack8(u32x4 w, float* f) { f[0] = bflo(w.x); f[1] = bfhi(w.x); f[2] = bflo(w.y); f[3] = bfhi(w.y); f[4] = bflo(w.z); f[5] = bfhi(w.z); f[6] = bflo(w.w); f[7] = bfhi(w.w); }
; DI u32x4 pack8(const float* f) { u32x4 w; w.x = pk2(f[0], f[1]); w.y = pk2(f[2], f[3]); w.z = pk2(f[4], f[5]); w.w = pk2(f[6], f[7]); return w; }
; DI float siluf_(float x) { return x / (1.f + __expf(-x)); }
; DI void phase_normgate(PP p, int l, int nblk, int bid) {
;     ...
;     for (int grp0 = bid * 128 + (TID() >> 4); grp0 < L * 8; grp0 += nblk * 128) {
;     ...
;         for (int q = 0; q < 4; ++q) { const int grp = grp0 + 32 * q; const size_t base = (size_t)(grp >> 3) * 1024 + (grp & 7) * 128 + o8 * 8;
;             float o[8], zz[8]; unpack8(ov[q], o); unpack8(zv[q], zz);
;             float ss = 0.f;
; #pragma unroll
;             for (int i = 0; i < 8; ++i) ss += o[i] * o[i];
;             ss += __shfl_xor(ss, 1); ss += __shfl_xor(ss, 2); ss += __shfl_xor(ss, 4); ss += __shfl_xor(ss, 8);
;             const float sc = rsqrtf(ss * (1.f / 128.f) + 1e-6f);
; #pragma unroll
;             for (int i = 0; i < 4; ++i) { o[i] = o[i] * sc * w0[i] * siluf_(zz[i]); o[4 + i] = o[4 + i] * sc * w1[i] * siluf_(zz[4 + i]); }
;             *(u32x4*)(obf + base) = pack8(o); }
	v_pk_add_f32 v[12:13], v[12:13], v[14:15]
	ds_bpermute_b32 v15, v71, v13
	ds_bpermute_b32 v14, v71, v12
	s_waitcnt lgkmcnt(0)
	v_pk_add_f32 v[12:13], v[12:13], v[14:15]
	ds_bpermute_b32 v15, v72, v13
	ds_bpermute_b32 v14, v72, v12
	s_waitcnt lgkmcnt(0)
	v_pk_add_f32 v[12:13], v[12:13], v[14:15]
	ds_bpermute_b32 v15, v73, v13
	ds_bpermute_b32 v14, v73, v12
	s_waitcnt lgkmcnt(0)
	v_pk_add_f32 v[12:13], v[12:13], v[14:15]
	s_nop 0
	v_pk_fma_f32 v[26:27], v[12:13], s[36:37], v[32:33] op_sel_hi:[1,0,0]
	s_nop 0
	v_mul_f32_e32 v2, 0x4b800000, v27
	v_cmp_gt_f32_e64 s[22:23], s10, v27
	v_cmp_gt_f32_e32 vcc, s10, v26
	s_nop 0
	v_cndmask_b32_e64 v2, v27, v2, s[22:23]
	v_rsq_f32_e32 v2, v2
	s_nop 0
	v_mul_f32_e32 v12, 0x45800000, v2
	v_cndmask_b32_e64 v2, v2, v12, s[22:23]
	v_pk_mul_f32 v[12:13], v[2:3], v[40:41] op_sel_hi:[0,1]
	v_pk_mul_f32 v[14:15], v[2:3], v[30:31] op_sel_hi:[0,1]
	v_pk_mul_f32 v[12:13], v[8:9], v[12:13]
	v_pk_mul_f32 v[14:15], v[4:5], v[14:15]
	v_pk_mul_f32 v[12:13], v[20:21], v[12:13]
	v_pk_mul_f32 v[14:15], v[22:23], v[14:15]
	v_pk_mul_f32 v[20:21], v[2:3], v[36:37] op_sel_hi:[0,1]
	v_pk_mul_f32 v[22:23], v[2:3], v[28:29] op_sel_hi:[0,1]
	v_mul_f32_e32 v2, 0x4b800000, v26
	v_cndmask_b32_e32 v2, v26, v2, vcc
	v_rsq_f32_e32 v2, v2
	v_pk_mul_f32 v[20:21], v[10:11], v[20:21]
	v_pk_mul_f32 v[22:23], v[6:7], v[22:23]
	v_pk_mul_f32 v[20:21], v[38:39], v[20:21]
	v_pk_mul_f32 v[22:23], v[24:25], v[22:23]
	v_cvt_pk_bf16_f32 v12, v12, v13
	v_cvt_pk_bf16_f32 v13, v20, v21
	v_cvt_pk_bf16_f32 v14, v14, v15
	v_cvt_pk_bf16_f32 v15, v22, v23
	global_store_dwordx4 v[48:49], v[12:15], off
	s_nop 1
	v_mul_f32_e32 v12, 0x45800000, v2
	v_cndmask_b32_e32 v2, v2, v12, vcc
	v_pk_mul_f32 v[12:13], v[2:3], v[64:65] op_sel_hi:[0,1]
	v_pk_mul_f32 v[14:15], v[2:3], v[54:55] op_sel_hi:[0,1]
	v_pk_mul_f32 v[12:13], v[8:9], v[12:13]
	v_pk_mul_f32 v[14:15], v[4:5], v[14:15]
	v_pk_mul_f32 v[12:13], v[16:17], v[12:13]
	v_pk_mul_f32 v[14:15], v[18:19], v[14:15]
	v_pk_mul_f32 v[16:17], v[2:3], v[58:59] op_sel_hi:[0,1]
	v_pk_mul_f32 v[18:19], v[2:3], v[50:51] op_sel_hi:[0,1]
	v_mul_f32_e32 v2, 0xbfb8aa3b, v76
	v_exp_f32_e32 v57, v2
	v_pk_mul_f32 v[16:17], v[10:11], v[16:17]
	v_pk_mul_f32 v[18:19], v[6:7], v[18:19]
	v_pk_mul_f32 v[16:17], v[62:63], v[16:17]
	v_pk_add_f32 v[20:21], v[56:57], 1.0 op_sel_hi:[1,0]
	v_cvt_pk_bf16_f32 v12, v12, v13
	v_rcp_f32_e32 v22, v21
	s_nop 0
	v_cvt_pk_bf16_f32 v13, v16, v17
	v_cvt_pk_bf16_f32 v14, v14, v15
	v_lshl_add_u64 v[16:17], v[46:47], 0, v[44:45]
	v_mul_f32_e32 v24, v76, v22
	v_fma_f32 v25, -v21, v24, v76
	v_fmac_f32_e32 v24, v25, v22
	v_div_fixup_f32 v21, v24, v21, v76
	v_rcp_f32_e32 v22, v20
	s_nop 0
	s_mov_b32 s2, 0x1ffff
	v_mul_f32_e32 v24, v75, v22
	v_fma_f32 v25, -v20, v24, v75
	v_fmac_f32_e32 v24, v25, v22
	v_div_fixup_f32 v20, v24, v20, v75
	v_pk_mul_f32 v[18:19], v[20:21], v[18:19]
	v_cmp_lt_i32_e32 vcc, s2, v69
	v_cvt_pk_bf16_f32 v15, v18, v19
	s_or_b64 s[34:35], vcc, s[34:35]
	global_store_dwordx4 v[16:17], v[12:15], off
	s_andn2_b64 exec, exec, s[34:35]
	s_cbranch_execnz .LBB0_98

; #define PG8_STAGE(bufoff, gbase, voff) do { _Pragma("unroll") for (int _i = 0; _i < 2; ++_i) \
;         __builtin_amdgcn_global_load_lds((const unsigned*)((const char*)(gbase) + (voff)[_i]), (LAS unsigned*)(lds + (bufoff) + ldsw + _i * 8192), 16, 0, 0); } while (0)
; #define PG8_LDA(dst, b, h) do { _Pragma("unroll") for (int m = 0; m < 4; ++m) _Pragma("unroll") for (int k = 0; k < 2; ++k) dst[m][k] = *(const LAS bf16x8*)(lds + PG8_SA(b, h) + aoff + m * 2048 + k * 1024); } while (0)
; #define PG8_LDB(dst, b, h) do { _Pragma("unroll") for (int n = 0; n < 2; ++n) _Pragma("unroll") for (int k = 0; k < 2; ++k) dst[n][k] = *(const LAS bf16x8*)(lds + PG8_SB(b, h) + boff + n * 2048 + k * 1024); } while (0)
; #define PG8_MMA(ai, bj, At, Bt) do { __builtin_amdgcn_s_setprio(1); _Pragma("unroll") for (int m = 0; m < 4; ++m) _Pragma("unroll") for (int n = 0; n < 2; ++n) _Pragma("unroll") for (int k = 0; k < 2; ++k) \
;         acc[ai][bj][m][n] = __builtin_amdgcn_mfma_f32_16x16x32_bf16(Bt[n][k], At[m][k], acc[ai][bj][m][n], 0, 0, 0); __builtin_amdgcn_s_setprio(0); } while (0)
; #define PG8_WAIT_L(n) asm volatile("s_waitcnt lgkmcnt(" #n ")" ::: "memory")
; #define PG8_BAR __builtin_amdgcn_s_barrier()
; #define PG8_SCHED __builtin_amdgcn_sched_barrier(0)
; template <class Epi, class Sched>
; DI void gemm_phase(LAS unsigned char* lds, const Gemm g, const Sched& S, const Epi& E) {
;     ...
;             PG8_LDB(B0, 0, 0); PG8_SCHED; PG8_LDA(At, 0, 0); PG8_STAGE(PG8_SA(1, 1), a1 + hstepA, voffA);
;             PG8_WAIT_L(8); PG8_BAR; PG8_WAIT_L(0); PG8_MMA(0, 0, At, B0); PG8_BAR; PG8_SCHED;
;             PG8_LDB(B1, 0, 1); PG8_STAGE(PG8_SB(0, 0), b2, voffB);
;             PG8_BAR; PG8_WAIT_L(0); PG8_MMA(0, 1, At, B1); PG8_BAR;
;             PG8_LDA(At, 0, 1); PG8_STAGE(PG8_SA(0, 0), a2, voffA);
;             PG8_BAR; PG8_WAIT_L(0); PG8_MMA(1, 0, At, B0); PG8_BAR; PG8_SCHED;
.LBB0_115:
	s_add_u32 s20, s2, 0x100
	s_addc_u32 s21, s3, 0
	s_add_i32 s61, 0, 0x10000
	v_add_u32_e32 v2, s61, v173
	ds_read_b128 v[20:23], v2
	ds_read_b128 v[24:27], v2 offset:1024
	ds_read_b128 v[124:127], v2 offset:2048
	ds_read_b128 v[136:139], v2 offset:3072
	s_cmp_eq_u32 s60, 6
	s_cselect_b32 s37, s27, s21
	s_cselect_b32 s36, s26, s20
	s_cselect_b32 s35, s31, s56
	s_cselect_b32 s34, s30, s55
	v_lshl_add_u64 v[170:171], s[2:3], 0, v[164:165]
	s_add_i32 m0, s41, 0xc000
	ds_read_b128 v[148:151], v175
	ds_read_b128 v[152:155], v175 offset:1024
	ds_read_b128 v[176:179], v175 offset:2048
	ds_read_b128 v[180:183], v175 offset:3072
	ds_read_b128 v[184:187], v175 offset:4096
	ds_read_b128 v[188:191], v175 offset:5120
	ds_read_b128 v[202:205], v175 offset:6144
	ds_read_b128 v[206:209], v175 offset:7168
	global_load_lds_dwordx4 v[170:171], off
	v_lshl_add_u64 v[170:171], s[2:3], 0, v[166:167]
	s_add_i32 m0, s41, 0xe000
	s_nop 0
	global_load_lds_dwordx4 v[170:171], off
	s_waitcnt lgkmcnt(8)
	s_barrier
	s_waitcnt lgkmcnt(0)
	s_setprio 1
	s_waitcnt lgkmcnt(0)
	v_mfma_f32_16x16x32_bf16 v[144:147], v[20:23], v[148:151], v[144:147]
	v_mfma_f32_16x16x32_bf16 v[140:143], v[124:127], v[148:151], v[140:143]
	v_mfma_f32_16x16x32_bf16 v[120:123], v[20:23], v[176:179], v[120:123]
	v_mfma_f32_16x16x32_bf16 v[116:119], v[124:127], v[176:179], v[116:119]
	v_mfma_f32_16x16x32_bf16 v[104:107], v[20:23], v[184:187], v[104:107]
	v_mfma_f32_16x16x32_bf16 v[100:103], v[124:127], v[184:187], v[100:103]
	v_mfma_f32_16x16x32_bf16 v[88:91], v[20:23], v[202:205], v[88:91]
	v_mfma_f32_16x16x32_bf16 v[84:87], v[124:127], v[202:205], v[84:87]
	v_mfma_f32_16x16x32_bf16 v[144:147], v[24:27], v[152:155], v[144:147]
	v_mfma_f32_16x16x32_bf16 v[140:143], v[136:139], v[152:155], v[140:143]
	v_mfma_f32_16x16x32_bf16 v[120:123], v[24:27], v[180:183], v[120:123]
	v_mfma_f32_16x16x32_bf16 v[116:119], v[136:139], v[180:183], v[116:119]
	v_mfma_f32_16x16x32_bf16 v[104:107], v[24:27], v[188:191], v[104:107]
	v_mfma_f32_16x16x32_bf16 v[100:103], v[136:139], v[188:191], v[100:103]
	v_mfma_f32_16x16x32_bf16 v[88:91], v[24:27], v[206:209], v[88:91]
	v_mfma_f32_16x16x32_bf16 v[84:87], v[136:139], v[206:209], v[84:87]
	s_setprio 0
	s_barrier
	s_add_i32 s64, 0, 0x14000
	s_add_i32 s2, s61, s40
	v_add_u32_e32 v2, s64, v173
	v_lshl_add_u64 v[170:171], s[34:35], 0, v[158:159]
	s_mov_b32 m0, s2
	ds_read_b128 v[210:213], v2
	ds_read_b128 v[214:217], v2 offset:1024
	ds_read_b128 v[230:233], v2 offset:2048
	ds_read_b128 v[234:237], v2 offset:3072
	global_load_lds_dwordx4 v[170:171], off
	v_lshl_add_u64 v[238:239], s[34:35], 0, v[0:1]
	s_add_i32 m0, s2, 0x2000
	s_nop 0
	global_load_lds_dwordx4 v[238:239], off
	s_barrier
	s_waitcnt lgkmcnt(0)
	s_setprio 1
	s_waitcnt lgkmcnt(0)
	v_mfma_f32_16x16x32_bf16 v[132:135], v[210:213], v[148:151], v[132:135]
	v_mfma_f32_16x16x32_bf16 v[128:131], v[230:233], v[148:151], v[128:131]
	v_mfma_f32_16x16x32_bf16 v[112:115], v[210:213], v[176:179], v[112:115]
	v_mfma_f32_16x16x32_bf16 v[108:111], v[230:233], v[176:179], v[108:111]
	v_mfma_f32_16x16x32_bf16 v[96:99], v[210:213], v[184:187], v[96:99]
	v_mfma_f32_16x16x32_bf16 v[92:95], v[230:233], v[184:187], v[92:95]
	v_mfma_f32_16x16x32_bf16 v[80:83], v[210:213], v[202:205], v[80:83]
	v_mfma_f32_16x16x32_bf16 v[76:79], v[230:233], v[202:205], v[76:79]
	v_mfma_f32_16x16x32_bf16 v[132:135], v[214:217], v[152:155], v[132:135]
	v_mfma_f32_16x16x32_bf16 v[128:131], v[234:237], v[152:155], v[128:131]
	v_mfma_f32_16x16x32_bf16 v[112:115], v[214:217], v[180:183], v[112:115]
	v_mfma_f32_16x16x32_bf16 v[108:111], v[234:237], v[180:183], v[108:111]
	v_mfma_f32_16x16x32_bf16 v[96:99], v[214:217], v[188:191], v[96:99]
	v_mfma_f32_16x16x32_bf16 v[92:95], v[234:237], v[188:191], v[92:95]
	v_mfma_f32_16x16x32_bf16 v[80:83], v[214:217], v[206:209], v[80:83]
	v_mfma_f32_16x16x32_bf16 v[76:79], v[234:237], v[206:209], v[76:79]
	s_setprio 0
	s_mov_b32 m0, s41
	v_lshl_add_u64 v[244:245], s[36:37], 0, v[160:161]
	s_barrier
	ds_read_b128 v[148:151], v175 offset:16384
	ds_read_b128 v[152:155], v175 offset:17408
	ds_read_b128 v[176:179], v175 offset:18432
	ds_read_b128 v[180:183], v175 offset:19456
	ds_read_b128 v[184:187], v175 offset:20480
	ds_read_b128 v[188:191], v175 offset:21504
	ds_read_b128 v[202:205], v175 offset:22528
	ds_read_b128 v[206:209], v175 offset:23552
	global_load_lds_dwordx4 v[244:245], off
	v_lshl_add_u64 v[246:247], s[36:37], 0, v[156:157]
	s_mov_b32 m0, s42
	s_nop 0
	global_load_lds_dwordx4 v[246:247], off
	s_barrier
	s_waitcnt lgkmcnt(0)
	s_setprio 1
	s_waitcnt lgkmcnt(0)
	v_mfma_f32_16x16x32_bf16 v[72:75], v[20:23], v[148:151], v[72:75]
	v_mfma_f32_16x16x32_bf16 v[68:71], v[124:127], v[148:151], v[68:71]
	v_mfma_f32_16x16x32_bf16 v[56:59], v[20:23], v[176:179], v[56:59]
	v_mfma_f32_16x16x32_bf16 v[52:55], v[124:127], v[176:179], v[52:55]
	v_mfma_f32_16x16x32_bf16 v[40:43], v[20:23], v[184:187], v[40:43]
	v_mfma_f32_16x16x32_bf16 v[36:39], v[124:127], v[184:187], v[36:39]
	v_mfma_f32_16x16x32_bf16 v[16:19], v[20:23], v[202:205], v[16:19]
	v_mfma_f32_16x16x32_bf16 v[12:15], v[124:127], v[202:205], v[12:15]
	v_mfma_f32_16x16x32_bf16 v[72:75], v[24:27], v[152:155], v[72:75]
	v_mfma_f32_16x16x32_bf16 v[68:71], v[136:139], v[152:155], v[68:71]
	v_mfma_f32_16x16x32_bf16 v[56:59], v[24:27], v[180:183], v[56:59]
	v_mfma_f32_16x16x32_bf16 v[52:55], v[136:139], v[180:183], v[52:55]
	v_mfma_f32_16x16x32_bf16 v[40:43], v[24:27], v[188:191], v[40:43]
	v_mfma_f32_16x16x32_bf16 v[36:39], v[136:139], v[188:191], v[36:39]
	v_mfma_f32_16x16x32_bf16 v[16:19], v[24:27], v[206:209], v[16:19]
	v_mfma_f32_16x16x32_bf16 v[12:15], v[136:139], v[206:209], v[12:15]
	s_setprio 0
	s_barrier
; #define PG8_STAGE(bufoff, gbase, voff) do { _Pragma("unroll") for (int _i = 0; _i < 2; ++_i) \
;         __builtin_amdgcn_global_load_lds((const unsigned*)((const char*)(gbase) + (voff)[_i]), (LAS unsigned*)(lds + (bufoff) + ldsw + _i * 8192), 16, 0, 0); } while (0)
; #define PG8_LDA(dst, b, h) do { _Pragma("unroll") for (int m = 0; m < 4; ++m) _Pragma("unroll") for (int k = 0; k < 2; ++k) dst[m][k] = *(const LAS bf16x8*)(lds + PG8_SA(b, h) + aoff + m * 2048 + k * 1024); } while (0)
; #define PG8_LDB(dst, b, h) do { _Pragma("unroll") for (int n = 0; n < 2; ++n) _Pragma("unroll") for (int k = 0; k < 2; ++k) dst[n][k] = *(const LAS bf16x8*)(lds + PG8_SB(b, h) + boff + n * 2048 + k * 1024); } while (0)
; #define PG8_MMA(ai, bj, At, Bt) do { __builtin_amdgcn_s_setprio(1); _Pragma("unroll") for (int m = 0; m < 4; ++m) _Pragma("unroll") for (int n = 0; n < 2; ++n) _Pragma("unroll") for (int k = 0; k < 2; ++k) \
;         acc[ai][bj][m][n] = __builtin_amdgcn_mfma_f32_16x16x32_bf16(Bt[n][k], At[m][k], acc[ai][bj][m][n], 0, 0, 0); __builtin_amdgcn_s_setprio(0); } while (0)
; #define PG8_WAIT_V(n) asm volatile("s_waitcnt vmcnt(" #n ")" ::: "memory")
; #define PG8_WAIT_L(n) asm volatile("s_waitcnt lgkmcnt(" #n ")" ::: "memory")
; #define PG8_BAR __builtin_amdgcn_s_barrier()
; #define PG8_SCHED __builtin_amdgcn_sched_barrier(0)
; template <class Epi, class Sched>
; DI void gemm_phase(LAS unsigned char* lds, const Gemm g, const Sched& S, const Epi& E) {
;     ...
;             PG8_STAGE(PG8_SB(0, 1), b2 + hstepB, voffB);
;             PG8_WAIT_V(6); PG8_BAR; PG8_MMA(1, 1, At, B1); PG8_BAR;
;             PG8_LDB(B0, 1, 0); PG8_SCHED; PG8_LDA(At, 1, 0); PG8_STAGE(PG8_SA(0, 1), a2 + hstepA, voffA);
;             PG8_WAIT_L(8); PG8_BAR; PG8_WAIT_L(0); PG8_MMA(0, 0, At, B0); PG8_BAR; PG8_SCHED;
;             PG8_LDB(B1, 1, 1); PG8_STAGE(PG8_SB(1, 0), b3, voffB);
;             PG8_BAR; PG8_WAIT_L(0); PG8_MMA(0, 1, At, B1); PG8_BAR;
;             PG8_LDA(At, 1, 1); PG8_STAGE(PG8_SA(1, 0), a3, voffA);
;             PG8_BAR; PG8_WAIT_L(0); PG8_MMA(1, 0, At, B0); PG8_BAR; PG8_SCHED;
	s_add_u32 s2, s34, 0x28000
	s_addc_u32 s3, s35, 0
	s_add_i32 s61, s64, s40
	v_lshl_add_u64 v[20:21], s[2:3], 0, v[158:159]
	s_mov_b32 m0, s61
	s_nop 0
	global_load_lds_dwordx4 v[20:21], off
	v_lshl_add_u64 v[20:21], s[2:3], 0, v[0:1]
	s_add_i32 m0, s61, 0x2000
	s_nop 0
	global_load_lds_dwordx4 v[20:21], off
	s_waitcnt vmcnt(6)
	s_barrier
	s_setprio 1
	v_mfma_f32_16x16x32_bf16 v[48:51], v[210:213], v[176:179], v[48:51]
	v_mfma_f32_16x16x32_bf16 v[44:47], v[230:233], v[176:179], v[44:47]
	v_mfma_f32_16x16x32_bf16 v[32:35], v[210:213], v[184:187], v[32:35]
	v_mfma_f32_16x16x32_bf16 v[28:31], v[230:233], v[184:187], v[28:31]
	v_mfma_f32_16x16x32_bf16 v[8:11], v[210:213], v[202:205], v[8:11]
	v_mfma_f32_16x16x32_bf16 v[4:7], v[230:233], v[202:205], v[4:7]
	v_mfma_f32_16x16x32_bf16 v[20:23], v[210:213], v[148:151], v[64:67]
	v_mfma_f32_16x16x32_bf16 v[24:27], v[230:233], v[148:151], v[60:63]
	v_mfma_f32_16x16x32_bf16 v[48:51], v[214:217], v[180:183], v[48:51]
	v_mfma_f32_16x16x32_bf16 v[44:47], v[234:237], v[180:183], v[44:47]
	v_mfma_f32_16x16x32_bf16 v[32:35], v[214:217], v[188:191], v[32:35]
	v_mfma_f32_16x16x32_bf16 v[28:31], v[234:237], v[188:191], v[28:31]
	v_mfma_f32_16x16x32_bf16 v[8:11], v[214:217], v[206:209], v[8:11]
	v_mfma_f32_16x16x32_bf16 v[4:7], v[234:237], v[206:209], v[4:7]
	v_mfma_f32_16x16x32_bf16 v[20:23], v[214:217], v[152:155], v[20:23]
	v_mfma_f32_16x16x32_bf16 v[24:27], v[234:237], v[152:155], v[24:27]
	s_setprio 0
	s_add_i32 s61, 0, 0x18000
	v_add_u32_e32 v2, s61, v173
	s_barrier
	ds_read_b128 v[60:63], v2
	ds_read_b128 v[64:67], v2 offset:1024
	ds_read_b128 v[124:127], v2 offset:2048
	ds_read_b128 v[136:139], v2 offset:3072
	s_add_u32 s2, s36, 0x28000
	s_addc_u32 s3, s37, 0
	s_mov_b32 m0, s43
	v_lshl_add_u64 v[210:211], s[2:3], 0, v[160:161]
	ds_read_b128 v[148:151], v175 offset:32768
	ds_read_b128 v[152:155], v175 offset:33792
	ds_read_b128 v[176:179], v175 offset:34816
	ds_read_b128 v[180:183], v175 offset:35840
	ds_read_b128 v[184:187], v175 offset:36864
	ds_read_b128 v[188:191], v175 offset:37888
	ds_read_b128 v[202:205], v175 offset:38912
	ds_read_b128 v[206:209], v175 offset:39936
	global_load_lds_dwordx4 v[210:211], off
	v_lshl_add_u64 v[210:211], s[2:3], 0, v[156:157]
	s_mov_b32 m0, s45
	s_nop 0
	global_load_lds_dwordx4 v[210:211], off
	s_waitcnt lgkmcnt(8)
	s_barrier
	s_waitcnt lgkmcnt(0)
	s_setprio 1
	s_waitcnt lgkmcnt(0)
	v_mfma_f32_16x16x32_bf16 v[144:147], v[60:63], v[148:151], v[144:147]
	v_mfma_f32_16x16x32_bf16 v[140:143], v[124:127], v[148:151], v[140:143]
	v_mfma_f32_16x16x32_bf16 v[120:123], v[60:63], v[176:179], v[120:123]
	v_mfma_f32_16x16x32_bf16 v[116:119], v[124:127], v[176:179], v[116:119]
	v_mfma_f32_16x16x32_bf16 v[104:107], v[60:63], v[184:187], v[104:107]
	v_mfma_f32_16x16x32_bf16 v[100:103], v[124:127], v[184:187], v[100:103]
	v_mfma_f32_16x16x32_bf16 v[88:91], v[60:63], v[202:205], v[88:91]
	v_mfma_f32_16x16x32_bf16 v[84:87], v[124:127], v[202:205], v[84:87]
	v_mfma_f32_16x16x32_bf16 v[144:147], v[64:67], v[152:155], v[144:147]
	v_mfma_f32_16x16x32_bf16 v[140:143], v[136:139], v[152:155], v[140:143]
	v_mfma_f32_16x16x32_bf16 v[120:123], v[64:67], v[180:183], v[120:123]
	v_mfma_f32_16x16x32_bf16 v[116:119], v[136:139], v[180:183], v[116:119]
	v_mfma_f32_16x16x32_bf16 v[104:107], v[64:67], v[188:191], v[104:107]
	v_mfma_f32_16x16x32_bf16 v[100:103], v[136:139], v[188:191], v[100:103]
	v_mfma_f32_16x16x32_bf16 v[88:91], v[64:67], v[206:209], v[88:91]
	v_mfma_f32_16x16x32_bf16 v[84:87], v[136:139], v[206:209], v[84:87]
	s_setprio 0
	s_barrier
	s_add_i32 s36, 0, 0x1c000
	s_add_i32 s2, s61, s40
	v_add_u32_e32 v2, s36, v173
	v_lshl_add_u64 v[170:171], v[170:171], 0, s[78:79]
	s_mov_b32 m0, s2
	ds_read_b128 v[210:213], v2
	ds_read_b128 v[214:217], v2 offset:1024
	ds_read_b128 v[230:233], v2 offset:2048
	ds_read_b128 v[234:237], v2 offset:3072
	global_load_lds_dwordx4 v[170:171], off
	v_lshl_add_u64 v[170:171], v[238:239], 0, s[78:79]
	s_add_i32 m0, s2, 0x2000
	s_nop 0
	global_load_lds_dwordx4 v[170:171], off
	s_barrier
	s_waitcnt lgkmcnt(0)
	s_setprio 1
	s_waitcnt lgkmcnt(0)
	v_mfma_f32_16x16x32_bf16 v[132:135], v[210:213], v[148:151], v[132:135]
	v_mfma_f32_16x16x32_bf16 v[128:131], v[230:233], v[148:151], v[128:131]
	v_mfma_f32_16x16x32_bf16 v[112:115], v[210:213], v[176:179], v[112:115]
	v_mfma_f32_16x16x32_bf16 v[108:111], v[230:233], v[176:179], v[108:111]
	v_mfma_f32_16x16x32_bf16 v[96:99], v[210:213], v[184:187], v[96:99]
	v_mfma_f32_16x16x32_bf16 v[92:95], v[230:233], v[184:187], v[92:95]
	v_mfma_f32_16x16x32_bf16 v[80:83], v[210:213], v[202:205], v[80:83]
	v_mfma_f32_16x16x32_bf16 v[76:79], v[230:233], v[202:205], v[76:79]
	v_mfma_f32_16x16x32_bf16 v[132:135], v[214:217], v[152:155], v[132:135]
	v_mfma_f32_16x16x32_bf16 v[128:131], v[234:237], v[152:155], v[128:131]
	v_mfma_f32_16x16x32_bf16 v[112:115], v[214:217], v[180:183], v[112:115]
	v_mfma_f32_16x16x32_bf16 v[108:111], v[234:237], v[180:183], v[108:111]
	v_mfma_f32_16x16x32_bf16 v[96:99], v[214:217], v[188:191], v[96:99]
	v_mfma_f32_16x16x32_bf16 v[92:95], v[234:237], v[188:191], v[92:95]
	v_mfma_f32_16x16x32_bf16 v[80:83], v[214:217], v[206:209], v[80:83]
	v_mfma_f32_16x16x32_bf16 v[76:79], v[234:237], v[206:209], v[76:79]
	s_setprio 0
	s_mov_b32 m0, s48
	v_lshl_add_u64 v[170:171], v[244:245], 0, s[78:79]
	s_barrier
	ds_read_b128 v[148:151], v175 offset:49152
	ds_read_b128 v[152:155], v175 offset:50176
	ds_read_b128 v[176:179], v175 offset:51200
	ds_read_b128 v[180:183], v175 offset:52224
	ds_read_b128 v[184:187], v175 offset:53248
	ds_read_b128 v[188:191], v175 offset:54272
	ds_read_b128 v[202:205], v175 offset:55296
	ds_read_b128 v[206:209], v175 offset:56320
	global_load_lds_dwordx4 v[170:171], off
	v_lshl_add_u64 v[170:171], v[246:247], 0, s[78:79]
	s_mov_b32 m0, s49
	s_nop 0
	global_load_lds_dwordx4 v[170:171], off
	s_barrier
; DI void unpack8(u32x4 w, float* f) { f[0] = bflo(w.x); f[1] = bfhi(w.x); f[2] = bflo(w.y); f[3] = bfhi(w.y); f[4] = bflo(w.z); f[5] = bfhi(w.z); f[6] = bflo(w.w); f[7] = bfhi(w.w); }
; DI u32x4 pack44(f32x4 a, f32x4 b) { u32x4 w; w.x = pk2(a[0], a[1]); w.y = pk2(a[2], a[3]); w.z = pk2(b[0], b[1]); w.w = pk2(b[2], b[3]); return w; }
; DI float gelu_tanh(float y) { float t = 0.7978845608f * (y + 0.044715f * y * y * y); float e = __expf(2.f * t); return 0.5f * y * (2.f - 2.f / (e + 1.f)); }
; #define PG8_WAIT_V(n) asm volatile("s_waitcnt vmcnt(" #n ")" ::: "memory")
; template <class Epi, class Sched>
; DI void gemm_phase(LAS unsigned char* lds, const Gemm g, const Sched& S, const Epi& E) {
;     ...
;             PG8_BAR; PG8_WAIT_L(0); PG8_MMA(1, 0, At, B0); PG8_BAR; PG8_SCHED;
;             PG8_STAGE(PG8_SB(1, 1), b3 + hstepB, voffB);
;             PG8_WAIT_V(6); PG8_BAR; PG8_MMA(1, 1, At, B1); PG8_BAR;
;     DI void operator()(const Acc& acc, const Unit& u, int wr, int wc, int fr, int fq) const {
;         const int g = u.pm >> 1, mt = u.pm & 1, nt = u.pn & 1, ho0 = 8 * (fq & 1);
;         const f32x4 d0 = *(const f32x4*)(dskip + g * 16 + ho0), d1 = *(const f32x4*)(dskip + g * 16 + ho0 + 4);
; #pragma unroll
;         for (int ai = 0; ai < 2; ++ai)
; #pragma unroll
;             for (int mp = 0; mp < 2; ++mp) {
;                 u32x4 uv[2][2];
; #pragma unroll
;                 for (int mi = 0; mi < 2; ++mi)
; #pragma unroll
;                     for (int bj = 0; bj < 2; ++bj) { const int chunk = mt * 256 + ai * 128 + wr * 64 + (2 * mp + mi) * 16 + fr, n0 = nt * 256 + bj * 128 + wc * 32 + 8 * fq;
;                         uv[mi][bj] = *(const u32x4*)(uperm + (size_t)(g * 512 + chunk) * 640 + n0); }
; #pragma unroll
;                 for (int mi = 0; mi < 2; ++mi)
; #pragma unroll
;                     for (int bj = 0; bj < 2; ++bj) { const int m = 2 * mp + mi, chunk = mt * 256 + ai * 128 + wr * 64 + m * 16 + fr, n0 = nt * 256 + bj * 128 + wc * 32 + 8 * fq, t = n0 >> 4;
;                         f32x4 v0 = acc[ai][bj][m][0], v1 = acc[ai][bj][m][1]; float uf[8]; unpack8(uv[mi][bj], uf);
;                         for (int j = 0; j < 4; ++j) { v0[j] = gelu_tanh(v0[j] + d0[j] * uf[j]); v1[j] = gelu_tanh(v1[j] + d1[j] * uf[4 + j]); }
;                         *(u32x4*)(zs + (size_t)(chunk * 32 + t) * 1024 + g * 16 + ho0) = pack44(v0, v1); }
	s_waitcnt lgkmcnt(0)
	s_setprio 1
	s_waitcnt lgkmcnt(0)
	v_mfma_f32_16x16x32_bf16 v[72:75], v[60:63], v[148:151], v[72:75]
	v_mfma_f32_16x16x32_bf16 v[68:71], v[124:127], v[148:151], v[68:71]
	v_mfma_f32_16x16x32_bf16 v[56:59], v[60:63], v[176:179], v[56:59]
	v_mfma_f32_16x16x32_bf16 v[52:55], v[124:127], v[176:179], v[52:55]
	v_mfma_f32_16x16x32_bf16 v[40:43], v[60:63], v[184:187], v[40:43]
	v_mfma_f32_16x16x32_bf16 v[36:39], v[124:127], v[184:187], v[36:39]
	v_mfma_f32_16x16x32_bf16 v[16:19], v[60:63], v[202:205], v[16:19]
	v_mfma_f32_16x16x32_bf16 v[12:15], v[124:127], v[202:205], v[12:15]
	v_mfma_f32_16x16x32_bf16 v[72:75], v[64:67], v[152:155], v[72:75]
	v_mfma_f32_16x16x32_bf16 v[68:71], v[136:139], v[152:155], v[68:71]
	v_mfma_f32_16x16x32_bf16 v[56:59], v[64:67], v[180:183], v[56:59]
	v_mfma_f32_16x16x32_bf16 v[52:55], v[136:139], v[180:183], v[52:55]
	v_mfma_f32_16x16x32_bf16 v[40:43], v[64:67], v[188:191], v[40:43]
	v_mfma_f32_16x16x32_bf16 v[36:39], v[136:139], v[188:191], v[36:39]
	v_mfma_f32_16x16x32_bf16 v[16:19], v[64:67], v[206:209], v[16:19]
	v_mfma_f32_16x16x32_bf16 v[12:15], v[136:139], v[206:209], v[12:15]
	s_setprio 0
	s_barrier
	s_add_u32 s2, s34, 0x28080
	s_addc_u32 s3, s35, 0
	s_add_i32 s34, s36, s40
	v_lshl_add_u64 v[60:61], s[2:3], 0, v[158:159]
	s_mov_b32 m0, s34
	s_nop 0
	global_load_lds_dwordx4 v[60:61], off
	v_lshl_add_u64 v[60:61], s[2:3], 0, v[0:1]
	s_add_i32 m0, s34, 0x2000
	s_nop 0
	global_load_lds_dwordx4 v[60:61], off
	s_waitcnt vmcnt(6)
	s_barrier
	s_setprio 1
	v_mfma_f32_16x16x32_bf16 v[20:23], v[210:213], v[148:151], v[20:23]
	v_mfma_f32_16x16x32_bf16 v[64:67], v[214:217], v[152:155], v[20:23]
	v_mfma_f32_16x16x32_bf16 v[20:23], v[230:233], v[148:151], v[24:27]
	v_mfma_f32_16x16x32_bf16 v[60:63], v[234:237], v[152:155], v[20:23]
	v_mfma_f32_16x16x32_bf16 v[20:23], v[210:213], v[176:179], v[48:51]
	v_mfma_f32_16x16x32_bf16 v[48:51], v[214:217], v[180:183], v[20:23]
	v_mfma_f32_16x16x32_bf16 v[20:23], v[230:233], v[176:179], v[44:47]
	v_mfma_f32_16x16x32_bf16 v[44:47], v[234:237], v[180:183], v[20:23]
	v_mfma_f32_16x16x32_bf16 v[20:23], v[210:213], v[184:187], v[32:35]
	v_mfma_f32_16x16x32_bf16 v[32:35], v[214:217], v[188:191], v[20:23]
	v_mfma_f32_16x16x32_bf16 v[20:23], v[230:233], v[184:187], v[28:31]
	v_mfma_f32_16x16x32_bf16 v[8:11], v[210:213], v[202:205], v[8:11]
	v_mfma_f32_16x16x32_bf16 v[4:7], v[230:233], v[202:205], v[4:7]
	v_mfma_f32_16x16x32_bf16 v[28:31], v[234:237], v[188:191], v[20:23]
	v_mfma_f32_16x16x32_bf16 v[8:11], v[214:217], v[206:209], v[8:11]
	v_mfma_f32_16x16x32_bf16 v[4:7], v[234:237], v[206:209], v[4:7]
	s_setprio 0
	s_add_i32 s60, s60, 2
	s_add_u32 s55, s55, 0x100
	s_addc_u32 s56, s56, 0
	s_cmp_gt_u32 s60, 7
	s_mov_b64 s[2:3], s[20:21]
	s_barrier
	s_cbranch_scc0 .LBB0_115
	s_lshl_b32 s3, s54, 8
	s_and_b32 s3, s3, 0x100
	s_lshl_b32 s34, s53, 8
	s_ashr_i32 s2, s54, 1
	s_and_b32 s34, s34, 0x100
	v_add_u32_e32 v176, s3, v172
	s_lshl_b32 s20, s2, 4
	v_or_b32_e32 v169, s34, v174
	v_lshl_add_u32 v177, s2, 9, v176
	v_mov_b64_e32 v[170:171], s[24:25]
	s_ashr_i32 s21, s20, 31
	v_mad_i64_i32 v[124:125], s[2:3], v177, s12, v[170:171]
	v_lshlrev_b32_e32 v2, 1, v169
	v_lshl_add_u64 v[24:25], s[20:21], 2, v[162:163]
	v_lshl_add_u64 v[124:125], v[124:125], 0, v[2:3]
	global_load_dwordx4 v[20:23], v[24:25], off offset:16
	s_nop 0
	global_load_dwordx4 v[24:27], v[24:25], off
	v_lshlrev_b32_e32 v176, 5, v176
	global_load_dwordx4 v[152:155], v[124:125], off
	global_load_dwordx4 v[148:151], v[124:125], off offset:256
	v_or_b32_e32 v124, 16, v177
	s_lshl_b64 s[34:35], s[20:21], 1
	v_or_b32_e32 v178, 0x80, v169
	v_mad_i64_i32 v[124:125], s[2:3], v124, s12, v[170:171]
	v_lshl_add_u64 v[124:125], v[124:125], 0, v[2:3]
	global_load_dwordx4 v[136:139], v[124:125], off
	s_nop 0
	global_load_dwordx4 v[124:127], v[124:125], off offset:256
	s_mov_b32 s53, s52
	s_mov_b32 s54, s51
	s_mov_b64 s[20:21], s[30:31]
	s_waitcnt vmcnt(0)
	v_lshlrev_b32_e32 v180, 16, v152
	v_and_b32_e32 v181, 0xffff0000, v152
	v_pk_fma_f32 v[144:145], v[24:25], v[180:181], v[144:145]
	s_nop 0
	v_mul_f32_e32 v152, 0x3d372713, v144
	v_mul_f32_e32 v152, v144, v152
	v_fma_f32 v152, v144, v152, v144
	v_mul_f32_e32 v152, 0x3f4c422a, v152
	v_add_f32_e32 v152, v152, v152
	v_mul_f32_e32 v152, 0x3fb8aa3b, v152
	v_exp_f32_e32 v180, v152
	v_mul_f32_e32 v152, 0x3d372713, v145
	v_mul_f32_e32 v152, v145, v152
	v_fma_f32 v152, v145, v152, v145
	v_mul_f32_e32 v152, 0x3f4c422a, v152
	v_add_f32_e32 v152, v152, v152
	v_mul_f32_e32 v152, 0x3fb8aa3b, v152
	v_exp_f32_e32 v181, v152
	v_pk_mul_f32 v[144:145], v[144:145], 0.5 op_sel_hi:[1,0]
	v_pk_add_f32 v[180:181], v[180:181], 1.0 op_sel_hi:[1,0]
	s_nop 0
	v_rcp_f32_e32 v179, v181
	s_nop 0
	v_mul_f32_e32 v183, 2.0, v179
	v_fma_f32 v184, -v181, v183, 2.0
	v_fmac_f32_e32 v183, v184, v179
	v_div_fixup_f32 v181, v183, v181, 2.0
	v_rcp_f32_e32 v179, v180
	s_nop 0
	v_mul_f32_e32 v183, 2.0, v179
	v_fma_f32 v184, -v180, v183, 2.0
	v_fmac_f32_e32 v183, v184, v179
	v_div_fixup_f32 v180, v183, v180, 2.0
	v_pk_add_f32 v[180:181], v[180:181], 2.0 op_sel_hi:[1,0] neg_lo:[1,0] neg_hi:[1,0]
	s_nop 0
	v_pk_mul_f32 v[144:145], v[144:145], v[180:181]
	v_lshlrev_b32_e32 v180, 16, v154
	v_and_b32_e32 v181, 0xffff0000, v154
	v_pk_fma_f32 v[140:141], v[20:21], v[180:181], v[140:141]
	v_cvt_pk_bf16_f32 v144, v144, v145
	v_mul_f32_e32 v152, 0x3d372713, v140
	v_mul_f32_e32 v152, v140, v152
	v_fma_f32 v152, v140, v152, v140
	v_mul_f32_e32 v152, 0x3f4c422a, v152
	v_add_f32_e32 v152, v152, v152
	v_mul_f32_e32 v152, 0x3fb8aa3b, v152
	v_exp_f32_e32 v180, v152
	v_mul_f32_e32 v152, 0x3d372713, v141
	v_mul_f32_e32 v152, v141, v152
; DI void unpack8(u32x4 w, float* f) { f[0] = bflo(w.x); f[1] = bfhi(w.x); f[2] = bflo(w.y); f[3] = bfhi(w.y); f[4] = bflo(w.z); f[5] = bfhi(w.z); f[6] = bflo(w.w); f[7] = bfhi(w.w); }
; DI u32x4 pack44(f32x4 a, f32x4 b) { u32x4 w; w.x = pk2(a[0], a[1]); w.y = pk2(a[2], a[3]); w.z = pk2(b[0], b[1]); w.w = pk2(b[2], b[3]); return w; }
; DI float gelu_tanh(float y) { float t = 0.7978845608f * (y + 0.044715f * y * y * y); float e = __expf(2.f * t); return 0.5f * y * (2.f - 2.f / (e + 1.f)); }
;     DI void operator()(const Acc& acc, const Unit& u, int wr, int wc, int fr, int fq) const {
;     ...
;                     for (int bj = 0; bj < 2; ++bj) { const int chunk = mt * 256 + ai * 128 + wr * 64 + (2 * mp + mi) * 16 + fr, n0 = nt * 256 + bj * 128 + wc * 32 + 8 * fq;
;                         uv[mi][bj] = *(const u32x4*)(uperm + (size_t)(g * 512 + chunk) * 640 + n0); }
; #pragma unroll
;                 for (int mi = 0; mi < 2; ++mi)
; #pragma unroll
;                     for (int bj = 0; bj < 2; ++bj) { const int m = 2 * mp + mi, chunk = mt * 256 + ai * 128 + wr * 64 + m * 16 + fr, n0 = nt * 256 + bj * 128 + wc * 32 + 8 * fq, t = n0 >> 4;
;                         f32x4 v0 = acc[ai][bj][m][0], v1 = acc[ai][bj][m][1]; float uf[8]; unpack8(uv[mi][bj], uf);
;                         for (int j = 0; j < 4; ++j) { v0[j] = gelu_tanh(v0[j] + d0[j] * uf[j]); v1[j] = gelu_tanh(v1[j] + d1[j] * uf[4 + j]); }
;                         *(u32x4*)(zs + (size_t)(chunk * 32 + t) * 1024 + g * 16 + ho0) = pack44(v0, v1); }
	v_fma_f32 v152, v141, v152, v141
	v_mul_f32_e32 v152, 0x3f4c422a, v152
	v_add_f32_e32 v152, v152, v152
	v_mul_f32_e32 v152, 0x3fb8aa3b, v152
	v_exp_f32_e32 v181, v152
	v_pk_mul_f32 v[140:141], v[140:141], 0.5 op_sel_hi:[1,0]
	v_pk_add_f32 v[180:181], v[180:181], 1.0 op_sel_hi:[1,0]
	s_nop 0
	v_rcp_f32_e32 v154, v181
	s_nop 0
	v_mul_f32_e32 v182, 2.0, v154
	v_fma_f32 v183, -v181, v182, 2.0
	v_fmac_f32_e32 v182, v183, v154
	v_div_fixup_f32 v181, v182, v181, 2.0
	v_rcp_f32_e32 v154, v180
	s_nop 0
	v_mul_f32_e32 v182, 2.0, v154
	v_fma_f32 v183, -v180, v182, 2.0
	v_fmac_f32_e32 v182, v183, v154
	v_div_fixup_f32 v180, v182, v180, 2.0
	v_lshlrev_b32_e32 v152, 16, v153
	v_and_b32_e32 v153, 0xffff0000, v153
	v_pk_fma_f32 v[146:147], v[26:27], v[152:153], v[146:147]
	v_pk_add_f32 v[180:181], v[180:181], 2.0 op_sel_hi:[1,0] neg_lo:[1,0] neg_hi:[1,0]
	v_mul_f32_e32 v152, 0x3d372713, v146
	v_mul_f32_e32 v153, 0x3d372713, v147
	v_mul_f32_e32 v152, v146, v152
	v_mul_f32_e32 v153, v147, v153
	v_fma_f32 v152, v146, v152, v146
	v_fma_f32 v153, v147, v153, v147
	v_mul_f32_e32 v152, 0x3f4c422a, v152
	v_mul_f32_e32 v153, 0x3f4c422a, v153
	v_add_f32_e32 v152, v152, v152
	v_add_f32_e32 v153, v153, v153
	v_mul_f32_e32 v152, 0x3fb8aa3b, v152
	v_mul_f32_e32 v153, 0x3fb8aa3b, v153
	v_exp_f32_e32 v152, v152
	v_exp_f32_e32 v153, v153
	v_pk_mul_f32 v[140:141], v[140:141], v[180:181]
	v_pk_mul_f32 v[146:147], v[146:147], 0.5 op_sel_hi:[1,0]
	v_pk_add_f32 v[152:153], v[152:153], 1.0 op_sel_hi:[1,0]
	s_nop 0
	v_rcp_f32_e32 v179, v153
	s_nop 0
	v_mul_f32_e32 v181, 2.0, v179
	v_fma_f32 v182, -v153, v181, 2.0
	v_fmac_f32_e32 v181, v182, v179
	v_div_fixup_f32 v153, v181, v153, 2.0
	v_rcp_f32_e32 v179, v152
	s_nop 0
	v_mul_f32_e32 v181, 2.0, v179
	v_fma_f32 v182, -v152, v181, 2.0
	v_fmac_f32_e32 v181, v182, v179
	v_div_fixup_f32 v152, v181, v152, 2.0
	v_pk_add_f32 v[152:153], v[152:153], 2.0 op_sel_hi:[1,0] neg_lo:[1,0] neg_hi:[1,0]
	s_nop 0
	v_pk_mul_f32 v[146:147], v[146:147], v[152:153]
	v_lshlrev_b32_e32 v152, 16, v155
	v_and_b32_e32 v153, 0xffff0000, v155
	v_pk_fma_f32 v[142:143], v[22:23], v[152:153], v[142:143]
	v_cvt_pk_bf16_f32 v145, v146, v147
	v_mul_f32_e32 v152, 0x3d372713, v142
	v_mul_f32_e32 v153, 0x3d372713, v143
	v_mul_f32_e32 v152, v142, v152
	v_mul_f32_e32 v153, v143, v153
	v_fma_f32 v152, v142, v152, v142
	v_fma_f32 v153, v143, v153, v143
	v_mul_f32_e32 v152, 0x3f4c422a, v152
	v_mul_f32_e32 v153, 0x3f4c422a, v153
	v_add_f32_e32 v152, v152, v152
	v_add_f32_e32 v153, v153, v153
	v_mul_f32_e32 v152, 0x3fb8aa3b, v152
	v_mul_f32_e32 v153, 0x3fb8aa3b, v153
	v_exp_f32_e32 v152, v152
	v_exp_f32_e32 v153, v153
	v_pk_mul_f32 v[142:143], v[142:143], 0.5 op_sel_hi:[1,0]
	v_cvt_pk_bf16_f32 v146, v140, v141
	v_pk_add_f32 v[152:153], v[152:153], 1.0 op_sel_hi:[1,0]
	s_nop 0
	v_rcp_f32_e32 v155, v153
	s_nop 0
	v_mul_f32_e32 v180, 2.0, v155
	v_fma_f32 v181, -v153, v180, 2.0
	v_fmac_f32_e32 v180, v181, v155
	v_div_fixup_f32 v153, v180, v153, 2.0
	v_rcp_f32_e32 v155, v152
	s_nop 0
	v_mul_f32_e32 v180, 2.0, v155
	v_fma_f32 v181, -v152, v180, 2.0
	v_fmac_f32_e32 v180, v181, v155
	v_div_fixup_f32 v152, v180, v152, 2.0
	v_pk_add_f32 v[152:153], v[152:153], 2.0 op_sel_hi:[1,0] neg_lo:[1,0] neg_hi:[1,0]
	s_nop 0
	v_pk_mul_f32 v[152:153], v[142:143], v[152:153]
	v_lshrrev_b32_e32 v142, 4, v169
	v_or_b32_e32 v140, v176, v142
	v_ashrrev_i32_e32 v141, 31, v140
	v_lshlrev_b64 v[140:141], 11, v[140:141]
	v_lshl_add_u64 v[140:141], s[4:5], 0, v[140:141]
	v_lshl_add_u64 v[140:141], v[140:141], 0, s[34:35]
	v_mov_b32_e32 v169, v3
	v_cvt_pk_bf16_f32 v147, v152, v153
	v_lshl_add_u64 v[140:141], v[140:141], 0, v[168:169]
	global_store_dwordx4 v[140:141], v[144:147], off
	v_lshlrev_b32_e32 v140, 16, v148
	v_and_b32_e32 v141, 0xffff0000, v148
	v_pk_fma_f32 v[132:133], v[24:25], v[140:141], v[132:133]
	s_nop 0
	v_mul_f32_e32 v140, 0x3d372713, v132
	v_mul_f32_e32 v141, 0x3d372713, v133
	v_mul_f32_e32 v140, v132, v140
	v_mul_f32_e32 v141, v133, v141
	v_fma_f32 v140, v132, v140, v132
	v_fma_f32 v141, v133, v141, v133
	v_mul_f32_e32 v140, 0x3f4c422a, v140
	v_mul_f32_e32 v141, 0x3f4c422a, v141
	v_add_f32_e32 v140, v140, v140
	v_add_f32_e32 v141, v141, v141
	v_mul_f32_e32 v140, 0x3fb8aa3b, v140
	v_mul_f32_e32 v141, 0x3fb8aa3b, v141
	v_exp_f32_e32 v140, v140
	v_exp_f32_e32 v141, v141
	v_pk_mul_f32 v[132:133], v[132:133], 0.5 op_sel_hi:[1,0]
	v_pk_add_f32 v[140:141], v[140:141], 1.0 op_sel_hi:[1,0]
	s_nop 0
	v_rcp_f32_e32 v144, v141
	s_nop 0
	v_mul_f32_e32 v146, 2.0, v144
	v_fma_f32 v147, -v141, v146, 2.0
	v_fmac_f32_e32 v146, v147, v144
	v_div_fixup_f32 v141, v146, v141, 2.0
	v_rcp_f32_e32 v144, v140
	s_nop 0
	v_mul_f32_e32 v146, 2.0, v144
	v_fma_f32 v147, -v140, v146, 2.0
	v_fmac_f32_e32 v146, v147, v144
	v_div_fixup_f32 v140, v146, v140, 2.0
	v_pk_add_f32 v[140:141], v[140:141], 2.0 op_sel_hi:[1,0] neg_lo:[1,0] neg_hi:[1,0]
	s_nop 0
	v_pk_mul_f32 v[132:133], v[132:133], v[140:141]
	v_lshlrev_b32_e32 v140, 16, v150
	v_and_b32_e32 v141, 0xffff0000, v150
	v_pk_fma_f32 v[128:129], v[20:21], v[140:141], v[128:129]
	v_cvt_pk_bf16_f32 v132, v132, v133
	v_mul_f32_e32 v140, 0x3d372713, v128
	v_mul_f32_e32 v141, 0x3d372713, v129
	v_mul_f32_e32 v140, v128, v140
	v_mul_f32_e32 v141, v129, v141
	v_fma_f32 v140, v128, v140, v128
	v_fma_f32 v141, v129, v141, v129
	v_mul_f32_e32 v140, 0x3f4c422a, v140
	v_mul_f32_e32 v141, 0x3f4c422a, v141
	v_add_f32_e32 v140, v140, v140
	v_add_f32_e32 v141, v141, v141
	v_mul_f32_e32 v140, 0x3fb8aa3b, v140
	v_mul_f32_e32 v141, 0x3fb8aa3b, v141
	v_exp_f32_e32 v140, v140
	v_exp_f32_e32 v141, v141
	v_pk_mul_f32 v[128:129], v[128:129], 0.5 op_sel_hi:[1,0]
; DI void unpack8(u32x4 w, float* f) { f[0] = bflo(w.x); f[1] = bfhi(w.x); f[2] = bflo(w.y); f[3] = bfhi(w.y); f[4] = bflo(w.z); f[5] = bfhi(w.z); f[6] = bflo(w.w); f[7] = bfhi(w.w); }
; DI u32x4 pack44(f32x4 a, f32x4 b) { u32x4 w; w.x = pk2(a[0], a[1]); w.y = pk2(a[2], a[3]); w.z = pk2(b[0], b[1]); w.w = pk2(b[2], b[3]); return w; }
; DI float gelu_tanh(float y) { float t = 0.7978845608f * (y + 0.044715f * y * y * y); float e = __expf(2.f * t); return 0.5f * y * (2.f - 2.f / (e + 1.f)); }
;     DI void operator()(const Acc& acc, const Unit& u, int wr, int wc, int fr, int fq) const {
;     ...
;                     for (int bj = 0; bj < 2; ++bj) { const int chunk = mt * 256 + ai * 128 + wr * 64 + (2 * mp + mi) * 16 + fr, n0 = nt * 256 + bj * 128 + wc * 32 + 8 * fq;
;                         uv[mi][bj] = *(const u32x4*)(uperm + (size_t)(g * 512 + chunk) * 640 + n0); }
; #pragma unroll
;                 for (int mi = 0; mi < 2; ++mi)
; #pragma unroll
;                     for (int bj = 0; bj < 2; ++bj) { const int m = 2 * mp + mi, chunk = mt * 256 + ai * 128 + wr * 64 + m * 16 + fr, n0 = nt * 256 + bj * 128 + wc * 32 + 8 * fq, t = n0 >> 4;
;                         f32x4 v0 = acc[ai][bj][m][0], v1 = acc[ai][bj][m][1]; float uf[8]; unpack8(uv[mi][bj], uf);
;                         for (int j = 0; j < 4; ++j) { v0[j] = gelu_tanh(v0[j] + d0[j] * uf[j]); v1[j] = gelu_tanh(v1[j] + d1[j] * uf[4 + j]); }
;                         *(u32x4*)(zs + (size_t)(chunk * 32 + t) * 1024 + g * 16 + ho0) = pack44(v0, v1); }
	v_pk_add_f32 v[140:141], v[140:141], 1.0 op_sel_hi:[1,0]
	s_nop 0
	v_rcp_f32_e32 v144, v141
	s_nop 0
	v_mul_f32_e32 v146, 2.0, v144
	v_fma_f32 v147, -v141, v146, 2.0
	v_fmac_f32_e32 v146, v147, v144
	v_div_fixup_f32 v141, v146, v141, 2.0
	v_rcp_f32_e32 v144, v140
	s_nop 0
	v_mul_f32_e32 v146, 2.0, v144
	v_fma_f32 v147, -v140, v146, 2.0
	v_fmac_f32_e32 v146, v147, v144
	v_div_fixup_f32 v140, v146, v140, 2.0
	v_pk_add_f32 v[140:141], v[140:141], 2.0 op_sel_hi:[1,0] neg_lo:[1,0] neg_hi:[1,0]
	s_nop 0
	v_pk_mul_f32 v[128:129], v[128:129], v[140:141]
	v_lshlrev_b32_e32 v140, 16, v149
	v_and_b32_e32 v141, 0xffff0000, v149
	v_pk_fma_f32 v[134:135], v[26:27], v[140:141], v[134:135]
	s_nop 0
	v_mul_f32_e32 v140, 0x3d372713, v134
	v_mul_f32_e32 v141, 0x3d372713, v135
	v_mul_f32_e32 v140, v134, v140
	v_mul_f32_e32 v141, v135, v141
	v_fma_f32 v140, v134, v140, v134
	v_fma_f32 v141, v135, v141, v135
	v_mul_f32_e32 v140, 0x3f4c422a, v140
	v_mul_f32_e32 v141, 0x3f4c422a, v141
	v_add_f32_e32 v140, v140, v140
	v_add_f32_e32 v141, v141, v141
	v_mul_f32_e32 v140, 0x3fb8aa3b, v140
	v_mul_f32_e32 v141, 0x3fb8aa3b, v141
	v_exp_f32_e32 v140, v140
	v_exp_f32_e32 v141, v141
	v_pk_mul_f32 v[134:135], v[134:135], 0.5 op_sel_hi:[1,0]
	v_pk_add_f32 v[140:141], v[140:141], 1.0 op_sel_hi:[1,0]
	s_nop 0
	v_rcp_f32_e32 v144, v141
	s_nop 0
	v_mul_f32_e32 v146, 2.0, v144
	v_fma_f32 v147, -v141, v146, 2.0
	v_fmac_f32_e32 v146, v147, v144
	v_div_fixup_f32 v141, v146, v141, 2.0
	v_rcp_f32_e32 v144, v140
	s_nop 0
	v_mul_f32_e32 v146, 2.0, v144
	v_fma_f32 v147, -v140, v146, 2.0
	v_fmac_f32_e32 v146, v147, v144
	v_div_fixup_f32 v140, v146, v140, 2.0
	v_pk_add_f32 v[140:141], v[140:141], 2.0 op_sel_hi:[1,0] neg_lo:[1,0] neg_hi:[1,0]
	s_nop 0
	v_pk_mul_f32 v[134:135], v[134:135], v[140:141]
	v_lshlrev_b32_e32 v140, 16, v151
	v_and_b32_e32 v141, 0xffff0000, v151
	v_pk_fma_f32 v[130:131], v[22:23], v[140:141], v[130:131]
	v_cvt_pk_bf16_f32 v133, v134, v135
	v_mul_f32_e32 v140, 0x3d372713, v130
	v_mul_f32_e32 v141, 0x3d372713, v131
	v_mul_f32_e32 v140, v130, v140
	v_mul_f32_e32 v141, v131, v141
	v_fma_f32 v140, v130, v140, v130
	v_fma_f32 v141, v131, v141, v131
	v_mul_f32_e32 v140, 0x3f4c422a, v140
	v_mul_f32_e32 v141, 0x3f4c422a, v141
	v_add_f32_e32 v140, v140, v140
	v_add_f32_e32 v141, v141, v141
	v_mul_f32_e32 v140, 0x3fb8aa3b, v140
	v_mul_f32_e32 v141, 0x3fb8aa3b, v141
	v_exp_f32_e32 v140, v140
	v_exp_f32_e32 v141, v141
	v_pk_mul_f32 v[130:131], v[130:131], 0.5 op_sel_hi:[1,0]
	v_cvt_pk_bf16_f32 v134, v128, v129
	v_pk_add_f32 v[140:141], v[140:141], 1.0 op_sel_hi:[1,0]
	s_nop 0
	v_rcp_f32_e32 v144, v141
	s_nop 0
	v_mul_f32_e32 v146, 2.0, v144
	v_fma_f32 v147, -v141, v146, 2.0
	v_fmac_f32_e32 v146, v147, v144
	v_div_fixup_f32 v141, v146, v141, 2.0
	v_rcp_f32_e32 v144, v140
	s_nop 0
	v_mul_f32_e32 v146, 2.0, v144
	v_fma_f32 v147, -v140, v146, 2.0
	v_fmac_f32_e32 v146, v147, v144
	v_div_fixup_f32 v140, v146, v140, 2.0
	v_pk_add_f32 v[140:141], v[140:141], 2.0 op_sel_hi:[1,0] neg_lo:[1,0] neg_hi:[1,0]
	s_nop 0
	v_pk_mul_f32 v[140:141], v[130:131], v[140:141]
	v_lshrrev_b32_e32 v130, 4, v178
	v_or_b32_e32 v128, v130, v176
	v_ashrrev_i32_e32 v129, 31, v128
	v_lshlrev_b64 v[128:129], 11, v[128:129]
	v_lshl_add_u64 v[128:129], s[4:5], 0, v[128:129]
	v_lshl_add_u64 v[128:129], v[128:129], 0, s[34:35]
	v_cvt_pk_bf16_f32 v135, v140, v141
	v_lshl_add_u64 v[128:129], v[128:129], 0, v[168:169]
	global_store_dwordx4 v[128:129], v[132:135], off
	v_or_b32_e32 v128, 0x200, v176
	s_nop 0
	v_lshlrev_b32_e32 v132, 16, v136
	v_and_b32_e32 v133, 0xffff0000, v136
	v_pk_fma_f32 v[120:121], v[24:25], v[132:133], v[120:121]
	s_nop 0
	v_mul_f32_e32 v129, 0x3d372713, v120
	v_mul_f32_e32 v129, v120, v129
	v_fma_f32 v129, v120, v129, v120
	v_mul_f32_e32 v129, 0x3f4c422a, v129
	v_add_f32_e32 v129, v129, v129
	v_mul_f32_e32 v129, 0x3fb8aa3b, v129
	v_exp_f32_e32 v132, v129
	v_mul_f32_e32 v129, 0x3d372713, v121
	v_mul_f32_e32 v129, v121, v129
	v_fma_f32 v129, v121, v129, v121
	v_mul_f32_e32 v129, 0x3f4c422a, v129
	v_add_f32_e32 v129, v129, v129
	v_mul_f32_e32 v129, 0x3fb8aa3b, v129
	v_exp_f32_e32 v133, v129
	v_pk_mul_f32 v[120:121], v[120:121], 0.5 op_sel_hi:[1,0]
	v_pk_add_f32 v[132:133], v[132:133], 1.0 op_sel_hi:[1,0]
	s_nop 0
	v_rcp_f32_e32 v131, v133
	s_nop 0
	v_mul_f32_e32 v135, 2.0, v131
	v_fma_f32 v136, -v133, v135, 2.0
	v_fmac_f32_e32 v135, v136, v131
	v_div_fixup_f32 v133, v135, v133, 2.0
	v_rcp_f32_e32 v131, v132
	s_nop 0
	v_mul_f32_e32 v135, 2.0, v131
	v_fma_f32 v136, -v132, v135, 2.0
	v_fmac_f32_e32 v135, v136, v131
	v_div_fixup_f32 v132, v135, v132, 2.0
	v_pk_add_f32 v[132:133], v[132:133], 2.0 op_sel_hi:[1,0] neg_lo:[1,0] neg_hi:[1,0]
	s_nop 0
	v_pk_mul_f32 v[120:121], v[120:121], v[132:133]
	v_lshlrev_b32_e32 v132, 16, v138
	v_and_b32_e32 v133, 0xffff0000, v138
	v_pk_fma_f32 v[116:117], v[20:21], v[132:133], v[116:117]
	s_nop 0
	v_mul_f32_e32 v129, 0x3d372713, v116
	v_mul_f32_e32 v129, v116, v129
	v_fma_f32 v129, v116, v129, v116
	v_mul_f32_e32 v129, 0x3f4c422a, v129
	v_add_f32_e32 v129, v129, v129
	v_mul_f32_e32 v129, 0x3fb8aa3b, v129
	v_exp_f32_e32 v132, v129
	v_mul_f32_e32 v129, 0x3d372713, v117
	v_mul_f32_e32 v129, v117, v129
	v_fma_f32 v129, v117, v129, v117
	v_mul_f32_e32 v129, 0x3f4c422a, v129
	v_add_f32_e32 v129, v129, v129
	v_mul_f32_e32 v129, 0x3fb8aa3b, v129
	v_exp_f32_e32 v133, v129
	v_pk_mul_f32 v[116:117], v[116:117], 0.5 op_sel_hi:[1,0]
	v_pk_add_f32 v[132:133], v[132:133], 1.0 op_sel_hi:[1,0]
	s_nop 0
	v_rcp_f32_e32 v131, v133
	s_nop 0
	v_mul_f32_e32 v135, 2.0, v131
	v_fma_f32 v136, -v133, v135, 2.0
	v_fmac_f32_e32 v135, v136, v131
	v_div_fixup_f32 v133, v135, v133, 2.0
; DI void unpack8(u32x4 w, float* f) { f[0] = bflo(w.x); f[1] = bfhi(w.x); f[2] = bflo(w.y); f[3] = bfhi(w.y); f[4] = bflo(w.z); f[5] = bfhi(w.z); f[6] = bflo(w.w); f[7] = bfhi(w.w); }
; DI u32x4 pack44(f32x4 a, f32x4 b) { u32x4 w; w.x = pk2(a[0], a[1]); w.y = pk2(a[2], a[3]); w.z = pk2(b[0], b[1]); w.w = pk2(b[2], b[3]); return w; }
; DI float gelu_tanh(float y) { float t = 0.7978845608f * (y + 0.044715f * y * y * y); float e = __expf(2.f * t); return 0.5f * y * (2.f - 2.f / (e + 1.f)); }
;     DI void operator()(const Acc& acc, const Unit& u, int wr, int wc, int fr, int fq) const {
;     ...
;                     for (int bj = 0; bj < 2; ++bj) { const int chunk = mt * 256 + ai * 128 + wr * 64 + (2 * mp + mi) * 16 + fr, n0 = nt * 256 + bj * 128 + wc * 32 + 8 * fq;
;                         uv[mi][bj] = *(const u32x4*)(uperm + (size_t)(g * 512 + chunk) * 640 + n0); }
; #pragma unroll
;                 for (int mi = 0; mi < 2; ++mi)
; #pragma unroll
;                     for (int bj = 0; bj < 2; ++bj) { const int m = 2 * mp + mi, chunk = mt * 256 + ai * 128 + wr * 64 + m * 16 + fr, n0 = nt * 256 + bj * 128 + wc * 32 + 8 * fq, t = n0 >> 4;
;                         f32x4 v0 = acc[ai][bj][m][0], v1 = acc[ai][bj][m][1]; float uf[8]; unpack8(uv[mi][bj], uf);
;                         for (int j = 0; j < 4; ++j) { v0[j] = gelu_tanh(v0[j] + d0[j] * uf[j]); v1[j] = gelu_tanh(v1[j] + d1[j] * uf[4 + j]); }
;                         *(u32x4*)(zs + (size_t)(chunk * 32 + t) * 1024 + g * 16 + ho0) = pack44(v0, v1); }
	v_rcp_f32_e32 v131, v132
	s_nop 0
	v_mul_f32_e32 v135, 2.0, v131
	v_fma_f32 v136, -v132, v135, 2.0
	v_fmac_f32_e32 v135, v136, v131
	v_div_fixup_f32 v132, v135, v132, 2.0
	v_pk_add_f32 v[132:133], v[132:133], 2.0 op_sel_hi:[1,0] neg_lo:[1,0] neg_hi:[1,0]
	s_nop 0
	v_pk_mul_f32 v[116:117], v[116:117], v[132:133]
	v_lshlrev_b32_e32 v132, 16, v137
	v_and_b32_e32 v133, 0xffff0000, v137
	v_pk_fma_f32 v[122:123], v[26:27], v[132:133], v[122:123]
	s_nop 0
	v_mul_f32_e32 v129, 0x3d372713, v122
	v_mul_f32_e32 v129, v122, v129
	v_fma_f32 v129, v122, v129, v122
	v_mul_f32_e32 v129, 0x3f4c422a, v129
	v_add_f32_e32 v129, v129, v129
	v_mul_f32_e32 v129, 0x3fb8aa3b, v129
	v_exp_f32_e32 v132, v129
	v_mul_f32_e32 v129, 0x3d372713, v123
	v_mul_f32_e32 v129, v123, v129
	v_fma_f32 v129, v123, v129, v123
	v_mul_f32_e32 v129, 0x3f4c422a, v129
	v_add_f32_e32 v129, v129, v129
	v_mul_f32_e32 v129, 0x3fb8aa3b, v129
	v_exp_f32_e32 v133, v129
	v_pk_mul_f32 v[122:123], v[122:123], 0.5 op_sel_hi:[1,0]
	v_pk_add_f32 v[132:133], v[132:133], 1.0 op_sel_hi:[1,0]
	s_nop 0
	v_rcp_f32_e32 v131, v133
	s_nop 0
	v_mul_f32_e32 v135, 2.0, v131
	v_fma_f32 v136, -v133, v135, 2.0
	v_fmac_f32_e32 v135, v136, v131
	v_div_fixup_f32 v133, v135, v133, 2.0
	v_rcp_f32_e32 v131, v132
	s_nop 0
	v_mul_f32_e32 v135, 2.0, v131
	v_fma_f32 v136, -v132, v135, 2.0
	v_fmac_f32_e32 v135, v136, v131
	v_div_fixup_f32 v132, v135, v132, 2.0
	v_pk_add_f32 v[132:133], v[132:133], 2.0 op_sel_hi:[1,0] neg_lo:[1,0] neg_hi:[1,0]
	s_nop 0
	v_pk_mul_f32 v[122:123], v[122:123], v[132:133]
	v_lshlrev_b32_e32 v132, 16, v139
	v_and_b32_e32 v133, 0xffff0000, v139
	v_pk_fma_f32 v[118:119], v[22:23], v[132:133], v[118:119]
	s_nop 0
	v_mul_f32_e32 v129, 0x3d372713, v118
	v_mul_f32_e32 v129, v118, v129
	v_fma_f32 v129, v118, v129, v118
	v_mul_f32_e32 v129, 0x3f4c422a, v129
	v_add_f32_e32 v129, v129, v129
	v_mul_f32_e32 v129, 0x3fb8aa3b, v129
	v_exp_f32_e32 v132, v129
	v_mul_f32_e32 v129, 0x3d372713, v119
	v_mul_f32_e32 v129, v119, v129
	v_fma_f32 v129, v119, v129, v119
	v_mul_f32_e32 v129, 0x3f4c422a, v129
	v_add_f32_e32 v129, v129, v129
	v_mul_f32_e32 v129, 0x3fb8aa3b, v129
	v_exp_f32_e32 v133, v129
	v_pk_mul_f32 v[118:119], v[118:119], 0.5 op_sel_hi:[1,0]
	v_pk_add_f32 v[132:133], v[132:133], 1.0 op_sel_hi:[1,0]
	s_nop 0
	v_rcp_f32_e32 v131, v133
	s_nop 0
	v_mul_f32_e32 v135, 2.0, v131
	v_fma_f32 v136, -v133, v135, 2.0
	v_fmac_f32_e32 v135, v136, v131
	v_div_fixup_f32 v133, v135, v133, 2.0
	v_rcp_f32_e32 v131, v132
	s_nop 0
	v_mul_f32_e32 v135, 2.0, v131
	v_fma_f32 v136, -v132, v135, 2.0
	v_fmac_f32_e32 v135, v136, v131
	v_div_fixup_f32 v132, v135, v132, 2.0
	v_pk_add_f32 v[132:133], v[132:133], 2.0 op_sel_hi:[1,0] neg_lo:[1,0] neg_hi:[1,0]
	s_nop 0
	v_pk_mul_f32 v[132:133], v[118:119], v[132:133]
	v_cvt_pk_bf16_f32 v118, v120, v121
	v_cvt_pk_bf16_f32 v120, v116, v117
	v_or_b32_e32 v116, v128, v142
	v_ashrrev_i32_e32 v117, 31, v116
	v_lshlrev_b64 v[116:117], 11, v[116:117]
	v_lshl_add_u64 v[116:117], s[4:5], 0, v[116:117]
	v_lshl_add_u64 v[116:117], v[116:117], 0, s[34:35]
	v_cvt_pk_bf16_f32 v119, v122, v123
	v_cvt_pk_bf16_f32 v121, v132, v133
	v_lshl_add_u64 v[116:117], v[116:117], 0, v[168:169]
	global_store_dwordx4 v[116:117], v[118:121], off
	v_lshlrev_b32_e32 v116, 16, v124
	v_and_b32_e32 v117, 0xffff0000, v124
	v_pk_fma_f32 v[112:113], v[24:25], v[116:117], v[112:113]
	v_or_b32_e32 v124, 0x400, v176
	v_mul_f32_e32 v116, 0x3d372713, v112
	v_mul_f32_e32 v117, 0x3d372713, v113
	v_mul_f32_e32 v116, v112, v116
	v_mul_f32_e32 v117, v113, v117
	v_fma_f32 v116, v112, v116, v112
	v_fma_f32 v117, v113, v117, v113
	v_mul_f32_e32 v116, 0x3f4c422a, v116
	v_mul_f32_e32 v117, 0x3f4c422a, v117
	v_add_f32_e32 v116, v116, v116
	v_add_f32_e32 v117, v117, v117
	v_mul_f32_e32 v116, 0x3fb8aa3b, v116
	v_mul_f32_e32 v117, 0x3fb8aa3b, v117
	v_exp_f32_e32 v116, v116
	v_exp_f32_e32 v117, v117
	v_pk_mul_f32 v[112:113], v[112:113], 0.5 op_sel_hi:[1,0]
	v_pk_add_f32 v[116:117], v[116:117], 1.0 op_sel_hi:[1,0]
	s_nop 0
	v_rcp_f32_e32 v119, v117
	s_nop 0
	v_mul_f32_e32 v121, 2.0, v119
	v_fma_f32 v122, -v117, v121, 2.0
	v_fmac_f32_e32 v121, v122, v119
	v_div_fixup_f32 v117, v121, v117, 2.0
	v_rcp_f32_e32 v119, v116
	s_nop 0
	v_mul_f32_e32 v121, 2.0, v119
	v_fma_f32 v122, -v116, v121, 2.0
	v_fmac_f32_e32 v121, v122, v119
	v_div_fixup_f32 v116, v121, v116, 2.0
	v_pk_add_f32 v[116:117], v[116:117], 2.0 op_sel_hi:[1,0] neg_lo:[1,0] neg_hi:[1,0]
	s_nop 0
	v_pk_mul_f32 v[112:113], v[112:113], v[116:117]
	v_lshlrev_b32_e32 v116, 16, v126
	v_and_b32_e32 v117, 0xffff0000, v126
	v_pk_fma_f32 v[108:109], v[20:21], v[116:117], v[108:109]
	s_nop 0
	v_mul_f32_e32 v116, 0x3d372713, v108
	v_mul_f32_e32 v117, 0x3d372713, v109
	v_mul_f32_e32 v116, v108, v116
	v_mul_f32_e32 v117, v109, v117
	v_fma_f32 v116, v108, v116, v108
	v_fma_f32 v117, v109, v117, v109
	v_mul_f32_e32 v116, 0x3f4c422a, v116
	v_mul_f32_e32 v117, 0x3f4c422a, v117
	v_add_f32_e32 v116, v116, v116
	v_add_f32_e32 v117, v117, v117
	v_mul_f32_e32 v116, 0x3fb8aa3b, v116
	v_mul_f32_e32 v117, 0x3fb8aa3b, v117
	v_exp_f32_e32 v116, v116
	v_exp_f32_e32 v117, v117
	v_pk_mul_f32 v[108:109], v[108:109], 0.5 op_sel_hi:[1,0]
	v_pk_add_f32 v[116:117], v[116:117], 1.0 op_sel_hi:[1,0]
	s_nop 0
	v_rcp_f32_e32 v119, v117
	s_nop 0
	v_mul_f32_e32 v121, 2.0, v119
	v_fma_f32 v122, -v117, v121, 2.0
	v_fmac_f32_e32 v121, v122, v119
	v_div_fixup_f32 v117, v121, v117, 2.0
	v_rcp_f32_e32 v119, v116
	s_nop 0
	v_mul_f32_e32 v121, 2.0, v119
	v_fma_f32 v122, -v116, v121, 2.0
	v_fmac_f32_e32 v121, v122, v119
	v_div_fixup_f32 v116, v121, v116, 2.0
	v_pk_add_f32 v[116:117], v[116:117], 2.0 op_sel_hi:[1,0] neg_lo:[1,0] neg_hi:[1,0]
; DI void unpack8(u32x4 w, float* f) { f[0] = bflo(w.x); f[1] = bfhi(w.x); f[2] = bflo(w.y); f[3] = bfhi(w.y); f[4] = bflo(w.z); f[5] = bfhi(w.z); f[6] = bflo(w.w); f[7] = bfhi(w.w); }
; DI u32x4 pack44(f32x4 a, f32x4 b) { u32x4 w; w.x = pk2(a[0], a[1]); w.y = pk2(a[2], a[3]); w.z = pk2(b[0], b[1]); w.w = pk2(b[2], b[3]); return w; }
; DI float gelu_tanh(float y) { float t = 0.7978845608f * (y + 0.044715f * y * y * y); float e = __expf(2.f * t); return 0.5f * y * (2.f - 2.f / (e + 1.f)); }
;     DI void operator()(const Acc& acc, const Unit& u, int wr, int wc, int fr, int fq) const {
;     ...
;                     for (int bj = 0; bj < 2; ++bj) { const int chunk = mt * 256 + ai * 128 + wr * 64 + (2 * mp + mi) * 16 + fr, n0 = nt * 256 + bj * 128 + wc * 32 + 8 * fq;
;                         uv[mi][bj] = *(const u32x4*)(uperm + (size_t)(g * 512 + chunk) * 640 + n0); }
; #pragma unroll
;                 for (int mi = 0; mi < 2; ++mi)
; #pragma unroll
;                     for (int bj = 0; bj < 2; ++bj) { const int m = 2 * mp + mi, chunk = mt * 256 + ai * 128 + wr * 64 + m * 16 + fr, n0 = nt * 256 + bj * 128 + wc * 32 + 8 * fq, t = n0 >> 4;
;                         f32x4 v0 = acc[ai][bj][m][0], v1 = acc[ai][bj][m][1]; float uf[8]; unpack8(uv[mi][bj], uf);
;                         for (int j = 0; j < 4; ++j) { v0[j] = gelu_tanh(v0[j] + d0[j] * uf[j]); v1[j] = gelu_tanh(v1[j] + d1[j] * uf[4 + j]); }
;                         *(u32x4*)(zs + (size_t)(chunk * 32 + t) * 1024 + g * 16 + ho0) = pack44(v0, v1); }
	s_nop 0
	v_pk_mul_f32 v[108:109], v[108:109], v[116:117]
	v_lshlrev_b32_e32 v116, 16, v125
	v_and_b32_e32 v117, 0xffff0000, v125
	v_pk_fma_f32 v[114:115], v[26:27], v[116:117], v[114:115]
	s_nop 0
	v_mul_f32_e32 v116, 0x3d372713, v114
	v_mul_f32_e32 v117, 0x3d372713, v115
	v_mul_f32_e32 v116, v114, v116
	v_mul_f32_e32 v117, v115, v117
	v_fma_f32 v116, v114, v116, v114
	v_fma_f32 v117, v115, v117, v115
	v_mul_f32_e32 v116, 0x3f4c422a, v116
	v_mul_f32_e32 v117, 0x3f4c422a, v117
	v_add_f32_e32 v116, v116, v116
	v_add_f32_e32 v117, v117, v117
	v_mul_f32_e32 v116, 0x3fb8aa3b, v116
	v_mul_f32_e32 v117, 0x3fb8aa3b, v117
	v_exp_f32_e32 v116, v116
	v_exp_f32_e32 v117, v117
	v_pk_mul_f32 v[114:115], v[114:115], 0.5 op_sel_hi:[1,0]
	v_pk_add_f32 v[116:117], v[116:117], 1.0 op_sel_hi:[1,0]
	s_nop 0
	v_rcp_f32_e32 v119, v117
	s_nop 0
	v_mul_f32_e32 v121, 2.0, v119
	v_fma_f32 v122, -v117, v121, 2.0
	v_fmac_f32_e32 v121, v122, v119
	v_div_fixup_f32 v117, v121, v117, 2.0
	v_rcp_f32_e32 v119, v116
	s_nop 0
	v_mul_f32_e32 v121, 2.0, v119
	v_fma_f32 v122, -v116, v121, 2.0
	v_fmac_f32_e32 v121, v122, v119
	v_div_fixup_f32 v116, v121, v116, 2.0
	v_pk_add_f32 v[116:117], v[116:117], 2.0 op_sel_hi:[1,0] neg_lo:[1,0] neg_hi:[1,0]
	s_nop 0
	v_pk_mul_f32 v[114:115], v[114:115], v[116:117]
	v_lshlrev_b32_e32 v116, 16, v127
	v_and_b32_e32 v117, 0xffff0000, v127
	v_pk_fma_f32 v[110:111], v[22:23], v[116:117], v[110:111]
	s_nop 0
	v_mul_f32_e32 v116, 0x3d372713, v110
	v_mul_f32_e32 v117, 0x3d372713, v111
	v_mul_f32_e32 v116, v110, v116
	v_mul_f32_e32 v117, v111, v117
	v_fma_f32 v116, v110, v116, v110
	v_fma_f32 v117, v111, v117, v111
	v_mul_f32_e32 v116, 0x3f4c422a, v116
	v_mul_f32_e32 v117, 0x3f4c422a, v117
	v_add_f32_e32 v116, v116, v116
	v_add_f32_e32 v117, v117, v117
	v_mul_f32_e32 v116, 0x3fb8aa3b, v116
	v_mul_f32_e32 v117, 0x3fb8aa3b, v117
	v_exp_f32_e32 v116, v116
	v_exp_f32_e32 v117, v117
	v_pk_mul_f32 v[110:111], v[110:111], 0.5 op_sel_hi:[1,0]
	v_pk_add_f32 v[116:117], v[116:117], 1.0 op_sel_hi:[1,0]
	s_nop 0
	v_rcp_f32_e32 v119, v117
	s_nop 0
	v_mul_f32_e32 v121, 2.0, v119
	v_fma_f32 v122, -v117, v121, 2.0
	v_fmac_f32_e32 v121, v122, v119
	v_div_fixup_f32 v117, v121, v117, 2.0
	v_rcp_f32_e32 v119, v116
	s_nop 0
	v_mul_f32_e32 v121, 2.0, v119
	v_fma_f32 v122, -v116, v121, 2.0
	v_fmac_f32_e32 v121, v122, v119
	v_div_fixup_f32 v116, v121, v116, 2.0
	v_pk_add_f32 v[116:117], v[116:117], 2.0 op_sel_hi:[1,0] neg_lo:[1,0] neg_hi:[1,0]
	s_nop 0
	v_pk_mul_f32 v[116:117], v[110:111], v[116:117]
	v_cvt_pk_bf16_f32 v110, v112, v113
	v_cvt_pk_bf16_f32 v112, v108, v109
	v_or_b32_e32 v108, v128, v130
	v_ashrrev_i32_e32 v109, 31, v108
	v_lshlrev_b64 v[108:109], 11, v[108:109]
	v_lshl_add_u64 v[108:109], s[4:5], 0, v[108:109]
	v_lshl_add_u64 v[108:109], v[108:109], 0, s[34:35]
	v_cvt_pk_bf16_f32 v111, v114, v115
	v_cvt_pk_bf16_f32 v113, v116, v117
	v_lshl_add_u64 v[108:109], v[108:109], 0, v[168:169]
	global_store_dwordx4 v[108:109], v[110:113], off
	v_or_b32_e32 v108, 32, v177
	v_mad_i64_i32 v[108:109], s[2:3], v108, s12, v[170:171]
	v_lshl_add_u64 v[108:109], v[108:109], 0, v[2:3]
	global_load_dwordx4 v[120:123], v[108:109], off
	global_load_dwordx4 v[116:119], v[108:109], off offset:256
	v_or_b32_e32 v108, 48, v177
	v_mad_i64_i32 v[108:109], s[2:3], v108, s12, v[170:171]
	v_lshl_add_u64 v[108:109], v[108:109], 0, v[2:3]
	global_load_dwordx4 v[112:115], v[108:109], off
	s_nop 0
	global_load_dwordx4 v[108:111], v[108:109], off offset:256
	s_waitcnt vmcnt(0)
	v_lshlrev_b32_e32 v126, 16, v120
	v_and_b32_e32 v127, 0xffff0000, v120
	v_pk_fma_f32 v[104:105], v[24:25], v[126:127], v[104:105]
	s_nop 0
	v_mul_f32_e32 v120, 0x3d372713, v104
	v_mul_f32_e32 v120, v104, v120
	v_fma_f32 v120, v104, v120, v104
	v_mul_f32_e32 v120, 0x3f4c422a, v120
	v_add_f32_e32 v120, v120, v120
	v_mul_f32_e32 v120, 0x3fb8aa3b, v120
	v_exp_f32_e32 v126, v120
	v_mul_f32_e32 v120, 0x3d372713, v105
	v_mul_f32_e32 v120, v105, v120
	v_fma_f32 v120, v105, v120, v105
	v_mul_f32_e32 v120, 0x3f4c422a, v120
	v_add_f32_e32 v120, v120, v120
	v_mul_f32_e32 v120, 0x3fb8aa3b, v120
	v_exp_f32_e32 v127, v120
	v_pk_mul_f32 v[104:105], v[104:105], 0.5 op_sel_hi:[1,0]
	v_pk_add_f32 v[126:127], v[126:127], 1.0 op_sel_hi:[1,0]
	s_nop 0
	v_rcp_f32_e32 v125, v127
	s_nop 0
	v_mul_f32_e32 v129, 2.0, v125
	v_fma_f32 v131, -v127, v129, 2.0
	v_fmac_f32_e32 v129, v131, v125
	v_div_fixup_f32 v127, v129, v127, 2.0
	v_rcp_f32_e32 v125, v126
	s_nop 0
	v_mul_f32_e32 v129, 2.0, v125
	v_fma_f32 v131, -v126, v129, 2.0
	v_fmac_f32_e32 v129, v131, v125
	v_div_fixup_f32 v126, v129, v126, 2.0
	v_pk_add_f32 v[126:127], v[126:127], 2.0 op_sel_hi:[1,0] neg_lo:[1,0] neg_hi:[1,0]
	s_nop 0
	v_pk_mul_f32 v[104:105], v[104:105], v[126:127]
	v_lshlrev_b32_e32 v126, 16, v122
	v_and_b32_e32 v127, 0xffff0000, v122
	v_pk_fma_f32 v[100:101], v[20:21], v[126:127], v[100:101]
	s_nop 0
	v_mul_f32_e32 v120, 0x3d372713, v100
	v_mul_f32_e32 v120, v100, v120
	v_fma_f32 v120, v100, v120, v100
	v_mul_f32_e32 v120, 0x3f4c422a, v120
	v_add_f32_e32 v120, v120, v120
	v_mul_f32_e32 v120, 0x3fb8aa3b, v120
	v_exp_f32_e32 v126, v120
	v_mul_f32_e32 v120, 0x3d372713, v101
	v_mul_f32_e32 v120, v101, v120
	v_fma_f32 v120, v101, v120, v101
	v_mul_f32_e32 v120, 0x3f4c422a, v120
	v_add_f32_e32 v120, v120, v120
	v_mul_f32_e32 v120, 0x3fb8aa3b, v120
	v_exp_f32_e32 v127, v120
	v_pk_mul_f32 v[100:101], v[100:101], 0.5 op_sel_hi:[1,0]
	v_pk_add_f32 v[126:127], v[126:127], 1.0 op_sel_hi:[1,0]
	s_nop 0
	v_rcp_f32_e32 v122, v127
	s_nop 0
	v_mul_f32_e32 v128, 2.0, v122
	v_fma_f32 v129, -v127, v128, 2.0
	v_fmac_f32_e32 v128, v129, v122
	v_div_fixup_f32 v127, v128, v127, 2.0
; DI void unpack8(u32x4 w, float* f) { f[0] = bflo(w.x); f[1] = bfhi(w.x); f[2] = bflo(w.y); f[3] = bfhi(w.y); f[4] = bflo(w.z); f[5] = bfhi(w.z); f[6] = bflo(w.w); f[7] = bfhi(w.w); }
; DI u32x4 pack44(f32x4 a, f32x4 b) { u32x4 w; w.x = pk2(a[0], a[1]); w.y = pk2(a[2], a[3]); w.z = pk2(b[0], b[1]); w.w = pk2(b[2], b[3]); return w; }
; DI float gelu_tanh(float y) { float t = 0.7978845608f * (y + 0.044715f * y * y * y); float e = __expf(2.f * t); return 0.5f * y * (2.f - 2.f / (e + 1.f)); }
;     DI void operator()(const Acc& acc, const Unit& u, int wr, int wc, int fr, int fq) const {
;     ...
;                     for (int bj = 0; bj < 2; ++bj) { const int chunk = mt * 256 + ai * 128 + wr * 64 + (2 * mp + mi) * 16 + fr, n0 = nt * 256 + bj * 128 + wc * 32 + 8 * fq;
;                         uv[mi][bj] = *(const u32x4*)(uperm + (size_t)(g * 512 + chunk) * 640 + n0); }
; #pragma unroll
;                 for (int mi = 0; mi < 2; ++mi)
; #pragma unroll
;                     for (int bj = 0; bj < 2; ++bj) { const int m = 2 * mp + mi, chunk = mt * 256 + ai * 128 + wr * 64 + m * 16 + fr, n0 = nt * 256 + bj * 128 + wc * 32 + 8 * fq, t = n0 >> 4;
;                         f32x4 v0 = acc[ai][bj][m][0], v1 = acc[ai][bj][m][1]; float uf[8]; unpack8(uv[mi][bj], uf);
;                         for (int j = 0; j < 4; ++j) { v0[j] = gelu_tanh(v0[j] + d0[j] * uf[j]); v1[j] = gelu_tanh(v1[j] + d1[j] * uf[4 + j]); }
;                         *(u32x4*)(zs + (size_t)(chunk * 32 + t) * 1024 + g * 16 + ho0) = pack44(v0, v1); }
	v_rcp_f32_e32 v122, v126
	s_nop 0
	v_mul_f32_e32 v128, 2.0, v122
	v_fma_f32 v129, -v126, v128, 2.0
	v_fmac_f32_e32 v128, v129, v122
	v_div_fixup_f32 v126, v128, v126, 2.0
	v_lshlrev_b32_e32 v120, 16, v121
	v_and_b32_e32 v121, 0xffff0000, v121
	v_pk_fma_f32 v[106:107], v[26:27], v[120:121], v[106:107]
	v_pk_add_f32 v[126:127], v[126:127], 2.0 op_sel_hi:[1,0] neg_lo:[1,0] neg_hi:[1,0]
	v_mul_f32_e32 v120, 0x3d372713, v106
	v_mul_f32_e32 v121, 0x3d372713, v107
	v_mul_f32_e32 v120, v106, v120
	v_mul_f32_e32 v121, v107, v121
	v_fma_f32 v120, v106, v120, v106
	v_fma_f32 v121, v107, v121, v107
	v_mul_f32_e32 v120, 0x3f4c422a, v120
	v_mul_f32_e32 v121, 0x3f4c422a, v121
	v_add_f32_e32 v120, v120, v120
	v_add_f32_e32 v121, v121, v121
	v_mul_f32_e32 v120, 0x3fb8aa3b, v120
	v_mul_f32_e32 v121, 0x3fb8aa3b, v121
	v_exp_f32_e32 v120, v120
	v_exp_f32_e32 v121, v121
	v_pk_mul_f32 v[100:101], v[100:101], v[126:127]
	v_pk_mul_f32 v[106:107], v[106:107], 0.5 op_sel_hi:[1,0]
	v_pk_add_f32 v[120:121], v[120:121], 1.0 op_sel_hi:[1,0]
	s_nop 0
	v_rcp_f32_e32 v125, v121
	s_nop 0
	v_mul_f32_e32 v127, 2.0, v125
	v_fma_f32 v128, -v121, v127, 2.0
	v_fmac_f32_e32 v127, v128, v125
	v_div_fixup_f32 v121, v127, v121, 2.0
	v_rcp_f32_e32 v125, v120
	s_nop 0
	v_mul_f32_e32 v127, 2.0, v125
	v_fma_f32 v128, -v120, v127, 2.0
	v_fmac_f32_e32 v127, v128, v125
	v_div_fixup_f32 v120, v127, v120, 2.0
	v_pk_add_f32 v[120:121], v[120:121], 2.0 op_sel_hi:[1,0] neg_lo:[1,0] neg_hi:[1,0]
	s_nop 0
	v_pk_mul_f32 v[106:107], v[106:107], v[120:121]
	v_lshlrev_b32_e32 v120, 16, v123
	v_and_b32_e32 v121, 0xffff0000, v123
	v_pk_fma_f32 v[102:103], v[22:23], v[120:121], v[102:103]
	s_nop 0
	v_mul_f32_e32 v120, 0x3d372713, v102
	v_mul_f32_e32 v121, 0x3d372713, v103
	v_mul_f32_e32 v120, v102, v120
	v_mul_f32_e32 v121, v103, v121
	v_fma_f32 v120, v102, v120, v102
	v_fma_f32 v121, v103, v121, v103
	v_mul_f32_e32 v120, 0x3f4c422a, v120
	v_mul_f32_e32 v121, 0x3f4c422a, v121
	v_add_f32_e32 v120, v120, v120
	v_add_f32_e32 v121, v121, v121
	v_mul_f32_e32 v120, 0x3fb8aa3b, v120
	v_mul_f32_e32 v121, 0x3fb8aa3b, v121
	v_exp_f32_e32 v120, v120
	v_exp_f32_e32 v121, v121
	v_pk_mul_f32 v[102:103], v[102:103], 0.5 op_sel_hi:[1,0]
	v_pk_add_f32 v[120:121], v[120:121], 1.0 op_sel_hi:[1,0]
	s_nop 0
	v_rcp_f32_e32 v123, v121
	s_nop 0
	v_mul_f32_e32 v126, 2.0, v123
	v_fma_f32 v127, -v121, v126, 2.0
	v_fmac_f32_e32 v126, v127, v123
	v_div_fixup_f32 v121, v126, v121, 2.0
	v_rcp_f32_e32 v123, v120
	s_nop 0
	v_mul_f32_e32 v126, 2.0, v123
	v_fma_f32 v127, -v120, v126, 2.0
	v_fmac_f32_e32 v126, v127, v123
	v_div_fixup_f32 v120, v126, v120, 2.0
	v_pk_add_f32 v[120:121], v[120:121], 2.0 op_sel_hi:[1,0] neg_lo:[1,0] neg_hi:[1,0]
	s_nop 0
	v_pk_mul_f32 v[120:121], v[102:103], v[120:121]
	v_cvt_pk_bf16_f32 v102, v104, v105
	v_cvt_pk_bf16_f32 v104, v100, v101
	v_or_b32_e32 v100, v124, v142
	v_ashrrev_i32_e32 v101, 31, v100
	v_lshlrev_b64 v[100:101], 11, v[100:101]
	v_lshl_add_u64 v[100:101], s[4:5], 0, v[100:101]
	v_lshl_add_u64 v[100:101], v[100:101], 0, s[34:35]
	v_cvt_pk_bf16_f32 v103, v106, v107
	v_cvt_pk_bf16_f32 v105, v120, v121
	v_lshl_add_u64 v[100:101], v[100:101], 0, v[168:169]
	global_store_dwordx4 v[100:101], v[102:105], off
	v_lshlrev_b32_e32 v100, 16, v116
	v_and_b32_e32 v101, 0xffff0000, v116
	v_pk_fma_f32 v[96:97], v[24:25], v[100:101], v[96:97]
	s_nop 0
	v_mul_f32_e32 v100, 0x3d372713, v96
	v_mul_f32_e32 v101, 0x3d372713, v97
	v_mul_f32_e32 v100, v96, v100
	v_mul_f32_e32 v101, v97, v101
	v_fma_f32 v100, v96, v100, v96
	v_fma_f32 v101, v97, v101, v97
	v_mul_f32_e32 v100, 0x3f4c422a, v100
	v_mul_f32_e32 v101, 0x3f4c422a, v101
	v_add_f32_e32 v100, v100, v100
	v_add_f32_e32 v101, v101, v101
	v_mul_f32_e32 v100, 0x3fb8aa3b, v100
	v_mul_f32_e32 v101, 0x3fb8aa3b, v101
	v_exp_f32_e32 v100, v100
	v_exp_f32_e32 v101, v101
	v_pk_mul_f32 v[96:97], v[96:97], 0.5 op_sel_hi:[1,0]
	v_pk_add_f32 v[100:101], v[100:101], 1.0 op_sel_hi:[1,0]
	s_nop 0
	v_rcp_f32_e32 v103, v101
	s_nop 0
	v_mul_f32_e32 v105, 2.0, v103
	v_fma_f32 v106, -v101, v105, 2.0
	v_fmac_f32_e32 v105, v106, v103
	v_div_fixup_f32 v101, v105, v101, 2.0
	v_rcp_f32_e32 v103, v100
	s_nop 0
	v_mul_f32_e32 v105, 2.0, v103
	v_fma_f32 v106, -v100, v105, 2.0
	v_fmac_f32_e32 v105, v106, v103
	v_div_fixup_f32 v100, v105, v100, 2.0
	v_pk_add_f32 v[100:101], v[100:101], 2.0 op_sel_hi:[1,0] neg_lo:[1,0] neg_hi:[1,0]
	s_nop 0
	v_pk_mul_f32 v[96:97], v[96:97], v[100:101]
	v_lshlrev_b32_e32 v100, 16, v118
	v_and_b32_e32 v101, 0xffff0000, v118
	v_pk_fma_f32 v[92:93], v[20:21], v[100:101], v[92:93]
	s_nop 0
	v_mul_f32_e32 v100, 0x3d372713, v92
	v_mul_f32_e32 v101, 0x3d372713, v93
	v_mul_f32_e32 v100, v92, v100
	v_mul_f32_e32 v101, v93, v101
	v_fma_f32 v100, v92, v100, v92
	v_fma_f32 v101, v93, v101, v93
	v_mul_f32_e32 v100, 0x3f4c422a, v100
	v_mul_f32_e32 v101, 0x3f4c422a, v101
	v_add_f32_e32 v100, v100, v100
	v_add_f32_e32 v101, v101, v101
	v_mul_f32_e32 v100, 0x3fb8aa3b, v100
	v_mul_f32_e32 v101, 0x3fb8aa3b, v101
	v_exp_f32_e32 v100, v100
	v_exp_f32_e32 v101, v101
	v_pk_mul_f32 v[92:93], v[92:93], 0.5 op_sel_hi:[1,0]
	v_pk_add_f32 v[100:101], v[100:101], 1.0 op_sel_hi:[1,0]
	s_nop 0
	v_rcp_f32_e32 v103, v101
	s_nop 0
	v_mul_f32_e32 v105, 2.0, v103
	v_fma_f32 v106, -v101, v105, 2.0
	v_fmac_f32_e32 v105, v106, v103
	v_div_fixup_f32 v101, v105, v101, 2.0
	v_rcp_f32_e32 v103, v100
	s_nop 0
	v_mul_f32_e32 v105, 2.0, v103
	v_fma_f32 v106, -v100, v105, 2.0
	v_fmac_f32_e32 v105, v106, v103
	v_div_fixup_f32 v100, v105, v100, 2.0
	v_pk_add_f32 v[100:101], v[100:101], 2.0 op_sel_hi:[1,0] neg_lo:[1,0] neg_hi:[1,0]
	s_nop 0
	v_pk_mul_f32 v[92:93], v[92:93], v[100:101]
	v_lshlrev_b32_e32 v100, 16, v117
; DI void unpack8(u32x4 w, float* f) { f[0] = bflo(w.x); f[1] = bfhi(w.x); f[2] = bflo(w.y); f[3] = bfhi(w.y); f[4] = bflo(w.z); f[5] = bfhi(w.z); f[6] = bflo(w.w); f[7] = bfhi(w.w); }
; DI u32x4 pack44(f32x4 a, f32x4 b) { u32x4 w; w.x = pk2(a[0], a[1]); w.y = pk2(a[2], a[3]); w.z = pk2(b[0], b[1]); w.w = pk2(b[2], b[3]); return w; }
; DI float gelu_tanh(float y) { float t = 0.7978845608f * (y + 0.044715f * y * y * y); float e = __expf(2.f * t); return 0.5f * y * (2.f - 2.f / (e + 1.f)); }
;     DI void operator()(const Acc& acc, const Unit& u, int wr, int wc, int fr, int fq) const {
;     ...
;                     for (int bj = 0; bj < 2; ++bj) { const int chunk = mt * 256 + ai * 128 + wr * 64 + (2 * mp + mi) * 16 + fr, n0 = nt * 256 + bj * 128 + wc * 32 + 8 * fq;
;                         uv[mi][bj] = *(const u32x4*)(uperm + (size_t)(g * 512 + chunk) * 640 + n0); }
; #pragma unroll
;                 for (int mi = 0; mi < 2; ++mi)
; #pragma unroll
;                     for (int bj = 0; bj < 2; ++bj) { const int m = 2 * mp + mi, chunk = mt * 256 + ai * 128 + wr * 64 + m * 16 + fr, n0 = nt * 256 + bj * 128 + wc * 32 + 8 * fq, t = n0 >> 4;
;                         f32x4 v0 = acc[ai][bj][m][0], v1 = acc[ai][bj][m][1]; float uf[8]; unpack8(uv[mi][bj], uf);
;                         for (int j = 0; j < 4; ++j) { v0[j] = gelu_tanh(v0[j] + d0[j] * uf[j]); v1[j] = gelu_tanh(v1[j] + d1[j] * uf[4 + j]); }
;                         *(u32x4*)(zs + (size_t)(chunk * 32 + t) * 1024 + g * 16 + ho0) = pack44(v0, v1); }
	v_and_b32_e32 v101, 0xffff0000, v117
	v_pk_fma_f32 v[98:99], v[26:27], v[100:101], v[98:99]
	s_nop 0
	v_mul_f32_e32 v100, 0x3d372713, v98
	v_mul_f32_e32 v101, 0x3d372713, v99
	v_mul_f32_e32 v100, v98, v100
	v_mul_f32_e32 v101, v99, v101
	v_fma_f32 v100, v98, v100, v98
	v_fma_f32 v101, v99, v101, v99
	v_mul_f32_e32 v100, 0x3f4c422a, v100
	v_mul_f32_e32 v101, 0x3f4c422a, v101
	v_add_f32_e32 v100, v100, v100
	v_add_f32_e32 v101, v101, v101
	v_mul_f32_e32 v100, 0x3fb8aa3b, v100
	v_mul_f32_e32 v101, 0x3fb8aa3b, v101
	v_exp_f32_e32 v100, v100
	v_exp_f32_e32 v101, v101
	v_pk_mul_f32 v[98:99], v[98:99], 0.5 op_sel_hi:[1,0]
	v_pk_add_f32 v[100:101], v[100:101], 1.0 op_sel_hi:[1,0]
	s_nop 0
	v_rcp_f32_e32 v103, v101
	s_nop 0
	v_mul_f32_e32 v105, 2.0, v103
	v_fma_f32 v106, -v101, v105, 2.0
	v_fmac_f32_e32 v105, v106, v103
	v_div_fixup_f32 v101, v105, v101, 2.0
	v_rcp_f32_e32 v103, v100
	s_nop 0
	v_mul_f32_e32 v105, 2.0, v103
	v_fma_f32 v106, -v100, v105, 2.0
	v_fmac_f32_e32 v105, v106, v103
	v_div_fixup_f32 v100, v105, v100, 2.0
	v_pk_add_f32 v[100:101], v[100:101], 2.0 op_sel_hi:[1,0] neg_lo:[1,0] neg_hi:[1,0]
	s_nop 0
	v_pk_mul_f32 v[98:99], v[98:99], v[100:101]
	v_lshlrev_b32_e32 v100, 16, v119
	v_and_b32_e32 v101, 0xffff0000, v119
	v_pk_fma_f32 v[94:95], v[22:23], v[100:101], v[94:95]
	s_nop 0
	v_mul_f32_e32 v100, 0x3d372713, v94
	v_mul_f32_e32 v101, 0x3d372713, v95
	v_mul_f32_e32 v100, v94, v100
	v_mul_f32_e32 v101, v95, v101
	v_fma_f32 v100, v94, v100, v94
	v_fma_f32 v101, v95, v101, v95
	v_mul_f32_e32 v100, 0x3f4c422a, v100
	v_mul_f32_e32 v101, 0x3f4c422a, v101
	v_add_f32_e32 v100, v100, v100
	v_add_f32_e32 v101, v101, v101
	v_mul_f32_e32 v100, 0x3fb8aa3b, v100
	v_mul_f32_e32 v101, 0x3fb8aa3b, v101
	v_exp_f32_e32 v100, v100
	v_exp_f32_e32 v101, v101
	v_pk_mul_f32 v[94:95], v[94:95], 0.5 op_sel_hi:[1,0]
	v_pk_add_f32 v[100:101], v[100:101], 1.0 op_sel_hi:[1,0]
	s_nop 0
	v_rcp_f32_e32 v103, v101
	s_nop 0
	v_mul_f32_e32 v105, 2.0, v103
	v_fma_f32 v106, -v101, v105, 2.0
	v_fmac_f32_e32 v105, v106, v103
	v_div_fixup_f32 v101, v105, v101, 2.0
	v_rcp_f32_e32 v103, v100
	s_nop 0
	v_mul_f32_e32 v105, 2.0, v103
	v_fma_f32 v106, -v100, v105, 2.0
	v_fmac_f32_e32 v105, v106, v103
	v_div_fixup_f32 v100, v105, v100, 2.0
	v_pk_add_f32 v[100:101], v[100:101], 2.0 op_sel_hi:[1,0] neg_lo:[1,0] neg_hi:[1,0]
	s_nop 0
	v_pk_mul_f32 v[100:101], v[94:95], v[100:101]
	v_cvt_pk_bf16_f32 v94, v96, v97
	v_cvt_pk_bf16_f32 v96, v92, v93
	v_or_b32_e32 v92, v124, v130
	v_ashrrev_i32_e32 v93, 31, v92
	v_lshlrev_b64 v[92:93], 11, v[92:93]
	v_lshl_add_u64 v[92:93], s[4:5], 0, v[92:93]
	v_lshl_add_u64 v[92:93], v[92:93], 0, s[34:35]
	v_cvt_pk_bf16_f32 v95, v98, v99
	v_cvt_pk_bf16_f32 v97, v100, v101
	v_lshl_add_u64 v[92:93], v[92:93], 0, v[168:169]
	global_store_dwordx4 v[92:93], v[94:97], off
	v_or_b32_e32 v92, 0x600, v176
	s_nop 0
	v_lshlrev_b32_e32 v94, 16, v112
	v_and_b32_e32 v95, 0xffff0000, v112
	v_pk_fma_f32 v[88:89], v[24:25], v[94:95], v[88:89]
	s_nop 0
	v_mul_f32_e32 v93, 0x3d372713, v88
	v_mul_f32_e32 v93, v88, v93
	v_fma_f32 v93, v88, v93, v88
	v_mul_f32_e32 v93, 0x3f4c422a, v93
	v_add_f32_e32 v93, v93, v93
	v_mul_f32_e32 v93, 0x3fb8aa3b, v93
	v_exp_f32_e32 v94, v93
	v_mul_f32_e32 v93, 0x3d372713, v89
	v_mul_f32_e32 v93, v89, v93
	v_fma_f32 v93, v89, v93, v89
	v_mul_f32_e32 v93, 0x3f4c422a, v93
	v_add_f32_e32 v93, v93, v93
	v_mul_f32_e32 v93, 0x3fb8aa3b, v93
	v_exp_f32_e32 v95, v93
	v_pk_mul_f32 v[88:89], v[88:89], 0.5 op_sel_hi:[1,0]
	v_pk_add_f32 v[94:95], v[94:95], 1.0 op_sel_hi:[1,0]
	s_nop 0
	v_rcp_f32_e32 v96, v95
	s_nop 0
	v_mul_f32_e32 v98, 2.0, v96
	v_fma_f32 v99, -v95, v98, 2.0
	v_fmac_f32_e32 v98, v99, v96
	v_div_fixup_f32 v95, v98, v95, 2.0
	v_rcp_f32_e32 v96, v94
	s_nop 0
	v_mul_f32_e32 v98, 2.0, v96
	v_fma_f32 v99, -v94, v98, 2.0
	v_fmac_f32_e32 v98, v99, v96
	v_div_fixup_f32 v94, v98, v94, 2.0
	v_pk_add_f32 v[94:95], v[94:95], 2.0 op_sel_hi:[1,0] neg_lo:[1,0] neg_hi:[1,0]
	s_nop 0
	v_pk_mul_f32 v[88:89], v[88:89], v[94:95]
	v_lshlrev_b32_e32 v94, 16, v114
	v_and_b32_e32 v95, 0xffff0000, v114
	v_pk_fma_f32 v[84:85], v[20:21], v[94:95], v[84:85]
	s_nop 0
	v_mul_f32_e32 v93, 0x3d372713, v84
	v_mul_f32_e32 v93, v84, v93
	v_fma_f32 v93, v84, v93, v84
	v_mul_f32_e32 v93, 0x3f4c422a, v93
	v_add_f32_e32 v93, v93, v93
	v_mul_f32_e32 v93, 0x3fb8aa3b, v93
	v_exp_f32_e32 v94, v93
	v_mul_f32_e32 v93, 0x3d372713, v85
	v_mul_f32_e32 v93, v85, v93
	v_fma_f32 v93, v85, v93, v85
	v_mul_f32_e32 v93, 0x3f4c422a, v93
	v_add_f32_e32 v93, v93, v93
	v_mul_f32_e32 v93, 0x3fb8aa3b, v93
	v_exp_f32_e32 v95, v93
	v_pk_mul_f32 v[84:85], v[84:85], 0.5 op_sel_hi:[1,0]
	v_pk_add_f32 v[94:95], v[94:95], 1.0 op_sel_hi:[1,0]
	s_nop 0
	v_rcp_f32_e32 v96, v95
	s_nop 0
	v_mul_f32_e32 v98, 2.0, v96
	v_fma_f32 v99, -v95, v98, 2.0
	v_fmac_f32_e32 v98, v99, v96
	v_div_fixup_f32 v95, v98, v95, 2.0
	v_rcp_f32_e32 v96, v94
	s_nop 0
	v_mul_f32_e32 v98, 2.0, v96
	v_fma_f32 v99, -v94, v98, 2.0
	v_fmac_f32_e32 v98, v99, v96
	v_div_fixup_f32 v94, v98, v94, 2.0
	v_pk_add_f32 v[94:95], v[94:95], 2.0 op_sel_hi:[1,0] neg_lo:[1,0] neg_hi:[1,0]
	s_nop 0
	v_pk_mul_f32 v[84:85], v[84:85], v[94:95]
	v_lshlrev_b32_e32 v94, 16, v113
	v_and_b32_e32 v95, 0xffff0000, v113
	v_pk_fma_f32 v[90:91], v[26:27], v[94:95], v[90:91]
	s_nop 0
	v_mul_f32_e32 v93, 0x3d372713, v90
	v_mul_f32_e32 v93, v90, v93
	v_fma_f32 v93, v90, v93, v90
	v_mul_f32_e32 v93, 0x3f4c422a, v93
	v_add_f32_e32 v93, v93, v93
	v_mul_f32_e32 v93, 0x3fb8aa3b, v93
	v_exp_f32_e32 v94, v93
	v_mul_f32_e32 v93, 0x3d372713, v91
	v_mul_f32_e32 v93, v91, v93
	v_fma_f32 v93, v91, v93, v91
	v_mul_f32_e32 v93, 0x3f4c422a, v93
	v_add_f32_e32 v93, v93, v93
; DI void unpack8(u32x4 w, float* f) { f[0] = bflo(w.x); f[1] = bfhi(w.x); f[2] = bflo(w.y); f[3] = bfhi(w.y); f[4] = bflo(w.z); f[5] = bfhi(w.z); f[6] = bflo(w.w); f[7] = bfhi(w.w); }
; DI u32x4 pack44(f32x4 a, f32x4 b) { u32x4 w; w.x = pk2(a[0], a[1]); w.y = pk2(a[2], a[3]); w.z = pk2(b[0], b[1]); w.w = pk2(b[2], b[3]); return w; }
; DI float gelu_tanh(float y) { float t = 0.7978845608f * (y + 0.044715f * y * y * y); float e = __expf(2.f * t); return 0.5f * y * (2.f - 2.f / (e + 1.f)); }
;     DI void operator()(const Acc& acc, const Unit& u, int wr, int wc, int fr, int fq) const {
;     ...
;                     for (int bj = 0; bj < 2; ++bj) { const int chunk = mt * 256 + ai * 128 + wr * 64 + (2 * mp + mi) * 16 + fr, n0 = nt * 256 + bj * 128 + wc * 32 + 8 * fq;
;                         uv[mi][bj] = *(const u32x4*)(uperm + (size_t)(g * 512 + chunk) * 640 + n0); }
; #pragma unroll
;                 for (int mi = 0; mi < 2; ++mi)
; #pragma unroll
;                     for (int bj = 0; bj < 2; ++bj) { const int m = 2 * mp + mi, chunk = mt * 256 + ai * 128 + wr * 64 + m * 16 + fr, n0 = nt * 256 + bj * 128 + wc * 32 + 8 * fq, t = n0 >> 4;
;                         f32x4 v0 = acc[ai][bj][m][0], v1 = acc[ai][bj][m][1]; float uf[8]; unpack8(uv[mi][bj], uf);
;                         for (int j = 0; j < 4; ++j) { v0[j] = gelu_tanh(v0[j] + d0[j] * uf[j]); v1[j] = gelu_tanh(v1[j] + d1[j] * uf[4 + j]); }
;                         *(u32x4*)(zs + (size_t)(chunk * 32 + t) * 1024 + g * 16 + ho0) = pack44(v0, v1); }
	v_mul_f32_e32 v93, 0x3fb8aa3b, v93
	v_exp_f32_e32 v95, v93
	v_pk_mul_f32 v[90:91], v[90:91], 0.5 op_sel_hi:[1,0]
	v_pk_add_f32 v[94:95], v[94:95], 1.0 op_sel_hi:[1,0]
	s_nop 0
	v_rcp_f32_e32 v96, v95
	s_nop 0
	v_mul_f32_e32 v98, 2.0, v96
	v_fma_f32 v99, -v95, v98, 2.0
	v_fmac_f32_e32 v98, v99, v96
	v_div_fixup_f32 v95, v98, v95, 2.0
	v_rcp_f32_e32 v96, v94
	s_nop 0
	v_mul_f32_e32 v98, 2.0, v96
	v_fma_f32 v99, -v94, v98, 2.0
	v_fmac_f32_e32 v98, v99, v96
	v_div_fixup_f32 v94, v98, v94, 2.0
	v_pk_add_f32 v[94:95], v[94:95], 2.0 op_sel_hi:[1,0] neg_lo:[1,0] neg_hi:[1,0]
	s_nop 0
	v_pk_mul_f32 v[90:91], v[90:91], v[94:95]
	v_lshlrev_b32_e32 v94, 16, v115
	v_and_b32_e32 v95, 0xffff0000, v115
	v_pk_fma_f32 v[86:87], v[22:23], v[94:95], v[86:87]
	s_nop 0
	v_mul_f32_e32 v93, 0x3d372713, v86
	v_mul_f32_e32 v93, v86, v93
	v_fma_f32 v93, v86, v93, v86
	v_mul_f32_e32 v93, 0x3f4c422a, v93
	v_add_f32_e32 v93, v93, v93
	v_mul_f32_e32 v93, 0x3fb8aa3b, v93
	v_exp_f32_e32 v94, v93
	v_mul_f32_e32 v93, 0x3d372713, v87
	v_mul_f32_e32 v93, v87, v93
	v_fma_f32 v93, v87, v93, v87
	v_mul_f32_e32 v93, 0x3f4c422a, v93
	v_add_f32_e32 v93, v93, v93
	v_mul_f32_e32 v93, 0x3fb8aa3b, v93
	v_exp_f32_e32 v95, v93
	v_pk_mul_f32 v[86:87], v[86:87], 0.5 op_sel_hi:[1,0]
	v_pk_add_f32 v[94:95], v[94:95], 1.0 op_sel_hi:[1,0]
	s_nop 0
	v_rcp_f32_e32 v96, v95
	s_nop 0
	v_mul_f32_e32 v98, 2.0, v96
	v_fma_f32 v99, -v95, v98, 2.0
	v_fmac_f32_e32 v98, v99, v96
	v_div_fixup_f32 v95, v98, v95, 2.0
	v_rcp_f32_e32 v96, v94
	s_nop 0
	v_mul_f32_e32 v98, 2.0, v96
	v_fma_f32 v99, -v94, v98, 2.0
	v_fmac_f32_e32 v98, v99, v96
	v_div_fixup_f32 v94, v98, v94, 2.0
	v_pk_add_f32 v[94:95], v[94:95], 2.0 op_sel_hi:[1,0] neg_lo:[1,0] neg_hi:[1,0]
	s_nop 0
	v_pk_mul_f32 v[94:95], v[86:87], v[94:95]
	v_cvt_pk_bf16_f32 v86, v88, v89
	v_cvt_pk_bf16_f32 v88, v84, v85
	v_or_b32_e32 v84, v92, v142
	v_ashrrev_i32_e32 v85, 31, v84
	v_lshlrev_b64 v[84:85], 11, v[84:85]
	v_lshl_add_u64 v[84:85], s[4:5], 0, v[84:85]
	v_lshl_add_u64 v[84:85], v[84:85], 0, s[34:35]
	v_cvt_pk_bf16_f32 v87, v90, v91
	v_cvt_pk_bf16_f32 v89, v94, v95
	v_lshl_add_u64 v[84:85], v[84:85], 0, v[168:169]
	global_store_dwordx4 v[84:85], v[86:89], off
	v_lshlrev_b32_e32 v84, 16, v108
	v_and_b32_e32 v85, 0xffff0000, v108
	v_pk_fma_f32 v[80:81], v[24:25], v[84:85], v[80:81]
	s_nop 0
	v_mul_f32_e32 v84, 0x3d372713, v80
	v_mul_f32_e32 v85, 0x3d372713, v81
	v_mul_f32_e32 v84, v80, v84
	v_mul_f32_e32 v85, v81, v85
	v_fma_f32 v84, v80, v84, v80
	v_fma_f32 v85, v81, v85, v81
	v_mul_f32_e32 v84, 0x3f4c422a, v84
	v_mul_f32_e32 v85, 0x3f4c422a, v85
	v_add_f32_e32 v84, v84, v84
	v_add_f32_e32 v85, v85, v85
	v_mul_f32_e32 v84, 0x3fb8aa3b, v84
	v_mul_f32_e32 v85, 0x3fb8aa3b, v85
	v_exp_f32_e32 v84, v84
	v_exp_f32_e32 v85, v85
	v_pk_mul_f32 v[80:81], v[80:81], 0.5 op_sel_hi:[1,0]
	v_pk_add_f32 v[84:85], v[84:85], 1.0 op_sel_hi:[1,0]
	s_nop 0
	v_rcp_f32_e32 v87, v85
	s_nop 0
	v_mul_f32_e32 v89, 2.0, v87
	v_fma_f32 v90, -v85, v89, 2.0
	v_fmac_f32_e32 v89, v90, v87
	v_div_fixup_f32 v85, v89, v85, 2.0
	v_rcp_f32_e32 v87, v84
	s_nop 0
	v_mul_f32_e32 v89, 2.0, v87
	v_fma_f32 v90, -v84, v89, 2.0
	v_fmac_f32_e32 v89, v90, v87
	v_div_fixup_f32 v84, v89, v84, 2.0
	v_pk_add_f32 v[84:85], v[84:85], 2.0 op_sel_hi:[1,0] neg_lo:[1,0] neg_hi:[1,0]
	s_nop 0
	v_pk_mul_f32 v[80:81], v[80:81], v[84:85]
	v_lshlrev_b32_e32 v84, 16, v110
	v_and_b32_e32 v85, 0xffff0000, v110
	v_pk_fma_f32 v[76:77], v[20:21], v[84:85], v[76:77]
	s_nop 0
	v_mul_f32_e32 v84, 0x3d372713, v76
	v_mul_f32_e32 v85, 0x3d372713, v77
	v_mul_f32_e32 v84, v76, v84
	v_mul_f32_e32 v85, v77, v85
	v_fma_f32 v84, v76, v84, v76
	v_fma_f32 v85, v77, v85, v77
	v_mul_f32_e32 v84, 0x3f4c422a, v84
	v_mul_f32_e32 v85, 0x3f4c422a, v85
	v_add_f32_e32 v84, v84, v84
	v_add_f32_e32 v85, v85, v85
	v_mul_f32_e32 v84, 0x3fb8aa3b, v84
	v_mul_f32_e32 v85, 0x3fb8aa3b, v85
	v_exp_f32_e32 v84, v84
	v_exp_f32_e32 v85, v85
	v_pk_mul_f32 v[76:77], v[76:77], 0.5 op_sel_hi:[1,0]
	v_pk_add_f32 v[84:85], v[84:85], 1.0 op_sel_hi:[1,0]
	s_nop 0
	v_rcp_f32_e32 v87, v85
	s_nop 0
	v_mul_f32_e32 v89, 2.0, v87
	v_fma_f32 v90, -v85, v89, 2.0
	v_fmac_f32_e32 v89, v90, v87
	v_div_fixup_f32 v85, v89, v85, 2.0
	v_rcp_f32_e32 v87, v84
	s_nop 0
	v_mul_f32_e32 v89, 2.0, v87
	v_fma_f32 v90, -v84, v89, 2.0
	v_fmac_f32_e32 v89, v90, v87
	v_div_fixup_f32 v84, v89, v84, 2.0
	v_pk_add_f32 v[84:85], v[84:85], 2.0 op_sel_hi:[1,0] neg_lo:[1,0] neg_hi:[1,0]
	s_nop 0
	v_pk_mul_f32 v[76:77], v[76:77], v[84:85]
	v_lshlrev_b32_e32 v84, 16, v109
	v_and_b32_e32 v85, 0xffff0000, v109
	v_pk_fma_f32 v[82:83], v[26:27], v[84:85], v[82:83]
	s_nop 0
	v_mul_f32_e32 v84, 0x3d372713, v82
	v_mul_f32_e32 v85, 0x3d372713, v83
	v_mul_f32_e32 v84, v82, v84
	v_mul_f32_e32 v85, v83, v85
	v_fma_f32 v84, v82, v84, v82
	v_fma_f32 v85, v83, v85, v83
	v_mul_f32_e32 v84, 0x3f4c422a, v84
	v_mul_f32_e32 v85, 0x3f4c422a, v85
	v_add_f32_e32 v84, v84, v84
	v_add_f32_e32 v85, v85, v85
	v_mul_f32_e32 v84, 0x3fb8aa3b, v84
	v_mul_f32_e32 v85, 0x3fb8aa3b, v85
	v_exp_f32_e32 v84, v84
	v_exp_f32_e32 v85, v85
	v_pk_mul_f32 v[82:83], v[82:83], 0.5 op_sel_hi:[1,0]
	v_pk_add_f32 v[84:85], v[84:85], 1.0 op_sel_hi:[1,0]
	s_nop 0
	v_rcp_f32_e32 v87, v85
	s_nop 0
	v_mul_f32_e32 v89, 2.0, v87
	v_fma_f32 v90, -v85, v89, 2.0
	v_fmac_f32_e32 v89, v90, v87
	v_div_fixup_f32 v85, v89, v85, 2.0
	v_rcp_f32_e32 v87, v84
	s_nop 0
	v_mul_f32_e32 v89, 2.0, v87
	v_fma_f32 v90, -v84, v89, 2.0
	v_fmac_f32_e32 v89, v90, v87
	v_div_fixup_f32 v84, v89, v84, 2.0
	v_pk_add_f32 v[84:85], v[84:85], 2.0 op_sel_hi:[1,0] neg_lo:[1,0] neg_hi:[1,0]
	s_nop 0
	v_pk_mul_f32 v[82:83], v[82:83], v[84:85]
	v_lshlrev_b32_e32 v84, 16, v111
; DI void unpack8(u32x4 w, float* f) { f[0] = bflo(w.x); f[1] = bfhi(w.x); f[2] = bflo(w.y); f[3] = bfhi(w.y); f[4] = bflo(w.z); f[5] = bfhi(w.z); f[6] = bflo(w.w); f[7] = bfhi(w.w); }
; DI u32x4 pack44(f32x4 a, f32x4 b) { u32x4 w; w.x = pk2(a[0], a[1]); w.y = pk2(a[2], a[3]); w.z = pk2(b[0], b[1]); w.w = pk2(b[2], b[3]); return w; }
; DI float gelu_tanh(float y) { float t = 0.7978845608f * (y + 0.044715f * y * y * y); float e = __expf(2.f * t); return 0.5f * y * (2.f - 2.f / (e + 1.f)); }
;     DI void operator()(const Acc& acc, const Unit& u, int wr, int wc, int fr, int fq) const {
;     ...
;                     for (int bj = 0; bj < 2; ++bj) { const int chunk = mt * 256 + ai * 128 + wr * 64 + (2 * mp + mi) * 16 + fr, n0 = nt * 256 + bj * 128 + wc * 32 + 8 * fq;
;                         uv[mi][bj] = *(const u32x4*)(uperm + (size_t)(g * 512 + chunk) * 640 + n0); }
; #pragma unroll
;                 for (int mi = 0; mi < 2; ++mi)
; #pragma unroll
;                     for (int bj = 0; bj < 2; ++bj) { const int m = 2 * mp + mi, chunk = mt * 256 + ai * 128 + wr * 64 + m * 16 + fr, n0 = nt * 256 + bj * 128 + wc * 32 + 8 * fq, t = n0 >> 4;
;                         f32x4 v0 = acc[ai][bj][m][0], v1 = acc[ai][bj][m][1]; float uf[8]; unpack8(uv[mi][bj], uf);
;                         for (int j = 0; j < 4; ++j) { v0[j] = gelu_tanh(v0[j] + d0[j] * uf[j]); v1[j] = gelu_tanh(v1[j] + d1[j] * uf[4 + j]); }
;                         *(u32x4*)(zs + (size_t)(chunk * 32 + t) * 1024 + g * 16 + ho0) = pack44(v0, v1); }
	v_and_b32_e32 v85, 0xffff0000, v111
	v_pk_fma_f32 v[78:79], v[22:23], v[84:85], v[78:79]
	s_nop 0
	v_mul_f32_e32 v84, 0x3d372713, v78
	v_mul_f32_e32 v85, 0x3d372713, v79
	v_mul_f32_e32 v84, v78, v84
	v_mul_f32_e32 v85, v79, v85
	v_fma_f32 v84, v78, v84, v78
	v_fma_f32 v85, v79, v85, v79
	v_mul_f32_e32 v84, 0x3f4c422a, v84
	v_mul_f32_e32 v85, 0x3f4c422a, v85
	v_add_f32_e32 v84, v84, v84
	v_add_f32_e32 v85, v85, v85
	v_mul_f32_e32 v84, 0x3fb8aa3b, v84
	v_mul_f32_e32 v85, 0x3fb8aa3b, v85
	v_exp_f32_e32 v84, v84
	v_exp_f32_e32 v85, v85
	v_pk_mul_f32 v[78:79], v[78:79], 0.5 op_sel_hi:[1,0]
	v_pk_add_f32 v[84:85], v[84:85], 1.0 op_sel_hi:[1,0]
	s_nop 0
	v_rcp_f32_e32 v87, v85
	s_nop 0
	v_mul_f32_e32 v89, 2.0, v87
	v_fma_f32 v90, -v85, v89, 2.0
	v_fmac_f32_e32 v89, v90, v87
	v_div_fixup_f32 v85, v89, v85, 2.0
	v_rcp_f32_e32 v87, v84
	s_nop 0
	v_mul_f32_e32 v89, 2.0, v87
	v_fma_f32 v90, -v84, v89, 2.0
	v_fmac_f32_e32 v89, v90, v87
	v_div_fixup_f32 v84, v89, v84, 2.0
	v_pk_add_f32 v[84:85], v[84:85], 2.0 op_sel_hi:[1,0] neg_lo:[1,0] neg_hi:[1,0]
	s_nop 0
	v_pk_mul_f32 v[84:85], v[78:79], v[84:85]
	v_cvt_pk_bf16_f32 v78, v80, v81
	v_cvt_pk_bf16_f32 v80, v76, v77
	v_or_b32_e32 v76, v92, v130
	v_ashrrev_i32_e32 v77, 31, v76
	v_lshlrev_b64 v[76:77], 11, v[76:77]
	v_lshl_add_u64 v[76:77], s[4:5], 0, v[76:77]
	v_lshl_add_u64 v[76:77], v[76:77], 0, s[34:35]
	v_cvt_pk_bf16_f32 v79, v82, v83
	v_cvt_pk_bf16_f32 v81, v84, v85
	v_lshl_add_u64 v[76:77], v[76:77], 0, v[168:169]
	global_store_dwordx4 v[76:77], v[78:81], off
	v_add_u32_e32 v76, 0x80, v177
	v_mad_i64_i32 v[76:77], s[2:3], v76, s12, v[170:171]
	v_lshl_add_u64 v[76:77], v[76:77], 0, v[2:3]
	global_load_dwordx4 v[88:91], v[76:77], off
	global_load_dwordx4 v[84:87], v[76:77], off offset:256
	v_add_u32_e32 v92, 0x1000, v176
	v_add_u32_e32 v76, 0x90, v177
	v_mad_i64_i32 v[76:77], s[2:3], v76, s12, v[170:171]
	v_lshl_add_u64 v[76:77], v[76:77], 0, v[2:3]
	global_load_dwordx4 v[80:83], v[76:77], off
	s_nop 0
	global_load_dwordx4 v[76:79], v[76:77], off offset:256
	s_waitcnt vmcnt(0)
	v_lshlrev_b32_e32 v94, 16, v88
	v_and_b32_e32 v95, 0xffff0000, v88
	v_pk_fma_f32 v[72:73], v[24:25], v[94:95], v[72:73]
	s_nop 0
	v_mul_f32_e32 v88, 0x3d372713, v72
	v_mul_f32_e32 v88, v72, v88
	v_fma_f32 v88, v72, v88, v72
	v_mul_f32_e32 v88, 0x3f4c422a, v88
	v_add_f32_e32 v88, v88, v88
	v_mul_f32_e32 v88, 0x3fb8aa3b, v88
	v_exp_f32_e32 v94, v88
	v_mul_f32_e32 v88, 0x3d372713, v73
	v_mul_f32_e32 v88, v73, v88
	v_fma_f32 v88, v73, v88, v73
	v_mul_f32_e32 v88, 0x3f4c422a, v88
	v_add_f32_e32 v88, v88, v88
	v_mul_f32_e32 v88, 0x3fb8aa3b, v88
	v_exp_f32_e32 v95, v88
	v_pk_mul_f32 v[72:73], v[72:73], 0.5 op_sel_hi:[1,0]
	v_pk_add_f32 v[94:95], v[94:95], 1.0 op_sel_hi:[1,0]
	s_nop 0
	v_rcp_f32_e32 v93, v95
	s_nop 0
	v_mul_f32_e32 v97, 2.0, v93
	v_fma_f32 v98, -v95, v97, 2.0
	v_fmac_f32_e32 v97, v98, v93
	v_div_fixup_f32 v95, v97, v95, 2.0
	v_rcp_f32_e32 v93, v94
	s_nop 0
	v_mul_f32_e32 v97, 2.0, v93
	v_fma_f32 v98, -v94, v97, 2.0
	v_fmac_f32_e32 v97, v98, v93
	v_div_fixup_f32 v94, v97, v94, 2.0
	v_pk_add_f32 v[94:95], v[94:95], 2.0 op_sel_hi:[1,0] neg_lo:[1,0] neg_hi:[1,0]
	s_nop 0
	v_pk_mul_f32 v[72:73], v[72:73], v[94:95]
	v_lshlrev_b32_e32 v94, 16, v90
	v_and_b32_e32 v95, 0xffff0000, v90
	v_pk_fma_f32 v[68:69], v[20:21], v[94:95], v[68:69]
	s_nop 0
	v_mul_f32_e32 v88, 0x3d372713, v68
	v_mul_f32_e32 v88, v68, v88
	v_fma_f32 v88, v68, v88, v68
	v_mul_f32_e32 v88, 0x3f4c422a, v88
	v_add_f32_e32 v88, v88, v88
	v_mul_f32_e32 v88, 0x3fb8aa3b, v88
	v_exp_f32_e32 v94, v88
	v_mul_f32_e32 v88, 0x3d372713, v69
	v_mul_f32_e32 v88, v69, v88
	v_fma_f32 v88, v69, v88, v69
	v_mul_f32_e32 v88, 0x3f4c422a, v88
	v_add_f32_e32 v88, v88, v88
	v_mul_f32_e32 v88, 0x3fb8aa3b, v88
	v_exp_f32_e32 v95, v88
	v_pk_mul_f32 v[68:69], v[68:69], 0.5 op_sel_hi:[1,0]
	v_pk_add_f32 v[94:95], v[94:95], 1.0 op_sel_hi:[1,0]
	s_nop 0
	v_rcp_f32_e32 v90, v95
	s_nop 0
	v_mul_f32_e32 v96, 2.0, v90
	v_fma_f32 v97, -v95, v96, 2.0
	v_fmac_f32_e32 v96, v97, v90
	v_div_fixup_f32 v95, v96, v95, 2.0
	v_rcp_f32_e32 v90, v94
	s_nop 0
	v_mul_f32_e32 v96, 2.0, v90
	v_fma_f32 v97, -v94, v96, 2.0
	v_fmac_f32_e32 v96, v97, v90
	v_div_fixup_f32 v94, v96, v94, 2.0
	v_lshlrev_b32_e32 v88, 16, v89
	v_and_b32_e32 v89, 0xffff0000, v89
	v_pk_fma_f32 v[74:75], v[26:27], v[88:89], v[74:75]
	v_pk_add_f32 v[94:95], v[94:95], 2.0 op_sel_hi:[1,0] neg_lo:[1,0] neg_hi:[1,0]
	v_mul_f32_e32 v88, 0x3d372713, v74
	v_mul_f32_e32 v89, 0x3d372713, v75
	v_mul_f32_e32 v88, v74, v88
	v_mul_f32_e32 v89, v75, v89
	v_fma_f32 v88, v74, v88, v74
	v_fma_f32 v89, v75, v89, v75
	v_mul_f32_e32 v88, 0x3f4c422a, v88
	v_mul_f32_e32 v89, 0x3f4c422a, v89
	v_add_f32_e32 v88, v88, v88
	v_add_f32_e32 v89, v89, v89
	v_mul_f32_e32 v88, 0x3fb8aa3b, v88
	v_mul_f32_e32 v89, 0x3fb8aa3b, v89
	v_exp_f32_e32 v88, v88
	v_exp_f32_e32 v89, v89
	v_pk_mul_f32 v[68:69], v[68:69], v[94:95]
	v_pk_mul_f32 v[74:75], v[74:75], 0.5 op_sel_hi:[1,0]
	v_pk_add_f32 v[88:89], v[88:89], 1.0 op_sel_hi:[1,0]
	s_nop 0
	v_rcp_f32_e32 v93, v89
	s_nop 0
	v_mul_f32_e32 v95, 2.0, v93
	v_fma_f32 v96, -v89, v95, 2.0
	v_fmac_f32_e32 v95, v96, v93
	v_div_fixup_f32 v89, v95, v89, 2.0
	v_rcp_f32_e32 v93, v88
	s_nop 0
	v_mul_f32_e32 v95, 2.0, v93
	v_fma_f32 v96, -v88, v95, 2.0
	v_fmac_f32_e32 v95, v96, v93
	v_div_fixup_f32 v88, v95, v88, 2.0
	v_pk_add_f32 v[88:89], v[88:89], 2.0 op_sel_hi:[1,0] neg_lo:[1,0] neg_hi:[1,0]
	s_nop 0
	v_pk_mul_f32 v[74:75], v[74:75], v[88:89]
	v_lshlrev_b32_e32 v88, 16, v91
	v_and_b32_e32 v89, 0xffff0000, v91
	v_pk_fma_f32 v[70:71], v[22:23], v[88:89], v[70:71]
	s_nop 0
	v_mul_f32_e32 v88, 0x3d372713, v70
	v_mul_f32_e32 v89, 0x3d372713, v71
; DI void unpack8(u32x4 w, float* f) { f[0] = bflo(w.x); f[1] = bfhi(w.x); f[2] = bflo(w.y); f[3] = bfhi(w.y); f[4] = bflo(w.z); f[5] = bfhi(w.z); f[6] = bflo(w.w); f[7] = bfhi(w.w); }
; DI u32x4 pack44(f32x4 a, f32x4 b) { u32x4 w; w.x = pk2(a[0], a[1]); w.y = pk2(a[2], a[3]); w.z = pk2(b[0], b[1]); w.w = pk2(b[2], b[3]); return w; }
; DI float gelu_tanh(float y) { float t = 0.7978845608f * (y + 0.044715f * y * y * y); float e = __expf(2.f * t); return 0.5f * y * (2.f - 2.f / (e + 1.f)); }
;     DI void operator()(const Acc& acc, const Unit& u, int wr, int wc, int fr, int fq) const {
;     ...
;                     for (int bj = 0; bj < 2; ++bj) { const int chunk = mt * 256 + ai * 128 + wr * 64 + (2 * mp + mi) * 16 + fr, n0 = nt * 256 + bj * 128 + wc * 32 + 8 * fq;
;                         uv[mi][bj] = *(const u32x4*)(uperm + (size_t)(g * 512 + chunk) * 640 + n0); }
; #pragma unroll
;                 for (int mi = 0; mi < 2; ++mi)
; #pragma unroll
;                     for (int bj = 0; bj < 2; ++bj) { const int m = 2 * mp + mi, chunk = mt * 256 + ai * 128 + wr * 64 + m * 16 + fr, n0 = nt * 256 + bj * 128 + wc * 32 + 8 * fq, t = n0 >> 4;
;                         f32x4 v0 = acc[ai][bj][m][0], v1 = acc[ai][bj][m][1]; float uf[8]; unpack8(uv[mi][bj], uf);
;                         for (int j = 0; j < 4; ++j) { v0[j] = gelu_tanh(v0[j] + d0[j] * uf[j]); v1[j] = gelu_tanh(v1[j] + d1[j] * uf[4 + j]); }
;                         *(u32x4*)(zs + (size_t)(chunk * 32 + t) * 1024 + g * 16 + ho0) = pack44(v0, v1); }
	v_mul_f32_e32 v88, v70, v88
	v_mul_f32_e32 v89, v71, v89
	v_fma_f32 v88, v70, v88, v70
	v_fma_f32 v89, v71, v89, v71
	v_mul_f32_e32 v88, 0x3f4c422a, v88
	v_mul_f32_e32 v89, 0x3f4c422a, v89
	v_add_f32_e32 v88, v88, v88
	v_add_f32_e32 v89, v89, v89
	v_mul_f32_e32 v88, 0x3fb8aa3b, v88
	v_mul_f32_e32 v89, 0x3fb8aa3b, v89
	v_exp_f32_e32 v88, v88
	v_exp_f32_e32 v89, v89
	v_pk_mul_f32 v[70:71], v[70:71], 0.5 op_sel_hi:[1,0]
	v_pk_add_f32 v[88:89], v[88:89], 1.0 op_sel_hi:[1,0]
	s_nop 0
	v_rcp_f32_e32 v91, v89
	s_nop 0
	v_mul_f32_e32 v94, 2.0, v91
	v_fma_f32 v95, -v89, v94, 2.0
	v_fmac_f32_e32 v94, v95, v91
	v_div_fixup_f32 v89, v94, v89, 2.0
	v_rcp_f32_e32 v91, v88
	s_nop 0
	v_mul_f32_e32 v94, 2.0, v91
	v_fma_f32 v95, -v88, v94, 2.0
	v_fmac_f32_e32 v94, v95, v91
	v_div_fixup_f32 v88, v94, v88, 2.0
	v_pk_add_f32 v[88:89], v[88:89], 2.0 op_sel_hi:[1,0] neg_lo:[1,0] neg_hi:[1,0]
	s_nop 0
	v_pk_mul_f32 v[88:89], v[70:71], v[88:89]
	v_cvt_pk_bf16_f32 v70, v72, v73
	v_cvt_pk_bf16_f32 v72, v68, v69
	v_or_b32_e32 v68, v92, v142
	v_ashrrev_i32_e32 v69, 31, v68
	v_lshlrev_b64 v[68:69], 11, v[68:69]
	v_lshl_add_u64 v[68:69], s[4:5], 0, v[68:69]
	v_lshl_add_u64 v[68:69], v[68:69], 0, s[34:35]
	v_cvt_pk_bf16_f32 v71, v74, v75
	v_cvt_pk_bf16_f32 v73, v88, v89
	v_lshl_add_u64 v[68:69], v[68:69], 0, v[168:169]
	global_store_dwordx4 v[68:69], v[70:73], off
	v_lshlrev_b32_e32 v68, 16, v84
	v_and_b32_e32 v69, 0xffff0000, v84
	v_pk_fma_f32 v[64:65], v[24:25], v[68:69], v[64:65]
	s_nop 0
	v_mul_f32_e32 v68, 0x3d372713, v64
	v_mul_f32_e32 v69, 0x3d372713, v65
	v_mul_f32_e32 v68, v64, v68
	v_mul_f32_e32 v69, v65, v69
	v_fma_f32 v68, v64, v68, v64
	v_fma_f32 v69, v65, v69, v65
	v_mul_f32_e32 v68, 0x3f4c422a, v68
	v_mul_f32_e32 v69, 0x3f4c422a, v69
	v_add_f32_e32 v68, v68, v68
	v_add_f32_e32 v69, v69, v69
	v_mul_f32_e32 v68, 0x3fb8aa3b, v68
	v_mul_f32_e32 v69, 0x3fb8aa3b, v69
	v_exp_f32_e32 v68, v68
	v_exp_f32_e32 v69, v69
	v_pk_mul_f32 v[64:65], v[64:65], 0.5 op_sel_hi:[1,0]
	v_pk_add_f32 v[68:69], v[68:69], 1.0 op_sel_hi:[1,0]
	s_nop 0
	v_rcp_f32_e32 v71, v69
	s_nop 0
	v_mul_f32_e32 v73, 2.0, v71
	v_fma_f32 v74, -v69, v73, 2.0
	v_fmac_f32_e32 v73, v74, v71
	v_div_fixup_f32 v69, v73, v69, 2.0
	v_rcp_f32_e32 v71, v68
	s_nop 0
	v_mul_f32_e32 v73, 2.0, v71
	v_fma_f32 v74, -v68, v73, 2.0
	v_fmac_f32_e32 v73, v74, v71
	v_div_fixup_f32 v68, v73, v68, 2.0
	v_pk_add_f32 v[68:69], v[68:69], 2.0 op_sel_hi:[1,0] neg_lo:[1,0] neg_hi:[1,0]
	s_nop 0
	v_pk_mul_f32 v[64:65], v[64:65], v[68:69]
	v_lshlrev_b32_e32 v68, 16, v86
	v_and_b32_e32 v69, 0xffff0000, v86
	v_pk_fma_f32 v[60:61], v[20:21], v[68:69], v[60:61]
	s_nop 0
	v_mul_f32_e32 v68, 0x3d372713, v60
	v_mul_f32_e32 v69, 0x3d372713, v61
	v_mul_f32_e32 v68, v60, v68
	v_mul_f32_e32 v69, v61, v69
	v_fma_f32 v68, v60, v68, v60
	v_fma_f32 v69, v61, v69, v61
	v_mul_f32_e32 v68, 0x3f4c422a, v68
	v_mul_f32_e32 v69, 0x3f4c422a, v69
	v_add_f32_e32 v68, v68, v68
	v_add_f32_e32 v69, v69, v69
	v_mul_f32_e32 v68, 0x3fb8aa3b, v68
	v_mul_f32_e32 v69, 0x3fb8aa3b, v69
	v_exp_f32_e32 v68, v68
	v_exp_f32_e32 v69, v69
	v_pk_mul_f32 v[60:61], v[60:61], 0.5 op_sel_hi:[1,0]
	v_pk_add_f32 v[68:69], v[68:69], 1.0 op_sel_hi:[1,0]
	s_nop 0
	v_rcp_f32_e32 v71, v69
	s_nop 0
	v_mul_f32_e32 v73, 2.0, v71
	v_fma_f32 v74, -v69, v73, 2.0
	v_fmac_f32_e32 v73, v74, v71
	v_div_fixup_f32 v69, v73, v69, 2.0
	v_rcp_f32_e32 v71, v68
	s_nop 0
	v_mul_f32_e32 v73, 2.0, v71
	v_fma_f32 v74, -v68, v73, 2.0
	v_fmac_f32_e32 v73, v74, v71
	v_div_fixup_f32 v68, v73, v68, 2.0
	v_pk_add_f32 v[68:69], v[68:69], 2.0 op_sel_hi:[1,0] neg_lo:[1,0] neg_hi:[1,0]
	s_nop 0
	v_pk_mul_f32 v[60:61], v[60:61], v[68:69]
	v_lshlrev_b32_e32 v68, 16, v85
	v_and_b32_e32 v69, 0xffff0000, v85
	v_pk_fma_f32 v[66:67], v[26:27], v[68:69], v[66:67]
	s_nop 0
	v_mul_f32_e32 v68, 0x3d372713, v66
	v_mul_f32_e32 v69, 0x3d372713, v67
	v_mul_f32_e32 v68, v66, v68
	v_mul_f32_e32 v69, v67, v69
	v_fma_f32 v68, v66, v68, v66
	v_fma_f32 v69, v67, v69, v67
	v_mul_f32_e32 v68, 0x3f4c422a, v68
	v_mul_f32_e32 v69, 0x3f4c422a, v69
	v_add_f32_e32 v68, v68, v68
	v_add_f32_e32 v69, v69, v69
	v_mul_f32_e32 v68, 0x3fb8aa3b, v68
	v_mul_f32_e32 v69, 0x3fb8aa3b, v69
	v_exp_f32_e32 v68, v68
	v_exp_f32_e32 v69, v69
	v_pk_mul_f32 v[66:67], v[66:67], 0.5 op_sel_hi:[1,0]
	v_pk_add_f32 v[68:69], v[68:69], 1.0 op_sel_hi:[1,0]
	s_nop 0
	v_rcp_f32_e32 v71, v69
	s_nop 0
	v_mul_f32_e32 v73, 2.0, v71
	v_fma_f32 v74, -v69, v73, 2.0
	v_fmac_f32_e32 v73, v74, v71
	v_div_fixup_f32 v69, v73, v69, 2.0
	v_rcp_f32_e32 v71, v68
	s_nop 0
	v_mul_f32_e32 v73, 2.0, v71
	v_fma_f32 v74, -v68, v73, 2.0
	v_fmac_f32_e32 v73, v74, v71
	v_div_fixup_f32 v68, v73, v68, 2.0
	v_pk_add_f32 v[68:69], v[68:69], 2.0 op_sel_hi:[1,0] neg_lo:[1,0] neg_hi:[1,0]
	s_nop 0
	v_pk_mul_f32 v[66:67], v[66:67], v[68:69]
	v_lshlrev_b32_e32 v68, 16, v87
	v_and_b32_e32 v69, 0xffff0000, v87
	v_pk_fma_f32 v[62:63], v[22:23], v[68:69], v[62:63]
	s_nop 0
	v_mul_f32_e32 v68, 0x3d372713, v62
	v_mul_f32_e32 v69, 0x3d372713, v63
	v_mul_f32_e32 v68, v62, v68
	v_mul_f32_e32 v69, v63, v69
	v_fma_f32 v68, v62, v68, v62
	v_fma_f32 v69, v63, v69, v63
	v_mul_f32_e32 v68, 0x3f4c422a, v68
	v_mul_f32_e32 v69, 0x3f4c422a, v69
	v_add_f32_e32 v68, v68, v68
	v_add_f32_e32 v69, v69, v69
	v_mul_f32_e32 v68, 0x3fb8aa3b, v68
	v_mul_f32_e32 v69, 0x3fb8aa3b, v69
	v_exp_f32_e32 v68, v68
	v_exp_f32_e32 v69, v69
	v_pk_mul_f32 v[62:63], v[62:63], 0.5 op_sel_hi:[1,0]
	v_pk_add_f32 v[68:69], v[68:69], 1.0 op_sel_hi:[1,0]
	s_nop 0
	v_rcp_f32_e32 v71, v69
	s_nop 0
	v_mul_f32_e32 v73, 2.0, v71
	v_fma_f32 v74, -v69, v73, 2.0
	v_fmac_f32_e32 v73, v74, v71
	v_div_fixup_f32 v69, v73, v69, 2.0
	v_rcp_f32_e32 v71, v68
; DI void unpack8(u32x4 w, float* f) { f[0] = bflo(w.x); f[1] = bfhi(w.x); f[2] = bflo(w.y); f[3] = bfhi(w.y); f[4] = bflo(w.z); f[5] = bfhi(w.z); f[6] = bflo(w.w); f[7] = bfhi(w.w); }
; DI u32x4 pack44(f32x4 a, f32x4 b) { u32x4 w; w.x = pk2(a[0], a[1]); w.y = pk2(a[2], a[3]); w.z = pk2(b[0], b[1]); w.w = pk2(b[2], b[3]); return w; }
; DI float gelu_tanh(float y) { float t = 0.7978845608f * (y + 0.044715f * y * y * y); float e = __expf(2.f * t); return 0.5f * y * (2.f - 2.f / (e + 1.f)); }
;     DI void operator()(const Acc& acc, const Unit& u, int wr, int wc, int fr, int fq) const {
;     ...
;                     for (int bj = 0; bj < 2; ++bj) { const int chunk = mt * 256 + ai * 128 + wr * 64 + (2 * mp + mi) * 16 + fr, n0 = nt * 256 + bj * 128 + wc * 32 + 8 * fq;
;                         uv[mi][bj] = *(const u32x4*)(uperm + (size_t)(g * 512 + chunk) * 640 + n0); }
; #pragma unroll
;                 for (int mi = 0; mi < 2; ++mi)
; #pragma unroll
;                     for (int bj = 0; bj < 2; ++bj) { const int m = 2 * mp + mi, chunk = mt * 256 + ai * 128 + wr * 64 + m * 16 + fr, n0 = nt * 256 + bj * 128 + wc * 32 + 8 * fq, t = n0 >> 4;
;                         f32x4 v0 = acc[ai][bj][m][0], v1 = acc[ai][bj][m][1]; float uf[8]; unpack8(uv[mi][bj], uf);
;                         for (int j = 0; j < 4; ++j) { v0[j] = gelu_tanh(v0[j] + d0[j] * uf[j]); v1[j] = gelu_tanh(v1[j] + d1[j] * uf[4 + j]); }
;                         *(u32x4*)(zs + (size_t)(chunk * 32 + t) * 1024 + g * 16 + ho0) = pack44(v0, v1); }
	s_nop 0
	v_mul_f32_e32 v73, 2.0, v71
	v_fma_f32 v74, -v68, v73, 2.0
	v_fmac_f32_e32 v73, v74, v71
	v_div_fixup_f32 v68, v73, v68, 2.0
	v_pk_add_f32 v[68:69], v[68:69], 2.0 op_sel_hi:[1,0] neg_lo:[1,0] neg_hi:[1,0]
	s_nop 0
	v_pk_mul_f32 v[68:69], v[62:63], v[68:69]
	v_cvt_pk_bf16_f32 v62, v64, v65
	v_cvt_pk_bf16_f32 v64, v60, v61
	v_or_b32_e32 v60, v92, v130
	v_ashrrev_i32_e32 v61, 31, v60
	v_lshlrev_b64 v[60:61], 11, v[60:61]
	v_lshl_add_u64 v[60:61], s[4:5], 0, v[60:61]
	v_lshl_add_u64 v[60:61], v[60:61], 0, s[34:35]
	v_cvt_pk_bf16_f32 v63, v66, v67
	v_cvt_pk_bf16_f32 v65, v68, v69
	v_lshl_add_u64 v[60:61], v[60:61], 0, v[168:169]
	global_store_dwordx4 v[60:61], v[62:65], off
	v_add_u32_e32 v60, 0x1200, v176
	s_nop 0
	v_lshlrev_b32_e32 v62, 16, v80
	v_and_b32_e32 v63, 0xffff0000, v80
	v_pk_fma_f32 v[56:57], v[24:25], v[62:63], v[56:57]
	s_nop 0
	v_mul_f32_e32 v61, 0x3d372713, v56
	v_mul_f32_e32 v61, v56, v61
	v_fma_f32 v61, v56, v61, v56
	v_mul_f32_e32 v61, 0x3f4c422a, v61
	v_add_f32_e32 v61, v61, v61
	v_mul_f32_e32 v61, 0x3fb8aa3b, v61
	v_exp_f32_e32 v62, v61
	v_mul_f32_e32 v61, 0x3d372713, v57
	v_mul_f32_e32 v61, v57, v61
	v_fma_f32 v61, v57, v61, v57
	v_mul_f32_e32 v61, 0x3f4c422a, v61
	v_add_f32_e32 v61, v61, v61
	v_mul_f32_e32 v61, 0x3fb8aa3b, v61
	v_exp_f32_e32 v63, v61
	v_pk_mul_f32 v[56:57], v[56:57], 0.5 op_sel_hi:[1,0]
	v_pk_add_f32 v[62:63], v[62:63], 1.0 op_sel_hi:[1,0]
	s_nop 0
	v_rcp_f32_e32 v64, v63
	s_nop 0
	v_mul_f32_e32 v66, 2.0, v64
	v_fma_f32 v67, -v63, v66, 2.0
	v_fmac_f32_e32 v66, v67, v64
	v_div_fixup_f32 v63, v66, v63, 2.0
	v_rcp_f32_e32 v64, v62
	s_nop 0
	v_mul_f32_e32 v66, 2.0, v64
	v_fma_f32 v67, -v62, v66, 2.0
	v_fmac_f32_e32 v66, v67, v64
	v_div_fixup_f32 v62, v66, v62, 2.0
	v_pk_add_f32 v[62:63], v[62:63], 2.0 op_sel_hi:[1,0] neg_lo:[1,0] neg_hi:[1,0]
	s_nop 0
	v_pk_mul_f32 v[56:57], v[56:57], v[62:63]
	v_lshlrev_b32_e32 v62, 16, v82
	v_and_b32_e32 v63, 0xffff0000, v82
	v_pk_fma_f32 v[52:53], v[20:21], v[62:63], v[52:53]
	s_nop 0
	v_mul_f32_e32 v61, 0x3d372713, v52
	v_mul_f32_e32 v61, v52, v61
	v_fma_f32 v61, v52, v61, v52
	v_mul_f32_e32 v61, 0x3f4c422a, v61
	v_add_f32_e32 v61, v61, v61
	v_mul_f32_e32 v61, 0x3fb8aa3b, v61
	v_exp_f32_e32 v62, v61
	v_mul_f32_e32 v61, 0x3d372713, v53
	v_mul_f32_e32 v61, v53, v61
	v_fma_f32 v61, v53, v61, v53
	v_mul_f32_e32 v61, 0x3f4c422a, v61
	v_add_f32_e32 v61, v61, v61
	v_mul_f32_e32 v61, 0x3fb8aa3b, v61
	v_exp_f32_e32 v63, v61
	v_pk_mul_f32 v[52:53], v[52:53], 0.5 op_sel_hi:[1,0]
	v_pk_add_f32 v[62:63], v[62:63], 1.0 op_sel_hi:[1,0]
	s_nop 0
	v_rcp_f32_e32 v64, v63
	s_nop 0
	v_mul_f32_e32 v66, 2.0, v64
	v_fma_f32 v67, -v63, v66, 2.0
	v_fmac_f32_e32 v66, v67, v64
	v_div_fixup_f32 v63, v66, v63, 2.0
	v_rcp_f32_e32 v64, v62
	s_nop 0
	v_mul_f32_e32 v66, 2.0, v64
	v_fma_f32 v67, -v62, v66, 2.0
	v_fmac_f32_e32 v66, v67, v64
	v_div_fixup_f32 v62, v66, v62, 2.0
	v_pk_add_f32 v[62:63], v[62:63], 2.0 op_sel_hi:[1,0] neg_lo:[1,0] neg_hi:[1,0]
	s_nop 0
	v_pk_mul_f32 v[52:53], v[52:53], v[62:63]
	v_lshlrev_b32_e32 v62, 16, v81
	v_and_b32_e32 v63, 0xffff0000, v81
	v_pk_fma_f32 v[58:59], v[26:27], v[62:63], v[58:59]
	s_nop 0
	v_mul_f32_e32 v61, 0x3d372713, v58
	v_mul_f32_e32 v61, v58, v61
	v_fma_f32 v61, v58, v61, v58
	v_mul_f32_e32 v61, 0x3f4c422a, v61
	v_add_f32_e32 v61, v61, v61
	v_mul_f32_e32 v61, 0x3fb8aa3b, v61
	v_exp_f32_e32 v62, v61
	v_mul_f32_e32 v61, 0x3d372713, v59
	v_mul_f32_e32 v61, v59, v61
	v_fma_f32 v61, v59, v61, v59
	v_mul_f32_e32 v61, 0x3f4c422a, v61
	v_add_f32_e32 v61, v61, v61
	v_mul_f32_e32 v61, 0x3fb8aa3b, v61
	v_exp_f32_e32 v63, v61
	v_pk_mul_f32 v[58:59], v[58:59], 0.5 op_sel_hi:[1,0]
	v_pk_add_f32 v[62:63], v[62:63], 1.0 op_sel_hi:[1,0]
	s_nop 0
	v_rcp_f32_e32 v64, v63
	s_nop 0
	v_mul_f32_e32 v66, 2.0, v64
	v_fma_f32 v67, -v63, v66, 2.0
	v_fmac_f32_e32 v66, v67, v64
	v_div_fixup_f32 v63, v66, v63, 2.0
	v_rcp_f32_e32 v64, v62
	s_nop 0
	v_mul_f32_e32 v66, 2.0, v64
	v_fma_f32 v67, -v62, v66, 2.0
	v_fmac_f32_e32 v66, v67, v64
	v_div_fixup_f32 v62, v66, v62, 2.0
	v_pk_add_f32 v[62:63], v[62:63], 2.0 op_sel_hi:[1,0] neg_lo:[1,0] neg_hi:[1,0]
	s_nop 0
	v_pk_mul_f32 v[58:59], v[58:59], v[62:63]
	v_lshlrev_b32_e32 v62, 16, v83
	v_and_b32_e32 v63, 0xffff0000, v83
	v_pk_fma_f32 v[54:55], v[22:23], v[62:63], v[54:55]
	s_nop 0
	v_mul_f32_e32 v61, 0x3d372713, v54
	v_mul_f32_e32 v61, v54, v61
	v_fma_f32 v61, v54, v61, v54
	v_mul_f32_e32 v61, 0x3f4c422a, v61
	v_add_f32_e32 v61, v61, v61
	v_mul_f32_e32 v61, 0x3fb8aa3b, v61
	v_exp_f32_e32 v62, v61
	v_mul_f32_e32 v61, 0x3d372713, v55
	v_mul_f32_e32 v61, v55, v61
	v_fma_f32 v61, v55, v61, v55
	v_mul_f32_e32 v61, 0x3f4c422a, v61
	v_add_f32_e32 v61, v61, v61
	v_mul_f32_e32 v61, 0x3fb8aa3b, v61
	v_exp_f32_e32 v63, v61
	v_pk_mul_f32 v[54:55], v[54:55], 0.5 op_sel_hi:[1,0]
	v_pk_add_f32 v[62:63], v[62:63], 1.0 op_sel_hi:[1,0]
	s_nop 0
	v_rcp_f32_e32 v64, v63
	s_nop 0
	v_mul_f32_e32 v66, 2.0, v64
	v_fma_f32 v67, -v63, v66, 2.0
	v_fmac_f32_e32 v66, v67, v64
	v_div_fixup_f32 v63, v66, v63, 2.0
	v_rcp_f32_e32 v64, v62
	s_nop 0
	v_mul_f32_e32 v66, 2.0, v64
	v_fma_f32 v67, -v62, v66, 2.0
	v_fmac_f32_e32 v66, v67, v64
	v_div_fixup_f32 v62, v66, v62, 2.0
	v_pk_add_f32 v[62:63], v[62:63], 2.0 op_sel_hi:[1,0] neg_lo:[1,0] neg_hi:[1,0]
	s_nop 0
	v_pk_mul_f32 v[62:63], v[54:55], v[62:63]
	v_cvt_pk_bf16_f32 v54, v56, v57
	v_cvt_pk_bf16_f32 v56, v52, v53
	v_or_b32_e32 v52, v60, v142
	v_ashrrev_i32_e32 v53, 31, v52
	v_lshlrev_b64 v[52:53], 11, v[52:53]
	v_lshl_add_u64 v[52:53], s[4:5], 0, v[52:53]
	v_lshl_add_u64 v[52:53], v[52:53], 0, s[34:35]
	v_cvt_pk_bf16_f32 v55, v58, v59
	v_cvt_pk_bf16_f32 v57, v62, v63
	v_lshl_add_u64 v[52:53], v[52:53], 0, v[168:169]
; DI void unpack8(u32x4 w, float* f) { f[0] = bflo(w.x); f[1] = bfhi(w.x); f[2] = bflo(w.y); f[3] = bfhi(w.y); f[4] = bflo(w.z); f[5] = bfhi(w.z); f[6] = bflo(w.w); f[7] = bfhi(w.w); }
; DI u32x4 pack44(f32x4 a, f32x4 b) { u32x4 w; w.x = pk2(a[0], a[1]); w.y = pk2(a[2], a[3]); w.z = pk2(b[0], b[1]); w.w = pk2(b[2], b[3]); return w; }
; DI float gelu_tanh(float y) { float t = 0.7978845608f * (y + 0.044715f * y * y * y); float e = __expf(2.f * t); return 0.5f * y * (2.f - 2.f / (e + 1.f)); }
;     DI void operator()(const Acc& acc, const Unit& u, int wr, int wc, int fr, int fq) const {
;     ...
;                     for (int bj = 0; bj < 2; ++bj) { const int chunk = mt * 256 + ai * 128 + wr * 64 + (2 * mp + mi) * 16 + fr, n0 = nt * 256 + bj * 128 + wc * 32 + 8 * fq;
;                         uv[mi][bj] = *(const u32x4*)(uperm + (size_t)(g * 512 + chunk) * 640 + n0); }
; #pragma unroll
;                 for (int mi = 0; mi < 2; ++mi)
; #pragma unroll
;                     for (int bj = 0; bj < 2; ++bj) { const int m = 2 * mp + mi, chunk = mt * 256 + ai * 128 + wr * 64 + m * 16 + fr, n0 = nt * 256 + bj * 128 + wc * 32 + 8 * fq, t = n0 >> 4;
;                         f32x4 v0 = acc[ai][bj][m][0], v1 = acc[ai][bj][m][1]; float uf[8]; unpack8(uv[mi][bj], uf);
;                         for (int j = 0; j < 4; ++j) { v0[j] = gelu_tanh(v0[j] + d0[j] * uf[j]); v1[j] = gelu_tanh(v1[j] + d1[j] * uf[4 + j]); }
;                         *(u32x4*)(zs + (size_t)(chunk * 32 + t) * 1024 + g * 16 + ho0) = pack44(v0, v1); }
	global_store_dwordx4 v[52:53], v[54:57], off
	v_lshlrev_b32_e32 v52, 16, v76
	v_and_b32_e32 v53, 0xffff0000, v76
	v_pk_fma_f32 v[48:49], v[24:25], v[52:53], v[48:49]
	s_nop 0
	v_mul_f32_e32 v52, 0x3d372713, v48
	v_mul_f32_e32 v53, 0x3d372713, v49
	v_mul_f32_e32 v52, v48, v52
	v_mul_f32_e32 v53, v49, v53
	v_fma_f32 v52, v48, v52, v48
	v_fma_f32 v53, v49, v53, v49
	v_mul_f32_e32 v52, 0x3f4c422a, v52
	v_mul_f32_e32 v53, 0x3f4c422a, v53
	v_add_f32_e32 v52, v52, v52
	v_add_f32_e32 v53, v53, v53
	v_mul_f32_e32 v52, 0x3fb8aa3b, v52
	v_mul_f32_e32 v53, 0x3fb8aa3b, v53
	v_exp_f32_e32 v52, v52
	v_exp_f32_e32 v53, v53
	v_pk_mul_f32 v[48:49], v[48:49], 0.5 op_sel_hi:[1,0]
	v_pk_add_f32 v[52:53], v[52:53], 1.0 op_sel_hi:[1,0]
	s_nop 0
	v_rcp_f32_e32 v55, v53
	s_nop 0
	v_mul_f32_e32 v57, 2.0, v55
	v_fma_f32 v58, -v53, v57, 2.0
	v_fmac_f32_e32 v57, v58, v55
	v_div_fixup_f32 v53, v57, v53, 2.0
	v_rcp_f32_e32 v55, v52
	s_nop 0
	v_mul_f32_e32 v57, 2.0, v55
	v_fma_f32 v58, -v52, v57, 2.0
	v_fmac_f32_e32 v57, v58, v55
	v_div_fixup_f32 v52, v57, v52, 2.0
	v_pk_add_f32 v[52:53], v[52:53], 2.0 op_sel_hi:[1,0] neg_lo:[1,0] neg_hi:[1,0]
	s_nop 0
	v_pk_mul_f32 v[48:49], v[48:49], v[52:53]
	v_lshlrev_b32_e32 v52, 16, v78
	v_and_b32_e32 v53, 0xffff0000, v78
	v_pk_fma_f32 v[44:45], v[20:21], v[52:53], v[44:45]
	s_nop 0
	v_mul_f32_e32 v52, 0x3d372713, v44
	v_mul_f32_e32 v53, 0x3d372713, v45
	v_mul_f32_e32 v52, v44, v52
	v_mul_f32_e32 v53, v45, v53
	v_fma_f32 v52, v44, v52, v44
	v_fma_f32 v53, v45, v53, v45
	v_mul_f32_e32 v52, 0x3f4c422a, v52
	v_mul_f32_e32 v53, 0x3f4c422a, v53
	v_add_f32_e32 v52, v52, v52
	v_add_f32_e32 v53, v53, v53
	v_mul_f32_e32 v52, 0x3fb8aa3b, v52
	v_mul_f32_e32 v53, 0x3fb8aa3b, v53
	v_exp_f32_e32 v52, v52
	v_exp_f32_e32 v53, v53
	v_pk_mul_f32 v[44:45], v[44:45], 0.5 op_sel_hi:[1,0]
	v_pk_add_f32 v[52:53], v[52:53], 1.0 op_sel_hi:[1,0]
	s_nop 0
	v_rcp_f32_e32 v55, v53
	s_nop 0
	v_mul_f32_e32 v57, 2.0, v55
	v_fma_f32 v58, -v53, v57, 2.0
	v_fmac_f32_e32 v57, v58, v55
	v_div_fixup_f32 v53, v57, v53, 2.0
	v_rcp_f32_e32 v55, v52
	s_nop 0
	v_mul_f32_e32 v57, 2.0, v55
	v_fma_f32 v58, -v52, v57, 2.0
	v_fmac_f32_e32 v57, v58, v55
	v_div_fixup_f32 v52, v57, v52, 2.0
	v_pk_add_f32 v[52:53], v[52:53], 2.0 op_sel_hi:[1,0] neg_lo:[1,0] neg_hi:[1,0]
	s_nop 0
	v_pk_mul_f32 v[44:45], v[44:45], v[52:53]
	v_lshlrev_b32_e32 v52, 16, v77
	v_and_b32_e32 v53, 0xffff0000, v77
	v_pk_fma_f32 v[50:51], v[26:27], v[52:53], v[50:51]
	s_nop 0
	v_mul_f32_e32 v52, 0x3d372713, v50
	v_mul_f32_e32 v53, 0x3d372713, v51
	v_mul_f32_e32 v52, v50, v52
	v_mul_f32_e32 v53, v51, v53
	v_fma_f32 v52, v50, v52, v50
	v_fma_f32 v53, v51, v53, v51
	v_mul_f32_e32 v52, 0x3f4c422a, v52
	v_mul_f32_e32 v53, 0x3f4c422a, v53
	v_add_f32_e32 v52, v52, v52
	v_add_f32_e32 v53, v53, v53
	v_mul_f32_e32 v52, 0x3fb8aa3b, v52
	v_mul_f32_e32 v53, 0x3fb8aa3b, v53
	v_exp_f32_e32 v52, v52
	v_exp_f32_e32 v53, v53
	v_pk_mul_f32 v[50:51], v[50:51], 0.5 op_sel_hi:[1,0]
	v_pk_add_f32 v[52:53], v[52:53], 1.0 op_sel_hi:[1,0]
	s_nop 0
	v_rcp_f32_e32 v55, v53
	s_nop 0
	v_mul_f32_e32 v57, 2.0, v55
	v_fma_f32 v58, -v53, v57, 2.0
	v_fmac_f32_e32 v57, v58, v55
	v_div_fixup_f32 v53, v57, v53, 2.0
	v_rcp_f32_e32 v55, v52
	s_nop 0
	v_mul_f32_e32 v57, 2.0, v55
	v_fma_f32 v58, -v52, v57, 2.0
	v_fmac_f32_e32 v57, v58, v55
	v_div_fixup_f32 v52, v57, v52, 2.0
	v_pk_add_f32 v[52:53], v[52:53], 2.0 op_sel_hi:[1,0] neg_lo:[1,0] neg_hi:[1,0]
	s_nop 0
	v_pk_mul_f32 v[50:51], v[50:51], v[52:53]
	v_lshlrev_b32_e32 v52, 16, v79
	v_and_b32_e32 v53, 0xffff0000, v79
	v_pk_fma_f32 v[46:47], v[22:23], v[52:53], v[46:47]
	s_nop 0
	v_mul_f32_e32 v52, 0x3d372713, v46
	v_mul_f32_e32 v53, 0x3d372713, v47
	v_mul_f32_e32 v52, v46, v52
	v_mul_f32_e32 v53, v47, v53
	v_fma_f32 v52, v46, v52, v46
	v_fma_f32 v53, v47, v53, v47
	v_mul_f32_e32 v52, 0x3f4c422a, v52
	v_mul_f32_e32 v53, 0x3f4c422a, v53
	v_add_f32_e32 v52, v52, v52
	v_add_f32_e32 v53, v53, v53
	v_mul_f32_e32 v52, 0x3fb8aa3b, v52
	v_mul_f32_e32 v53, 0x3fb8aa3b, v53
	v_exp_f32_e32 v52, v52
	v_exp_f32_e32 v53, v53
	v_pk_mul_f32 v[46:47], v[46:47], 0.5 op_sel_hi:[1,0]
	v_pk_add_f32 v[52:53], v[52:53], 1.0 op_sel_hi:[1,0]
	s_nop 0
	v_rcp_f32_e32 v55, v53
	s_nop 0
	v_mul_f32_e32 v57, 2.0, v55
	v_fma_f32 v58, -v53, v57, 2.0
	v_fmac_f32_e32 v57, v58, v55
	v_div_fixup_f32 v53, v57, v53, 2.0
	v_rcp_f32_e32 v55, v52
	s_nop 0
	v_mul_f32_e32 v57, 2.0, v55
	v_fma_f32 v58, -v52, v57, 2.0
	v_fmac_f32_e32 v57, v58, v55
	v_div_fixup_f32 v52, v57, v52, 2.0
	v_pk_add_f32 v[52:53], v[52:53], 2.0 op_sel_hi:[1,0] neg_lo:[1,0] neg_hi:[1,0]
	s_nop 0
	v_pk_mul_f32 v[52:53], v[46:47], v[52:53]
	v_cvt_pk_bf16_f32 v46, v48, v49
	v_cvt_pk_bf16_f32 v48, v44, v45
	v_or_b32_e32 v44, v60, v130
	v_ashrrev_i32_e32 v45, 31, v44
	v_lshlrev_b64 v[44:45], 11, v[44:45]
	v_lshl_add_u64 v[44:45], s[4:5], 0, v[44:45]
	v_lshl_add_u64 v[44:45], v[44:45], 0, s[34:35]
	v_cvt_pk_bf16_f32 v47, v50, v51
	v_cvt_pk_bf16_f32 v49, v52, v53
	v_lshl_add_u64 v[44:45], v[44:45], 0, v[168:169]
	global_store_dwordx4 v[44:45], v[46:49], off
	v_add_u32_e32 v44, 0xa0, v177
	v_mad_i64_i32 v[44:45], s[2:3], v44, s12, v[170:171]
	v_lshl_add_u64 v[44:45], v[44:45], 0, v[2:3]
	global_load_dwordx4 v[56:59], v[44:45], off
	global_load_dwordx4 v[52:55], v[44:45], off offset:256
	v_add_u32_e32 v44, 0xb0, v177
	v_mad_i64_i32 v[44:45], s[2:3], v44, s12, v[170:171]
	v_lshl_add_u64 v[44:45], v[44:45], 0, v[2:3]
	v_add_u32_e32 v2, 0x1400, v176
	global_load_dwordx4 v[48:51], v[44:45], off
	s_nop 0
	global_load_dwordx4 v[44:47], v[44:45], off offset:256
	s_waitcnt vmcnt(0)
; DI void unpack8(u32x4 w, float* f) { f[0] = bflo(w.x); f[1] = bfhi(w.x); f[2] = bflo(w.y); f[3] = bfhi(w.y); f[4] = bflo(w.z); f[5] = bfhi(w.z); f[6] = bflo(w.w); f[7] = bfhi(w.w); }
; DI u32x4 pack44(f32x4 a, f32x4 b) { u32x4 w; w.x = pk2(a[0], a[1]); w.y = pk2(a[2], a[3]); w.z = pk2(b[0], b[1]); w.w = pk2(b[2], b[3]); return w; }
; DI float gelu_tanh(float y) { float t = 0.7978845608f * (y + 0.044715f * y * y * y); float e = __expf(2.f * t); return 0.5f * y * (2.f - 2.f / (e + 1.f)); }
;     DI void operator()(const Acc& acc, const Unit& u, int wr, int wc, int fr, int fq) const {
;     ...
;                     for (int bj = 0; bj < 2; ++bj) { const int chunk = mt * 256 + ai * 128 + wr * 64 + (2 * mp + mi) * 16 + fr, n0 = nt * 256 + bj * 128 + wc * 32 + 8 * fq;
;                         uv[mi][bj] = *(const u32x4*)(uperm + (size_t)(g * 512 + chunk) * 640 + n0); }
; #pragma unroll
;                 for (int mi = 0; mi < 2; ++mi)
; #pragma unroll
;                     for (int bj = 0; bj < 2; ++bj) { const int m = 2 * mp + mi, chunk = mt * 256 + ai * 128 + wr * 64 + m * 16 + fr, n0 = nt * 256 + bj * 128 + wc * 32 + 8 * fq, t = n0 >> 4;
;                         f32x4 v0 = acc[ai][bj][m][0], v1 = acc[ai][bj][m][1]; float uf[8]; unpack8(uv[mi][bj], uf);
;                         for (int j = 0; j < 4; ++j) { v0[j] = gelu_tanh(v0[j] + d0[j] * uf[j]); v1[j] = gelu_tanh(v1[j] + d1[j] * uf[4 + j]); }
;                         *(u32x4*)(zs + (size_t)(chunk * 32 + t) * 1024 + g * 16 + ho0) = pack44(v0, v1); }
	v_lshlrev_b32_e32 v60, 16, v56
	v_and_b32_e32 v61, 0xffff0000, v56
	v_pk_fma_f32 v[40:41], v[24:25], v[60:61], v[40:41]
	s_nop 0
	v_mul_f32_e32 v56, 0x3d372713, v40
	v_mul_f32_e32 v56, v40, v56
	v_fma_f32 v56, v40, v56, v40
	v_mul_f32_e32 v56, 0x3f4c422a, v56
	v_add_f32_e32 v56, v56, v56
	v_mul_f32_e32 v56, 0x3fb8aa3b, v56
	v_exp_f32_e32 v60, v56
	v_mul_f32_e32 v56, 0x3d372713, v41
	v_mul_f32_e32 v56, v41, v56
	v_fma_f32 v56, v41, v56, v41
	v_mul_f32_e32 v56, 0x3f4c422a, v56
	v_add_f32_e32 v56, v56, v56
	v_mul_f32_e32 v56, 0x3fb8aa3b, v56
	v_exp_f32_e32 v61, v56
	v_pk_mul_f32 v[40:41], v[40:41], 0.5 op_sel_hi:[1,0]
	v_pk_add_f32 v[60:61], v[60:61], 1.0 op_sel_hi:[1,0]
	s_nop 0
	v_rcp_f32_e32 v62, v61
	s_nop 0
	v_mul_f32_e32 v64, 2.0, v62
	v_fma_f32 v65, -v61, v64, 2.0
	v_fmac_f32_e32 v64, v65, v62
	v_div_fixup_f32 v61, v64, v61, 2.0
	v_rcp_f32_e32 v62, v60
	s_nop 0
	v_mul_f32_e32 v64, 2.0, v62
	v_fma_f32 v65, -v60, v64, 2.0
	v_fmac_f32_e32 v64, v65, v62
	v_div_fixup_f32 v60, v64, v60, 2.0
	v_pk_add_f32 v[60:61], v[60:61], 2.0 op_sel_hi:[1,0] neg_lo:[1,0] neg_hi:[1,0]
	s_nop 0
	v_pk_mul_f32 v[40:41], v[40:41], v[60:61]
	v_lshlrev_b32_e32 v60, 16, v58
	v_and_b32_e32 v61, 0xffff0000, v58
	v_pk_fma_f32 v[36:37], v[20:21], v[60:61], v[36:37]
	s_nop 0
	v_mul_f32_e32 v56, 0x3d372713, v36
	v_mul_f32_e32 v56, v36, v56
	v_fma_f32 v56, v36, v56, v36
	v_mul_f32_e32 v56, 0x3f4c422a, v56
	v_add_f32_e32 v56, v56, v56
	v_mul_f32_e32 v56, 0x3fb8aa3b, v56
	v_exp_f32_e32 v60, v56
	v_mul_f32_e32 v56, 0x3d372713, v37
	v_mul_f32_e32 v56, v37, v56
	v_fma_f32 v56, v37, v56, v37
	v_mul_f32_e32 v56, 0x3f4c422a, v56
	v_add_f32_e32 v56, v56, v56
	v_mul_f32_e32 v56, 0x3fb8aa3b, v56
	v_exp_f32_e32 v61, v56
	v_pk_mul_f32 v[36:37], v[36:37], 0.5 op_sel_hi:[1,0]
	v_pk_add_f32 v[60:61], v[60:61], 1.0 op_sel_hi:[1,0]
	s_nop 0
	v_rcp_f32_e32 v58, v61
	s_nop 0
	v_mul_f32_e32 v63, 2.0, v58
	v_fma_f32 v64, -v61, v63, 2.0
	v_fmac_f32_e32 v63, v64, v58
	v_div_fixup_f32 v61, v63, v61, 2.0
	v_rcp_f32_e32 v58, v60
	s_nop 0
	v_mul_f32_e32 v63, 2.0, v58
	v_fma_f32 v64, -v60, v63, 2.0
	v_fmac_f32_e32 v63, v64, v58
	v_div_fixup_f32 v60, v63, v60, 2.0
	v_lshlrev_b32_e32 v56, 16, v57
	v_and_b32_e32 v57, 0xffff0000, v57
	v_pk_fma_f32 v[42:43], v[26:27], v[56:57], v[42:43]
	v_pk_add_f32 v[60:61], v[60:61], 2.0 op_sel_hi:[1,0] neg_lo:[1,0] neg_hi:[1,0]
	v_mul_f32_e32 v56, 0x3d372713, v42
	v_mul_f32_e32 v57, 0x3d372713, v43
	v_mul_f32_e32 v56, v42, v56
	v_mul_f32_e32 v57, v43, v57
	v_fma_f32 v56, v42, v56, v42
	v_fma_f32 v57, v43, v57, v43
	v_mul_f32_e32 v56, 0x3f4c422a, v56
	v_mul_f32_e32 v57, 0x3f4c422a, v57
	v_add_f32_e32 v56, v56, v56
	v_add_f32_e32 v57, v57, v57
	v_mul_f32_e32 v56, 0x3fb8aa3b, v56
	v_mul_f32_e32 v57, 0x3fb8aa3b, v57
	v_exp_f32_e32 v56, v56
	v_exp_f32_e32 v57, v57
	v_pk_mul_f32 v[36:37], v[36:37], v[60:61]
	v_pk_mul_f32 v[42:43], v[42:43], 0.5 op_sel_hi:[1,0]
	v_pk_add_f32 v[56:57], v[56:57], 1.0 op_sel_hi:[1,0]
	s_nop 0
	v_rcp_f32_e32 v60, v57
	s_nop 0
	v_mul_f32_e32 v62, 2.0, v60
	v_fma_f32 v63, -v57, v62, 2.0
	v_fmac_f32_e32 v62, v63, v60
	v_div_fixup_f32 v57, v62, v57, 2.0
	v_rcp_f32_e32 v60, v56
	s_nop 0
	v_mul_f32_e32 v62, 2.0, v60
	v_fma_f32 v63, -v56, v62, 2.0
	v_fmac_f32_e32 v62, v63, v60
	v_div_fixup_f32 v56, v62, v56, 2.0
	v_pk_add_f32 v[56:57], v[56:57], 2.0 op_sel_hi:[1,0] neg_lo:[1,0] neg_hi:[1,0]
	s_nop 0
	v_pk_mul_f32 v[42:43], v[42:43], v[56:57]
	v_lshlrev_b32_e32 v56, 16, v59
	v_and_b32_e32 v57, 0xffff0000, v59
	v_pk_fma_f32 v[38:39], v[22:23], v[56:57], v[38:39]
	s_nop 0
	v_mul_f32_e32 v56, 0x3d372713, v38
	v_mul_f32_e32 v57, 0x3d372713, v39
	v_mul_f32_e32 v56, v38, v56
	v_mul_f32_e32 v57, v39, v57
	v_fma_f32 v56, v38, v56, v38
	v_fma_f32 v57, v39, v57, v39
	v_mul_f32_e32 v56, 0x3f4c422a, v56
	v_mul_f32_e32 v57, 0x3f4c422a, v57
	v_add_f32_e32 v56, v56, v56
	v_add_f32_e32 v57, v57, v57
	v_mul_f32_e32 v56, 0x3fb8aa3b, v56
	v_mul_f32_e32 v57, 0x3fb8aa3b, v57
	v_exp_f32_e32 v56, v56
	v_exp_f32_e32 v57, v57
	v_pk_mul_f32 v[38:39], v[38:39], 0.5 op_sel_hi:[1,0]
	v_pk_add_f32 v[56:57], v[56:57], 1.0 op_sel_hi:[1,0]
	s_nop 0
	v_rcp_f32_e32 v59, v57
	s_nop 0
	v_mul_f32_e32 v61, 2.0, v59
	v_fma_f32 v62, -v57, v61, 2.0
	v_fmac_f32_e32 v61, v62, v59
	v_div_fixup_f32 v57, v61, v57, 2.0
	v_rcp_f32_e32 v59, v56
	s_nop 0
	v_mul_f32_e32 v61, 2.0, v59
	v_fma_f32 v62, -v56, v61, 2.0
	v_fmac_f32_e32 v61, v62, v59
	v_div_fixup_f32 v56, v61, v56, 2.0
	v_pk_add_f32 v[56:57], v[56:57], 2.0 op_sel_hi:[1,0] neg_lo:[1,0] neg_hi:[1,0]
	s_nop 0
	v_pk_mul_f32 v[56:57], v[38:39], v[56:57]
	v_cvt_pk_bf16_f32 v38, v40, v41
	v_cvt_pk_bf16_f32 v40, v36, v37
	v_or_b32_e32 v36, v2, v142
	v_ashrrev_i32_e32 v37, 31, v36
	v_lshlrev_b64 v[36:37], 11, v[36:37]
	v_lshl_add_u64 v[36:37], s[4:5], 0, v[36:37]
	v_lshl_add_u64 v[36:37], v[36:37], 0, s[34:35]
	v_cvt_pk_bf16_f32 v39, v42, v43
	v_cvt_pk_bf16_f32 v41, v56, v57
	v_lshl_add_u64 v[36:37], v[36:37], 0, v[168:169]
	global_store_dwordx4 v[36:37], v[38:41], off
	v_lshlrev_b32_e32 v36, 16, v52
	v_and_b32_e32 v37, 0xffff0000, v52
	v_pk_fma_f32 v[32:33], v[24:25], v[36:37], v[32:33]
	s_nop 0
	v_mul_f32_e32 v36, 0x3d372713, v32
	v_mul_f32_e32 v37, 0x3d372713, v33
	v_mul_f32_e32 v36, v32, v36
	v_mul_f32_e32 v37, v33, v37
	v_fma_f32 v36, v32, v36, v32
	v_fma_f32 v37, v33, v37, v33
	v_mul_f32_e32 v36, 0x3f4c422a, v36
	v_mul_f32_e32 v37, 0x3f4c422a, v37
	v_add_f32_e32 v36, v36, v36
	v_add_f32_e32 v37, v37, v37
	v_mul_f32_e32 v36, 0x3fb8aa3b, v36
	v_mul_f32_e32 v37, 0x3fb8aa3b, v37
	v_exp_f32_e32 v36, v36
	v_exp_f32_e32 v37, v37
	v_pk_mul_f32 v[32:33], v[32:33], 0.5 op_sel_hi:[1,0]
	v_pk_add_f32 v[36:37], v[36:37], 1.0 op_sel_hi:[1,0]
	s_nop 0
; DI void unpack8(u32x4 w, float* f) { f[0] = bflo(w.x); f[1] = bfhi(w.x); f[2] = bflo(w.y); f[3] = bfhi(w.y); f[4] = bflo(w.z); f[5] = bfhi(w.z); f[6] = bflo(w.w); f[7] = bfhi(w.w); }
; DI u32x4 pack44(f32x4 a, f32x4 b) { u32x4 w; w.x = pk2(a[0], a[1]); w.y = pk2(a[2], a[3]); w.z = pk2(b[0], b[1]); w.w = pk2(b[2], b[3]); return w; }
; DI float gelu_tanh(float y) { float t = 0.7978845608f * (y + 0.044715f * y * y * y); float e = __expf(2.f * t); return 0.5f * y * (2.f - 2.f / (e + 1.f)); }
;     DI void operator()(const Acc& acc, const Unit& u, int wr, int wc, int fr, int fq) const {
;     ...
;                     for (int bj = 0; bj < 2; ++bj) { const int chunk = mt * 256 + ai * 128 + wr * 64 + (2 * mp + mi) * 16 + fr, n0 = nt * 256 + bj * 128 + wc * 32 + 8 * fq;
;                         uv[mi][bj] = *(const u32x4*)(uperm + (size_t)(g * 512 + chunk) * 640 + n0); }
; #pragma unroll
;                 for (int mi = 0; mi < 2; ++mi)
; #pragma unroll
;                     for (int bj = 0; bj < 2; ++bj) { const int m = 2 * mp + mi, chunk = mt * 256 + ai * 128 + wr * 64 + m * 16 + fr, n0 = nt * 256 + bj * 128 + wc * 32 + 8 * fq, t = n0 >> 4;
;                         f32x4 v0 = acc[ai][bj][m][0], v1 = acc[ai][bj][m][1]; float uf[8]; unpack8(uv[mi][bj], uf);
;                         for (int j = 0; j < 4; ++j) { v0[j] = gelu_tanh(v0[j] + d0[j] * uf[j]); v1[j] = gelu_tanh(v1[j] + d1[j] * uf[4 + j]); }
;                         *(u32x4*)(zs + (size_t)(chunk * 32 + t) * 1024 + g * 16 + ho0) = pack44(v0, v1); }
	v_rcp_f32_e32 v39, v37
	s_nop 0
	v_mul_f32_e32 v41, 2.0, v39
	v_fma_f32 v42, -v37, v41, 2.0
	v_fmac_f32_e32 v41, v42, v39
	v_div_fixup_f32 v37, v41, v37, 2.0
	v_rcp_f32_e32 v39, v36
	s_nop 0
	v_mul_f32_e32 v41, 2.0, v39
	v_fma_f32 v42, -v36, v41, 2.0
	v_fmac_f32_e32 v41, v42, v39
	v_div_fixup_f32 v36, v41, v36, 2.0
	v_pk_add_f32 v[36:37], v[36:37], 2.0 op_sel_hi:[1,0] neg_lo:[1,0] neg_hi:[1,0]
	s_nop 0
	v_pk_mul_f32 v[32:33], v[32:33], v[36:37]
	v_lshlrev_b32_e32 v36, 16, v54
	v_and_b32_e32 v37, 0xffff0000, v54
	v_pk_fma_f32 v[28:29], v[20:21], v[36:37], v[28:29]
	s_nop 0
	v_mul_f32_e32 v36, 0x3d372713, v28
	v_mul_f32_e32 v37, 0x3d372713, v29
	v_mul_f32_e32 v36, v28, v36
	v_mul_f32_e32 v37, v29, v37
	v_fma_f32 v36, v28, v36, v28
	v_fma_f32 v37, v29, v37, v29
	v_mul_f32_e32 v36, 0x3f4c422a, v36
	v_mul_f32_e32 v37, 0x3f4c422a, v37
	v_add_f32_e32 v36, v36, v36
	v_add_f32_e32 v37, v37, v37
	v_mul_f32_e32 v36, 0x3fb8aa3b, v36
	v_mul_f32_e32 v37, 0x3fb8aa3b, v37
	v_exp_f32_e32 v36, v36
	v_exp_f32_e32 v37, v37
	v_pk_mul_f32 v[28:29], v[28:29], 0.5 op_sel_hi:[1,0]
	v_pk_add_f32 v[36:37], v[36:37], 1.0 op_sel_hi:[1,0]
	s_nop 0
	v_rcp_f32_e32 v39, v37
	s_nop 0
	v_mul_f32_e32 v41, 2.0, v39
	v_fma_f32 v42, -v37, v41, 2.0
	v_fmac_f32_e32 v41, v42, v39
	v_div_fixup_f32 v37, v41, v37, 2.0
	v_rcp_f32_e32 v39, v36
	s_nop 0
	v_mul_f32_e32 v41, 2.0, v39
	v_fma_f32 v42, -v36, v41, 2.0
	v_fmac_f32_e32 v41, v42, v39
	v_div_fixup_f32 v36, v41, v36, 2.0
	v_pk_add_f32 v[36:37], v[36:37], 2.0 op_sel_hi:[1,0] neg_lo:[1,0] neg_hi:[1,0]
	s_nop 0
	v_pk_mul_f32 v[28:29], v[28:29], v[36:37]
	v_lshlrev_b32_e32 v36, 16, v53
	v_and_b32_e32 v37, 0xffff0000, v53
	v_pk_fma_f32 v[34:35], v[26:27], v[36:37], v[34:35]
	s_nop 0
	v_mul_f32_e32 v36, 0x3d372713, v34
	v_mul_f32_e32 v37, 0x3d372713, v35
	v_mul_f32_e32 v36, v34, v36
	v_mul_f32_e32 v37, v35, v37
	v_fma_f32 v36, v34, v36, v34
	v_fma_f32 v37, v35, v37, v35
	v_mul_f32_e32 v36, 0x3f4c422a, v36
	v_mul_f32_e32 v37, 0x3f4c422a, v37
	v_add_f32_e32 v36, v36, v36
	v_add_f32_e32 v37, v37, v37
	v_mul_f32_e32 v36, 0x3fb8aa3b, v36
	v_mul_f32_e32 v37, 0x3fb8aa3b, v37
	v_exp_f32_e32 v36, v36
	v_exp_f32_e32 v37, v37
	v_pk_mul_f32 v[34:35], v[34:35], 0.5 op_sel_hi:[1,0]
	v_pk_add_f32 v[36:37], v[36:37], 1.0 op_sel_hi:[1,0]
	s_nop 0
	v_rcp_f32_e32 v39, v37
	s_nop 0
	v_mul_f32_e32 v41, 2.0, v39
	v_fma_f32 v42, -v37, v41, 2.0
	v_fmac_f32_e32 v41, v42, v39
	v_div_fixup_f32 v37, v41, v37, 2.0
	v_rcp_f32_e32 v39, v36
	s_nop 0
	v_mul_f32_e32 v41, 2.0, v39
	v_fma_f32 v42, -v36, v41, 2.0
	v_fmac_f32_e32 v41, v42, v39
	v_div_fixup_f32 v36, v41, v36, 2.0
	v_pk_add_f32 v[36:37], v[36:37], 2.0 op_sel_hi:[1,0] neg_lo:[1,0] neg_hi:[1,0]
	s_nop 0
	v_pk_mul_f32 v[34:35], v[34:35], v[36:37]
	v_lshlrev_b32_e32 v36, 16, v55
	v_and_b32_e32 v37, 0xffff0000, v55
	v_pk_fma_f32 v[30:31], v[22:23], v[36:37], v[30:31]
	s_nop 0
	v_mul_f32_e32 v36, 0x3d372713, v30
	v_mul_f32_e32 v37, 0x3d372713, v31
	v_mul_f32_e32 v36, v30, v36
	v_mul_f32_e32 v37, v31, v37
	v_fma_f32 v36, v30, v36, v30
	v_fma_f32 v37, v31, v37, v31
	v_mul_f32_e32 v36, 0x3f4c422a, v36
	v_mul_f32_e32 v37, 0x3f4c422a, v37
	v_add_f32_e32 v36, v36, v36
	v_add_f32_e32 v37, v37, v37
	v_mul_f32_e32 v36, 0x3fb8aa3b, v36
	v_mul_f32_e32 v37, 0x3fb8aa3b, v37
	v_exp_f32_e32 v36, v36
	v_exp_f32_e32 v37, v37
	v_pk_mul_f32 v[30:31], v[30:31], 0.5 op_sel_hi:[1,0]
	v_pk_add_f32 v[36:37], v[36:37], 1.0 op_sel_hi:[1,0]
	s_nop 0
	v_rcp_f32_e32 v39, v37
	s_nop 0
	v_mul_f32_e32 v41, 2.0, v39
	v_fma_f32 v42, -v37, v41, 2.0
	v_fmac_f32_e32 v41, v42, v39
	v_div_fixup_f32 v37, v41, v37, 2.0
	v_rcp_f32_e32 v39, v36
	s_nop 0
	v_mul_f32_e32 v41, 2.0, v39
	v_fma_f32 v42, -v36, v41, 2.0
	v_fmac_f32_e32 v41, v42, v39
	v_div_fixup_f32 v36, v41, v36, 2.0
	v_pk_add_f32 v[36:37], v[36:37], 2.0 op_sel_hi:[1,0] neg_lo:[1,0] neg_hi:[1,0]
	s_nop 0
	v_pk_mul_f32 v[36:37], v[30:31], v[36:37]
	v_cvt_pk_bf16_f32 v30, v32, v33
	v_cvt_pk_bf16_f32 v32, v28, v29
	v_or_b32_e32 v28, v2, v130
	v_ashrrev_i32_e32 v29, 31, v28
	v_lshlrev_b64 v[28:29], 11, v[28:29]
	v_lshl_add_u64 v[28:29], s[4:5], 0, v[28:29]
	v_lshl_add_u64 v[28:29], v[28:29], 0, s[34:35]
	v_cvt_pk_bf16_f32 v31, v34, v35
	v_cvt_pk_bf16_f32 v33, v36, v37
	v_lshl_add_u64 v[28:29], v[28:29], 0, v[168:169]
	global_store_dwordx4 v[28:29], v[30:33], off
	v_lshlrev_b32_e32 v28, 16, v48
	v_and_b32_e32 v29, 0xffff0000, v48
	v_pk_fma_f32 v[16:17], v[24:25], v[28:29], v[16:17]
	v_add_u32_e32 v2, 0x1600, v176
	v_mul_f32_e32 v28, 0x3d372713, v16
	v_mul_f32_e32 v29, 0x3d372713, v17
	v_mul_f32_e32 v28, v16, v28
	v_mul_f32_e32 v29, v17, v29
	v_fma_f32 v28, v16, v28, v16
	v_fma_f32 v29, v17, v29, v17
	v_mul_f32_e32 v28, 0x3f4c422a, v28
	v_mul_f32_e32 v29, 0x3f4c422a, v29
	v_add_f32_e32 v28, v28, v28
	v_add_f32_e32 v29, v29, v29
	v_mul_f32_e32 v28, 0x3fb8aa3b, v28
	v_mul_f32_e32 v29, 0x3fb8aa3b, v29
	v_exp_f32_e32 v28, v28
	v_exp_f32_e32 v29, v29
	v_pk_mul_f32 v[16:17], v[16:17], 0.5 op_sel_hi:[1,0]
	v_pk_add_f32 v[28:29], v[28:29], 1.0 op_sel_hi:[1,0]
	s_nop 0
	v_rcp_f32_e32 v31, v29
	s_nop 0
	v_mul_f32_e32 v33, 2.0, v31
	v_fma_f32 v34, -v29, v33, 2.0
	v_fmac_f32_e32 v33, v34, v31
	v_div_fixup_f32 v29, v33, v29, 2.0
	v_rcp_f32_e32 v31, v28
	s_nop 0
	v_mul_f32_e32 v33, 2.0, v31
	v_fma_f32 v34, -v28, v33, 2.0
	v_fmac_f32_e32 v33, v34, v31
	v_div_fixup_f32 v28, v33, v28, 2.0
	v_pk_add_f32 v[28:29], v[28:29], 2.0 op_sel_hi:[1,0] neg_lo:[1,0] neg_hi:[1,0]
	s_nop 0
	v_pk_mul_f32 v[16:17], v[16:17], v[28:29]
	v_lshlrev_b32_e32 v28, 16, v50
	v_and_b32_e32 v29, 0xffff0000, v50
	v_pk_fma_f32 v[12:13], v[20:21], v[28:29], v[12:13]
	s_nop 0
	v_mul_f32_e32 v28, 0x3d372713, v12
	v_mul_f32_e32 v29, 0x3d372713, v13
; DI void unpack8(u32x4 w, float* f) { f[0] = bflo(w.x); f[1] = bfhi(w.x); f[2] = bflo(w.y); f[3] = bfhi(w.y); f[4] = bflo(w.z); f[5] = bfhi(w.z); f[6] = bflo(w.w); f[7] = bfhi(w.w); }
; DI u32x4 pack44(f32x4 a, f32x4 b) { u32x4 w; w.x = pk2(a[0], a[1]); w.y = pk2(a[2], a[3]); w.z = pk2(b[0], b[1]); w.w = pk2(b[2], b[3]); return w; }
; DI float gelu_tanh(float y) { float t = 0.7978845608f * (y + 0.044715f * y * y * y); float e = __expf(2.f * t); return 0.5f * y * (2.f - 2.f / (e + 1.f)); }
;     DI void operator()(const Acc& acc, const Unit& u, int wr, int wc, int fr, int fq) const {
;     ...
;                     for (int bj = 0; bj < 2; ++bj) { const int chunk = mt * 256 + ai * 128 + wr * 64 + (2 * mp + mi) * 16 + fr, n0 = nt * 256 + bj * 128 + wc * 32 + 8 * fq;
;                         uv[mi][bj] = *(const u32x4*)(uperm + (size_t)(g * 512 + chunk) * 640 + n0); }
; #pragma unroll
;                 for (int mi = 0; mi < 2; ++mi)
; #pragma unroll
;                     for (int bj = 0; bj < 2; ++bj) { const int m = 2 * mp + mi, chunk = mt * 256 + ai * 128 + wr * 64 + m * 16 + fr, n0 = nt * 256 + bj * 128 + wc * 32 + 8 * fq, t = n0 >> 4;
;                         f32x4 v0 = acc[ai][bj][m][0], v1 = acc[ai][bj][m][1]; float uf[8]; unpack8(uv[mi][bj], uf);
;                         for (int j = 0; j < 4; ++j) { v0[j] = gelu_tanh(v0[j] + d0[j] * uf[j]); v1[j] = gelu_tanh(v1[j] + d1[j] * uf[4 + j]); }
;                         *(u32x4*)(zs + (size_t)(chunk * 32 + t) * 1024 + g * 16 + ho0) = pack44(v0, v1); }
	v_mul_f32_e32 v28, v12, v28
	v_mul_f32_e32 v29, v13, v29
	v_fma_f32 v28, v12, v28, v12
	v_fma_f32 v29, v13, v29, v13
	v_mul_f32_e32 v28, 0x3f4c422a, v28
	v_mul_f32_e32 v29, 0x3f4c422a, v29
	v_add_f32_e32 v28, v28, v28
	v_add_f32_e32 v29, v29, v29
	v_mul_f32_e32 v28, 0x3fb8aa3b, v28
	v_mul_f32_e32 v29, 0x3fb8aa3b, v29
	v_exp_f32_e32 v28, v28
	v_exp_f32_e32 v29, v29
	v_pk_mul_f32 v[12:13], v[12:13], 0.5 op_sel_hi:[1,0]
	v_pk_add_f32 v[28:29], v[28:29], 1.0 op_sel_hi:[1,0]
	s_nop 0
	v_rcp_f32_e32 v31, v29
	s_nop 0
	v_mul_f32_e32 v33, 2.0, v31
	v_fma_f32 v34, -v29, v33, 2.0
	v_fmac_f32_e32 v33, v34, v31
	v_div_fixup_f32 v29, v33, v29, 2.0
	v_rcp_f32_e32 v31, v28
	s_nop 0
	v_mul_f32_e32 v33, 2.0, v31
	v_fma_f32 v34, -v28, v33, 2.0
	v_fmac_f32_e32 v33, v34, v31
	v_div_fixup_f32 v28, v33, v28, 2.0
	v_pk_add_f32 v[28:29], v[28:29], 2.0 op_sel_hi:[1,0] neg_lo:[1,0] neg_hi:[1,0]
	s_nop 0
	v_pk_mul_f32 v[12:13], v[12:13], v[28:29]
	v_lshlrev_b32_e32 v28, 16, v49
	v_and_b32_e32 v29, 0xffff0000, v49
	v_pk_fma_f32 v[18:19], v[26:27], v[28:29], v[18:19]
	s_nop 0
	v_mul_f32_e32 v28, 0x3d372713, v18
	v_mul_f32_e32 v29, 0x3d372713, v19
	v_mul_f32_e32 v28, v18, v28
	v_mul_f32_e32 v29, v19, v29
	v_fma_f32 v28, v18, v28, v18
	v_fma_f32 v29, v19, v29, v19
	v_mul_f32_e32 v28, 0x3f4c422a, v28
	v_mul_f32_e32 v29, 0x3f4c422a, v29
	v_add_f32_e32 v28, v28, v28
	v_add_f32_e32 v29, v29, v29
	v_mul_f32_e32 v28, 0x3fb8aa3b, v28
	v_mul_f32_e32 v29, 0x3fb8aa3b, v29
	v_exp_f32_e32 v28, v28
	v_exp_f32_e32 v29, v29
	v_pk_mul_f32 v[18:19], v[18:19], 0.5 op_sel_hi:[1,0]
	v_pk_add_f32 v[28:29], v[28:29], 1.0 op_sel_hi:[1,0]
	s_nop 0
	v_rcp_f32_e32 v31, v29
	s_nop 0
	v_mul_f32_e32 v33, 2.0, v31
	v_fma_f32 v34, -v29, v33, 2.0
	v_fmac_f32_e32 v33, v34, v31
	v_div_fixup_f32 v29, v33, v29, 2.0
	v_rcp_f32_e32 v31, v28
	s_nop 0
	v_mul_f32_e32 v33, 2.0, v31
	v_fma_f32 v34, -v28, v33, 2.0
	v_fmac_f32_e32 v33, v34, v31
	v_div_fixup_f32 v28, v33, v28, 2.0
	v_pk_add_f32 v[28:29], v[28:29], 2.0 op_sel_hi:[1,0] neg_lo:[1,0] neg_hi:[1,0]
	s_nop 0
	v_pk_mul_f32 v[18:19], v[18:19], v[28:29]
	v_lshlrev_b32_e32 v28, 16, v51
	v_and_b32_e32 v29, 0xffff0000, v51
	v_pk_fma_f32 v[14:15], v[22:23], v[28:29], v[14:15]
	s_nop 0
	v_mul_f32_e32 v28, 0x3d372713, v14
	v_mul_f32_e32 v29, 0x3d372713, v15
	v_mul_f32_e32 v28, v14, v28
	v_mul_f32_e32 v29, v15, v29
	v_fma_f32 v28, v14, v28, v14
	v_fma_f32 v29, v15, v29, v15
	v_mul_f32_e32 v28, 0x3f4c422a, v28
	v_mul_f32_e32 v29, 0x3f4c422a, v29
	v_add_f32_e32 v28, v28, v28
	v_add_f32_e32 v29, v29, v29
	v_mul_f32_e32 v28, 0x3fb8aa3b, v28
	v_mul_f32_e32 v29, 0x3fb8aa3b, v29
	v_exp_f32_e32 v28, v28
	v_exp_f32_e32 v29, v29
	v_pk_mul_f32 v[14:15], v[14:15], 0.5 op_sel_hi:[1,0]
	v_pk_add_f32 v[28:29], v[28:29], 1.0 op_sel_hi:[1,0]
	s_nop 0
	v_rcp_f32_e32 v31, v29
	s_nop 0
	v_mul_f32_e32 v33, 2.0, v31
	v_fma_f32 v34, -v29, v33, 2.0
	v_fmac_f32_e32 v33, v34, v31
	v_div_fixup_f32 v29, v33, v29, 2.0
	v_rcp_f32_e32 v31, v28
	s_nop 0
	v_mul_f32_e32 v33, 2.0, v31
	v_fma_f32 v34, -v28, v33, 2.0
	v_fmac_f32_e32 v33, v34, v31
	v_div_fixup_f32 v28, v33, v28, 2.0
	v_pk_add_f32 v[28:29], v[28:29], 2.0 op_sel_hi:[1,0] neg_lo:[1,0] neg_hi:[1,0]
	s_nop 0
	v_pk_mul_f32 v[28:29], v[14:15], v[28:29]
	v_cvt_pk_bf16_f32 v14, v16, v17
	v_cvt_pk_bf16_f32 v16, v12, v13
	v_or_b32_e32 v12, v2, v142
	v_ashrrev_i32_e32 v13, 31, v12
	v_lshlrev_b64 v[12:13], 11, v[12:13]
	v_lshl_add_u64 v[12:13], s[4:5], 0, v[12:13]
	v_lshl_add_u64 v[12:13], v[12:13], 0, s[34:35]
	v_cvt_pk_bf16_f32 v15, v18, v19
	v_cvt_pk_bf16_f32 v17, v28, v29
	v_lshl_add_u64 v[12:13], v[12:13], 0, v[168:169]
	global_store_dwordx4 v[12:13], v[14:17], off
	v_lshlrev_b32_e32 v12, 16, v44
	v_and_b32_e32 v13, 0xffff0000, v44
	v_pk_fma_f32 v[8:9], v[24:25], v[12:13], v[8:9]
	s_nop 0
	v_mul_f32_e32 v12, 0x3d372713, v8
	v_mul_f32_e32 v13, 0x3d372713, v9
	v_mul_f32_e32 v12, v8, v12
	v_mul_f32_e32 v13, v9, v13
	v_fma_f32 v12, v8, v12, v8
	v_fma_f32 v13, v9, v13, v9
	v_mul_f32_e32 v12, 0x3f4c422a, v12
	v_mul_f32_e32 v13, 0x3f4c422a, v13
	v_add_f32_e32 v12, v12, v12
	v_add_f32_e32 v13, v13, v13
	v_mul_f32_e32 v12, 0x3fb8aa3b, v12
	v_mul_f32_e32 v13, 0x3fb8aa3b, v13
	v_exp_f32_e32 v12, v12
	v_exp_f32_e32 v13, v13
	v_pk_mul_f32 v[8:9], v[8:9], 0.5 op_sel_hi:[1,0]
	v_pk_add_f32 v[12:13], v[12:13], 1.0 op_sel_hi:[1,0]
	s_nop 0
	v_rcp_f32_e32 v15, v13
	s_nop 0
; DI void unpack8(u32x4 w, float* f) { f[0] = bflo(w.x); f[1] = bfhi(w.x); f[2] = bflo(w.y); f[3] = bfhi(w.y); f[4] = bflo(w.z); f[5] = bfhi(w.z); f[6] = bflo(w.w); f[7] = bfhi(w.w); }
; DI u32x4 pack44(f32x4 a, f32x4 b) { u32x4 w; w.x = pk2(a[0], a[1]); w.y = pk2(a[2], a[3]); w.z = pk2(b[0], b[1]); w.w = pk2(b[2], b[3]); return w; }
; DI float gelu_tanh(float y) { float t = 0.7978845608f * (y + 0.044715f * y * y * y); float e = __expf(2.f * t); return 0.5f * y * (2.f - 2.f / (e + 1.f)); }
; template <class Epi, class Sched>
; DI void gemm_phase(LAS unsigned char* lds, const Gemm g, const Sched& S, const Epi& E) {
;     ...
;         E(acc, cur, wr, wc, fr, fq);
;         if (!has_next) break;
;     DI void operator()(const Acc& acc, const Unit& u, int wr, int wc, int fr, int fq) const {
;     ...
;                     for (int bj = 0; bj < 2; ++bj) { const int chunk = mt * 256 + ai * 128 + wr * 64 + (2 * mp + mi) * 16 + fr, n0 = nt * 256 + bj * 128 + wc * 32 + 8 * fq;
;                         uv[mi][bj] = *(const u32x4*)(uperm + (size_t)(g * 512 + chunk) * 640 + n0); }
; #pragma unroll
;                 for (int mi = 0; mi < 2; ++mi)
; #pragma unroll
;                     for (int bj = 0; bj < 2; ++bj) { const int m = 2 * mp + mi, chunk = mt * 256 + ai * 128 + wr * 64 + m * 16 + fr, n0 = nt * 256 + bj * 128 + wc * 32 + 8 * fq, t = n0 >> 4;
;                         f32x4 v0 = acc[ai][bj][m][0], v1 = acc[ai][bj][m][1]; float uf[8]; unpack8(uv[mi][bj], uf);
;                         for (int j = 0; j < 4; ++j) { v0[j] = gelu_tanh(v0[j] + d0[j] * uf[j]); v1[j] = gelu_tanh(v1[j] + d1[j] * uf[4 + j]); }
;                         *(u32x4*)(zs + (size_t)(chunk * 32 + t) * 1024 + g * 16 + ho0) = pack44(v0, v1); }
	v_mul_f32_e32 v17, 2.0, v15
	v_fma_f32 v18, -v13, v17, 2.0
	v_fmac_f32_e32 v17, v18, v15
	v_div_fixup_f32 v13, v17, v13, 2.0
	v_rcp_f32_e32 v15, v12
	s_nop 0
	v_mul_f32_e32 v17, 2.0, v15
	v_fma_f32 v18, -v12, v17, 2.0
	v_fmac_f32_e32 v17, v18, v15
	v_div_fixup_f32 v12, v17, v12, 2.0
	v_pk_add_f32 v[12:13], v[12:13], 2.0 op_sel_hi:[1,0] neg_lo:[1,0] neg_hi:[1,0]
	s_nop 0
	v_pk_mul_f32 v[8:9], v[8:9], v[12:13]
	v_lshlrev_b32_e32 v12, 16, v46
	v_and_b32_e32 v13, 0xffff0000, v46
	v_pk_fma_f32 v[4:5], v[20:21], v[12:13], v[4:5]
	s_nop 0
	v_mul_f32_e32 v12, 0x3d372713, v4
	v_mul_f32_e32 v13, 0x3d372713, v5
	v_mul_f32_e32 v12, v4, v12
	v_mul_f32_e32 v13, v5, v13
	v_fma_f32 v12, v4, v12, v4
	v_fma_f32 v13, v5, v13, v5
	v_mul_f32_e32 v12, 0x3f4c422a, v12
	v_mul_f32_e32 v13, 0x3f4c422a, v13
	v_add_f32_e32 v12, v12, v12
	v_add_f32_e32 v13, v13, v13
	v_mul_f32_e32 v12, 0x3fb8aa3b, v12
	v_mul_f32_e32 v13, 0x3fb8aa3b, v13
	v_exp_f32_e32 v12, v12
	v_exp_f32_e32 v13, v13
	v_pk_mul_f32 v[4:5], v[4:5], 0.5 op_sel_hi:[1,0]
	v_pk_add_f32 v[12:13], v[12:13], 1.0 op_sel_hi:[1,0]
	s_nop 0
	v_rcp_f32_e32 v15, v13
	s_nop 0
	v_mul_f32_e32 v17, 2.0, v15
	v_fma_f32 v18, -v13, v17, 2.0
	v_fmac_f32_e32 v17, v18, v15
	v_div_fixup_f32 v13, v17, v13, 2.0
	v_rcp_f32_e32 v15, v12
	s_nop 0
	v_mul_f32_e32 v17, 2.0, v15
	v_fma_f32 v18, -v12, v17, 2.0
	v_fmac_f32_e32 v17, v18, v15
	v_div_fixup_f32 v12, v17, v12, 2.0
	v_pk_add_f32 v[12:13], v[12:13], 2.0 op_sel_hi:[1,0] neg_lo:[1,0] neg_hi:[1,0]
	s_nop 0
	v_pk_mul_f32 v[4:5], v[4:5], v[12:13]
	v_lshlrev_b32_e32 v12, 16, v45
	v_and_b32_e32 v13, 0xffff0000, v45
	v_pk_fma_f32 v[10:11], v[26:27], v[12:13], v[10:11]
	s_nop 0
	v_mul_f32_e32 v12, 0x3d372713, v10
	v_mul_f32_e32 v13, 0x3d372713, v11
	v_mul_f32_e32 v12, v10, v12
	v_mul_f32_e32 v13, v11, v13
	v_fma_f32 v12, v10, v12, v10
	v_fma_f32 v13, v11, v13, v11
	v_mul_f32_e32 v12, 0x3f4c422a, v12
	v_mul_f32_e32 v13, 0x3f4c422a, v13
	v_add_f32_e32 v12, v12, v12
	v_add_f32_e32 v13, v13, v13
	v_mul_f32_e32 v12, 0x3fb8aa3b, v12
	v_mul_f32_e32 v13, 0x3fb8aa3b, v13
	v_exp_f32_e32 v12, v12
	v_exp_f32_e32 v13, v13
	v_pk_mul_f32 v[10:11], v[10:11], 0.5 op_sel_hi:[1,0]
	v_pk_add_f32 v[12:13], v[12:13], 1.0 op_sel_hi:[1,0]
	s_nop 0
	v_rcp_f32_e32 v15, v13
	s_nop 0
	v_mul_f32_e32 v17, 2.0, v15
	v_fma_f32 v18, -v13, v17, 2.0
	v_fmac_f32_e32 v17, v18, v15
	v_div_fixup_f32 v13, v17, v13, 2.0
	v_rcp_f32_e32 v15, v12
	s_nop 0
	v_mul_f32_e32 v17, 2.0, v15
	v_fma_f32 v18, -v12, v17, 2.0
	v_fmac_f32_e32 v17, v18, v15
	v_div_fixup_f32 v12, v17, v12, 2.0
	v_pk_add_f32 v[12:13], v[12:13], 2.0 op_sel_hi:[1,0] neg_lo:[1,0] neg_hi:[1,0]
	s_nop 0
	v_pk_mul_f32 v[10:11], v[10:11], v[12:13]
	v_lshlrev_b32_e32 v12, 16, v47
	v_and_b32_e32 v13, 0xffff0000, v47
	v_pk_fma_f32 v[6:7], v[22:23], v[12:13], v[6:7]
	s_nop 0
	v_mul_f32_e32 v12, 0x3d372713, v6
	v_mul_f32_e32 v13, 0x3d372713, v7
	v_mul_f32_e32 v12, v6, v12
	v_mul_f32_e32 v13, v7, v13
	v_fma_f32 v12, v6, v12, v6
	v_fma_f32 v13, v7, v13, v7
	v_mul_f32_e32 v12, 0x3f4c422a, v12
	v_mul_f32_e32 v13, 0x3f4c422a, v13
	v_add_f32_e32 v12, v12, v12
	v_add_f32_e32 v13, v13, v13
	v_mul_f32_e32 v12, 0x3fb8aa3b, v12
	v_mul_f32_e32 v13, 0x3fb8aa3b, v13
	v_exp_f32_e32 v12, v12
	v_exp_f32_e32 v13, v13
	v_pk_mul_f32 v[6:7], v[6:7], 0.5 op_sel_hi:[1,0]
	v_pk_add_f32 v[12:13], v[12:13], 1.0 op_sel_hi:[1,0]
	s_nop 0
	v_rcp_f32_e32 v15, v13
	s_nop 0
	v_mul_f32_e32 v17, 2.0, v15
	v_fma_f32 v18, -v13, v17, 2.0
	v_fmac_f32_e32 v17, v18, v15
	v_div_fixup_f32 v13, v17, v13, 2.0
	v_rcp_f32_e32 v15, v12
	s_nop 0
	s_mov_b64 s[2:3], s[26:27]
	v_mul_f32_e32 v17, 2.0, v15
	v_fma_f32 v18, -v12, v17, 2.0
	v_fmac_f32_e32 v17, v18, v15
	v_div_fixup_f32 v12, v17, v12, 2.0
	v_pk_add_f32 v[12:13], v[12:13], 2.0 op_sel_hi:[1,0] neg_lo:[1,0] neg_hi:[1,0]
	s_and_b64 vcc, exec, s[28:29]
	v_pk_mul_f32 v[12:13], v[6:7], v[12:13]
	v_cvt_pk_bf16_f32 v6, v8, v9
	v_cvt_pk_bf16_f32 v8, v4, v5
	v_or_b32_e32 v4, v2, v130
	v_ashrrev_i32_e32 v5, 31, v4
	v_lshlrev_b64 v[4:5], 11, v[4:5]
	v_lshl_add_u64 v[4:5], s[4:5], 0, v[4:5]
	v_lshl_add_u64 v[4:5], v[4:5], 0, s[34:35]
	v_cvt_pk_bf16_f32 v7, v10, v11
	v_cvt_pk_bf16_f32 v9, v12, v13
	v_lshl_add_u64 v[4:5], v[4:5], 0, v[168:169]
	global_store_dwordx4 v[4:5], v[6:9], off
	s_cbranch_vccz .LBB0_110
	s_waitcnt vmcnt(0)
	s_cmpk_gt_u32 s39, 0xff
	s_cbranch_scc1 .LBB0_119
	s_barrier

; #define PG8_STAGE(bufoff, gbase, voff) do { _Pragma("unroll") for (int _i = 0; _i < 2; ++_i) \
;         __builtin_amdgcn_global_load_lds((const unsigned*)((const char*)(gbase) + (voff)[_i]), (LAS unsigned*)(lds + (bufoff) + ldsw + _i * 8192), 16, 0, 0); } while (0)
; #define PG8_LDA(dst, b, h) do { _Pragma("unroll") for (int m = 0; m < 4; ++m) _Pragma("unroll") for (int k = 0; k < 2; ++k) dst[m][k] = *(const LAS bf16x8*)(lds + PG8_SA(b, h) + aoff + m * 2048 + k * 1024); } while (0)
; #define PG8_LDB(dst, b, h) do { _Pragma("unroll") for (int n = 0; n < 2; ++n) _Pragma("unroll") for (int k = 0; k < 2; ++k) dst[n][k] = *(const LAS bf16x8*)(lds + PG8_SB(b, h) + boff + n * 2048 + k * 1024); } while (0)
; #define PG8_MMA(ai, bj, At, Bt) do { __builtin_amdgcn_s_setprio(1); _Pragma("unroll") for (int m = 0; m < 4; ++m) _Pragma("unroll") for (int n = 0; n < 2; ++n) _Pragma("unroll") for (int k = 0; k < 2; ++k) \
;         acc[ai][bj][m][n] = __builtin_amdgcn_mfma_f32_16x16x32_bf16(Bt[n][k], At[m][k], acc[ai][bj][m][n], 0, 0, 0); __builtin_amdgcn_s_setprio(0); } while (0)
; #define PG8_WAIT_L(n) asm volatile("s_waitcnt lgkmcnt(" #n ")" ::: "memory")
; #define PG8_BAR __builtin_amdgcn_s_barrier()
; #define PG8_SCHED __builtin_amdgcn_sched_barrier(0)
; template <class Epi, class Sched>
; DI void gemm_phase(LAS unsigned char* lds, const Gemm g, const Sched& S, const Epi& E) {
;     ...
;         for (int t = 0; t < nt; t += 2) {
;             const bool last = (t == nt - 2);
;             const char* a1 = cA + (size_t)(t + 1) * kstep;
;             const char* a2 = last ? nA : cA + (size_t)(t + 2) * kstep; const char* b2 = last ? nB : cB + (size_t)(t + 2) * kstep;
;             const char* a3 = a2 + kstep; const char* b3 = b2 + kstep;
;             PG8_LDB(B0, 0, 0); PG8_SCHED; PG8_LDA(At, 0, 0); PG8_STAGE(PG8_SA(1, 1), a1 + hstepA, voffA);
;             PG8_WAIT_L(8); PG8_BAR; PG8_WAIT_L(0); PG8_MMA(0, 0, At, B0); PG8_BAR; PG8_SCHED;
;             PG8_LDB(B1, 0, 1); PG8_STAGE(PG8_SB(0, 0), b2, voffB);
;             PG8_BAR; PG8_WAIT_L(0); PG8_MMA(0, 1, At, B1); PG8_BAR;
;             PG8_LDA(At, 0, 1); PG8_STAGE(PG8_SA(0, 0), a2, voffA);
;             PG8_BAR; PG8_WAIT_L(0); PG8_MMA(1, 0, At, B0); PG8_BAR; PG8_SCHED;
.LBB0_137:
	s_add_u32 s2, s20, 0xfffc0080
	s_addc_u32 s3, s21, -1
	s_add_i32 s83, 0, 0x10000
	v_add_u32_e32 v40, s83, v181
	ds_read_b128 v[20:23], v40
	ds_read_b128 v[24:27], v40 offset:1024
	ds_read_b128 v[36:39], v40 offset:2048
	ds_read_b128 v[40:43], v40 offset:3072
	s_cmp_eq_u32 s82, 12
	s_cselect_b32 s39, s31, s3
	s_cselect_b32 s38, s55, s2
	s_cselect_b32 s3, s29, s65
	s_cselect_b32 s2, s56, s64
	v_lshl_add_u64 v[202:203], s[20:21], 0, v[168:169]
	s_add_i32 m0, s43, 0xc000
	ds_read_b128 v[132:135], v183
	ds_read_b128 v[144:147], v183 offset:1024
	ds_read_b128 v[152:155], v183 offset:2048
	ds_read_b128 v[160:163], v183 offset:3072
	ds_read_b128 v[172:175], v183 offset:4096
	ds_read_b128 v[176:179], v183 offset:5120
	ds_read_b128 v[184:187], v183 offset:6144
	ds_read_b128 v[188:191], v183 offset:7168
	global_load_lds_dwordx4 v[202:203], off
	v_lshl_add_u64 v[202:203], s[20:21], 0, v[170:171]
	s_add_i32 m0, s43, 0xe000
	s_nop 0
	global_load_lds_dwordx4 v[202:203], off
	s_waitcnt lgkmcnt(8)
	s_barrier
	s_waitcnt lgkmcnt(0)
	s_setprio 1
	s_waitcnt lgkmcnt(0)
	v_mfma_f32_16x16x32_bf16 v[156:159], v[20:23], v[132:135], v[156:159]
	v_mfma_f32_16x16x32_bf16 v[148:151], v[36:39], v[132:135], v[148:151]
	v_mfma_f32_16x16x32_bf16 v[128:131], v[20:23], v[152:155], v[128:131]
	v_mfma_f32_16x16x32_bf16 v[124:127], v[36:39], v[152:155], v[124:127]
	v_mfma_f32_16x16x32_bf16 v[112:115], v[20:23], v[172:175], v[112:115]
	v_mfma_f32_16x16x32_bf16 v[108:111], v[36:39], v[172:175], v[108:111]
	v_mfma_f32_16x16x32_bf16 v[96:99], v[20:23], v[184:187], v[96:99]
	v_mfma_f32_16x16x32_bf16 v[92:95], v[36:39], v[184:187], v[92:95]
	v_mfma_f32_16x16x32_bf16 v[156:159], v[24:27], v[144:147], v[156:159]
	v_mfma_f32_16x16x32_bf16 v[148:151], v[40:43], v[144:147], v[148:151]
	v_mfma_f32_16x16x32_bf16 v[128:131], v[24:27], v[160:163], v[128:131]
	v_mfma_f32_16x16x32_bf16 v[124:127], v[40:43], v[160:163], v[124:127]
	v_mfma_f32_16x16x32_bf16 v[112:115], v[24:27], v[176:179], v[112:115]
	v_mfma_f32_16x16x32_bf16 v[108:111], v[40:43], v[176:179], v[108:111]
	v_mfma_f32_16x16x32_bf16 v[96:99], v[24:27], v[188:191], v[96:99]
	v_mfma_f32_16x16x32_bf16 v[92:95], v[40:43], v[188:191], v[92:95]
	s_setprio 0
	s_barrier
	s_add_i32 s92, 0, 0x14000
	s_add_i32 s83, s83, s42
	v_add_u32_e32 v214, s92, v181
	v_lshl_add_u64 v[230:231], s[2:3], 0, v[2:3]
	s_mov_b32 m0, s83
	ds_read_b128 v[202:205], v214
	ds_read_b128 v[206:209], v214 offset:1024
	ds_read_b128 v[210:213], v214 offset:2048
	ds_read_b128 v[214:217], v214 offset:3072
	global_load_lds_dwordx4 v[230:231], off
	v_lshl_add_u64 v[232:233], s[2:3], 0, v[0:1]
	s_add_i32 m0, s83, 0x2000
	s_nop 0
	global_load_lds_dwordx4 v[232:233], off
	s_barrier
	s_waitcnt lgkmcnt(0)
	s_setprio 1
	s_waitcnt lgkmcnt(0)
	v_mfma_f32_16x16x32_bf16 v[140:143], v[202:205], v[132:135], v[140:143]
	v_mfma_f32_16x16x32_bf16 v[120:123], v[202:205], v[152:155], v[120:123]
	v_mfma_f32_16x16x32_bf16 v[116:119], v[210:213], v[152:155], v[116:119]
	v_mfma_f32_16x16x32_bf16 v[104:107], v[202:205], v[172:175], v[104:107]
	v_mfma_f32_16x16x32_bf16 v[100:103], v[210:213], v[172:175], v[100:103]
	v_mfma_f32_16x16x32_bf16 v[88:91], v[202:205], v[184:187], v[88:91]
	v_mfma_f32_16x16x32_bf16 v[84:87], v[210:213], v[184:187], v[84:87]
	v_mfma_f32_16x16x32_bf16 v[140:143], v[206:209], v[144:147], v[140:143]
	v_mfma_f32_16x16x32_bf16 v[132:135], v[210:213], v[132:135], v[136:139]
	v_mfma_f32_16x16x32_bf16 v[120:123], v[206:209], v[160:163], v[120:123]
	v_mfma_f32_16x16x32_bf16 v[116:119], v[214:217], v[160:163], v[116:119]
	v_mfma_f32_16x16x32_bf16 v[104:107], v[206:209], v[176:179], v[104:107]
	v_mfma_f32_16x16x32_bf16 v[100:103], v[214:217], v[176:179], v[100:103]
	v_mfma_f32_16x16x32_bf16 v[88:91], v[206:209], v[188:191], v[88:91]
	v_mfma_f32_16x16x32_bf16 v[84:87], v[214:217], v[188:191], v[84:87]
	v_mfma_f32_16x16x32_bf16 v[132:135], v[214:217], v[144:147], v[132:135]
	s_setprio 0
	s_mov_b32 m0, s43
	v_lshl_add_u64 v[234:235], s[38:39], 0, v[166:167]
	s_barrier
	ds_read_b128 v[136:139], v183 offset:16384
	ds_read_b128 v[144:147], v183 offset:17408
	ds_read_b128 v[152:155], v183 offset:18432
	ds_read_b128 v[160:163], v183 offset:19456
	ds_read_b128 v[172:175], v183 offset:20480
	ds_read_b128 v[176:179], v183 offset:21504
	ds_read_b128 v[184:187], v183 offset:22528
	ds_read_b128 v[188:191], v183 offset:23552
	global_load_lds_dwordx4 v[234:235], off
	v_lshl_add_u64 v[236:237], s[38:39], 0, v[164:165]
	s_mov_b32 m0, s45
	s_nop 0
	global_load_lds_dwordx4 v[236:237], off
	s_barrier
	s_waitcnt lgkmcnt(0)
	s_setprio 1
	s_waitcnt lgkmcnt(0)
	v_mfma_f32_16x16x32_bf16 v[80:83], v[20:23], v[136:139], v[80:83]
	v_mfma_f32_16x16x32_bf16 v[76:79], v[36:39], v[136:139], v[76:79]
	v_mfma_f32_16x16x32_bf16 v[64:67], v[20:23], v[152:155], v[64:67]
	v_mfma_f32_16x16x32_bf16 v[60:63], v[36:39], v[152:155], v[60:63]
	v_mfma_f32_16x16x32_bf16 v[48:51], v[20:23], v[172:175], v[48:51]
	v_mfma_f32_16x16x32_bf16 v[44:47], v[36:39], v[172:175], v[44:47]
	v_mfma_f32_16x16x32_bf16 v[16:19], v[20:23], v[184:187], v[16:19]
	v_mfma_f32_16x16x32_bf16 v[12:15], v[36:39], v[184:187], v[12:15]
	v_mfma_f32_16x16x32_bf16 v[80:83], v[24:27], v[144:147], v[80:83]
	v_mfma_f32_16x16x32_bf16 v[76:79], v[40:43], v[144:147], v[76:79]
	v_mfma_f32_16x16x32_bf16 v[64:67], v[24:27], v[160:163], v[64:67]
	v_mfma_f32_16x16x32_bf16 v[60:63], v[40:43], v[160:163], v[60:63]
	v_mfma_f32_16x16x32_bf16 v[48:51], v[24:27], v[176:179], v[48:51]
	v_mfma_f32_16x16x32_bf16 v[44:47], v[40:43], v[176:179], v[44:47]
	v_mfma_f32_16x16x32_bf16 v[16:19], v[24:27], v[188:191], v[16:19]
	v_mfma_f32_16x16x32_bf16 v[12:15], v[40:43], v[188:191], v[12:15]
	s_setprio 0
	s_barrier
; #define PG8_STAGE(bufoff, gbase, voff) do { _Pragma("unroll") for (int _i = 0; _i < 2; ++_i) \
;         __builtin_amdgcn_global_load_lds((const unsigned*)((const char*)(gbase) + (voff)[_i]), (LAS unsigned*)(lds + (bufoff) + ldsw + _i * 8192), 16, 0, 0); } while (0)
; #define PG8_LDA(dst, b, h) do { _Pragma("unroll") for (int m = 0; m < 4; ++m) _Pragma("unroll") for (int k = 0; k < 2; ++k) dst[m][k] = *(const LAS bf16x8*)(lds + PG8_SA(b, h) + aoff + m * 2048 + k * 1024); } while (0)
; #define PG8_LDB(dst, b, h) do { _Pragma("unroll") for (int n = 0; n < 2; ++n) _Pragma("unroll") for (int k = 0; k < 2; ++k) dst[n][k] = *(const LAS bf16x8*)(lds + PG8_SB(b, h) + boff + n * 2048 + k * 1024); } while (0)
; #define PG8_MMA(ai, bj, At, Bt) do { __builtin_amdgcn_s_setprio(1); _Pragma("unroll") for (int m = 0; m < 4; ++m) _Pragma("unroll") for (int n = 0; n < 2; ++n) _Pragma("unroll") for (int k = 0; k < 2; ++k) \
;         acc[ai][bj][m][n] = __builtin_amdgcn_mfma_f32_16x16x32_bf16(Bt[n][k], At[m][k], acc[ai][bj][m][n], 0, 0, 0); __builtin_amdgcn_s_setprio(0); } while (0)
; #define PG8_WAIT_V(n) asm volatile("s_waitcnt vmcnt(" #n ")" ::: "memory")
; #define PG8_WAIT_L(n) asm volatile("s_waitcnt lgkmcnt(" #n ")" ::: "memory")
; #define PG8_BAR __builtin_amdgcn_s_barrier()
; #define PG8_SCHED __builtin_amdgcn_sched_barrier(0)
; template <class Epi, class Sched>
; DI void gemm_phase(LAS unsigned char* lds, const Gemm g, const Sched& S, const Epi& E) {
;     ...
;             PG8_STAGE(PG8_SB(0, 1), b2 + hstepB, voffB);
;             PG8_WAIT_V(6); PG8_BAR; PG8_MMA(1, 1, At, B1); PG8_BAR;
;             PG8_LDB(B0, 1, 0); PG8_SCHED; PG8_LDA(At, 1, 0); PG8_STAGE(PG8_SA(0, 1), a2 + hstepA, voffA);
;             PG8_WAIT_L(8); PG8_BAR; PG8_WAIT_L(0); PG8_MMA(0, 0, At, B0); PG8_BAR; PG8_SCHED;
;             PG8_LDB(B1, 1, 1); PG8_STAGE(PG8_SB(1, 0), b3, voffB);
;             PG8_BAR; PG8_WAIT_L(0); PG8_MMA(0, 1, At, B1); PG8_BAR;
;             PG8_LDA(At, 1, 1); PG8_STAGE(PG8_SA(1, 0), a3, voffA);
;             PG8_BAR; PG8_WAIT_L(0); PG8_MMA(1, 0, At, B0); PG8_BAR; PG8_SCHED;
	s_add_u32 s84, s2, 0x40000
	s_addc_u32 s85, s3, 0
	s_add_i32 s83, s92, s42
	v_lshl_add_u64 v[20:21], s[84:85], 0, v[2:3]
	s_mov_b32 m0, s83
	s_nop 0
	global_load_lds_dwordx4 v[20:21], off
	v_lshl_add_u64 v[20:21], s[84:85], 0, v[0:1]
	s_add_i32 m0, s83, 0x2000
	s_nop 0
	global_load_lds_dwordx4 v[20:21], off
	s_waitcnt vmcnt(6)
	s_barrier
	s_setprio 1
	v_mfma_f32_16x16x32_bf16 v[32:35], v[202:205], v[172:175], v[32:35]
	v_mfma_f32_16x16x32_bf16 v[28:31], v[210:213], v[172:175], v[28:31]
	v_mfma_f32_16x16x32_bf16 v[8:11], v[202:205], v[184:187], v[8:11]
	v_mfma_f32_16x16x32_bf16 v[4:7], v[210:213], v[184:187], v[4:7]
	v_mfma_f32_16x16x32_bf16 v[20:23], v[202:205], v[136:139], v[72:75]
	v_mfma_f32_16x16x32_bf16 v[24:27], v[210:213], v[136:139], v[68:71]
	v_mfma_f32_16x16x32_bf16 v[36:39], v[202:205], v[152:155], v[56:59]
	v_mfma_f32_16x16x32_bf16 v[40:43], v[210:213], v[152:155], v[52:55]
	v_mfma_f32_16x16x32_bf16 v[32:35], v[206:209], v[176:179], v[32:35]
	v_mfma_f32_16x16x32_bf16 v[28:31], v[214:217], v[176:179], v[28:31]
	v_mfma_f32_16x16x32_bf16 v[8:11], v[206:209], v[188:191], v[8:11]
	v_mfma_f32_16x16x32_bf16 v[4:7], v[214:217], v[188:191], v[4:7]
	v_mfma_f32_16x16x32_bf16 v[20:23], v[206:209], v[144:147], v[20:23]
	v_mfma_f32_16x16x32_bf16 v[24:27], v[214:217], v[144:147], v[24:27]
	v_mfma_f32_16x16x32_bf16 v[36:39], v[206:209], v[160:163], v[36:39]
	v_mfma_f32_16x16x32_bf16 v[40:43], v[214:217], v[160:163], v[40:43]
	s_setprio 0
	s_add_i32 s83, 0, 0x18000
	v_add_u32_e32 v72, s83, v181
	s_barrier
	ds_read_b128 v[52:55], v72
	ds_read_b128 v[56:59], v72 offset:1024
	ds_read_b128 v[68:71], v72 offset:2048
	ds_read_b128 v[72:75], v72 offset:3072
	s_add_u32 s38, s38, 0x40000
	s_addc_u32 s39, s39, 0
	s_mov_b32 m0, s48
	v_lshl_add_u64 v[202:203], s[38:39], 0, v[166:167]
	ds_read_b128 v[136:139], v183 offset:32768
	ds_read_b128 v[144:147], v183 offset:33792
	ds_read_b128 v[152:155], v183 offset:34816
	ds_read_b128 v[160:163], v183 offset:35840
	ds_read_b128 v[172:175], v183 offset:36864
	ds_read_b128 v[176:179], v183 offset:37888
	ds_read_b128 v[184:187], v183 offset:38912
	ds_read_b128 v[188:191], v183 offset:39936
	global_load_lds_dwordx4 v[202:203], off
	v_lshl_add_u64 v[202:203], s[38:39], 0, v[164:165]
	s_mov_b32 m0, s49
	s_nop 0
	global_load_lds_dwordx4 v[202:203], off
	s_waitcnt lgkmcnt(8)
	s_barrier
	s_waitcnt lgkmcnt(0)
	s_setprio 1
	s_waitcnt lgkmcnt(0)
	v_mfma_f32_16x16x32_bf16 v[156:159], v[52:55], v[136:139], v[156:159]
	v_mfma_f32_16x16x32_bf16 v[148:151], v[68:71], v[136:139], v[148:151]
	v_mfma_f32_16x16x32_bf16 v[128:131], v[52:55], v[152:155], v[128:131]
	v_mfma_f32_16x16x32_bf16 v[124:127], v[68:71], v[152:155], v[124:127]
	v_mfma_f32_16x16x32_bf16 v[112:115], v[52:55], v[172:175], v[112:115]
	v_mfma_f32_16x16x32_bf16 v[108:111], v[68:71], v[172:175], v[108:111]
	v_mfma_f32_16x16x32_bf16 v[96:99], v[52:55], v[184:187], v[96:99]
	v_mfma_f32_16x16x32_bf16 v[92:95], v[68:71], v[184:187], v[92:95]
	v_mfma_f32_16x16x32_bf16 v[156:159], v[56:59], v[144:147], v[156:159]
	v_mfma_f32_16x16x32_bf16 v[148:151], v[72:75], v[144:147], v[148:151]
	v_mfma_f32_16x16x32_bf16 v[128:131], v[56:59], v[160:163], v[128:131]
	v_mfma_f32_16x16x32_bf16 v[124:127], v[72:75], v[160:163], v[124:127]
	v_mfma_f32_16x16x32_bf16 v[112:115], v[56:59], v[176:179], v[112:115]
	v_mfma_f32_16x16x32_bf16 v[108:111], v[72:75], v[176:179], v[108:111]
	v_mfma_f32_16x16x32_bf16 v[96:99], v[56:59], v[188:191], v[96:99]
	v_mfma_f32_16x16x32_bf16 v[92:95], v[72:75], v[188:191], v[92:95]
	s_setprio 0
	s_barrier
	s_add_i32 s38, 0, 0x1c000
	s_add_i32 s39, s83, s42
	v_add_u32_e32 v214, s38, v181
	v_lshl_add_u64 v[230:231], v[230:231], 0, s[78:79]
	s_mov_b32 m0, s39
	ds_read_b128 v[202:205], v214
	ds_read_b128 v[206:209], v214 offset:1024
	ds_read_b128 v[210:213], v214 offset:2048
	ds_read_b128 v[214:217], v214 offset:3072
	global_load_lds_dwordx4 v[230:231], off
	v_lshl_add_u64 v[230:231], v[232:233], 0, s[78:79]
	s_add_i32 m0, s39, 0x2000
	s_nop 0
	global_load_lds_dwordx4 v[230:231], off
	s_barrier
	s_waitcnt lgkmcnt(0)
	s_setprio 1
	s_waitcnt lgkmcnt(0)
	v_mfma_f32_16x16x32_bf16 v[140:143], v[202:205], v[136:139], v[140:143]
	v_mfma_f32_16x16x32_bf16 v[132:135], v[210:213], v[136:139], v[132:135]
	v_mfma_f32_16x16x32_bf16 v[120:123], v[202:205], v[152:155], v[120:123]
	v_mfma_f32_16x16x32_bf16 v[116:119], v[210:213], v[152:155], v[116:119]
	v_mfma_f32_16x16x32_bf16 v[104:107], v[202:205], v[172:175], v[104:107]
	v_mfma_f32_16x16x32_bf16 v[100:103], v[210:213], v[172:175], v[100:103]
	v_mfma_f32_16x16x32_bf16 v[88:91], v[202:205], v[184:187], v[88:91]
	v_mfma_f32_16x16x32_bf16 v[84:87], v[210:213], v[184:187], v[84:87]
	v_mfma_f32_16x16x32_bf16 v[140:143], v[206:209], v[144:147], v[140:143]
	v_mfma_f32_16x16x32_bf16 v[136:139], v[214:217], v[144:147], v[132:135]
	v_mfma_f32_16x16x32_bf16 v[120:123], v[206:209], v[160:163], v[120:123]
	v_mfma_f32_16x16x32_bf16 v[116:119], v[214:217], v[160:163], v[116:119]
	v_mfma_f32_16x16x32_bf16 v[104:107], v[206:209], v[176:179], v[104:107]
	v_mfma_f32_16x16x32_bf16 v[100:103], v[214:217], v[176:179], v[100:103]
	v_mfma_f32_16x16x32_bf16 v[88:91], v[206:209], v[188:191], v[88:91]
	v_mfma_f32_16x16x32_bf16 v[84:87], v[214:217], v[188:191], v[84:87]
	s_setprio 0
	s_mov_b32 m0, s50
	v_lshl_add_u64 v[230:231], v[234:235], 0, s[78:79]
	s_barrier
	ds_read_b128 v[132:135], v183 offset:49152
	ds_read_b128 v[144:147], v183 offset:50176
	ds_read_b128 v[152:155], v183 offset:51200
	ds_read_b128 v[160:163], v183 offset:52224
	ds_read_b128 v[172:175], v183 offset:53248
	ds_read_b128 v[176:179], v183 offset:54272
	ds_read_b128 v[184:187], v183 offset:55296
	ds_read_b128 v[188:191], v183 offset:56320
	global_load_lds_dwordx4 v[230:231], off
	v_lshl_add_u64 v[230:231], v[236:237], 0, s[78:79]
	s_mov_b32 m0, s51
	s_nop 0
	global_load_lds_dwordx4 v[230:231], off
	s_barrier
; DI void unpack8(u32x4 w, float* f) { f[0] = bflo(w.x); f[1] = bfhi(w.x); f[2] = bflo(w.y); f[3] = bfhi(w.y); f[4] = bflo(w.z); f[5] = bfhi(w.z); f[6] = bflo(w.w); f[7] = bfhi(w.w); }
; DI float sigmoidf_(float x) { return 1.f / (1.f + __expf(-x)); }
; template <class Epi, class Sched>
; DI void gemm_phase(LAS unsigned char* lds, const Gemm g, const Sched& S, const Epi& E) {
;     ...
;             PG8_WAIT_L(8); PG8_BAR; PG8_WAIT_L(0); PG8_MMA(0, 0, At, B0); PG8_BAR; PG8_SCHED;
;             PG8_LDB(B1, 1, 1); PG8_STAGE(PG8_SB(1, 0), b3, voffB);
;             PG8_BAR; PG8_WAIT_L(0); PG8_MMA(0, 1, At, B1); PG8_BAR;
;             PG8_LDA(At, 1, 1); PG8_STAGE(PG8_SA(1, 0), a3, voffA);
;             PG8_BAR; PG8_WAIT_L(0); PG8_MMA(1, 0, At, B0); PG8_BAR; PG8_SCHED;
;             PG8_STAGE(PG8_SB(1, 1), b3 + hstepB, voffB);
;             PG8_WAIT_V(6); PG8_BAR; PG8_MMA(1, 1, At, B1); PG8_BAR;
;     DI void operator()(const Acc& acc, const Unit& u, int wr, int wc, int fr, int fq) const {
;         f32x4 bv[2][2];
; #pragma unroll
;         for (int bj = 0; bj < 2; ++bj) { const int col = u.pn * 256 + bj * 128 + wc * 32 + 8 * fq; bv[bj][0] = *(const f32x4*)(bias + col); bv[bj][1] = *(const f32x4*)(bias + col + 4); }
; #pragma unroll
;         for (int ai = 0; ai < 2; ++ai)
; #pragma unroll
;             for (int mp = 0; mp < 2; ++mp) {
;                 u32x4 zv[2][2];
; #pragma unroll
;                 for (int mi = 0; mi < 2; ++mi)
; #pragma unroll
;                     for (int bj = 0; bj < 2; ++bj) { const int row = u.pm * 256 + ai * 128 + wr * 64 + (2 * mp + mi) * 16 + fr, col = u.pn * 256 + bj * 128 + wc * 32 + 8 * fq;
;                         zv[mi][bj] = *(const u32x4*)(zs + (size_t)row * 1024 + col); }
; #pragma unroll
;                 for (int mi = 0; mi < 2; ++mi)
; #pragma unroll
;                     for (int bj = 0; bj < 2; ++bj) { const int m = 2 * mp + mi, row = u.pm * 256 + ai * 128 + wr * 64 + m * 16 + fr, col = u.pn * 256 + bj * 128 + wc * 32 + 8 * fq;
;                         f32x4 v0 = acc[ai][bj][m][0], v1 = acc[ai][bj][m][1]; float zf[8]; unpack8(zv[mi][bj], zf);
;                         for (int j = 0; j < 4; ++j) { v0[j] = zf[j] * sigmoidf_(v0[j] + bv[bj][0][j]); v1[j] = zf[4 + j] * sigmoidf_(v1[j] + bv[bj][1][j]); }
;                         *(u32x4*)(y2 + (size_t)row * 1024 + col) = pack44(v0, v1); }
	s_waitcnt lgkmcnt(0)
	s_setprio 1
	s_waitcnt lgkmcnt(0)
	v_mfma_f32_16x16x32_bf16 v[80:83], v[52:55], v[132:135], v[80:83]
	v_mfma_f32_16x16x32_bf16 v[76:79], v[68:71], v[132:135], v[76:79]
	v_mfma_f32_16x16x32_bf16 v[64:67], v[52:55], v[152:155], v[64:67]
	v_mfma_f32_16x16x32_bf16 v[60:63], v[68:71], v[152:155], v[60:63]
	v_mfma_f32_16x16x32_bf16 v[48:51], v[52:55], v[172:175], v[48:51]
	v_mfma_f32_16x16x32_bf16 v[44:47], v[68:71], v[172:175], v[44:47]
	v_mfma_f32_16x16x32_bf16 v[16:19], v[52:55], v[184:187], v[16:19]
	v_mfma_f32_16x16x32_bf16 v[12:15], v[68:71], v[184:187], v[12:15]
	v_mfma_f32_16x16x32_bf16 v[80:83], v[56:59], v[144:147], v[80:83]
	v_mfma_f32_16x16x32_bf16 v[76:79], v[72:75], v[144:147], v[76:79]
	v_mfma_f32_16x16x32_bf16 v[64:67], v[56:59], v[160:163], v[64:67]
	v_mfma_f32_16x16x32_bf16 v[60:63], v[72:75], v[160:163], v[60:63]
	v_mfma_f32_16x16x32_bf16 v[48:51], v[56:59], v[176:179], v[48:51]
	v_mfma_f32_16x16x32_bf16 v[44:47], v[72:75], v[176:179], v[44:47]
	v_mfma_f32_16x16x32_bf16 v[16:19], v[56:59], v[188:191], v[16:19]
	v_mfma_f32_16x16x32_bf16 v[12:15], v[72:75], v[188:191], v[12:15]
	s_setprio 0
	s_barrier
	s_add_u32 s2, s2, 0x40080
	s_addc_u32 s3, s3, 0
	s_add_i32 s38, s38, s42
	v_lshl_add_u64 v[52:53], s[2:3], 0, v[2:3]
	s_mov_b32 m0, s38
	s_nop 0
	global_load_lds_dwordx4 v[52:53], off
	v_lshl_add_u64 v[52:53], s[2:3], 0, v[0:1]
	s_add_i32 m0, s38, 0x2000
	s_nop 0
	global_load_lds_dwordx4 v[52:53], off
	s_waitcnt vmcnt(6)
	s_barrier
	s_setprio 1
	v_mfma_f32_16x16x32_bf16 v[20:23], v[202:205], v[132:135], v[20:23]
	v_mfma_f32_16x16x32_bf16 v[72:75], v[206:209], v[144:147], v[20:23]
	v_mfma_f32_16x16x32_bf16 v[20:23], v[210:213], v[132:135], v[24:27]
	v_mfma_f32_16x16x32_bf16 v[68:71], v[214:217], v[144:147], v[20:23]
	v_mfma_f32_16x16x32_bf16 v[20:23], v[202:205], v[152:155], v[36:39]
	v_mfma_f32_16x16x32_bf16 v[56:59], v[206:209], v[160:163], v[20:23]
	v_mfma_f32_16x16x32_bf16 v[20:23], v[210:213], v[152:155], v[40:43]
	v_mfma_f32_16x16x32_bf16 v[52:55], v[214:217], v[160:163], v[20:23]
	v_mfma_f32_16x16x32_bf16 v[20:23], v[202:205], v[172:175], v[32:35]
	v_mfma_f32_16x16x32_bf16 v[32:35], v[206:209], v[176:179], v[20:23]
	v_mfma_f32_16x16x32_bf16 v[20:23], v[210:213], v[172:175], v[28:31]
	v_mfma_f32_16x16x32_bf16 v[8:11], v[202:205], v[184:187], v[8:11]
	v_mfma_f32_16x16x32_bf16 v[4:7], v[210:213], v[184:187], v[4:7]
	v_mfma_f32_16x16x32_bf16 v[28:31], v[214:217], v[176:179], v[20:23]
	v_mfma_f32_16x16x32_bf16 v[8:11], v[206:209], v[188:191], v[8:11]
	v_mfma_f32_16x16x32_bf16 v[4:7], v[214:217], v[188:191], v[4:7]
	s_setprio 0
	s_add_i32 s82, s82, 2
	s_add_u32 s20, s20, 0x100
	s_addc_u32 s21, s21, 0
	s_add_u32 s64, s64, 0x100
	s_addc_u32 s65, s65, 0
	s_cmp_gt_u32 s82, 13
	s_barrier
	s_cbranch_scc0 .LBB0_137
	v_lshl_or_b32 v132, s54, 8, v182
	v_ashrrev_i32_e32 v133, 31, v132
	v_lshl_add_u64 v[24:25], v[132:133], 2, s[26:27]
	global_load_dwordx4 v[36:39], v[24:25], off offset:16
	global_load_dwordx4 v[40:43], v[24:25], off
	global_load_dwordx4 v[20:23], v[24:25], off offset:528
	s_nop 0
	global_load_dwordx4 v[24:27], v[24:25], off offset:512
	v_lshl_add_u32 v174, s53, 8, v180
	v_ashrrev_i32_e32 v175, 31, v174
	v_lshlrev_b64 v[178:179], 11, v[174:175]
	v_lshl_add_u64 v[134:135], s[4:5], 0, v[178:179]
	v_lshlrev_b64 v[172:173], 1, v[132:133]
	v_lshl_add_u64 v[132:133], v[134:135], 0, v[172:173]
	global_load_dwordx4 v[160:163], v[132:133], off
	global_load_dwordx4 v[152:155], v[132:133], off offset:256
	v_or_b32_e32 v132, 16, v174
	v_ashrrev_i32_e32 v133, 31, v132
	v_lshlrev_b64 v[176:177], 11, v[132:133]
	v_lshl_add_u64 v[132:133], s[4:5], 0, v[176:177]
	v_lshl_add_u64 v[132:133], v[132:133], 0, v[172:173]
	global_load_dwordx4 v[144:147], v[132:133], off
	s_nop 0
	global_load_dwordx4 v[132:135], v[132:133], off offset:256
	s_mov_b32 s54, s28
	s_mov_b32 s53, s30
	s_mov_b64 s[20:21], s[34:35]
	v_readlane_b32 s85, v254, 37
	s_waitcnt vmcnt(0)
	v_add_f32_e32 v148, v148, v36
	v_add_f32_e32 v156, v156, v40
	v_add_f32_e32 v157, v157, v41
	v_mul_f32_e32 v156, 0xbfb8aa3b, v156
	v_mul_f32_e32 v157, 0xbfb8aa3b, v157
	v_exp_f32_e32 v156, v156
	v_exp_f32_e32 v157, v157
	v_add_f32_e32 v149, v149, v37
	v_mul_f32_e32 v148, 0xbfb8aa3b, v148
	v_lshlrev_b32_e32 v184, 16, v160
	v_pk_add_f32 v[156:157], v[156:157], 1.0 op_sel_hi:[1,0]
	v_and_b32_e32 v185, 0xffff0000, v160
	v_rcp_f32_e32 v175, v157
	s_nop 0
	v_mul_f32_e32 v149, 0xbfb8aa3b, v149
	v_exp_f32_e32 v148, v148
	v_exp_f32_e32 v149, v149
	v_mul_f32_e32 v187, 1.0, v175
	v_fma_f32 v188, -v157, v187, 1.0
	v_fmac_f32_e32 v187, v188, v175
	v_div_fixup_f32 v157, v187, v157, 1.0
	v_rcp_f32_e32 v175, v156
	s_nop 0
	v_pk_add_f32 v[148:149], v[148:149], 1.0 op_sel_hi:[1,0]
	v_add_f32_e32 v158, v158, v42
	v_mul_f32_e32 v158, 0xbfb8aa3b, v158
	v_mul_f32_e32 v187, 1.0, v175
	v_fma_f32 v188, -v156, v187, 1.0
	v_fmac_f32_e32 v187, v188, v175
	v_div_fixup_f32 v156, v187, v156, 1.0
	v_div_scale_f32 v160, s[2:3], v149, v149, 1.0
	v_pk_mul_f32 v[156:157], v[156:157], v[184:185]
	v_lshlrev_b32_e32 v184, 16, v162
	v_and_b32_e32 v185, 0xffff0000, v162
	v_rcp_f32_e32 v162, v160
	v_add_f32_e32 v150, v150, v38
	v_add_f32_e32 v151, v151, v39
	v_mul_f32_e32 v150, 0xbfb8aa3b, v150
	v_fma_f32 v175, -v160, v162, 1.0
	v_fmac_f32_e32 v162, v175, v162
	v_div_scale_f32 v175, vcc, 1.0, v149, 1.0
	v_mul_f32_e32 v186, v175, v162
	v_fma_f32 v187, -v160, v186, v175
	v_fmac_f32_e32 v186, v187, v162
	v_fma_f32 v160, -v160, v186, v175
	v_div_fmas_f32 v160, v160, v162, v186
	v_div_fixup_f32 v149, v160, v149, 1.0
	v_rcp_f32_e32 v162, v148
	s_nop 0
	v_mul_f32_e32 v151, 0xbfb8aa3b, v151
	v_exp_f32_e32 v150, v150
; DI void unpack8(u32x4 w, float* f) { f[0] = bflo(w.x); f[1] = bfhi(w.x); f[2] = bflo(w.y); f[3] = bfhi(w.y); f[4] = bflo(w.z); f[5] = bfhi(w.z); f[6] = bflo(w.w); f[7] = bfhi(w.w); }
; DI u32x4 pack44(f32x4 a, f32x4 b) { u32x4 w; w.x = pk2(a[0], a[1]); w.y = pk2(a[2], a[3]); w.z = pk2(b[0], b[1]); w.w = pk2(b[2], b[3]); return w; }
; DI float sigmoidf_(float x) { return 1.f / (1.f + __expf(-x)); }
;     DI void operator()(const Acc& acc, const Unit& u, int wr, int wc, int fr, int fq) const {
;     ...
;                 for (int mi = 0; mi < 2; ++mi)
; #pragma unroll
;                     for (int bj = 0; bj < 2; ++bj) { const int row = u.pm * 256 + ai * 128 + wr * 64 + (2 * mp + mi) * 16 + fr, col = u.pn * 256 + bj * 128 + wc * 32 + 8 * fq;
;                         zv[mi][bj] = *(const u32x4*)(zs + (size_t)row * 1024 + col); }
; #pragma unroll
;                 for (int mi = 0; mi < 2; ++mi)
; #pragma unroll
;                     for (int bj = 0; bj < 2; ++bj) { const int m = 2 * mp + mi, row = u.pm * 256 + ai * 128 + wr * 64 + m * 16 + fr, col = u.pn * 256 + bj * 128 + wc * 32 + 8 * fq;
;                         f32x4 v0 = acc[ai][bj][m][0], v1 = acc[ai][bj][m][1]; float zf[8]; unpack8(zv[mi][bj], zf);
;                         for (int j = 0; j < 4; ++j) { v0[j] = zf[j] * sigmoidf_(v0[j] + bv[bj][0][j]); v1[j] = zf[4 + j] * sigmoidf_(v1[j] + bv[bj][1][j]); }
;                         *(u32x4*)(y2 + (size_t)row * 1024 + col) = pack44(v0, v1); }
	v_exp_f32_e32 v151, v151
	v_mul_f32_e32 v186, 1.0, v162
	v_fma_f32 v187, -v148, v186, 1.0
	v_fmac_f32_e32 v186, v187, v162
	v_div_fixup_f32 v148, v186, v148, 1.0
	v_pk_mul_f32 v[148:149], v[148:149], v[184:185]
	v_exp_f32_e32 v184, v158
	v_add_f32_e32 v158, v159, v43
	v_mul_f32_e32 v158, 0xbfb8aa3b, v158
	v_exp_f32_e32 v185, v158
	v_lshlrev_b32_e32 v158, 16, v161
	v_and_b32_e32 v159, 0xffff0000, v161
	v_pk_add_f32 v[150:151], v[150:151], 1.0 op_sel_hi:[1,0]
	v_pk_add_f32 v[160:161], v[184:185], 1.0 op_sel_hi:[1,0]
	v_add_f32_e32 v140, v140, v24
	v_rcp_f32_e32 v175, v161
	s_nop 0
	v_add_f32_e32 v141, v141, v25
	v_mul_f32_e32 v140, 0xbfb8aa3b, v140
	v_mul_f32_e32 v141, 0xbfb8aa3b, v141
	v_mul_f32_e32 v185, 1.0, v175
	v_fma_f32 v186, -v161, v185, 1.0
	v_fmac_f32_e32 v185, v186, v175
	v_div_fixup_f32 v161, v185, v161, 1.0
	v_rcp_f32_e32 v175, v160
	s_nop 0
	v_exp_f32_e32 v140, v140
	v_exp_f32_e32 v141, v141
	v_cvt_pk_bf16_f32 v156, v156, v157
	v_mul_f32_e32 v185, 1.0, v175
	v_fma_f32 v186, -v160, v185, 1.0
	v_fmac_f32_e32 v185, v186, v175
	v_div_fixup_f32 v160, v185, v160, 1.0
	v_div_scale_f32 v162, s[2:3], v151, v151, 1.0
	v_pk_mul_f32 v[158:159], v[160:161], v[158:159]
	v_lshlrev_b32_e32 v160, 16, v163
	v_and_b32_e32 v161, 0xffff0000, v163
	v_rcp_f32_e32 v163, v162
	v_cvt_pk_bf16_f32 v157, v158, v159
	v_cvt_pk_bf16_f32 v158, v148, v149
	v_lshl_add_u64 v[148:149], s[68:69], 0, v[178:179]
	v_fma_f32 v175, -v162, v163, 1.0
	v_fmac_f32_e32 v163, v175, v163
	v_div_scale_f32 v175, vcc, 1.0, v151, 1.0
	v_mul_f32_e32 v184, v175, v163
	v_fma_f32 v185, -v162, v184, v175
	v_fmac_f32_e32 v184, v185, v163
	v_fma_f32 v162, -v162, v184, v175
	v_div_fmas_f32 v162, v162, v163, v184
	v_div_fixup_f32 v151, v162, v151, 1.0
	v_rcp_f32_e32 v163, v150
	s_nop 0
	v_pk_add_f32 v[140:141], v[140:141], 1.0 op_sel_hi:[1,0]
	v_lshl_add_u64 v[148:149], v[148:149], 0, v[172:173]
	v_add_f32_e32 v136, v136, v20
	v_mul_f32_e32 v184, 1.0, v163
	v_fma_f32 v185, -v150, v184, 1.0
	v_fmac_f32_e32 v184, v185, v163
	v_div_fixup_f32 v150, v184, v150, 1.0
	v_pk_mul_f32 v[150:151], v[150:151], v[160:161]
	v_add_f32_e32 v137, v137, v21
	v_cvt_pk_bf16_f32 v159, v150, v151
	v_lshlrev_b32_e32 v150, 16, v152
	v_and_b32_e32 v151, 0xffff0000, v152
	v_div_scale_f32 v152, s[2:3], v141, v141, 1.0
	global_store_dwordx4 v[148:149], v[156:159], off
	v_mul_f32_e32 v136, 0xbfb8aa3b, v136
	v_mul_f32_e32 v137, 0xbfb8aa3b, v137
	v_rcp_f32_e32 v156, v152
	v_exp_f32_e32 v136, v136
	v_exp_f32_e32 v137, v137
	v_add_f32_e32 v128, v128, v40
	v_fma_f32 v157, -v152, v156, 1.0
	v_fmac_f32_e32 v156, v157, v156
	v_div_scale_f32 v157, vcc, 1.0, v141, 1.0
	v_mul_f32_e32 v158, v157, v156
	v_fma_f32 v159, -v152, v158, v157
	v_fmac_f32_e32 v158, v159, v156
	v_fma_f32 v152, -v152, v158, v157
	v_div_fmas_f32 v152, v152, v156, v158
	v_div_fixup_f32 v141, v152, v141, 1.0
	v_rcp_f32_e32 v156, v140
	s_nop 0
	v_pk_add_f32 v[136:137], v[136:137], 1.0 op_sel_hi:[1,0]
	v_add_f32_e32 v129, v129, v41
	v_mul_f32_e32 v128, 0xbfb8aa3b, v128
	v_mul_f32_e32 v158, 1.0, v156
	v_fma_f32 v159, -v140, v158, 1.0
	v_fmac_f32_e32 v158, v159, v156
	v_div_fixup_f32 v140, v158, v140, 1.0
	v_div_scale_f32 v152, s[2:3], v137, v137, 1.0
	v_pk_mul_f32 v[140:141], v[140:141], v[150:151]
	v_lshlrev_b32_e32 v150, 16, v154
	v_and_b32_e32 v151, 0xffff0000, v154
	v_rcp_f32_e32 v154, v152
	v_mul_f32_e32 v129, 0xbfb8aa3b, v129
	v_exp_f32_e32 v128, v128
	v_exp_f32_e32 v129, v129
	v_fma_f32 v156, -v152, v154, 1.0
	v_fmac_f32_e32 v154, v156, v154
	v_div_scale_f32 v156, vcc, 1.0, v137, 1.0
	v_mul_f32_e32 v157, v156, v154
	v_fma_f32 v158, -v152, v157, v156
	v_fmac_f32_e32 v157, v158, v154
	v_fma_f32 v152, -v152, v157, v156
	v_div_fmas_f32 v152, v152, v154, v157
	v_div_fixup_f32 v137, v152, v137, 1.0
	v_rcp_f32_e32 v154, v136
	s_nop 0
	v_pk_add_f32 v[128:129], v[128:129], 1.0 op_sel_hi:[1,0]
	v_add_f32_e32 v124, v124, v36
	v_add_f32_e32 v125, v125, v37
	v_mul_f32_e32 v157, 1.0, v154
	v_fma_f32 v158, -v136, v157, 1.0
	v_fmac_f32_e32 v157, v158, v154
	v_div_fixup_f32 v136, v157, v136, 1.0
	v_pk_mul_f32 v[150:151], v[136:137], v[150:151]
	v_add_f32_e32 v137, v138, v22
	v_mul_f32_e32 v137, 0xbfb8aa3b, v137
	v_add_f32_e32 v136, v142, v26
	v_exp_f32_e32 v138, v137
	v_add_f32_e32 v137, v143, v27
	v_mul_f32_e32 v136, 0xbfb8aa3b, v136
	v_mul_f32_e32 v137, 0xbfb8aa3b, v137
	v_exp_f32_e32 v136, v136
	v_exp_f32_e32 v137, v137
	v_lshlrev_b32_e32 v142, 16, v153
	v_and_b32_e32 v143, 0xffff0000, v153
	v_mul_f32_e32 v124, 0xbfb8aa3b, v124
	v_pk_add_f32 v[136:137], v[136:137], 1.0 op_sel_hi:[1,0]
	v_mul_f32_e32 v125, 0xbfb8aa3b, v125
	v_rcp_f32_e32 v153, v137
	s_nop 0
	v_exp_f32_e32 v124, v124
	v_exp_f32_e32 v125, v125
	v_add_f32_e32 v130, v130, v42
	v_mul_f32_e32 v156, 1.0, v153
	v_fma_f32 v157, -v137, v156, 1.0
	v_fmac_f32_e32 v156, v157, v153
	v_div_fixup_f32 v137, v156, v137, 1.0
	v_rcp_f32_e32 v153, v136
	s_nop 0
	v_pk_add_f32 v[124:125], v[124:125], 1.0 op_sel_hi:[1,0]
	v_add_f32_e32 v131, v131, v43
	v_mul_f32_e32 v130, 0xbfb8aa3b, v130
	v_mul_f32_e32 v156, 1.0, v153
	v_fma_f32 v157, -v136, v156, 1.0
	v_fmac_f32_e32 v156, v157, v153
	v_div_fixup_f32 v136, v156, v136, 1.0
	v_pk_mul_f32 v[142:143], v[136:137], v[142:143]
	v_add_f32_e32 v136, v139, v23
	v_mul_f32_e32 v136, 0xbfb8aa3b, v136
	v_exp_f32_e32 v139, v136
	v_lshlrev_b32_e32 v136, 16, v155
	v_and_b32_e32 v137, 0xffff0000, v155
	v_mul_f32_e32 v131, 0xbfb8aa3b, v131
	v_pk_add_f32 v[138:139], v[138:139], 1.0 op_sel_hi:[1,0]
	v_exp_f32_e32 v130, v130
	v_rcp_f32_e32 v153, v139
	s_nop 0
	v_exp_f32_e32 v131, v131
	v_add_f32_e32 v126, v126, v38
	v_add_f32_e32 v127, v127, v39
	v_mul_f32_e32 v155, 1.0, v153
; DI void unpack8(u32x4 w, float* f) { f[0] = bflo(w.x); f[1] = bfhi(w.x); f[2] = bflo(w.y); f[3] = bfhi(w.y); f[4] = bflo(w.z); f[5] = bfhi(w.z); f[6] = bflo(w.w); f[7] = bfhi(w.w); }
; DI u32x4 pack44(f32x4 a, f32x4 b) { u32x4 w; w.x = pk2(a[0], a[1]); w.y = pk2(a[2], a[3]); w.z = pk2(b[0], b[1]); w.w = pk2(b[2], b[3]); return w; }
; DI float sigmoidf_(float x) { return 1.f / (1.f + __expf(-x)); }
;     DI void operator()(const Acc& acc, const Unit& u, int wr, int wc, int fr, int fq) const {
;     ...
;                 for (int mi = 0; mi < 2; ++mi)
; #pragma unroll
;                     for (int bj = 0; bj < 2; ++bj) { const int row = u.pm * 256 + ai * 128 + wr * 64 + (2 * mp + mi) * 16 + fr, col = u.pn * 256 + bj * 128 + wc * 32 + 8 * fq;
;                         zv[mi][bj] = *(const u32x4*)(zs + (size_t)row * 1024 + col); }
; #pragma unroll
;                 for (int mi = 0; mi < 2; ++mi)
; #pragma unroll
;                     for (int bj = 0; bj < 2; ++bj) { const int m = 2 * mp + mi, row = u.pm * 256 + ai * 128 + wr * 64 + m * 16 + fr, col = u.pn * 256 + bj * 128 + wc * 32 + 8 * fq;
;                         f32x4 v0 = acc[ai][bj][m][0], v1 = acc[ai][bj][m][1]; float zf[8]; unpack8(zv[mi][bj], zf);
;                         for (int j = 0; j < 4; ++j) { v0[j] = zf[j] * sigmoidf_(v0[j] + bv[bj][0][j]); v1[j] = zf[4 + j] * sigmoidf_(v1[j] + bv[bj][1][j]); }
;                         *(u32x4*)(y2 + (size_t)row * 1024 + col) = pack44(v0, v1); }
	v_fma_f32 v156, -v139, v155, 1.0
	v_fmac_f32_e32 v155, v156, v153
	v_div_fixup_f32 v139, v155, v139, 1.0
	v_rcp_f32_e32 v153, v138
	s_nop 0
	v_pk_add_f32 v[130:131], v[130:131], 1.0 op_sel_hi:[1,0]
	v_mul_f32_e32 v126, 0xbfb8aa3b, v126
	v_mul_f32_e32 v127, 0xbfb8aa3b, v127
	v_mul_f32_e32 v155, 1.0, v153
	v_fma_f32 v156, -v138, v155, 1.0
	v_fmac_f32_e32 v155, v156, v153
	v_div_fixup_f32 v138, v155, v138, 1.0
	v_pk_mul_f32 v[152:153], v[138:139], v[136:137]
	v_cvt_pk_bf16_f32 v136, v140, v141
	v_cvt_pk_bf16_f32 v137, v142, v143
	v_cvt_pk_bf16_f32 v138, v150, v151
	v_cvt_pk_bf16_f32 v139, v152, v153
	global_store_dwordx4 v[148:149], v[136:139], off offset:256
	v_exp_f32_e32 v126, v126
	v_exp_f32_e32 v127, v127
	v_rcp_f32_e32 v139, v129
	s_nop 0
	v_pk_add_f32 v[126:127], v[126:127], 1.0 op_sel_hi:[1,0]
	v_add_f32_e32 v120, v120, v24
	v_add_f32_e32 v121, v121, v25
	v_mul_f32_e32 v141, 1.0, v139
	v_fma_f32 v142, -v129, v141, 1.0
	v_fmac_f32_e32 v141, v142, v139
	v_div_fixup_f32 v129, v141, v129, 1.0
	v_rcp_f32_e32 v139, v128
	s_nop 0
	v_lshlrev_b32_e32 v136, 16, v144
	v_and_b32_e32 v137, 0xffff0000, v144
	v_mul_f32_e32 v120, 0xbfb8aa3b, v120
	v_mul_f32_e32 v141, 1.0, v139
	v_fma_f32 v142, -v128, v141, 1.0
	v_fmac_f32_e32 v141, v142, v139
	v_div_fixup_f32 v128, v141, v128, 1.0
	v_rcp_f32_e32 v139, v125
	s_nop 0
	v_mul_f32_e32 v121, 0xbfb8aa3b, v121
	v_pk_mul_f32 v[128:129], v[128:129], v[136:137]
	v_lshlrev_b32_e32 v136, 16, v146
	v_mul_f32_e32 v141, 1.0, v139
	v_fma_f32 v142, -v125, v141, 1.0
	v_fmac_f32_e32 v141, v142, v139
	v_div_fixup_f32 v125, v141, v125, 1.0
	v_rcp_f32_e32 v139, v124
	s_nop 0
	v_and_b32_e32 v137, 0xffff0000, v146
	v_exp_f32_e32 v120, v120
	v_exp_f32_e32 v121, v121
	v_mul_f32_e32 v141, 1.0, v139
	v_fma_f32 v142, -v124, v141, 1.0
	v_fmac_f32_e32 v141, v142, v139
	v_div_fixup_f32 v124, v141, v124, 1.0
	v_rcp_f32_e32 v139, v131
	s_nop 0
	v_pk_mul_f32 v[124:125], v[124:125], v[136:137]
	v_lshlrev_b32_e32 v136, 16, v145
	v_and_b32_e32 v137, 0xffff0000, v145
	v_mul_f32_e32 v141, 1.0, v139
	v_fma_f32 v142, -v131, v141, 1.0
	v_fmac_f32_e32 v141, v142, v139
	v_div_fixup_f32 v131, v141, v131, 1.0
	v_rcp_f32_e32 v139, v130
	s_nop 0
	v_pk_add_f32 v[120:121], v[120:121], 1.0 op_sel_hi:[1,0]
	v_add_f32_e32 v116, v116, v20
	v_add_f32_e32 v117, v117, v21
	v_mul_f32_e32 v141, 1.0, v139
	v_fma_f32 v142, -v130, v141, 1.0
	v_fmac_f32_e32 v141, v142, v139
	v_div_fixup_f32 v130, v141, v130, 1.0
	v_rcp_f32_e32 v139, v127
	s_nop 0
	v_pk_mul_f32 v[130:131], v[130:131], v[136:137]
	v_lshlrev_b32_e32 v136, 16, v147
	v_and_b32_e32 v137, 0xffff0000, v147
	v_mul_f32_e32 v141, 1.0, v139
	v_fma_f32 v142, -v127, v141, 1.0
	v_fmac_f32_e32 v141, v142, v139
	v_div_fixup_f32 v127, v141, v127, 1.0
	v_rcp_f32_e32 v139, v126
	s_nop 0
	v_mul_f32_e32 v116, 0xbfb8aa3b, v116
	v_mul_f32_e32 v117, 0xbfb8aa3b, v117
	v_exp_f32_e32 v116, v116
	v_mul_f32_e32 v141, 1.0, v139
	v_fma_f32 v142, -v126, v141, 1.0
	v_fmac_f32_e32 v141, v142, v139
	v_div_fixup_f32 v126, v141, v126, 1.0
	v_pk_mul_f32 v[136:137], v[126:127], v[136:137]
	v_cvt_pk_bf16_f32 v126, v128, v129
	v_cvt_pk_bf16_f32 v128, v124, v125
	v_lshl_add_u64 v[124:125], s[68:69], 0, v[176:177]
	v_cvt_pk_bf16_f32 v127, v130, v131
	v_cvt_pk_bf16_f32 v129, v136, v137
	v_lshl_add_u64 v[124:125], v[124:125], 0, v[172:173]
	global_store_dwordx4 v[124:125], v[126:129], off
	v_exp_f32_e32 v117, v117
	v_add_f32_e32 v112, v112, v40
	v_div_scale_f32 v128, s[2:3], v121, v121, 1.0
	v_rcp_f32_e32 v129, v128
	v_lshlrev_b32_e32 v126, 16, v132
	v_and_b32_e32 v127, 0xffff0000, v132
	v_pk_add_f32 v[116:117], v[116:117], 1.0 op_sel_hi:[1,0]
	v_fma_f32 v130, -v128, v129, 1.0
	v_fmac_f32_e32 v129, v130, v129
	v_div_scale_f32 v130, vcc, 1.0, v121, 1.0
	v_mul_f32_e32 v131, v130, v129
	v_fma_f32 v132, -v128, v131, v130
	v_fmac_f32_e32 v131, v132, v129
	v_fma_f32 v128, -v128, v131, v130
	v_div_fmas_f32 v128, v128, v129, v131
	v_div_fixup_f32 v121, v128, v121, 1.0
	v_rcp_f32_e32 v129, v120
	s_nop 0
	v_add_f32_e32 v113, v113, v41
	v_mul_f32_e32 v112, 0xbfb8aa3b, v112
	v_mul_f32_e32 v113, 0xbfb8aa3b, v113
	v_mul_f32_e32 v131, 1.0, v129
	v_fma_f32 v132, -v120, v131, 1.0
	v_fmac_f32_e32 v131, v132, v129
	v_div_fixup_f32 v120, v131, v120, 1.0
	v_rcp_f32_e32 v129, v117
	s_nop 0
	v_pk_mul_f32 v[120:121], v[120:121], v[126:127]
	v_lshlrev_b32_e32 v126, 16, v134
	v_and_b32_e32 v127, 0xffff0000, v134
	v_mul_f32_e32 v131, 1.0, v129
	v_fma_f32 v132, -v117, v131, 1.0
	v_fmac_f32_e32 v131, v132, v129
	v_div_fixup_f32 v117, v131, v117, 1.0
	v_rcp_f32_e32 v129, v116
	s_nop 0
	v_exp_f32_e32 v112, v112
	v_exp_f32_e32 v113, v113
	v_add_f32_e32 v108, v108, v36
	v_mul_f32_e32 v131, 1.0, v129
	v_fma_f32 v132, -v116, v131, 1.0
	v_fmac_f32_e32 v131, v132, v129
	v_div_fixup_f32 v116, v131, v116, 1.0
	v_pk_mul_f32 v[126:127], v[116:117], v[126:127]
	v_add_f32_e32 v117, v118, v22
	v_mul_f32_e32 v117, 0xbfb8aa3b, v117
	v_add_f32_e32 v116, v122, v26
	v_exp_f32_e32 v118, v117
	v_add_f32_e32 v117, v123, v27
	v_mul_f32_e32 v116, 0xbfb8aa3b, v116
	v_mul_f32_e32 v117, 0xbfb8aa3b, v117
	v_exp_f32_e32 v116, v116
	v_exp_f32_e32 v117, v117
	v_lshlrev_b32_e32 v122, 16, v133
	v_and_b32_e32 v123, 0xffff0000, v133
	v_pk_add_f32 v[112:113], v[112:113], 1.0 op_sel_hi:[1,0]
	v_pk_add_f32 v[116:117], v[116:117], 1.0 op_sel_hi:[1,0]
	v_add_f32_e32 v109, v109, v37
	v_rcp_f32_e32 v129, v117
	s_nop 0
	v_mul_f32_e32 v108, 0xbfb8aa3b, v108
	v_mul_f32_e32 v109, 0xbfb8aa3b, v109
	v_exp_f32_e32 v108, v108
	v_mul_f32_e32 v131, 1.0, v129
	v_fma_f32 v132, -v117, v131, 1.0
	v_fmac_f32_e32 v131, v132, v129
	v_div_fixup_f32 v117, v131, v117, 1.0
	v_rcp_f32_e32 v129, v116
	s_nop 0
	v_exp_f32_e32 v109, v109
; DI void unpack8(u32x4 w, float* f) { f[0] = bflo(w.x); f[1] = bfhi(w.x); f[2] = bflo(w.y); f[3] = bfhi(w.y); f[4] = bflo(w.z); f[5] = bfhi(w.z); f[6] = bflo(w.w); f[7] = bfhi(w.w); }
; DI u32x4 pack44(f32x4 a, f32x4 b) { u32x4 w; w.x = pk2(a[0], a[1]); w.y = pk2(a[2], a[3]); w.z = pk2(b[0], b[1]); w.w = pk2(b[2], b[3]); return w; }
; DI float sigmoidf_(float x) { return 1.f / (1.f + __expf(-x)); }
;     DI void operator()(const Acc& acc, const Unit& u, int wr, int wc, int fr, int fq) const {
;     ...
;                 for (int mi = 0; mi < 2; ++mi)
; #pragma unroll
;                     for (int bj = 0; bj < 2; ++bj) { const int row = u.pm * 256 + ai * 128 + wr * 64 + (2 * mp + mi) * 16 + fr, col = u.pn * 256 + bj * 128 + wc * 32 + 8 * fq;
;                         zv[mi][bj] = *(const u32x4*)(zs + (size_t)row * 1024 + col); }
; #pragma unroll
;                 for (int mi = 0; mi < 2; ++mi)
; #pragma unroll
;                     for (int bj = 0; bj < 2; ++bj) { const int m = 2 * mp + mi, row = u.pm * 256 + ai * 128 + wr * 64 + m * 16 + fr, col = u.pn * 256 + bj * 128 + wc * 32 + 8 * fq;
;                         f32x4 v0 = acc[ai][bj][m][0], v1 = acc[ai][bj][m][1]; float zf[8]; unpack8(zv[mi][bj], zf);
;                         for (int j = 0; j < 4; ++j) { v0[j] = zf[j] * sigmoidf_(v0[j] + bv[bj][0][j]); v1[j] = zf[4 + j] * sigmoidf_(v1[j] + bv[bj][1][j]); }
;                         *(u32x4*)(y2 + (size_t)row * 1024 + col) = pack44(v0, v1); }
	v_add_f32_e32 v114, v114, v42
	v_add_f32_e32 v115, v115, v43
	v_mul_f32_e32 v131, 1.0, v129
	v_fma_f32 v132, -v116, v131, 1.0
	v_fmac_f32_e32 v131, v132, v129
	v_div_fixup_f32 v116, v131, v116, 1.0
	v_pk_mul_f32 v[122:123], v[116:117], v[122:123]
	v_add_f32_e32 v116, v119, v23
	v_mul_f32_e32 v116, 0xbfb8aa3b, v116
	v_exp_f32_e32 v119, v116
	v_lshlrev_b32_e32 v116, 16, v135
	v_and_b32_e32 v117, 0xffff0000, v135
	v_pk_add_f32 v[108:109], v[108:109], 1.0 op_sel_hi:[1,0]
	v_pk_add_f32 v[118:119], v[118:119], 1.0 op_sel_hi:[1,0]
	v_mul_f32_e32 v114, 0xbfb8aa3b, v114
	v_rcp_f32_e32 v129, v119
	s_nop 0
	v_mul_f32_e32 v115, 0xbfb8aa3b, v115
	v_exp_f32_e32 v114, v114
	v_exp_f32_e32 v115, v115
	v_mul_f32_e32 v131, 1.0, v129
	v_fma_f32 v132, -v119, v131, 1.0
	v_fmac_f32_e32 v131, v132, v129
	v_div_fixup_f32 v119, v131, v119, 1.0
	v_rcp_f32_e32 v129, v118
	s_nop 0
	v_pk_add_f32 v[114:115], v[114:115], 1.0 op_sel_hi:[1,0]
	v_add_f32_e32 v110, v110, v38
	v_add_f32_e32 v111, v111, v39
	v_mul_f32_e32 v131, 1.0, v129
	v_fma_f32 v132, -v118, v131, 1.0
	v_fmac_f32_e32 v131, v132, v129
	v_div_fixup_f32 v118, v131, v118, 1.0
	v_pk_mul_f32 v[128:129], v[118:119], v[116:117]
	v_cvt_pk_bf16_f32 v116, v120, v121
	v_cvt_pk_bf16_f32 v117, v122, v123
	v_cvt_pk_bf16_f32 v118, v126, v127
	v_cvt_pk_bf16_f32 v119, v128, v129
	global_store_dwordx4 v[124:125], v[116:119], off offset:256
	v_mul_f32_e32 v110, 0xbfb8aa3b, v110
	v_mul_f32_e32 v111, 0xbfb8aa3b, v111
	v_or_b32_e32 v116, 32, v174
	v_ashrrev_i32_e32 v117, 31, v116
	v_lshlrev_b64 v[134:135], 11, v[116:117]
	v_lshl_add_u64 v[116:117], s[4:5], 0, v[134:135]
	v_lshl_add_u64 v[116:117], v[116:117], 0, v[172:173]
	global_load_dwordx4 v[128:131], v[116:117], off
	global_load_dwordx4 v[124:127], v[116:117], off offset:256
	v_exp_f32_e32 v110, v110
	v_exp_f32_e32 v111, v111
	v_add_f32_e32 v104, v104, v24
	v_add_f32_e32 v105, v105, v25
	v_mul_f32_e32 v104, 0xbfb8aa3b, v104
	v_pk_add_f32 v[110:111], v[110:111], 1.0 op_sel_hi:[1,0]
	v_mul_f32_e32 v105, 0xbfb8aa3b, v105
	v_or_b32_e32 v116, 48, v174
	v_exp_f32_e32 v104, v104
	v_exp_f32_e32 v105, v105
	v_ashrrev_i32_e32 v117, 31, v116
	v_lshlrev_b64 v[132:133], 11, v[116:117]
	v_lshl_add_u64 v[116:117], s[4:5], 0, v[132:133]
	v_lshl_add_u64 v[116:117], v[116:117], 0, v[172:173]
	v_pk_add_f32 v[104:105], v[104:105], 1.0 op_sel_hi:[1,0]
	global_load_dwordx4 v[120:123], v[116:117], off
	s_nop 0
	global_load_dwordx4 v[116:119], v[116:117], off offset:256
	v_add_f32_e32 v100, v100, v20
	v_add_f32_e32 v101, v101, v21
	v_mul_f32_e32 v100, 0xbfb8aa3b, v100
	v_mul_f32_e32 v101, 0xbfb8aa3b, v101
	v_exp_f32_e32 v100, v100
	v_exp_f32_e32 v101, v101
	v_add_f32_e32 v96, v96, v40
	v_add_f32_e32 v97, v97, v41
	v_mul_f32_e32 v96, 0xbfb8aa3b, v96
	v_pk_add_f32 v[100:101], v[100:101], 1.0 op_sel_hi:[1,0]
	v_mul_f32_e32 v97, 0xbfb8aa3b, v97
	v_exp_f32_e32 v96, v96
	v_exp_f32_e32 v97, v97
	v_add_f32_e32 v92, v92, v36
	v_add_f32_e32 v93, v93, v37
	v_mul_f32_e32 v92, 0xbfb8aa3b, v92
	v_pk_add_f32 v[96:97], v[96:97], 1.0 op_sel_hi:[1,0]
	v_mul_f32_e32 v93, 0xbfb8aa3b, v93
	v_exp_f32_e32 v92, v92
	v_exp_f32_e32 v93, v93
	v_add_f32_e32 v98, v98, v42
	v_add_f32_e32 v99, v99, v43
	v_mul_f32_e32 v98, 0xbfb8aa3b, v98
	v_pk_add_f32 v[92:93], v[92:93], 1.0 op_sel_hi:[1,0]
	v_mul_f32_e32 v99, 0xbfb8aa3b, v99
	v_exp_f32_e32 v98, v98
	v_exp_f32_e32 v99, v99
	v_add_f32_e32 v94, v94, v38
	v_add_f32_e32 v95, v95, v39
	v_mul_f32_e32 v94, 0xbfb8aa3b, v94
	v_pk_add_f32 v[98:99], v[98:99], 1.0 op_sel_hi:[1,0]
	v_mul_f32_e32 v95, 0xbfb8aa3b, v95
	v_exp_f32_e32 v94, v94
	v_exp_f32_e32 v95, v95
	v_add_f32_e32 v88, v88, v24
	v_add_f32_e32 v89, v89, v25
	v_mul_f32_e32 v88, 0xbfb8aa3b, v88
	v_pk_add_f32 v[94:95], v[94:95], 1.0 op_sel_hi:[1,0]
	v_mul_f32_e32 v89, 0xbfb8aa3b, v89
	v_exp_f32_e32 v88, v88
	v_exp_f32_e32 v89, v89
	v_add_f32_e32 v84, v84, v20
	v_add_f32_e32 v85, v85, v21
	v_mul_f32_e32 v84, 0xbfb8aa3b, v84
	v_pk_add_f32 v[88:89], v[88:89], 1.0 op_sel_hi:[1,0]
	v_mul_f32_e32 v85, 0xbfb8aa3b, v85
	v_exp_f32_e32 v84, v84
	v_exp_f32_e32 v85, v85
	v_add_f32_e32 v80, v80, v40
	v_add_f32_e32 v81, v81, v41
	v_mul_f32_e32 v80, 0xbfb8aa3b, v80
	v_pk_add_f32 v[84:85], v[84:85], 1.0 op_sel_hi:[1,0]
	v_mul_f32_e32 v81, 0xbfb8aa3b, v81
	v_exp_f32_e32 v80, v80
	v_exp_f32_e32 v81, v81
	v_add_f32_e32 v76, v76, v36
	v_add_f32_e32 v77, v77, v37
	v_mul_f32_e32 v76, 0xbfb8aa3b, v76
	v_pk_add_f32 v[80:81], v[80:81], 1.0 op_sel_hi:[1,0]
	v_mul_f32_e32 v77, 0xbfb8aa3b, v77
	v_exp_f32_e32 v76, v76
	v_exp_f32_e32 v77, v77
	s_waitcnt vmcnt(0)
; DI void unpack8(u32x4 w, float* f) { f[0] = bflo(w.x); f[1] = bfhi(w.x); f[2] = bflo(w.y); f[3] = bfhi(w.y); f[4] = bflo(w.z); f[5] = bfhi(w.z); f[6] = bflo(w.w); f[7] = bfhi(w.w); }
; DI u32x4 pack44(f32x4 a, f32x4 b) { u32x4 w; w.x = pk2(a[0], a[1]); w.y = pk2(a[2], a[3]); w.z = pk2(b[0], b[1]); w.w = pk2(b[2], b[3]); return w; }
; DI float sigmoidf_(float x) { return 1.f / (1.f + __expf(-x)); }
;     DI void operator()(const Acc& acc, const Unit& u, int wr, int wc, int fr, int fq) const {
;     ...
;                 for (int mi = 0; mi < 2; ++mi)
; #pragma unroll
;                     for (int bj = 0; bj < 2; ++bj) { const int row = u.pm * 256 + ai * 128 + wr * 64 + (2 * mp + mi) * 16 + fr, col = u.pn * 256 + bj * 128 + wc * 32 + 8 * fq;
;                         zv[mi][bj] = *(const u32x4*)(zs + (size_t)row * 1024 + col); }
; #pragma unroll
;                 for (int mi = 0; mi < 2; ++mi)
; #pragma unroll
;                     for (int bj = 0; bj < 2; ++bj) { const int m = 2 * mp + mi, row = u.pm * 256 + ai * 128 + wr * 64 + m * 16 + fr, col = u.pn * 256 + bj * 128 + wc * 32 + 8 * fq;
;                         f32x4 v0 = acc[ai][bj][m][0], v1 = acc[ai][bj][m][1]; float zf[8]; unpack8(zv[mi][bj], zf);
;                         for (int j = 0; j < 4; ++j) { v0[j] = zf[j] * sigmoidf_(v0[j] + bv[bj][0][j]); v1[j] = zf[4 + j] * sigmoidf_(v1[j] + bv[bj][1][j]); }
;                         *(u32x4*)(y2 + (size_t)row * 1024 + col) = pack44(v0, v1); }
	v_lshlrev_b32_e32 v136, 16, v128
	v_and_b32_e32 v137, 0xffff0000, v128
	v_rcp_f32_e32 v138, v113
	s_nop 0
	v_pk_add_f32 v[76:77], v[76:77], 1.0 op_sel_hi:[1,0]
	v_add_f32_e32 v82, v82, v42
	v_add_f32_e32 v83, v83, v43
	v_mul_f32_e32 v140, 1.0, v138
	v_fma_f32 v141, -v113, v140, 1.0
	v_fmac_f32_e32 v140, v141, v138
	v_div_fixup_f32 v113, v140, v113, 1.0
	v_rcp_f32_e32 v138, v112
	s_nop 0
	v_mul_f32_e32 v82, 0xbfb8aa3b, v82
	v_mul_f32_e32 v83, 0xbfb8aa3b, v83
	v_exp_f32_e32 v82, v82
	v_mul_f32_e32 v140, 1.0, v138
	v_fma_f32 v141, -v112, v140, 1.0
	v_fmac_f32_e32 v140, v141, v138
	v_div_fixup_f32 v112, v140, v112, 1.0
	v_div_scale_f32 v128, s[2:3], v109, v109, 1.0
	v_pk_mul_f32 v[112:113], v[112:113], v[136:137]
	v_lshlrev_b32_e32 v136, 16, v130
	v_and_b32_e32 v137, 0xffff0000, v130
	v_rcp_f32_e32 v130, v128
	v_exp_f32_e32 v83, v83
	v_add_f32_e32 v78, v78, v38
	v_add_f32_e32 v79, v79, v39
	v_fma_f32 v138, -v128, v130, 1.0
	v_fmac_f32_e32 v130, v138, v130
	v_div_scale_f32 v138, vcc, 1.0, v109, 1.0
	v_mul_f32_e32 v139, v138, v130
	v_fma_f32 v140, -v128, v139, v138
	v_fmac_f32_e32 v139, v140, v130
	v_fma_f32 v128, -v128, v139, v138
	v_div_fmas_f32 v128, v128, v130, v139
	v_div_fixup_f32 v109, v128, v109, 1.0
	v_rcp_f32_e32 v130, v108
	s_nop 0
	v_pk_add_f32 v[82:83], v[82:83], 1.0 op_sel_hi:[1,0]
	v_mul_f32_e32 v78, 0xbfb8aa3b, v78
	v_mul_f32_e32 v79, 0xbfb8aa3b, v79
	v_mul_f32_e32 v139, 1.0, v130
	v_fma_f32 v140, -v108, v139, 1.0
	v_fmac_f32_e32 v139, v140, v130
	v_div_fixup_f32 v108, v139, v108, 1.0
	v_div_scale_f32 v130, s[2:3], v115, v115, 1.0
	v_pk_mul_f32 v[108:109], v[108:109], v[136:137]
	v_rcp_f32_e32 v136, v130
	v_lshlrev_b32_e32 v128, 16, v129
	v_and_b32_e32 v129, 0xffff0000, v129
	v_exp_f32_e32 v78, v78
	v_fma_f32 v137, -v130, v136, 1.0
	v_fmac_f32_e32 v136, v137, v136
	v_div_scale_f32 v137, vcc, 1.0, v115, 1.0
	v_mul_f32_e32 v138, v137, v136
	v_fma_f32 v139, -v130, v138, v137
	v_fmac_f32_e32 v138, v139, v136
	v_fma_f32 v130, -v130, v138, v137
	v_div_fmas_f32 v130, v130, v136, v138
	v_div_fixup_f32 v115, v130, v115, 1.0
	v_rcp_f32_e32 v136, v114
	s_nop 0
	v_exp_f32_e32 v79, v79
	v_add_f32_e32 v72, v72, v24
	v_add_f32_e32 v73, v73, v25
	v_mul_f32_e32 v138, 1.0, v136
	v_fma_f32 v139, -v114, v138, 1.0
	v_fmac_f32_e32 v138, v139, v136
	v_div_fixup_f32 v114, v138, v114, 1.0
	v_div_scale_f32 v130, s[2:3], v111, v111, 1.0
	v_pk_mul_f32 v[114:115], v[114:115], v[128:129]
	v_lshlrev_b32_e32 v128, 16, v131
	v_and_b32_e32 v129, 0xffff0000, v131
	v_rcp_f32_e32 v131, v130
	v_pk_add_f32 v[78:79], v[78:79], 1.0 op_sel_hi:[1,0]
	v_mul_f32_e32 v72, 0xbfb8aa3b, v72
	v_mul_f32_e32 v73, 0xbfb8aa3b, v73
	v_fma_f32 v136, -v130, v131, 1.0
	v_fmac_f32_e32 v131, v136, v131
	v_div_scale_f32 v136, vcc, 1.0, v111, 1.0
	v_mul_f32_e32 v137, v136, v131
	v_fma_f32 v138, -v130, v137, v136
	v_fmac_f32_e32 v137, v138, v131
	v_fma_f32 v130, -v130, v137, v136
	v_div_fmas_f32 v130, v130, v131, v137
	v_div_fixup_f32 v111, v130, v111, 1.0
	v_rcp_f32_e32 v131, v110
	s_nop 0
	v_exp_f32_e32 v72, v72
	v_exp_f32_e32 v73, v73
	v_add_f32_e32 v68, v68, v20
	v_mul_f32_e32 v137, 1.0, v131
	v_fma_f32 v138, -v110, v137, 1.0
	v_fmac_f32_e32 v137, v138, v131
	v_div_fixup_f32 v110, v137, v110, 1.0
	v_pk_mul_f32 v[128:129], v[110:111], v[128:129]
	v_cvt_pk_bf16_f32 v110, v112, v113
	v_cvt_pk_bf16_f32 v112, v108, v109
	v_lshl_add_u64 v[108:109], s[68:69], 0, v[134:135]
	v_cvt_pk_bf16_f32 v111, v114, v115
	v_cvt_pk_bf16_f32 v113, v128, v129
	v_lshl_add_u64 v[108:109], v[108:109], 0, v[172:173]
	global_store_dwordx4 v[108:109], v[110:113], off
	v_pk_add_f32 v[72:73], v[72:73], 1.0 op_sel_hi:[1,0]
	v_add_f32_e32 v69, v69, v21
	v_div_scale_f32 v112, s[2:3], v105, v105, 1.0
	v_rcp_f32_e32 v113, v112
	v_lshlrev_b32_e32 v110, 16, v124
	v_and_b32_e32 v111, 0xffff0000, v124
	v_mul_f32_e32 v68, 0xbfb8aa3b, v68
	v_fma_f32 v114, -v112, v113, 1.0
	v_fmac_f32_e32 v113, v114, v113
	v_div_scale_f32 v114, vcc, 1.0, v105, 1.0
	v_mul_f32_e32 v115, v114, v113
	v_fma_f32 v124, -v112, v115, v114
	v_fmac_f32_e32 v115, v124, v113
	v_fma_f32 v112, -v112, v115, v114
	v_div_fmas_f32 v112, v112, v113, v115
	v_div_fixup_f32 v105, v112, v105, 1.0
	v_rcp_f32_e32 v113, v104
	s_nop 0
	v_mul_f32_e32 v69, 0xbfb8aa3b, v69
	v_exp_f32_e32 v68, v68
	v_exp_f32_e32 v69, v69
	v_mul_f32_e32 v115, 1.0, v113
	v_fma_f32 v124, -v104, v115, 1.0
	v_fmac_f32_e32 v115, v124, v113
	v_div_fixup_f32 v104, v115, v104, 1.0
	v_rcp_f32_e32 v113, v101
	s_nop 0
	v_pk_mul_f32 v[104:105], v[104:105], v[110:111]
	v_lshlrev_b32_e32 v110, 16, v126
	v_and_b32_e32 v111, 0xffff0000, v126
	v_mul_f32_e32 v115, 1.0, v113
	v_fma_f32 v124, -v101, v115, 1.0
	v_fmac_f32_e32 v115, v124, v113
	v_div_fixup_f32 v101, v115, v101, 1.0
	v_rcp_f32_e32 v113, v100
	s_nop 0
	v_pk_add_f32 v[68:69], v[68:69], 1.0 op_sel_hi:[1,0]
	v_add_f32_e32 v64, v64, v40
	v_add_f32_e32 v65, v65, v41
	v_mul_f32_e32 v115, 1.0, v113
	v_fma_f32 v124, -v100, v115, 1.0
	v_fmac_f32_e32 v115, v124, v113
	v_div_fixup_f32 v100, v115, v100, 1.0
	v_pk_mul_f32 v[110:111], v[100:101], v[110:111]
	v_add_f32_e32 v101, v102, v22
	v_mul_f32_e32 v101, 0xbfb8aa3b, v101
	v_add_f32_e32 v100, v106, v26
	v_exp_f32_e32 v102, v101
	v_add_f32_e32 v101, v107, v27
	v_mul_f32_e32 v100, 0xbfb8aa3b, v100
	v_mul_f32_e32 v101, 0xbfb8aa3b, v101
	v_exp_f32_e32 v100, v100
	v_exp_f32_e32 v101, v101
	v_lshlrev_b32_e32 v106, 16, v125
	v_and_b32_e32 v107, 0xffff0000, v125
	v_mul_f32_e32 v64, 0xbfb8aa3b, v64
	v_pk_add_f32 v[100:101], v[100:101], 1.0 op_sel_hi:[1,0]
	v_mul_f32_e32 v65, 0xbfb8aa3b, v65
	v_rcp_f32_e32 v113, v101
	s_nop 0
	v_exp_f32_e32 v64, v64
	v_exp_f32_e32 v65, v65
	v_add_f32_e32 v60, v60, v36
; DI void unpack8(u32x4 w, float* f) { f[0] = bflo(w.x); f[1] = bfhi(w.x); f[2] = bflo(w.y); f[3] = bfhi(w.y); f[4] = bflo(w.z); f[5] = bfhi(w.z); f[6] = bflo(w.w); f[7] = bfhi(w.w); }
; DI u32x4 pack44(f32x4 a, f32x4 b) { u32x4 w; w.x = pk2(a[0], a[1]); w.y = pk2(a[2], a[3]); w.z = pk2(b[0], b[1]); w.w = pk2(b[2], b[3]); return w; }
; DI float sigmoidf_(float x) { return 1.f / (1.f + __expf(-x)); }
;     DI void operator()(const Acc& acc, const Unit& u, int wr, int wc, int fr, int fq) const {
;     ...
;                 for (int mi = 0; mi < 2; ++mi)
; #pragma unroll
;                     for (int bj = 0; bj < 2; ++bj) { const int row = u.pm * 256 + ai * 128 + wr * 64 + (2 * mp + mi) * 16 + fr, col = u.pn * 256 + bj * 128 + wc * 32 + 8 * fq;
;                         zv[mi][bj] = *(const u32x4*)(zs + (size_t)row * 1024 + col); }
; #pragma unroll
;                 for (int mi = 0; mi < 2; ++mi)
; #pragma unroll
;                     for (int bj = 0; bj < 2; ++bj) { const int m = 2 * mp + mi, row = u.pm * 256 + ai * 128 + wr * 64 + m * 16 + fr, col = u.pn * 256 + bj * 128 + wc * 32 + 8 * fq;
;                         f32x4 v0 = acc[ai][bj][m][0], v1 = acc[ai][bj][m][1]; float zf[8]; unpack8(zv[mi][bj], zf);
;                         for (int j = 0; j < 4; ++j) { v0[j] = zf[j] * sigmoidf_(v0[j] + bv[bj][0][j]); v1[j] = zf[4 + j] * sigmoidf_(v1[j] + bv[bj][1][j]); }
;                         *(u32x4*)(y2 + (size_t)row * 1024 + col) = pack44(v0, v1); }
	v_mul_f32_e32 v115, 1.0, v113
	v_fma_f32 v124, -v101, v115, 1.0
	v_fmac_f32_e32 v115, v124, v113
	v_div_fixup_f32 v101, v115, v101, 1.0
	v_rcp_f32_e32 v113, v100
	s_nop 0
	v_pk_add_f32 v[64:65], v[64:65], 1.0 op_sel_hi:[1,0]
	v_add_f32_e32 v61, v61, v37
	v_mul_f32_e32 v60, 0xbfb8aa3b, v60
	v_mul_f32_e32 v115, 1.0, v113
	v_fma_f32 v124, -v100, v115, 1.0
	v_fmac_f32_e32 v115, v124, v113
	v_div_fixup_f32 v100, v115, v100, 1.0
	v_pk_mul_f32 v[106:107], v[100:101], v[106:107]
	v_add_f32_e32 v100, v103, v23
	v_mul_f32_e32 v100, 0xbfb8aa3b, v100
	v_exp_f32_e32 v103, v100
	v_lshlrev_b32_e32 v100, 16, v127
	v_and_b32_e32 v101, 0xffff0000, v127
	v_mul_f32_e32 v61, 0xbfb8aa3b, v61
	v_pk_add_f32 v[102:103], v[102:103], 1.0 op_sel_hi:[1,0]
	v_exp_f32_e32 v60, v60
	v_rcp_f32_e32 v113, v103
	s_nop 0
	v_exp_f32_e32 v61, v61
	v_add_f32_e32 v66, v66, v42
	v_add_f32_e32 v67, v67, v43
	v_mul_f32_e32 v115, 1.0, v113
	v_fma_f32 v124, -v103, v115, 1.0
	v_fmac_f32_e32 v115, v124, v113
	v_div_fixup_f32 v103, v115, v103, 1.0
	v_rcp_f32_e32 v113, v102
	s_nop 0
	v_pk_add_f32 v[60:61], v[60:61], 1.0 op_sel_hi:[1,0]
	v_mul_f32_e32 v66, 0xbfb8aa3b, v66
	v_mul_f32_e32 v67, 0xbfb8aa3b, v67
	v_mul_f32_e32 v115, 1.0, v113
	v_fma_f32 v124, -v102, v115, 1.0
	v_fmac_f32_e32 v115, v124, v113
	v_div_fixup_f32 v102, v115, v102, 1.0
	v_pk_mul_f32 v[112:113], v[102:103], v[100:101]
	v_cvt_pk_bf16_f32 v100, v104, v105
	v_cvt_pk_bf16_f32 v101, v106, v107
	v_cvt_pk_bf16_f32 v102, v110, v111
	v_cvt_pk_bf16_f32 v103, v112, v113
	global_store_dwordx4 v[108:109], v[100:103], off offset:256
	v_exp_f32_e32 v66, v66
	v_exp_f32_e32 v67, v67
	v_rcp_f32_e32 v103, v97
	s_nop 0
	v_lshlrev_b32_e32 v100, 16, v120
	v_and_b32_e32 v101, 0xffff0000, v120
	v_pk_add_f32 v[66:67], v[66:67], 1.0 op_sel_hi:[1,0]
	v_mul_f32_e32 v105, 1.0, v103
	v_fma_f32 v106, -v97, v105, 1.0
	v_fmac_f32_e32 v105, v106, v103
	v_div_fixup_f32 v97, v105, v97, 1.0
	v_rcp_f32_e32 v103, v96
	s_nop 0
	v_add_f32_e32 v62, v62, v38
	v_add_f32_e32 v63, v63, v39
	v_mul_f32_e32 v62, 0xbfb8aa3b, v62
	v_mul_f32_e32 v105, 1.0, v103
	v_fma_f32 v106, -v96, v105, 1.0
	v_fmac_f32_e32 v105, v106, v103
	v_div_fixup_f32 v96, v105, v96, 1.0
	v_rcp_f32_e32 v103, v93
	s_nop 0
	v_pk_mul_f32 v[96:97], v[96:97], v[100:101]
	v_lshlrev_b32_e32 v100, 16, v122
	v_and_b32_e32 v101, 0xffff0000, v122
	v_mul_f32_e32 v105, 1.0, v103
	v_fma_f32 v106, -v93, v105, 1.0
	v_fmac_f32_e32 v105, v106, v103
	v_div_fixup_f32 v93, v105, v93, 1.0
	v_rcp_f32_e32 v103, v92
	s_nop 0
	v_mul_f32_e32 v63, 0xbfb8aa3b, v63
	v_exp_f32_e32 v62, v62
	v_exp_f32_e32 v63, v63
	v_mul_f32_e32 v105, 1.0, v103
	v_fma_f32 v106, -v92, v105, 1.0
	v_fmac_f32_e32 v105, v106, v103
	v_div_fixup_f32 v92, v105, v92, 1.0
	v_rcp_f32_e32 v103, v99
	s_nop 0
	v_pk_mul_f32 v[92:93], v[92:93], v[100:101]
	v_lshlrev_b32_e32 v100, 16, v121
	v_and_b32_e32 v101, 0xffff0000, v121
	v_mul_f32_e32 v105, 1.0, v103
	v_fma_f32 v106, -v99, v105, 1.0
	v_fmac_f32_e32 v105, v106, v103
	v_div_fixup_f32 v99, v105, v99, 1.0
	v_rcp_f32_e32 v103, v98
	s_nop 0
	v_pk_add_f32 v[62:63], v[62:63], 1.0 op_sel_hi:[1,0]
	v_add_f32_e32 v56, v56, v24
	v_add_f32_e32 v57, v57, v25
	v_mul_f32_e32 v105, 1.0, v103
	v_fma_f32 v106, -v98, v105, 1.0
	v_fmac_f32_e32 v105, v106, v103
	v_div_fixup_f32 v98, v105, v98, 1.0
	v_rcp_f32_e32 v103, v95
	s_nop 0
	v_pk_mul_f32 v[98:99], v[98:99], v[100:101]
	v_lshlrev_b32_e32 v100, 16, v123
	v_and_b32_e32 v101, 0xffff0000, v123
	v_mul_f32_e32 v105, 1.0, v103
	v_fma_f32 v106, -v95, v105, 1.0
	v_fmac_f32_e32 v105, v106, v103
	v_div_fixup_f32 v95, v105, v95, 1.0
	v_rcp_f32_e32 v103, v94
	s_nop 0
	v_mul_f32_e32 v56, 0xbfb8aa3b, v56
	v_mul_f32_e32 v57, 0xbfb8aa3b, v57
	v_exp_f32_e32 v56, v56
	v_mul_f32_e32 v105, 1.0, v103
	v_fma_f32 v106, -v94, v105, 1.0
	v_fmac_f32_e32 v105, v106, v103
	v_div_fixup_f32 v94, v105, v94, 1.0
	v_pk_mul_f32 v[100:101], v[94:95], v[100:101]
	v_cvt_pk_bf16_f32 v94, v96, v97
	v_cvt_pk_bf16_f32 v96, v92, v93
	v_lshl_add_u64 v[92:93], s[68:69], 0, v[132:133]
	v_cvt_pk_bf16_f32 v95, v98, v99
	v_cvt_pk_bf16_f32 v97, v100, v101
	v_lshl_add_u64 v[92:93], v[92:93], 0, v[172:173]
	global_store_dwordx4 v[92:93], v[94:97], off
	v_exp_f32_e32 v57, v57
	v_add_f32_e32 v52, v52, v20
	v_rcp_f32_e32 v97, v89
	s_nop 0
	v_lshlrev_b32_e32 v94, 16, v116
	v_and_b32_e32 v95, 0xffff0000, v116
	v_pk_add_f32 v[56:57], v[56:57], 1.0 op_sel_hi:[1,0]
	v_mul_f32_e32 v99, 1.0, v97
	v_fma_f32 v100, -v89, v99, 1.0
	v_fmac_f32_e32 v99, v100, v97
	v_div_fixup_f32 v89, v99, v89, 1.0
	v_rcp_f32_e32 v97, v88
	s_nop 0
	v_add_f32_e32 v53, v53, v21
	v_mul_f32_e32 v52, 0xbfb8aa3b, v52
	v_mul_f32_e32 v53, 0xbfb8aa3b, v53
	v_mul_f32_e32 v99, 1.0, v97
	v_fma_f32 v100, -v88, v99, 1.0
	v_fmac_f32_e32 v99, v100, v97
	v_div_fixup_f32 v88, v99, v88, 1.0
	v_rcp_f32_e32 v97, v85
	s_nop 0
	v_pk_mul_f32 v[88:89], v[88:89], v[94:95]
	v_lshlrev_b32_e32 v94, 16, v118
	v_and_b32_e32 v95, 0xffff0000, v118
	v_mul_f32_e32 v99, 1.0, v97
	v_fma_f32 v100, -v85, v99, 1.0
	v_fmac_f32_e32 v99, v100, v97
	v_div_fixup_f32 v85, v99, v85, 1.0
	v_rcp_f32_e32 v97, v84
	s_nop 0
	v_exp_f32_e32 v52, v52
	v_exp_f32_e32 v53, v53
	v_add_f32_e32 v48, v48, v40
	v_mul_f32_e32 v99, 1.0, v97
	v_fma_f32 v100, -v84, v99, 1.0
	v_fmac_f32_e32 v99, v100, v97
	v_div_fixup_f32 v84, v99, v84, 1.0
	v_pk_mul_f32 v[94:95], v[84:85], v[94:95]
	v_add_f32_e32 v85, v86, v22
	v_mul_f32_e32 v85, 0xbfb8aa3b, v85
	v_add_f32_e32 v84, v90, v26
	v_exp_f32_e32 v86, v85
	v_add_f32_e32 v85, v91, v27
	v_mul_f32_e32 v84, 0xbfb8aa3b, v84
	v_mul_f32_e32 v85, 0xbfb8aa3b, v85
	v_exp_f32_e32 v84, v84
	v_exp_f32_e32 v85, v85
	v_lshlrev_b32_e32 v90, 16, v117
	v_and_b32_e32 v91, 0xffff0000, v117
; DI void unpack8(u32x4 w, float* f) { f[0] = bflo(w.x); f[1] = bfhi(w.x); f[2] = bflo(w.y); f[3] = bfhi(w.y); f[4] = bflo(w.z); f[5] = bfhi(w.z); f[6] = bflo(w.w); f[7] = bfhi(w.w); }
; DI u32x4 pack44(f32x4 a, f32x4 b) { u32x4 w; w.x = pk2(a[0], a[1]); w.y = pk2(a[2], a[3]); w.z = pk2(b[0], b[1]); w.w = pk2(b[2], b[3]); return w; }
; DI float sigmoidf_(float x) { return 1.f / (1.f + __expf(-x)); }
;     DI void operator()(const Acc& acc, const Unit& u, int wr, int wc, int fr, int fq) const {
;     ...
;                 for (int mi = 0; mi < 2; ++mi)
; #pragma unroll
;                     for (int bj = 0; bj < 2; ++bj) { const int row = u.pm * 256 + ai * 128 + wr * 64 + (2 * mp + mi) * 16 + fr, col = u.pn * 256 + bj * 128 + wc * 32 + 8 * fq;
;                         zv[mi][bj] = *(const u32x4*)(zs + (size_t)row * 1024 + col); }
; #pragma unroll
;                 for (int mi = 0; mi < 2; ++mi)
; #pragma unroll
;                     for (int bj = 0; bj < 2; ++bj) { const int m = 2 * mp + mi, row = u.pm * 256 + ai * 128 + wr * 64 + m * 16 + fr, col = u.pn * 256 + bj * 128 + wc * 32 + 8 * fq;
;                         f32x4 v0 = acc[ai][bj][m][0], v1 = acc[ai][bj][m][1]; float zf[8]; unpack8(zv[mi][bj], zf);
;                         for (int j = 0; j < 4; ++j) { v0[j] = zf[j] * sigmoidf_(v0[j] + bv[bj][0][j]); v1[j] = zf[4 + j] * sigmoidf_(v1[j] + bv[bj][1][j]); }
;                         *(u32x4*)(y2 + (size_t)row * 1024 + col) = pack44(v0, v1); }
	v_pk_add_f32 v[52:53], v[52:53], 1.0 op_sel_hi:[1,0]
	v_pk_add_f32 v[84:85], v[84:85], 1.0 op_sel_hi:[1,0]
	v_add_f32_e32 v49, v49, v41
	v_rcp_f32_e32 v97, v85
	s_nop 0
	v_mul_f32_e32 v48, 0xbfb8aa3b, v48
	v_mul_f32_e32 v49, 0xbfb8aa3b, v49
	v_exp_f32_e32 v48, v48
	v_mul_f32_e32 v99, 1.0, v97
	v_fma_f32 v100, -v85, v99, 1.0
	v_fmac_f32_e32 v99, v100, v97
	v_div_fixup_f32 v85, v99, v85, 1.0
	v_rcp_f32_e32 v97, v84
	s_nop 0
	v_exp_f32_e32 v49, v49
	v_add_f32_e32 v44, v44, v36
	v_add_f32_e32 v45, v45, v37
	v_mul_f32_e32 v99, 1.0, v97
	v_fma_f32 v100, -v84, v99, 1.0
	v_fmac_f32_e32 v99, v100, v97
	v_div_fixup_f32 v84, v99, v84, 1.0
	v_pk_mul_f32 v[90:91], v[84:85], v[90:91]
	v_add_f32_e32 v84, v87, v23
	v_mul_f32_e32 v84, 0xbfb8aa3b, v84
	v_exp_f32_e32 v87, v84
	v_lshlrev_b32_e32 v84, 16, v119
	v_and_b32_e32 v85, 0xffff0000, v119
	v_pk_add_f32 v[48:49], v[48:49], 1.0 op_sel_hi:[1,0]
	v_pk_add_f32 v[86:87], v[86:87], 1.0 op_sel_hi:[1,0]
	v_mul_f32_e32 v44, 0xbfb8aa3b, v44
	v_rcp_f32_e32 v97, v87
	s_nop 0
	v_mul_f32_e32 v45, 0xbfb8aa3b, v45
	v_exp_f32_e32 v44, v44
	v_exp_f32_e32 v45, v45
	v_mul_f32_e32 v99, 1.0, v97
	v_fma_f32 v100, -v87, v99, 1.0
	v_fmac_f32_e32 v99, v100, v97
	v_div_fixup_f32 v87, v99, v87, 1.0
	v_rcp_f32_e32 v97, v86
	s_nop 0
	v_pk_add_f32 v[44:45], v[44:45], 1.0 op_sel_hi:[1,0]
	v_add_f32_e32 v50, v50, v42
	v_add_f32_e32 v51, v51, v43
	v_mul_f32_e32 v99, 1.0, v97
	v_fma_f32 v100, -v86, v99, 1.0
	v_fmac_f32_e32 v99, v100, v97
	v_div_fixup_f32 v86, v99, v86, 1.0
	v_pk_mul_f32 v[96:97], v[86:87], v[84:85]
	v_cvt_pk_bf16_f32 v84, v88, v89
	v_cvt_pk_bf16_f32 v85, v90, v91
	v_cvt_pk_bf16_f32 v86, v94, v95
	v_cvt_pk_bf16_f32 v87, v96, v97
	global_store_dwordx4 v[92:93], v[84:87], off offset:256
	v_mul_f32_e32 v50, 0xbfb8aa3b, v50
	v_mul_f32_e32 v51, 0xbfb8aa3b, v51
	v_add_u32_e32 v84, 0x80, v174
	v_ashrrev_i32_e32 v85, 31, v84
	v_lshlrev_b64 v[102:103], 11, v[84:85]
	v_lshl_add_u64 v[84:85], s[4:5], 0, v[102:103]
	v_lshl_add_u64 v[84:85], v[84:85], 0, v[172:173]
	global_load_dwordx4 v[96:99], v[84:85], off
	global_load_dwordx4 v[92:95], v[84:85], off offset:256
	v_add_u32_e32 v84, 0x90, v174
	v_ashrrev_i32_e32 v85, 31, v84
	v_lshlrev_b64 v[100:101], 11, v[84:85]
	v_lshl_add_u64 v[84:85], s[4:5], 0, v[100:101]
	v_lshl_add_u64 v[84:85], v[84:85], 0, v[172:173]
	global_load_dwordx4 v[88:91], v[84:85], off
	s_nop 0
	global_load_dwordx4 v[84:87], v[84:85], off offset:256
	v_exp_f32_e32 v50, v50
	v_exp_f32_e32 v51, v51
	v_add_f32_e32 v46, v46, v38
	v_add_f32_e32 v47, v47, v39
	v_mul_f32_e32 v46, 0xbfb8aa3b, v46
	v_pk_add_f32 v[50:51], v[50:51], 1.0 op_sel_hi:[1,0]
	v_mul_f32_e32 v47, 0xbfb8aa3b, v47
	v_exp_f32_e32 v46, v46
	v_exp_f32_e32 v47, v47
	v_add_f32_e32 v32, v32, v24
	v_add_f32_e32 v33, v33, v25
	v_mul_f32_e32 v32, 0xbfb8aa3b, v32
	v_pk_add_f32 v[46:47], v[46:47], 1.0 op_sel_hi:[1,0]
	v_mul_f32_e32 v33, 0xbfb8aa3b, v33
	v_exp_f32_e32 v32, v32
	v_exp_f32_e32 v33, v33
	v_add_f32_e32 v28, v28, v20
	v_add_f32_e32 v29, v29, v21
	v_mul_f32_e32 v28, 0xbfb8aa3b, v28
	v_pk_add_f32 v[32:33], v[32:33], 1.0 op_sel_hi:[1,0]
	v_mul_f32_e32 v29, 0xbfb8aa3b, v29
	v_exp_f32_e32 v28, v28
	v_exp_f32_e32 v29, v29
	v_add_f32_e32 v16, v16, v40
	v_add_f32_e32 v17, v17, v41
	v_mul_f32_e32 v16, 0xbfb8aa3b, v16
	v_pk_add_f32 v[28:29], v[28:29], 1.0 op_sel_hi:[1,0]
	v_mul_f32_e32 v17, 0xbfb8aa3b, v17
	v_exp_f32_e32 v16, v16
	v_exp_f32_e32 v17, v17
	v_add_f32_e32 v12, v12, v36
	v_add_f32_e32 v13, v13, v37
	v_mul_f32_e32 v12, 0xbfb8aa3b, v12
	v_pk_add_f32 v[16:17], v[16:17], 1.0 op_sel_hi:[1,0]
	v_mul_f32_e32 v13, 0xbfb8aa3b, v13
	v_exp_f32_e32 v12, v12
	v_exp_f32_e32 v13, v13
	v_add_f32_e32 v18, v18, v42
	v_add_f32_e32 v19, v19, v43
	v_mul_f32_e32 v18, 0xbfb8aa3b, v18
	v_pk_add_f32 v[12:13], v[12:13], 1.0 op_sel_hi:[1,0]
	v_mul_f32_e32 v19, 0xbfb8aa3b, v19
	v_exp_f32_e32 v18, v18
	v_exp_f32_e32 v19, v19
	v_add_f32_e32 v14, v14, v38
	v_add_f32_e32 v15, v15, v39
	v_mul_f32_e32 v14, 0xbfb8aa3b, v14
	v_pk_add_f32 v[18:19], v[18:19], 1.0 op_sel_hi:[1,0]
	v_mul_f32_e32 v15, 0xbfb8aa3b, v15
	v_exp_f32_e32 v14, v14
	v_exp_f32_e32 v15, v15
	v_add_f32_e32 v8, v8, v24
	v_add_f32_e32 v9, v9, v25
	v_mul_f32_e32 v8, 0xbfb8aa3b, v8
	v_pk_add_f32 v[14:15], v[14:15], 1.0 op_sel_hi:[1,0]
	v_mul_f32_e32 v9, 0xbfb8aa3b, v9
	v_exp_f32_e32 v8, v8
	v_exp_f32_e32 v9, v9
	v_add_f32_e32 v4, v4, v20
	v_add_f32_e32 v5, v5, v21
	v_mul_f32_e32 v4, 0xbfb8aa3b, v4
	v_pk_add_f32 v[8:9], v[8:9], 1.0 op_sel_hi:[1,0]
	v_mul_f32_e32 v5, 0xbfb8aa3b, v5
	v_exp_f32_e32 v4, v4
	v_exp_f32_e32 v5, v5
	s_waitcnt vmcnt(0)
; DI void unpack8(u32x4 w, float* f) { f[0] = bflo(w.x); f[1] = bfhi(w.x); f[2] = bflo(w.y); f[3] = bfhi(w.y); f[4] = bflo(w.z); f[5] = bfhi(w.z); f[6] = bflo(w.w); f[7] = bfhi(w.w); }
; DI u32x4 pack44(f32x4 a, f32x4 b) { u32x4 w; w.x = pk2(a[0], a[1]); w.y = pk2(a[2], a[3]); w.z = pk2(b[0], b[1]); w.w = pk2(b[2], b[3]); return w; }
; DI float sigmoidf_(float x) { return 1.f / (1.f + __expf(-x)); }
;     DI void operator()(const Acc& acc, const Unit& u, int wr, int wc, int fr, int fq) const {
;     ...
;                 for (int mi = 0; mi < 2; ++mi)
; #pragma unroll
;                     for (int bj = 0; bj < 2; ++bj) { const int row = u.pm * 256 + ai * 128 + wr * 64 + (2 * mp + mi) * 16 + fr, col = u.pn * 256 + bj * 128 + wc * 32 + 8 * fq;
;                         zv[mi][bj] = *(const u32x4*)(zs + (size_t)row * 1024 + col); }
; #pragma unroll
;                 for (int mi = 0; mi < 2; ++mi)
; #pragma unroll
;                     for (int bj = 0; bj < 2; ++bj) { const int m = 2 * mp + mi, row = u.pm * 256 + ai * 128 + wr * 64 + m * 16 + fr, col = u.pn * 256 + bj * 128 + wc * 32 + 8 * fq;
;                         f32x4 v0 = acc[ai][bj][m][0], v1 = acc[ai][bj][m][1]; float zf[8]; unpack8(zv[mi][bj], zf);
;                         for (int j = 0; j < 4; ++j) { v0[j] = zf[j] * sigmoidf_(v0[j] + bv[bj][0][j]); v1[j] = zf[4 + j] * sigmoidf_(v1[j] + bv[bj][1][j]); }
;                         *(u32x4*)(y2 + (size_t)row * 1024 + col) = pack44(v0, v1); }
	v_lshlrev_b32_e32 v104, 16, v96
	v_and_b32_e32 v105, 0xffff0000, v96
	v_rcp_f32_e32 v106, v81
	s_nop 0
	v_pk_add_f32 v[4:5], v[4:5], 1.0 op_sel_hi:[1,0]
	v_mul_f32_e32 v108, 1.0, v106
	v_fma_f32 v109, -v81, v108, 1.0
	v_fmac_f32_e32 v108, v109, v106
	v_div_fixup_f32 v81, v108, v81, 1.0
	v_rcp_f32_e32 v106, v80
	s_nop 0
	v_mul_f32_e32 v108, 1.0, v106
	v_fma_f32 v109, -v80, v108, 1.0
	v_fmac_f32_e32 v108, v109, v106
	v_div_fixup_f32 v80, v108, v80, 1.0
	v_div_scale_f32 v96, s[2:3], v77, v77, 1.0
	v_pk_mul_f32 v[80:81], v[80:81], v[104:105]
	v_lshlrev_b32_e32 v104, 16, v98
	v_and_b32_e32 v105, 0xffff0000, v98
	v_rcp_f32_e32 v98, v96
	s_nop 0
	v_fma_f32 v106, -v96, v98, 1.0
	v_fmac_f32_e32 v98, v106, v98
	v_div_scale_f32 v106, vcc, 1.0, v77, 1.0
	v_mul_f32_e32 v107, v106, v98
	v_fma_f32 v108, -v96, v107, v106
	v_fmac_f32_e32 v107, v108, v98
	v_fma_f32 v96, -v96, v107, v106
	v_div_fmas_f32 v96, v96, v98, v107
	v_div_fixup_f32 v77, v96, v77, 1.0
	v_rcp_f32_e32 v98, v76
	s_nop 0
	v_mul_f32_e32 v107, 1.0, v98
	v_fma_f32 v108, -v76, v107, 1.0
	v_fmac_f32_e32 v107, v108, v98
	v_div_fixup_f32 v76, v107, v76, 1.0
	v_div_scale_f32 v98, s[2:3], v83, v83, 1.0
	v_pk_mul_f32 v[76:77], v[76:77], v[104:105]
	v_rcp_f32_e32 v104, v98
	v_lshlrev_b32_e32 v96, 16, v97
	v_and_b32_e32 v97, 0xffff0000, v97
	v_fma_f32 v105, -v98, v104, 1.0
	v_fmac_f32_e32 v104, v105, v104
	v_div_scale_f32 v105, vcc, 1.0, v83, 1.0
	v_mul_f32_e32 v106, v105, v104
	v_fma_f32 v107, -v98, v106, v105
	v_fmac_f32_e32 v106, v107, v104
	v_fma_f32 v98, -v98, v106, v105
	v_div_fmas_f32 v98, v98, v104, v106
	v_div_fixup_f32 v83, v98, v83, 1.0
	v_rcp_f32_e32 v104, v82
	s_nop 0
	v_mul_f32_e32 v106, 1.0, v104
	v_fma_f32 v107, -v82, v106, 1.0
	v_fmac_f32_e32 v106, v107, v104
	v_div_fixup_f32 v82, v106, v82, 1.0
	v_div_scale_f32 v98, s[2:3], v79, v79, 1.0
	v_pk_mul_f32 v[82:83], v[82:83], v[96:97]
	v_lshlrev_b32_e32 v96, 16, v99
	v_and_b32_e32 v97, 0xffff0000, v99
	v_rcp_f32_e32 v99, v98
	s_nop 0
	v_fma_f32 v104, -v98, v99, 1.0
	v_fmac_f32_e32 v99, v104, v99
	v_div_scale_f32 v104, vcc, 1.0, v79, 1.0
	v_mul_f32_e32 v105, v104, v99
	v_fma_f32 v106, -v98, v105, v104
	v_fmac_f32_e32 v105, v106, v99
	v_fma_f32 v98, -v98, v105, v104
	v_div_fmas_f32 v98, v98, v99, v105
	v_div_fixup_f32 v79, v98, v79, 1.0
	v_rcp_f32_e32 v99, v78
	s_nop 0
	v_mul_f32_e32 v105, 1.0, v99
	v_fma_f32 v106, -v78, v105, 1.0
	v_fmac_f32_e32 v105, v106, v99
	v_div_fixup_f32 v78, v105, v78, 1.0
	v_pk_mul_f32 v[96:97], v[78:79], v[96:97]
	v_cvt_pk_bf16_f32 v78, v80, v81
	v_cvt_pk_bf16_f32 v80, v76, v77
	v_lshl_add_u64 v[76:77], s[68:69], 0, v[102:103]
	v_cvt_pk_bf16_f32 v79, v82, v83
	v_cvt_pk_bf16_f32 v81, v96, v97
	v_lshl_add_u64 v[76:77], v[76:77], 0, v[172:173]
	global_store_dwordx4 v[76:77], v[78:81], off
	s_nop 1
	v_div_scale_f32 v80, s[2:3], v73, v73, 1.0
	v_rcp_f32_e32 v81, v80
	v_lshlrev_b32_e32 v78, 16, v92
	v_and_b32_e32 v79, 0xffff0000, v92
	v_fma_f32 v82, -v80, v81, 1.0
	v_fmac_f32_e32 v81, v82, v81
	v_div_scale_f32 v82, vcc, 1.0, v73, 1.0
	v_mul_f32_e32 v83, v82, v81
	v_fma_f32 v92, -v80, v83, v82
	v_fmac_f32_e32 v83, v92, v81
	v_fma_f32 v80, -v80, v83, v82
	v_div_fmas_f32 v80, v80, v81, v83
	v_div_fixup_f32 v73, v80, v73, 1.0
	v_rcp_f32_e32 v81, v72
	s_nop 0
	v_mul_f32_e32 v83, 1.0, v81
	v_fma_f32 v92, -v72, v83, 1.0
	v_fmac_f32_e32 v83, v92, v81
	v_div_fixup_f32 v72, v83, v72, 1.0
	v_rcp_f32_e32 v81, v69
	s_nop 0
	v_pk_mul_f32 v[72:73], v[72:73], v[78:79]
	v_lshlrev_b32_e32 v78, 16, v94
	v_and_b32_e32 v79, 0xffff0000, v94
	v_mul_f32_e32 v83, 1.0, v81
	v_fma_f32 v92, -v69, v83, 1.0
	v_fmac_f32_e32 v83, v92, v81
	v_div_fixup_f32 v69, v83, v69, 1.0
	v_rcp_f32_e32 v81, v68
	s_nop 0
	v_mul_f32_e32 v83, 1.0, v81
	v_fma_f32 v92, -v68, v83, 1.0
	v_fmac_f32_e32 v83, v92, v81
	v_div_fixup_f32 v68, v83, v68, 1.0
	v_pk_mul_f32 v[78:79], v[68:69], v[78:79]
	v_add_f32_e32 v69, v70, v22
	v_mul_f32_e32 v69, 0xbfb8aa3b, v69
	v_add_f32_e32 v68, v74, v26
	v_exp_f32_e32 v70, v69
	v_add_f32_e32 v69, v75, v27
	v_mul_f32_e32 v68, 0xbfb8aa3b, v68
	v_mul_f32_e32 v69, 0xbfb8aa3b, v69
	v_exp_f32_e32 v68, v68
	v_exp_f32_e32 v69, v69
	v_lshlrev_b32_e32 v74, 16, v93
	v_and_b32_e32 v75, 0xffff0000, v93
	v_pk_add_f32 v[68:69], v[68:69], 1.0 op_sel_hi:[1,0]
	s_nop 0
	v_rcp_f32_e32 v81, v69
	s_nop 0
	v_mul_f32_e32 v83, 1.0, v81
	v_fma_f32 v92, -v69, v83, 1.0
	v_fmac_f32_e32 v83, v92, v81
	v_div_fixup_f32 v69, v83, v69, 1.0
	v_rcp_f32_e32 v81, v68
	s_nop 0
	v_mul_f32_e32 v83, 1.0, v81
	v_fma_f32 v92, -v68, v83, 1.0
	v_fmac_f32_e32 v83, v92, v81
	v_div_fixup_f32 v68, v83, v68, 1.0
	v_pk_mul_f32 v[74:75], v[68:69], v[74:75]
	v_add_f32_e32 v68, v71, v23
	v_mul_f32_e32 v68, 0xbfb8aa3b, v68
	v_exp_f32_e32 v71, v68
	v_lshlrev_b32_e32 v68, 16, v95
	v_and_b32_e32 v69, 0xffff0000, v95
	v_pk_add_f32 v[70:71], v[70:71], 1.0 op_sel_hi:[1,0]
	s_nop 0
	v_rcp_f32_e32 v81, v71
	s_nop 0
	v_mul_f32_e32 v83, 1.0, v81
	v_fma_f32 v92, -v71, v83, 1.0
	v_fmac_f32_e32 v83, v92, v81
	v_div_fixup_f32 v71, v83, v71, 1.0
	v_rcp_f32_e32 v81, v70
	s_nop 0
	v_mul_f32_e32 v83, 1.0, v81
	v_fma_f32 v92, -v70, v83, 1.0
	v_fmac_f32_e32 v83, v92, v81
	v_div_fixup_f32 v70, v83, v70, 1.0
	v_pk_mul_f32 v[80:81], v[70:71], v[68:69]
	v_cvt_pk_bf16_f32 v68, v72, v73
	v_cvt_pk_bf16_f32 v69, v74, v75
	v_cvt_pk_bf16_f32 v70, v78, v79
	v_cvt_pk_bf16_f32 v71, v80, v81
	global_store_dwordx4 v[76:77], v[68:71], off offset:256
	s_nop 1
	v_rcp_f32_e32 v71, v65
	s_nop 0
	v_lshlrev_b32_e32 v68, 16, v88
	v_and_b32_e32 v69, 0xffff0000, v88
	v_mul_f32_e32 v73, 1.0, v71
	v_fma_f32 v74, -v65, v73, 1.0
	v_fmac_f32_e32 v73, v74, v71
	v_div_fixup_f32 v65, v73, v65, 1.0
	v_rcp_f32_e32 v71, v64
	s_nop 0
; DI void unpack8(u32x4 w, float* f) { f[0] = bflo(w.x); f[1] = bfhi(w.x); f[2] = bflo(w.y); f[3] = bfhi(w.y); f[4] = bflo(w.z); f[5] = bfhi(w.z); f[6] = bflo(w.w); f[7] = bfhi(w.w); }
; DI u32x4 pack44(f32x4 a, f32x4 b) { u32x4 w; w.x = pk2(a[0], a[1]); w.y = pk2(a[2], a[3]); w.z = pk2(b[0], b[1]); w.w = pk2(b[2], b[3]); return w; }
; DI float sigmoidf_(float x) { return 1.f / (1.f + __expf(-x)); }
;     DI void operator()(const Acc& acc, const Unit& u, int wr, int wc, int fr, int fq) const {
;     ...
;                 for (int mi = 0; mi < 2; ++mi)
; #pragma unroll
;                     for (int bj = 0; bj < 2; ++bj) { const int row = u.pm * 256 + ai * 128 + wr * 64 + (2 * mp + mi) * 16 + fr, col = u.pn * 256 + bj * 128 + wc * 32 + 8 * fq;
;                         zv[mi][bj] = *(const u32x4*)(zs + (size_t)row * 1024 + col); }
; #pragma unroll
;                 for (int mi = 0; mi < 2; ++mi)
; #pragma unroll
;                     for (int bj = 0; bj < 2; ++bj) { const int m = 2 * mp + mi, row = u.pm * 256 + ai * 128 + wr * 64 + m * 16 + fr, col = u.pn * 256 + bj * 128 + wc * 32 + 8 * fq;
;                         f32x4 v0 = acc[ai][bj][m][0], v1 = acc[ai][bj][m][1]; float zf[8]; unpack8(zv[mi][bj], zf);
;                         for (int j = 0; j < 4; ++j) { v0[j] = zf[j] * sigmoidf_(v0[j] + bv[bj][0][j]); v1[j] = zf[4 + j] * sigmoidf_(v1[j] + bv[bj][1][j]); }
;                         *(u32x4*)(y2 + (size_t)row * 1024 + col) = pack44(v0, v1); }
	v_mul_f32_e32 v73, 1.0, v71
	v_fma_f32 v74, -v64, v73, 1.0
	v_fmac_f32_e32 v73, v74, v71
	v_div_fixup_f32 v64, v73, v64, 1.0
	v_rcp_f32_e32 v71, v61
	s_nop 0
	v_pk_mul_f32 v[64:65], v[64:65], v[68:69]
	v_lshlrev_b32_e32 v68, 16, v90
	v_and_b32_e32 v69, 0xffff0000, v90
	v_mul_f32_e32 v73, 1.0, v71
	v_fma_f32 v74, -v61, v73, 1.0
	v_fmac_f32_e32 v73, v74, v71
	v_div_fixup_f32 v61, v73, v61, 1.0
	v_rcp_f32_e32 v71, v60
	s_nop 0
	v_mul_f32_e32 v73, 1.0, v71
	v_fma_f32 v74, -v60, v73, 1.0
	v_fmac_f32_e32 v73, v74, v71
	v_div_fixup_f32 v60, v73, v60, 1.0
	v_rcp_f32_e32 v71, v67
	s_nop 0
	v_pk_mul_f32 v[60:61], v[60:61], v[68:69]
	v_lshlrev_b32_e32 v68, 16, v89
	v_and_b32_e32 v69, 0xffff0000, v89
	v_mul_f32_e32 v73, 1.0, v71
	v_fma_f32 v74, -v67, v73, 1.0
	v_fmac_f32_e32 v73, v74, v71
	v_div_fixup_f32 v67, v73, v67, 1.0
	v_rcp_f32_e32 v71, v66
	s_nop 0
	v_mul_f32_e32 v73, 1.0, v71
	v_fma_f32 v74, -v66, v73, 1.0
	v_fmac_f32_e32 v73, v74, v71
	v_div_fixup_f32 v66, v73, v66, 1.0
	v_rcp_f32_e32 v71, v63
	s_nop 0
	v_pk_mul_f32 v[66:67], v[66:67], v[68:69]
	v_lshlrev_b32_e32 v68, 16, v91
	v_and_b32_e32 v69, 0xffff0000, v91
	v_mul_f32_e32 v73, 1.0, v71
	v_fma_f32 v74, -v63, v73, 1.0
	v_fmac_f32_e32 v73, v74, v71
	v_div_fixup_f32 v63, v73, v63, 1.0
	v_rcp_f32_e32 v71, v62
	s_nop 0
	v_mul_f32_e32 v73, 1.0, v71
	v_fma_f32 v74, -v62, v73, 1.0
	v_fmac_f32_e32 v73, v74, v71
	v_div_fixup_f32 v62, v73, v62, 1.0
	v_pk_mul_f32 v[68:69], v[62:63], v[68:69]
	v_cvt_pk_bf16_f32 v62, v64, v65
	v_cvt_pk_bf16_f32 v64, v60, v61
	v_lshl_add_u64 v[60:61], s[68:69], 0, v[100:101]
	v_cvt_pk_bf16_f32 v63, v66, v67
	v_cvt_pk_bf16_f32 v65, v68, v69
	v_lshl_add_u64 v[60:61], v[60:61], 0, v[172:173]
	global_store_dwordx4 v[60:61], v[62:65], off
	s_nop 1
	v_rcp_f32_e32 v65, v57
	s_nop 0
	v_lshlrev_b32_e32 v62, 16, v84
	v_and_b32_e32 v63, 0xffff0000, v84
	v_mul_f32_e32 v67, 1.0, v65
	v_fma_f32 v68, -v57, v67, 1.0
	v_fmac_f32_e32 v67, v68, v65
	v_div_fixup_f32 v57, v67, v57, 1.0
	v_rcp_f32_e32 v65, v56
	s_nop 0
	v_mul_f32_e32 v67, 1.0, v65
	v_fma_f32 v68, -v56, v67, 1.0
	v_fmac_f32_e32 v67, v68, v65
	v_div_fixup_f32 v56, v67, v56, 1.0
	v_rcp_f32_e32 v65, v53
	s_nop 0
	v_pk_mul_f32 v[56:57], v[56:57], v[62:63]
	v_lshlrev_b32_e32 v62, 16, v86
	v_and_b32_e32 v63, 0xffff0000, v86
	v_mul_f32_e32 v67, 1.0, v65
	v_fma_f32 v68, -v53, v67, 1.0
	v_fmac_f32_e32 v67, v68, v65
	v_div_fixup_f32 v53, v67, v53, 1.0
	v_rcp_f32_e32 v65, v52
	s_nop 0
	v_mul_f32_e32 v67, 1.0, v65
	v_fma_f32 v68, -v52, v67, 1.0
	v_fmac_f32_e32 v67, v68, v65
	v_div_fixup_f32 v52, v67, v52, 1.0
	v_pk_mul_f32 v[62:63], v[52:53], v[62:63]
	v_add_f32_e32 v53, v54, v22
	v_mul_f32_e32 v53, 0xbfb8aa3b, v53
	v_add_f32_e32 v52, v58, v26
	v_exp_f32_e32 v54, v53
	v_add_f32_e32 v53, v59, v27
	v_mul_f32_e32 v52, 0xbfb8aa3b, v52
	v_mul_f32_e32 v53, 0xbfb8aa3b, v53
	v_exp_f32_e32 v52, v52
	v_exp_f32_e32 v53, v53
	v_lshlrev_b32_e32 v58, 16, v85
	v_and_b32_e32 v59, 0xffff0000, v85
	v_pk_add_f32 v[52:53], v[52:53], 1.0 op_sel_hi:[1,0]
	s_nop 0
	v_rcp_f32_e32 v65, v53
	s_nop 0
	v_mul_f32_e32 v67, 1.0, v65
	v_fma_f32 v68, -v53, v67, 1.0
	v_fmac_f32_e32 v67, v68, v65
	v_div_fixup_f32 v53, v67, v53, 1.0
	v_rcp_f32_e32 v65, v52
	s_nop 0
	v_mul_f32_e32 v67, 1.0, v65
	v_fma_f32 v68, -v52, v67, 1.0
	v_fmac_f32_e32 v67, v68, v65
	v_div_fixup_f32 v52, v67, v52, 1.0
	v_pk_mul_f32 v[58:59], v[52:53], v[58:59]
	v_add_f32_e32 v52, v55, v23
	v_mul_f32_e32 v52, 0xbfb8aa3b, v52
	v_exp_f32_e32 v55, v52
	v_lshlrev_b32_e32 v52, 16, v87
	v_and_b32_e32 v53, 0xffff0000, v87
	v_pk_add_f32 v[54:55], v[54:55], 1.0 op_sel_hi:[1,0]
	s_nop 0
	v_rcp_f32_e32 v65, v55
	s_nop 0
	v_mul_f32_e32 v67, 1.0, v65
	v_fma_f32 v68, -v55, v67, 1.0
	v_fmac_f32_e32 v67, v68, v65
	v_div_fixup_f32 v55, v67, v55, 1.0
	v_rcp_f32_e32 v65, v54
	s_nop 0
	v_mul_f32_e32 v67, 1.0, v65
	v_fma_f32 v68, -v54, v67, 1.0
	v_fmac_f32_e32 v67, v68, v65
	v_div_fixup_f32 v54, v67, v54, 1.0
	v_pk_mul_f32 v[64:65], v[54:55], v[52:53]
	v_cvt_pk_bf16_f32 v52, v56, v57
	v_cvt_pk_bf16_f32 v53, v58, v59
	v_cvt_pk_bf16_f32 v54, v62, v63
	v_cvt_pk_bf16_f32 v55, v64, v65
	global_store_dwordx4 v[60:61], v[52:55], off offset:256
	s_nop 1
	v_add_u32_e32 v52, 0xa0, v174
	v_ashrrev_i32_e32 v53, 31, v52
	v_lshlrev_b64 v[70:71], 11, v[52:53]
	v_lshl_add_u64 v[52:53], s[4:5], 0, v[70:71]
	v_lshl_add_u64 v[52:53], v[52:53], 0, v[172:173]
	global_load_dwordx4 v[64:67], v[52:53], off
	global_load_dwordx4 v[60:63], v[52:53], off offset:256
	v_add_u32_e32 v52, 0xb0, v174
	v_ashrrev_i32_e32 v53, 31, v52
	v_lshlrev_b64 v[68:69], 11, v[52:53]
	v_lshl_add_u64 v[52:53], s[4:5], 0, v[68:69]
	v_lshl_add_u64 v[52:53], v[52:53], 0, v[172:173]
	global_load_dwordx4 v[56:59], v[52:53], off
	s_nop 0
	global_load_dwordx4 v[52:55], v[52:53], off offset:256
	s_waitcnt vmcnt(0)
; DI void unpack8(u32x4 w, float* f) { f[0] = bflo(w.x); f[1] = bfhi(w.x); f[2] = bflo(w.y); f[3] = bfhi(w.y); f[4] = bflo(w.z); f[5] = bfhi(w.z); f[6] = bflo(w.w); f[7] = bfhi(w.w); }
; DI u32x4 pack44(f32x4 a, f32x4 b) { u32x4 w; w.x = pk2(a[0], a[1]); w.y = pk2(a[2], a[3]); w.z = pk2(b[0], b[1]); w.w = pk2(b[2], b[3]); return w; }
; DI float sigmoidf_(float x) { return 1.f / (1.f + __expf(-x)); }
;     DI void operator()(const Acc& acc, const Unit& u, int wr, int wc, int fr, int fq) const {
;     ...
;                 for (int mi = 0; mi < 2; ++mi)
; #pragma unroll
;                     for (int bj = 0; bj < 2; ++bj) { const int row = u.pm * 256 + ai * 128 + wr * 64 + (2 * mp + mi) * 16 + fr, col = u.pn * 256 + bj * 128 + wc * 32 + 8 * fq;
;                         zv[mi][bj] = *(const u32x4*)(zs + (size_t)row * 1024 + col); }
; #pragma unroll
;                 for (int mi = 0; mi < 2; ++mi)
; #pragma unroll
;                     for (int bj = 0; bj < 2; ++bj) { const int m = 2 * mp + mi, row = u.pm * 256 + ai * 128 + wr * 64 + m * 16 + fr, col = u.pn * 256 + bj * 128 + wc * 32 + 8 * fq;
;                         f32x4 v0 = acc[ai][bj][m][0], v1 = acc[ai][bj][m][1]; float zf[8]; unpack8(zv[mi][bj], zf);
;                         for (int j = 0; j < 4; ++j) { v0[j] = zf[j] * sigmoidf_(v0[j] + bv[bj][0][j]); v1[j] = zf[4 + j] * sigmoidf_(v1[j] + bv[bj][1][j]); }
;                         *(u32x4*)(y2 + (size_t)row * 1024 + col) = pack44(v0, v1); }
	v_lshlrev_b32_e32 v72, 16, v64
	v_and_b32_e32 v73, 0xffff0000, v64
	v_rcp_f32_e32 v74, v49
	s_nop 0
	v_mul_f32_e32 v76, 1.0, v74
	v_fma_f32 v77, -v49, v76, 1.0
	v_fmac_f32_e32 v76, v77, v74
	v_div_fixup_f32 v49, v76, v49, 1.0
	v_rcp_f32_e32 v74, v48
	s_nop 0
	v_mul_f32_e32 v76, 1.0, v74
	v_fma_f32 v77, -v48, v76, 1.0
	v_fmac_f32_e32 v76, v77, v74
	v_div_fixup_f32 v48, v76, v48, 1.0
	v_div_scale_f32 v64, s[2:3], v45, v45, 1.0
	v_pk_mul_f32 v[48:49], v[48:49], v[72:73]
	v_lshlrev_b32_e32 v72, 16, v66
	v_and_b32_e32 v73, 0xffff0000, v66
	v_rcp_f32_e32 v66, v64
	s_nop 0
	v_fma_f32 v74, -v64, v66, 1.0
	v_fmac_f32_e32 v66, v74, v66
	v_div_scale_f32 v74, vcc, 1.0, v45, 1.0
	v_mul_f32_e32 v75, v74, v66
	v_fma_f32 v76, -v64, v75, v74
	v_fmac_f32_e32 v75, v76, v66
	v_fma_f32 v64, -v64, v75, v74
	v_div_fmas_f32 v64, v64, v66, v75
	v_div_fixup_f32 v45, v64, v45, 1.0
	v_rcp_f32_e32 v66, v44
	s_nop 0
	v_mul_f32_e32 v75, 1.0, v66
	v_fma_f32 v76, -v44, v75, 1.0
	v_fmac_f32_e32 v75, v76, v66
	v_div_fixup_f32 v44, v75, v44, 1.0
	v_div_scale_f32 v66, s[2:3], v51, v51, 1.0
	v_pk_mul_f32 v[44:45], v[44:45], v[72:73]
	v_rcp_f32_e32 v72, v66
	v_lshlrev_b32_e32 v64, 16, v65
	v_and_b32_e32 v65, 0xffff0000, v65
	v_fma_f32 v73, -v66, v72, 1.0
	v_fmac_f32_e32 v72, v73, v72
	v_div_scale_f32 v73, vcc, 1.0, v51, 1.0
	v_mul_f32_e32 v74, v73, v72
	v_fma_f32 v75, -v66, v74, v73
	v_fmac_f32_e32 v74, v75, v72
	v_fma_f32 v66, -v66, v74, v73
	v_div_fmas_f32 v66, v66, v72, v74
	v_div_fixup_f32 v51, v66, v51, 1.0
	v_rcp_f32_e32 v72, v50
	s_nop 0
	v_mul_f32_e32 v74, 1.0, v72
	v_fma_f32 v75, -v50, v74, 1.0
	v_fmac_f32_e32 v74, v75, v72
	v_div_fixup_f32 v50, v74, v50, 1.0
	v_div_scale_f32 v66, s[2:3], v47, v47, 1.0
	v_pk_mul_f32 v[50:51], v[50:51], v[64:65]
	v_lshlrev_b32_e32 v64, 16, v67
	v_and_b32_e32 v65, 0xffff0000, v67
	v_rcp_f32_e32 v67, v66
	s_nop 0
	v_fma_f32 v72, -v66, v67, 1.0
	v_fmac_f32_e32 v67, v72, v67
	v_div_scale_f32 v72, vcc, 1.0, v47, 1.0
	v_mul_f32_e32 v73, v72, v67
	v_fma_f32 v74, -v66, v73, v72
	v_fmac_f32_e32 v73, v74, v67
	v_fma_f32 v66, -v66, v73, v72
	v_div_fmas_f32 v66, v66, v67, v73
	v_div_fixup_f32 v47, v66, v47, 1.0
	v_rcp_f32_e32 v67, v46
	s_nop 0
	v_mul_f32_e32 v73, 1.0, v67
	v_fma_f32 v74, -v46, v73, 1.0
	v_fmac_f32_e32 v73, v74, v67
	v_div_fixup_f32 v46, v73, v46, 1.0
	v_pk_mul_f32 v[64:65], v[46:47], v[64:65]
	v_cvt_pk_bf16_f32 v46, v48, v49
	v_cvt_pk_bf16_f32 v48, v44, v45
	v_lshl_add_u64 v[44:45], s[68:69], 0, v[70:71]
	v_cvt_pk_bf16_f32 v47, v50, v51
	v_cvt_pk_bf16_f32 v49, v64, v65
	v_lshl_add_u64 v[44:45], v[44:45], 0, v[172:173]
	global_store_dwordx4 v[44:45], v[46:49], off
	s_nop 1
	v_div_scale_f32 v48, s[2:3], v33, v33, 1.0
	v_rcp_f32_e32 v49, v48
	v_lshlrev_b32_e32 v46, 16, v60
	v_and_b32_e32 v47, 0xffff0000, v60
	v_fma_f32 v50, -v48, v49, 1.0
	v_fmac_f32_e32 v49, v50, v49
	v_div_scale_f32 v50, vcc, 1.0, v33, 1.0
	v_mul_f32_e32 v51, v50, v49
	v_fma_f32 v60, -v48, v51, v50
	v_fmac_f32_e32 v51, v60, v49
	v_fma_f32 v48, -v48, v51, v50
	v_div_fmas_f32 v48, v48, v49, v51
	v_div_fixup_f32 v33, v48, v33, 1.0
	v_rcp_f32_e32 v49, v32
	s_nop 0
	v_mul_f32_e32 v51, 1.0, v49
	v_fma_f32 v60, -v32, v51, 1.0
	v_fmac_f32_e32 v51, v60, v49
	v_div_fixup_f32 v32, v51, v32, 1.0
	v_rcp_f32_e32 v49, v29
	s_nop 0
	v_pk_mul_f32 v[32:33], v[32:33], v[46:47]
	v_lshlrev_b32_e32 v46, 16, v62
	v_and_b32_e32 v47, 0xffff0000, v62
	v_mul_f32_e32 v51, 1.0, v49
	v_fma_f32 v60, -v29, v51, 1.0
	v_fmac_f32_e32 v51, v60, v49
	v_div_fixup_f32 v29, v51, v29, 1.0
	v_rcp_f32_e32 v49, v28
	s_nop 0
	v_mul_f32_e32 v51, 1.0, v49
	v_fma_f32 v60, -v28, v51, 1.0
	v_fmac_f32_e32 v51, v60, v49
	v_div_fixup_f32 v28, v51, v28, 1.0
	v_pk_mul_f32 v[46:47], v[28:29], v[46:47]
	v_add_f32_e32 v29, v30, v22
	v_mul_f32_e32 v29, 0xbfb8aa3b, v29
	v_add_f32_e32 v28, v34, v26
	v_exp_f32_e32 v30, v29
	v_add_f32_e32 v29, v35, v27
	v_mul_f32_e32 v28, 0xbfb8aa3b, v28
	v_mul_f32_e32 v29, 0xbfb8aa3b, v29
	v_exp_f32_e32 v28, v28
	v_exp_f32_e32 v29, v29
	v_lshlrev_b32_e32 v34, 16, v61
	v_and_b32_e32 v35, 0xffff0000, v61
	v_pk_add_f32 v[28:29], v[28:29], 1.0 op_sel_hi:[1,0]
	s_nop 0
	v_rcp_f32_e32 v49, v29
	s_nop 0
	v_mul_f32_e32 v51, 1.0, v49
	v_fma_f32 v60, -v29, v51, 1.0
	v_fmac_f32_e32 v51, v60, v49
	v_div_fixup_f32 v29, v51, v29, 1.0
	v_rcp_f32_e32 v49, v28
	s_nop 0
	v_mul_f32_e32 v51, 1.0, v49
	v_fma_f32 v60, -v28, v51, 1.0
	v_fmac_f32_e32 v51, v60, v49
	v_div_fixup_f32 v28, v51, v28, 1.0
	v_pk_mul_f32 v[34:35], v[28:29], v[34:35]
	v_add_f32_e32 v28, v31, v23
	v_mul_f32_e32 v28, 0xbfb8aa3b, v28
	v_exp_f32_e32 v31, v28
	v_lshlrev_b32_e32 v28, 16, v63
	v_and_b32_e32 v29, 0xffff0000, v63
	v_pk_add_f32 v[30:31], v[30:31], 1.0 op_sel_hi:[1,0]
	s_nop 0
	v_rcp_f32_e32 v49, v31
	s_nop 0
	v_mul_f32_e32 v51, 1.0, v49
	v_fma_f32 v60, -v31, v51, 1.0
	v_fmac_f32_e32 v51, v60, v49
	v_div_fixup_f32 v31, v51, v31, 1.0
	v_rcp_f32_e32 v49, v30
; DI void unpack8(u32x4 w, float* f) { f[0] = bflo(w.x); f[1] = bfhi(w.x); f[2] = bflo(w.y); f[3] = bfhi(w.y); f[4] = bflo(w.z); f[5] = bfhi(w.z); f[6] = bflo(w.w); f[7] = bfhi(w.w); }
; DI u32x4 pack44(f32x4 a, f32x4 b) { u32x4 w; w.x = pk2(a[0], a[1]); w.y = pk2(a[2], a[3]); w.z = pk2(b[0], b[1]); w.w = pk2(b[2], b[3]); return w; }
; DI float sigmoidf_(float x) { return 1.f / (1.f + __expf(-x)); }
; #define PG8_WAIT_V(n) asm volatile("s_waitcnt vmcnt(" #n ")" ::: "memory")
; #define PG8_BAR __builtin_amdgcn_s_barrier()
; template <class Epi, class Sched>
; DI void gemm_phase(LAS unsigned char* lds, const Gemm g, const Sched& S, const Epi& E) {
;     ...
;         if (!has_next) break;
; #pragma unroll
;         for (int a = 0; a < 2; ++a)
; #pragma unroll
;             for (int b = 0; b < 2; ++b)
; #pragma unroll
;                 for (int m = 0; m < 4; ++m)
; #pragma unroll
;                     for (int n = 0; n < 2; ++n) acc[a][b][m][n] = (f32x4){0.f, 0.f, 0.f, 0.f};
;         cur = nxt; cA = nA; cB = nB; ++ui;
;     }
;     PG8_WAIT_V(0);
;     if (wr == 0) PG8_BAR;
;     PG8_BAR;
;     DI void operator()(const Acc& acc, const Unit& u, int wr, int wc, int fr, int fq) const {
;     ...
;                 for (int mi = 0; mi < 2; ++mi)
; #pragma unroll
;                     for (int bj = 0; bj < 2; ++bj) { const int m = 2 * mp + mi, row = u.pm * 256 + ai * 128 + wr * 64 + m * 16 + fr, col = u.pn * 256 + bj * 128 + wc * 32 + 8 * fq;
;                         f32x4 v0 = acc[ai][bj][m][0], v1 = acc[ai][bj][m][1]; float zf[8]; unpack8(zv[mi][bj], zf);
;                         for (int j = 0; j < 4; ++j) { v0[j] = zf[j] * sigmoidf_(v0[j] + bv[bj][0][j]); v1[j] = zf[4 + j] * sigmoidf_(v1[j] + bv[bj][1][j]); }
;                         *(u32x4*)(y2 + (size_t)row * 1024 + col) = pack44(v0, v1); }
	s_nop 0
	v_mul_f32_e32 v51, 1.0, v49
	v_fma_f32 v60, -v30, v51, 1.0
	v_fmac_f32_e32 v51, v60, v49
	v_div_fixup_f32 v30, v51, v30, 1.0
	v_pk_mul_f32 v[48:49], v[30:31], v[28:29]
	v_cvt_pk_bf16_f32 v28, v32, v33
	v_cvt_pk_bf16_f32 v29, v34, v35
	v_cvt_pk_bf16_f32 v30, v46, v47
	v_cvt_pk_bf16_f32 v31, v48, v49
	global_store_dwordx4 v[44:45], v[28:31], off offset:256
	s_nop 1
	v_rcp_f32_e32 v31, v17
	s_nop 0
	v_lshlrev_b32_e32 v28, 16, v56
	v_and_b32_e32 v29, 0xffff0000, v56
	v_mul_f32_e32 v33, 1.0, v31
	v_fma_f32 v34, -v17, v33, 1.0
	v_fmac_f32_e32 v33, v34, v31
	v_div_fixup_f32 v17, v33, v17, 1.0
	v_rcp_f32_e32 v31, v16
	s_nop 0
	v_mul_f32_e32 v33, 1.0, v31
	v_fma_f32 v34, -v16, v33, 1.0
	v_fmac_f32_e32 v33, v34, v31
	v_div_fixup_f32 v16, v33, v16, 1.0
	v_rcp_f32_e32 v31, v13
	s_nop 0
	v_pk_mul_f32 v[16:17], v[16:17], v[28:29]
	v_lshlrev_b32_e32 v28, 16, v58
	v_and_b32_e32 v29, 0xffff0000, v58
	v_mul_f32_e32 v33, 1.0, v31
	v_fma_f32 v34, -v13, v33, 1.0
	v_fmac_f32_e32 v33, v34, v31
	v_div_fixup_f32 v13, v33, v13, 1.0
	v_rcp_f32_e32 v31, v12
	s_nop 0
	v_mul_f32_e32 v33, 1.0, v31
	v_fma_f32 v34, -v12, v33, 1.0
	v_fmac_f32_e32 v33, v34, v31
	v_div_fixup_f32 v12, v33, v12, 1.0
	v_rcp_f32_e32 v31, v19
	s_nop 0
	v_pk_mul_f32 v[12:13], v[12:13], v[28:29]
	v_lshlrev_b32_e32 v28, 16, v57
	v_and_b32_e32 v29, 0xffff0000, v57
	v_mul_f32_e32 v33, 1.0, v31
	v_fma_f32 v34, -v19, v33, 1.0
	v_fmac_f32_e32 v33, v34, v31
	v_div_fixup_f32 v19, v33, v19, 1.0
	v_rcp_f32_e32 v31, v18
	s_nop 0
	v_mul_f32_e32 v33, 1.0, v31
	v_fma_f32 v34, -v18, v33, 1.0
	v_fmac_f32_e32 v33, v34, v31
	v_div_fixup_f32 v18, v33, v18, 1.0
	v_rcp_f32_e32 v31, v15
	s_nop 0
	v_pk_mul_f32 v[18:19], v[18:19], v[28:29]
	v_lshlrev_b32_e32 v28, 16, v59
	v_and_b32_e32 v29, 0xffff0000, v59
	v_mul_f32_e32 v33, 1.0, v31
	v_fma_f32 v34, -v15, v33, 1.0
	v_fmac_f32_e32 v33, v34, v31
	v_div_fixup_f32 v15, v33, v15, 1.0
	v_rcp_f32_e32 v31, v14
	s_nop 0
	v_mul_f32_e32 v33, 1.0, v31
	v_fma_f32 v34, -v14, v33, 1.0
	v_fmac_f32_e32 v33, v34, v31
	v_div_fixup_f32 v14, v33, v14, 1.0
	v_pk_mul_f32 v[28:29], v[14:15], v[28:29]
	v_cvt_pk_bf16_f32 v14, v16, v17
	v_cvt_pk_bf16_f32 v16, v12, v13
	v_lshl_add_u64 v[12:13], s[68:69], 0, v[68:69]
	v_cvt_pk_bf16_f32 v15, v18, v19
	v_cvt_pk_bf16_f32 v17, v28, v29
	v_lshl_add_u64 v[12:13], v[12:13], 0, v[172:173]
	global_store_dwordx4 v[12:13], v[14:17], off
	s_nop 1
	v_rcp_f32_e32 v17, v9
	s_nop 0
	v_lshlrev_b32_e32 v14, 16, v52
	v_and_b32_e32 v15, 0xffff0000, v52
	v_mul_f32_e32 v19, 1.0, v17
	v_fma_f32 v20, -v9, v19, 1.0
	v_fmac_f32_e32 v19, v20, v17
	v_div_fixup_f32 v9, v19, v9, 1.0
	v_rcp_f32_e32 v17, v8
	s_nop 0
	v_mul_f32_e32 v19, 1.0, v17
	v_fma_f32 v20, -v8, v19, 1.0
	v_fmac_f32_e32 v19, v20, v17
	v_div_fixup_f32 v8, v19, v8, 1.0
	v_rcp_f32_e32 v17, v5
	s_nop 0
	v_pk_mul_f32 v[8:9], v[8:9], v[14:15]
	v_lshlrev_b32_e32 v14, 16, v54
	v_and_b32_e32 v15, 0xffff0000, v54
	v_mul_f32_e32 v19, 1.0, v17
	v_fma_f32 v20, -v5, v19, 1.0
	v_fmac_f32_e32 v19, v20, v17
	v_div_fixup_f32 v5, v19, v5, 1.0
	v_rcp_f32_e32 v17, v4
	s_nop 0
	v_mul_f32_e32 v19, 1.0, v17
	v_fma_f32 v20, -v4, v19, 1.0
	v_fmac_f32_e32 v19, v20, v17
	v_div_fixup_f32 v4, v19, v4, 1.0
	v_pk_mul_f32 v[14:15], v[4:5], v[14:15]
	v_add_f32_e32 v5, v6, v22
	v_mul_f32_e32 v5, 0xbfb8aa3b, v5
	v_add_f32_e32 v4, v10, v26
	v_exp_f32_e32 v6, v5
	v_add_f32_e32 v5, v11, v27
	v_mul_f32_e32 v4, 0xbfb8aa3b, v4
	v_mul_f32_e32 v5, 0xbfb8aa3b, v5
	v_exp_f32_e32 v4, v4
	v_exp_f32_e32 v5, v5
	v_lshlrev_b32_e32 v10, 16, v53
	v_and_b32_e32 v11, 0xffff0000, v53
	v_pk_add_f32 v[4:5], v[4:5], 1.0 op_sel_hi:[1,0]
	s_nop 0
	v_rcp_f32_e32 v17, v5
	s_nop 0
	v_mul_f32_e32 v19, 1.0, v17
	v_fma_f32 v20, -v5, v19, 1.0
	v_fmac_f32_e32 v19, v20, v17
	v_div_fixup_f32 v5, v19, v5, 1.0
	v_rcp_f32_e32 v17, v4
	s_nop 0
	v_mul_f32_e32 v19, 1.0, v17
	v_fma_f32 v20, -v4, v19, 1.0
	v_fmac_f32_e32 v19, v20, v17
	v_div_fixup_f32 v4, v19, v4, 1.0
	v_pk_mul_f32 v[10:11], v[4:5], v[10:11]
	v_add_f32_e32 v4, v7, v23
	v_mul_f32_e32 v4, 0xbfb8aa3b, v4
	v_exp_f32_e32 v7, v4
	v_lshlrev_b32_e32 v4, 16, v55
	v_and_b32_e32 v5, 0xffff0000, v55
	v_pk_add_f32 v[6:7], v[6:7], 1.0 op_sel_hi:[1,0]
	s_nop 0
	v_rcp_f32_e32 v17, v7
	s_nop 0
	v_mul_f32_e32 v19, 1.0, v17
	v_fma_f32 v20, -v7, v19, 1.0
	v_fmac_f32_e32 v19, v20, v17
	v_div_fixup_f32 v7, v19, v7, 1.0
	v_rcp_f32_e32 v17, v6
	s_nop 0
	s_mov_b64 s[2:3], s[36:37]
	v_mul_f32_e32 v19, 1.0, v17
	v_fma_f32 v20, -v6, v19, 1.0
	v_fmac_f32_e32 v19, v20, v17
	v_div_fixup_f32 v6, v19, v6, 1.0
	v_pk_mul_f32 v[16:17], v[6:7], v[4:5]
	v_cvt_pk_bf16_f32 v4, v8, v9
	v_cvt_pk_bf16_f32 v5, v10, v11
	v_cvt_pk_bf16_f32 v6, v14, v15
	v_cvt_pk_bf16_f32 v7, v16, v17
	s_and_b64 vcc, exec, s[22:23]
	global_store_dwordx4 v[12:13], v[4:7], off offset:256
	s_cbranch_vccz .LBB0_130
	s_waitcnt vmcnt(0)
	s_cmpk_gt_u32 s41, 0xff
	s_cbranch_scc1 .LBB0_141
	s_barrier

.LBB0_362:
	s_cmp_lt_u32 s37, 64
	s_cselect_b64 vcc, -1, 0
	s_cmpk_lt_u32 s37, 0x80
	s_cselect_b64 s[30:31], -1, 0
	s_cmpk_lt_u32 s37, 0xc0
	s_cselect_b64 s[34:35], -1, 0
	v_cndmask_b32_e64 v0, v234, v233, s[34:35]
	s_cmpk_gt_u32 s37, 0xfd
	v_cndmask_b32_e64 v0, v0, v232, s[30:31]
	s_cselect_b64 s[20:21], -1, 0
	s_add_i32 s36, s37, 2
	v_cndmask_b32_e32 v0, v0, v231, vcc
	s_cmpk_lt_u32 s37, 0xfe
	v_readlane_b32 s2, v0, s37
	s_cselect_b32 s38, s36, 0xff
	s_and_saveexec_b64 s[30:31], s[22:23]
	s_cbranch_execz .LBB0_372
	ds_read_b128 v[4:7], v203
	ds_read_b128 v[8:11], v203 offset:1024
	ds_read_b128 v[12:15], v203 offset:2048
	ds_read_b128 v[16:19], v203 offset:3072
	ds_read_b128 v[20:23], v203 offset:4096
	ds_read_b128 v[24:27], v203 offset:5120
	ds_read_b128 v[28:31], v203 offset:6144
	s_and_saveexec_b64 s[34:35], s[26:27]
	s_xor_b64 s[34:35], exec, s[34:35]
	s_cbranch_execz .LBB0_365
	s_waitcnt vmcnt(24)

.LBB0_367:
	s_or_b64 exec, exec, s[34:35]
	s_mul_i32 s56, s38, 0xe000
	s_waitcnt lgkmcnt(6)
	v_mfma_f32_32x32x16_bf16 v[48:63], v[72:75], v[4:7], 0
	ds_read_b128 v[4:7], v203 offset:7168
	s_waitcnt lgkmcnt(6)
	v_mfma_f32_32x32x16_bf16 v[48:63], v[68:71], v[8:11], v[48:63]
	s_waitcnt lgkmcnt(5)
	v_mfma_f32_32x32x16_bf16 v[48:63], v[88:91], v[12:15], v[48:63]
	s_waitcnt lgkmcnt(4)
	v_mfma_f32_32x32x16_bf16 v[48:63], v[84:87], v[16:19], v[48:63]
	s_waitcnt lgkmcnt(3)
	v_mfma_f32_32x32x16_bf16 v[48:63], v[100:103], v[20:23], v[48:63]
	s_waitcnt lgkmcnt(2)
	v_mfma_f32_32x32x16_bf16 v[48:63], v[92:95], v[24:27], v[48:63]
	s_waitcnt lgkmcnt(1)
	v_mfma_f32_32x32x16_bf16 v[48:63], v[152:155], v[28:31], v[48:63]
	s_waitcnt lgkmcnt(0)
	v_mfma_f32_32x32x16_bf16 v[48:63], v[144:147], v[4:7], v[48:63]
	v_lshl_add_u64 v[4:5], v[206:207], 0, s[56:57]
	global_load_dwordx4 v[72:75], v[4:5], off
	v_lshl_add_u64 v[6:7], v[4:5], 0, s[48:49]
	global_load_dwordx4 v[68:71], v[6:7], off
	v_lshl_add_u64 v[6:7], v[4:5], 0, s[50:51]
	global_load_dwordx4 v[88:91], v[6:7], off
	v_lshl_add_u64 v[6:7], v[4:5], 0, s[52:53]
	global_load_dwordx4 v[84:87], v[6:7], off
	v_lshl_add_u64 v[6:7], v[4:5], 0, s[42:43]
	global_load_dwordx4 v[100:103], v[6:7], off
	v_lshl_add_u64 v[6:7], v[4:5], 0, s[58:59]
	global_load_dwordx4 v[92:95], v[6:7], off
	v_lshl_add_u64 v[6:7], v[4:5], 0, s[44:45]
	global_load_dwordx4 v[152:155], v[6:7], off
	v_lshl_add_u64 v[4:5], v[4:5], 0, s[60:61]
	global_load_dwordx4 v[144:147], v[4:5], off
	s_and_saveexec_b64 s[34:35], s[26:27]
	s_xor_b64 s[34:35], exec, s[34:35]
	s_cbranch_execnz .LBB0_405
	s_andn2_saveexec_b64 s[34:35], s[34:35]
	s_cbranch_execnz .LBB0_406

.LBB0_372:
	s_or_b64 exec, exec, s[30:31]
	s_waitcnt lgkmcnt(0)
	s_barrier
	s_and_saveexec_b64 s[30:31], s[22:23]
	s_cbranch_execz .LBB0_384
	ds_read_b128 v[4:7], v203 offset:8192
	ds_read_b128 v[8:11], v203 offset:9216
	ds_read_b128 v[12:15], v203 offset:10240
	ds_read_b128 v[16:19], v203 offset:11264
	v_pk_mul_f32 v[46:47], v[46:47], s[2:3] op_sel_hi:[1,0]
	v_pk_mul_f32 v[44:45], v[44:45], s[2:3] op_sel_hi:[1,0]
	v_pk_mul_f32 v[42:43], v[42:43], s[2:3] op_sel_hi:[1,0]
	v_pk_mul_f32 v[40:41], v[40:41], s[2:3] op_sel_hi:[1,0]
	v_pk_mul_f32 v[38:39], v[38:39], s[2:3] op_sel_hi:[1,0]
	v_pk_mul_f32 v[36:37], v[36:37], s[2:3] op_sel_hi:[1,0]
	v_pk_mul_f32 v[34:35], v[34:35], s[2:3] op_sel_hi:[1,0]
	v_pk_mul_f32 v[32:33], v[32:33], s[2:3] op_sel_hi:[1,0]
	s_waitcnt lgkmcnt(3)
	s_nop 0
	v_mfma_f32_32x32x16_bf16 v[32:47], v[112:115], v[4:7], v[32:47]
	s_and_saveexec_b64 s[2:3], s[24:25]
	v_mfma_f32_32x32x16_bf16 v[48:63], v[120:123], v[4:7], v[48:63]
	s_or_b64 exec, exec, s[2:3]
	s_waitcnt lgkmcnt(2)
	v_mfma_f32_32x32x16_bf16 v[32:47], v[104:107], v[8:11], v[32:47]
	s_and_saveexec_b64 s[2:3], s[24:25]
	v_mfma_f32_32x32x16_bf16 v[48:63], v[108:111], v[8:11], v[48:63]
	s_or_b64 exec, exec, s[2:3]
	s_waitcnt lgkmcnt(1)
	v_mfma_f32_32x32x16_bf16 v[32:47], v[80:83], v[12:15], v[32:47]
	s_and_saveexec_b64 s[2:3], s[24:25]
	v_mfma_f32_32x32x16_bf16 v[48:63], v[96:99], v[12:15], v[48:63]
	s_or_b64 exec, exec, s[2:3]
	s_waitcnt lgkmcnt(0)
	v_mfma_f32_32x32x16_bf16 v[32:47], v[64:67], v[16:19], v[32:47]
	s_and_saveexec_b64 s[2:3], s[24:25]
	v_mfma_f32_32x32x16_bf16 v[48:63], v[76:79], v[16:19], v[48:63]
	s_or_b64 exec, exec, s[2:3]
	v_mov_b32_e32 v1, 0xe000
	v_mad_u64_u32 v[4:5], s[2:3], s38, v1, v[208:209]
	v_mad_u64_u32 v[6:7], s[2:3], v202, s38, v[204:205]
	global_load_dwordx4 v[112:115], v[4:5], off
	s_mov_b64 s[2:3], 0x400
	s_nop 0
	v_lshl_add_u64 v[8:9], v[4:5], 0, s[2:3]
	global_load_dwordx4 v[104:107], v[8:9], off
	s_mov_b64 s[34:35], 0x800
	v_lshl_add_u64 v[8:9], v[4:5], 0, s[34:35]
	global_load_dwordx4 v[80:83], v[8:9], off
	s_mov_b64 s[38:39], 0xc00
	v_lshl_add_u64 v[4:5], v[4:5], 0, s[38:39]
	global_load_dwordx4 v[64:67], v[4:5], off
	global_load_dwordx4 v[120:123], v[6:7], off
	v_lshl_add_u64 v[4:5], v[6:7], 0, s[2:3]
	global_load_dwordx4 v[108:111], v[4:5], off
	v_lshl_add_u64 v[4:5], v[6:7], 0, s[34:35]
	global_load_dwordx4 v[96:99], v[4:5], off
	v_lshl_add_u64 v[4:5], v[6:7], 0, s[38:39]
	global_load_dwordx4 v[76:79], v[4:5], off
	s_mov_b64 s[48:49], 0x400
	s_mov_b64 s[50:51], 0x800
	s_mov_b64 s[52:53], 0xc00
	s_and_saveexec_b64 s[2:3], s[24:25]
	s_cbranch_execz .LBB0_383
	v_cvt_pk_bf16_f32 v1, v48, s0
	v_add_u32_e32 v2, v235, v237
	ds_write_b16 v2, v1 offset:12288
	v_cvt_pk_bf16_f32 v1, v49, s0
	ds_write_b16 v2, v1 offset:12368
	v_cvt_pk_bf16_f32 v1, v50, s0
	ds_write_b16 v2, v1 offset:12448
	v_cvt_pk_bf16_f32 v1, v51, s0
	ds_write_b16 v2, v1 offset:12528
	v_cvt_pk_bf16_f32 v1, v52, s0
	ds_write_b16 v2, v1 offset:12928
	v_cvt_pk_bf16_f32 v1, v53, s0
	ds_write_b16 v2, v1 offset:13008
	v_cvt_pk_bf16_f32 v1, v54, s0
	ds_write_b16 v2, v1 offset:13088
	v_cvt_pk_bf16_f32 v1, v55, s0
	ds_write_b16 v2, v1 offset:13168
	v_cvt_pk_bf16_f32 v1, v56, s0
	ds_write_b16 v2, v1 offset:13568
	v_cvt_pk_bf16_f32 v1, v57, s0
	ds_write_b16 v2, v1 offset:13648
	v_cvt_pk_bf16_f32 v1, v58, s0
	ds_write_b16 v2, v1 offset:13728
	v_cvt_pk_bf16_f32 v1, v59, s0
	ds_write_b16 v2, v1 offset:13808
	v_cvt_pk_bf16_f32 v1, v60, s0
	ds_write_b16 v2, v1 offset:14208
	v_cvt_pk_bf16_f32 v1, v61, s0
	ds_write_b16 v2, v1 offset:14288
	v_cvt_pk_bf16_f32 v1, v62, s0
	ds_write_b16 v2, v1 offset:14368
	v_cvt_pk_bf16_f32 v1, v63, s0
	ds_write_b16 v2, v1 offset:14448
	v_add_u32_e32 v1, v236, v238
	ds_read_b128 v[4:7], v1 offset:12288
	v_mov_b32_e32 v213, v3
	v_lshlrev_b64 v[8:9], 11, v[212:213]
	v_lshl_add_u64 v[12:13], v[210:211], 0, v[8:9]
	ds_read_b128 v[8:11], v1 offset:13568
	v_add_u32_e32 v2, 16, v212
	s_waitcnt lgkmcnt(1)
	global_store_dwordx4 v[12:13], v[4:7], off
	s_nop 1
	v_lshlrev_b64 v[4:5], 11, v[2:3]
	v_lshl_add_u64 v[4:5], v[210:211], 0, v[4:5]
	s_waitcnt lgkmcnt(0)
	global_store_dwordx4 v[4:5], v[8:11], off

.LBB0_384:
	s_or_b64 exec, exec, s[30:31]
	s_waitcnt lgkmcnt(0)
	s_barrier
	s_min_u32 s3, s37, 0xfc
	s_add_i32 s2, s37, 1
	v_readlane_b32 s2, v0, s2
	s_add_i32 s37, s3, 3
	s_mul_i32 s56, s37, 0xe000
	s_and_saveexec_b64 s[30:31], s[22:23]
	s_cbranch_execz .LBB0_394
	ds_read_b128 v[4:7], v203
	ds_read_b128 v[8:11], v203 offset:1024
	ds_read_b128 v[12:15], v203 offset:2048
	ds_read_b128 v[16:19], v203 offset:3072
	ds_read_b128 v[20:23], v203 offset:4096
	ds_read_b128 v[24:27], v203 offset:5120
	ds_read_b128 v[28:31], v203 offset:6144
	s_and_saveexec_b64 s[34:35], s[26:27]
	s_xor_b64 s[34:35], exec, s[34:35]
	s_cbranch_execz .LBB0_387
	s_waitcnt vmcnt(24)

.LBB0_389:
	s_or_b64 exec, exec, s[34:35]
	v_lshl_add_u64 v[0:1], v[206:207], 0, s[56:57]
	s_waitcnt lgkmcnt(6)
	v_mfma_f32_32x32x16_bf16 v[48:63], v[128:131], v[4:7], 0
	ds_read_b128 v[4:7], v203 offset:7168
	s_waitcnt lgkmcnt(6)
	v_mfma_f32_32x32x16_bf16 v[48:63], v[124:127], v[8:11], v[48:63]
	s_waitcnt lgkmcnt(5)
	v_mfma_f32_32x32x16_bf16 v[48:63], v[148:151], v[12:15], v[48:63]
	s_waitcnt lgkmcnt(4)
	v_mfma_f32_32x32x16_bf16 v[48:63], v[132:135], v[16:19], v[48:63]
	s_waitcnt lgkmcnt(3)
	v_mfma_f32_32x32x16_bf16 v[48:63], v[160:163], v[20:23], v[48:63]
	s_waitcnt lgkmcnt(2)
	v_mfma_f32_32x32x16_bf16 v[48:63], v[156:159], v[24:27], v[48:63]
	s_waitcnt lgkmcnt(1)
	v_mfma_f32_32x32x16_bf16 v[48:63], v[188:191], v[28:31], v[48:63]
	s_waitcnt lgkmcnt(0)
	v_mfma_f32_32x32x16_bf16 v[48:63], v[184:187], v[4:7], v[48:63]
	global_load_dwordx4 v[128:131], v[0:1], off
	v_lshl_add_u64 v[4:5], v[0:1], 0, s[48:49]
	global_load_dwordx4 v[124:127], v[4:5], off
	v_lshl_add_u64 v[4:5], v[0:1], 0, s[50:51]
	global_load_dwordx4 v[148:151], v[4:5], off
	v_lshl_add_u64 v[4:5], v[0:1], 0, s[52:53]
	global_load_dwordx4 v[132:135], v[4:5], off
	v_lshl_add_u64 v[4:5], v[0:1], 0, s[42:43]
	global_load_dwordx4 v[160:163], v[4:5], off
	v_lshl_add_u64 v[4:5], v[0:1], 0, s[58:59]
	global_load_dwordx4 v[156:159], v[4:5], off
	v_lshl_add_u64 v[4:5], v[0:1], 0, s[44:45]
	global_load_dwordx4 v[188:191], v[4:5], off
	v_lshl_add_u64 v[0:1], v[0:1], 0, s[60:61]
	global_load_dwordx4 v[184:187], v[0:1], off
	s_and_saveexec_b64 s[34:35], s[26:27]
	s_xor_b64 s[34:35], exec, s[34:35]
	s_cbranch_execnz .LBB0_407
	s_andn2_saveexec_b64 s[34:35], s[34:35]
	s_cbranch_execnz .LBB0_408

.LBB0_394:
	s_or_b64 exec, exec, s[30:31]
	s_waitcnt lgkmcnt(0)
	s_barrier
	s_and_saveexec_b64 s[30:31], s[22:23]
	s_cbranch_execz .LBB0_361
	ds_read_b128 v[4:7], v203 offset:8192
	ds_read_b128 v[8:11], v203 offset:9216
	ds_read_b128 v[12:15], v203 offset:10240
	ds_read_b128 v[16:19], v203 offset:11264
	v_pk_mul_f32 v[46:47], v[46:47], s[2:3] op_sel_hi:[1,0]
	v_pk_mul_f32 v[44:45], v[44:45], s[2:3] op_sel_hi:[1,0]
	v_pk_mul_f32 v[42:43], v[42:43], s[2:3] op_sel_hi:[1,0]
	v_pk_mul_f32 v[40:41], v[40:41], s[2:3] op_sel_hi:[1,0]
	v_pk_mul_f32 v[38:39], v[38:39], s[2:3] op_sel_hi:[1,0]
	v_pk_mul_f32 v[36:37], v[36:37], s[2:3] op_sel_hi:[1,0]
	v_pk_mul_f32 v[34:35], v[34:35], s[2:3] op_sel_hi:[1,0]
	v_pk_mul_f32 v[32:33], v[32:33], s[2:3] op_sel_hi:[1,0]
	s_waitcnt lgkmcnt(3)
	s_nop 0
	v_mfma_f32_32x32x16_bf16 v[32:47], v[176:179], v[4:7], v[32:47]
	s_and_saveexec_b64 s[2:3], s[24:25]
	v_mfma_f32_32x32x16_bf16 v[48:63], v[180:183], v[4:7], v[48:63]
	s_or_b64 exec, exec, s[2:3]
	s_waitcnt lgkmcnt(2)
	v_mfma_f32_32x32x16_bf16 v[32:47], v[168:171], v[8:11], v[32:47]
	s_and_saveexec_b64 s[2:3], s[24:25]
	v_mfma_f32_32x32x16_bf16 v[48:63], v[172:175], v[8:11], v[48:63]
	s_or_b64 exec, exec, s[2:3]
	s_waitcnt lgkmcnt(1)
	v_mfma_f32_32x32x16_bf16 v[32:47], v[136:139], v[12:15], v[32:47]
	s_and_saveexec_b64 s[2:3], s[24:25]
	v_mfma_f32_32x32x16_bf16 v[48:63], v[164:167], v[12:15], v[48:63]
	s_or_b64 exec, exec, s[2:3]
	s_waitcnt lgkmcnt(0)
	v_mfma_f32_32x32x16_bf16 v[32:47], v[116:119], v[16:19], v[32:47]
	s_and_saveexec_b64 s[2:3], s[24:25]
	v_mfma_f32_32x32x16_bf16 v[48:63], v[140:143], v[16:19], v[48:63]
	s_or_b64 exec, exec, s[2:3]
	v_mad_u64_u32 v[4:5], s[2:3], v202, s37, v[204:205]
	v_lshl_add_u64 v[0:1], v[208:209], 0, s[56:57]
	global_load_dwordx4 v[176:179], v[0:1], off
	s_mov_b64 s[2:3], 0x400
	v_lshl_add_u64 v[6:7], v[0:1], 0, s[2:3]
	global_load_dwordx4 v[168:171], v[6:7], off
	s_mov_b64 s[34:35], 0x800
	v_lshl_add_u64 v[6:7], v[0:1], 0, s[34:35]
	global_load_dwordx4 v[136:139], v[6:7], off
	s_mov_b64 s[38:39], 0xc00
	v_lshl_add_u64 v[0:1], v[0:1], 0, s[38:39]
	global_load_dwordx4 v[116:119], v[0:1], off
	global_load_dwordx4 v[180:183], v[4:5], off
	v_lshl_add_u64 v[0:1], v[4:5], 0, s[2:3]
	global_load_dwordx4 v[172:175], v[0:1], off
	v_lshl_add_u64 v[0:1], v[4:5], 0, s[34:35]
	global_load_dwordx4 v[164:167], v[0:1], off
	v_lshl_add_u64 v[0:1], v[4:5], 0, s[38:39]
	global_load_dwordx4 v[140:143], v[0:1], off
	s_mov_b64 s[48:49], 0x400
	s_mov_b64 s[50:51], 0x800
	s_mov_b64 s[52:53], 0xc00
	s_and_saveexec_b64 s[2:3], s[24:25]
	s_cbranch_execz .LBB0_360
	v_cvt_pk_bf16_f32 v0, v48, s0
	v_add_u32_e32 v1, v235, v237
	ds_write_b16 v1, v0 offset:12288
	v_cvt_pk_bf16_f32 v0, v49, s0
	ds_write_b16 v1, v0 offset:12368
	v_cvt_pk_bf16_f32 v0, v50, s0
	ds_write_b16 v1, v0 offset:12448
	v_cvt_pk_bf16_f32 v0, v51, s0
	ds_write_b16 v1, v0 offset:12528
	v_cvt_pk_bf16_f32 v0, v52, s0
	ds_write_b16 v1, v0 offset:12928
	v_cvt_pk_bf16_f32 v0, v53, s0
	ds_write_b16 v1, v0 offset:13008
	v_cvt_pk_bf16_f32 v0, v54, s0
	ds_write_b16 v1, v0 offset:13088
	v_cvt_pk_bf16_f32 v0, v55, s0
	ds_write_b16 v1, v0 offset:13168
	v_cvt_pk_bf16_f32 v0, v56, s0
	ds_write_b16 v1, v0 offset:13568
	v_cvt_pk_bf16_f32 v0, v57, s0
	ds_write_b16 v1, v0 offset:13648
	v_cvt_pk_bf16_f32 v0, v58, s0
	ds_write_b16 v1, v0 offset:13728
	v_cvt_pk_bf16_f32 v0, v59, s0
	ds_write_b16 v1, v0 offset:13808
	v_cvt_pk_bf16_f32 v0, v60, s0
	ds_write_b16 v1, v0 offset:14208
	v_cvt_pk_bf16_f32 v0, v61, s0
	ds_write_b16 v1, v0 offset:14288
	v_cvt_pk_bf16_f32 v0, v62, s0
	ds_write_b16 v1, v0 offset:14368
	v_cvt_pk_bf16_f32 v0, v63, s0
	ds_write_b16 v1, v0 offset:14448
	v_add_u32_e32 v0, v236, v238
	ds_read_b128 v[4:7], v0 offset:12288
	ds_read_b128 v[8:11], v0 offset:13568
	s_waitcnt lgkmcnt(1)
	global_store_dwordx4 v[216:217], v[4:7], off
	s_waitcnt lgkmcnt(0)
	global_store_dwordx4 v[214:215], v[8:11], off
	s_branch .LBB0_360

; DI void gdn_intra(LAS unsigned char* lds, PP p, int l, int first, int stride) {
;     ...
;         const float bl = LG0, al = LG1;
;         const float beta = 1.f / (1.f + __expf(-bl));
;         const float xx = al + p->in[17][l * 8 + hd];
;         const float ex = __expf(fminf(xx, 20.f));
;         const float sp = xx > 20.f ? xx : (ex < 0.05f ? ex * (1.f - ex * (0.5f - ex * (0.33333333f - ex * 0.25f))) : __logf(1.f + ex));
;         float gc = -__expf(p->in[16][l * 8 + hd]) * sp;
; #pragma unroll
;         for (int off = 1; off < 64; off <<= 1) { const float t = __shfl_up(gc, off); if (tid >= off) gc += t; }
;         const float gl = __shfl(gc, 63);
;         scb[tid] = beta; scg[tid] = gc; sce[tid] = __expf(gc); scl[tid] = __expf(gl - gc);
;         if (tid == 0) ((float*)(p->ws + O_GL))[hd * 256 + n] = __expf(gl);
.LBB0_428:
	s_or_b64 exec, exec, s[26:27]
	v_mul_f32_e32 v2, 0xbfb8aa3b, v135
	v_exp_f32_e32 v2, v2
	s_nop 0
	v_add_f32_e32 v2, 1.0, v2
	v_rcp_f32_e32 v5, v2
	s_nop 0
	s_load_dwordx2 s[24:25], s[0:1], 0x80
	v_mul_f32_e32 v7, 1.0, v5
	v_fma_f32 v8, -v2, v7, 1.0
	v_fmac_f32_e32 v7, v8, v5
	s_waitcnt lgkmcnt(0)
	s_add_u32 s20, s24, s20
	s_addc_u32 s21, s25, s21
	v_div_fixup_f32 v2, v7, v2, 1.0
	global_load_dword v4, v3, s[20:21]
	v_and_b32_e32 v6, 64, v220
	v_add_u32_e32 v7, -1, v220
	v_cmp_lt_i32_e32 vcc, v7, v6
	s_waitcnt vmcnt(0)
	v_mul_f32_e32 v4, 0x3fb8aa3b, v4
	v_exp_f32_e32 v4, v4
	v_cndmask_b32_e32 v7, v7, v220, vcc
	v_lshlrev_b32_e32 v7, 2, v7
	v_cmp_gt_i32_e32 vcc, 1, v138
	v_mul_f32_e64 v5, v1, -v4
	ds_bpermute_b32 v7, v7, v5
	s_waitcnt lgkmcnt(0)
	v_fma_f32 v1, v1, -v4, v7
	v_add_u32_e32 v4, -2, v220
	v_cndmask_b32_e32 v1, v1, v5, vcc
	v_cmp_lt_i32_e32 vcc, v4, v6
	v_lshlrev_b32_e32 v5, 2, v138
	s_nop 0
	v_cndmask_b32_e32 v4, v4, v220, vcc
	v_lshlrev_b32_e32 v4, 2, v4
	ds_bpermute_b32 v4, v4, v1
	v_cmp_gt_i32_e32 vcc, 2, v138
	s_waitcnt lgkmcnt(0)
	v_add_f32_e32 v4, v1, v4
	v_cndmask_b32_e32 v1, v4, v1, vcc
	v_add_u32_e32 v4, -4, v220
	v_cmp_lt_i32_e32 vcc, v4, v6
	s_nop 1
	v_cndmask_b32_e32 v4, v4, v220, vcc
	v_lshlrev_b32_e32 v4, 2, v4
	ds_bpermute_b32 v4, v4, v1
	v_cmp_gt_i32_e32 vcc, 4, v138
	s_waitcnt lgkmcnt(0)
	v_add_f32_e32 v4, v1, v4
	v_cndmask_b32_e32 v1, v4, v1, vcc
	v_add_u32_e32 v4, -8, v220
	v_cmp_lt_i32_e32 vcc, v4, v6
	s_nop 1
	v_cndmask_b32_e32 v4, v4, v220, vcc
	v_lshlrev_b32_e32 v4, 2, v4
	ds_bpermute_b32 v4, v4, v1
	v_cmp_gt_i32_e32 vcc, 8, v138
	s_waitcnt lgkmcnt(0)
	v_add_f32_e32 v4, v1, v4
	v_cndmask_b32_e32 v1, v4, v1, vcc
	v_add_u32_e32 v4, -16, v220
	v_cmp_lt_i32_e32 vcc, v4, v6
	s_nop 1
	v_cndmask_b32_e32 v4, v4, v220, vcc
	v_lshlrev_b32_e32 v4, 2, v4
	ds_bpermute_b32 v4, v4, v1
	v_cmp_gt_i32_e32 vcc, 16, v138
	s_waitcnt lgkmcnt(0)
	v_add_f32_e32 v4, v1, v4
	v_cndmask_b32_e32 v1, v4, v1, vcc
	v_subrev_u32_e32 v4, 32, v220
	v_cmp_lt_i32_e32 vcc, v4, v6
	v_add_u32_e32 v6, v23, v5
	ds_write_b32 v6, v2
	v_cndmask_b32_e32 v4, v4, v220, vcc
	v_lshlrev_b32_e32 v4, 2, v4
	ds_bpermute_b32 v4, v4, v1
	v_cmp_gt_i32_e32 vcc, 32, v138
	v_add_u32_e32 v2, v22, v5
	v_add_u32_e32 v6, v35, v5
	s_waitcnt lgkmcnt(0)
	v_add_f32_e32 v4, v1, v4
	v_cndmask_b32_e32 v4, v4, v1, vcc
	v_bfrev_b32_e32 v1, 0.5
	v_lshl_or_b32 v1, v220, 2, v1
	ds_bpermute_b32 v1, v1, v4
	ds_write_b32 v2, v4
	v_mul_f32_e32 v2, 0x3fb8aa3b, v4
	v_exp_f32_e32 v2, v2
	v_cmp_eq_u32_e32 vcc, 0, v138
	ds_write_b32 v6, v2
	s_waitcnt lgkmcnt(2)
	v_sub_f32_e32 v2, v1, v4
	v_mul_f32_e32 v2, 0x3fb8aa3b, v2
	v_exp_f32_e32 v2, v2
	v_add_u32_e32 v4, v30, v5
	ds_write_b32 v4, v2
	s_and_b64 exec, exec, vcc
	s_cbranch_execz .LBB0_430
	v_mul_f32_e32 v1, 0x3fb8aa3b, v1
	v_exp_f32_e32 v1, v1
	s_lshl_b64 s[20:21], s[54:55], 2
	s_add_u32 s20, s82, s20
	s_addc_u32 s21, s83, s21
	global_store_dword v3, v1, s[20:21]

; #define LAS __attribute__((address_space(3)))
; DI unsigned pk2(float lo, float hi) { f32x2 v = {lo, hi}; bf2_t b = __builtin_convertvector(v, bf2_t); return __builtin_bit_cast(unsigned, b); }
; DI void unpack8(u32x4 w, float* f) { f[0] = bflo(w.x); f[1] = bfhi(w.x); f[2] = bflo(w.y); f[3] = bfhi(w.y); f[4] = bflo(w.z); f[5] = bfhi(w.z); f[6] = bflo(w.w); f[7] = bfhi(w.w); }
; DI u32x4 pack8(const float* f) { u32x4 w; w.x = pk2(f[0], f[1]); w.y = pk2(f[2], f[3]); w.z = pk2(f[4], f[5]); w.w = pk2(f[6], f[7]); return w; }
; DI void gdn_intra(LAS unsigned char* lds, PP p, int l, int first, int stride) {
;     ...
;             const int id = tid + NTHR * it, j = id >> 4, o = id & 15;
;             float a[8];
; #pragma unroll
;             for (int i = 0; i < 8; ++i) a[i] = 0.f;
; #pragma unroll
;             for (int kk = 0; kk < 4; ++kk) { const bool ok = tok0 + j - 3 + kk >= 0;
;                 float x[8]; unpack8(R[(mat * 2 + it) * 4 + kk], x);
;                 const f32x4 w0 = *(const LAS f32x4*)(CW + kk * 384 + mat * 128 + o * 8), w1 = *(const LAS f32x4*)(CW + kk * 384 + mat * 128 + o * 8 + 4);
;                 for (int i = 0; i < 4; ++i) { a[i] += ok ? w0[i] * x[i] : 0.f; a[4 + i] += ok ? w1[i] * x[4 + i] : 0.f; } }
; #pragma unroll
;             for (int i = 0; i < 8; ++i) a[i] = a[i] / (1.f + __expf(-a[i]));
;             if (mat < 2) {
;                 float ss = 0.f;
; #pragma unroll
;                 for (int i = 0; i < 8; ++i) ss += a[i] * a[i];
;                 ss += __shfl_xor(ss, 1); ss += __shfl_xor(ss, 2); ss += __shfl_xor(ss, 4); ss += __shfl_xor(ss, 8);
;                 const float sc = rsqrtf(ss + 1e-6f) * (mat == 0 ? 0.08838834764831845f : 1.f);
; #pragma unroll
;                 for (int i = 0; i < 8; ++i) a[i] *= sc;
;             }
;             if (mat == 0) {
;                 *(LAS u32x4*)(Qn + j * 136 + o * 8) = pack8(a);
;                 const float eg = sce[j]; const int ct = j >> 5, s = o >> 1, part = o & 1;
;                 unsigned char* q0 = fb + 16384 + ((size_t)((ct * 8 + s) * 64 + (j & 31))) * 16 + 8 * part;
;                 u32x2 lo, hi2; lo.x = pk2(a[0] * eg, a[1] * eg); lo.y = pk2(a[2] * eg, a[3] * eg); hi2.x = pk2(a[4] * eg, a[5] * eg); hi2.y = pk2(a[6] * eg, a[7] * eg);
;                 *(u32x2*)q0 = lo; *(u32x2*)(q0 + 32 * 16) = hi2;
.LBB0_484:
	s_or_b64 exec, exec, s[2:3]
	s_mul_i32 s3, s54, 0xe000
	s_mul_hi_i32 s2, s54, 0xe000
	s_add_u32 s58, s56, s3
	v_lshlrev_b32_e32 v25, 3, v138
	s_addc_u32 s59, s60, s2
	v_and_b32_e32 v2, 8, v25
	s_waitcnt lgkmcnt(1)
	v_lshl_add_u64 v[12:13], s[58:59], 0, v[2:3]
	v_add_f32_e32 v2, v0, v11
	v_mul_f32_e32 v0, 0xbfb8aa3b, v2
	s_waitcnt lgkmcnt(0)
	v_and_b32_e32 v18, 64, v220
	s_mov_b64 s[2:3], 0x4000
	v_exp_f32_e32 v1, v0
	v_mul_f32_e32 v0, 0xbfb8aa3b, v4
	v_xor_b32_e32 v11, 1, v220
	v_add_u32_e32 v18, 64, v18
	v_and_b32_e32 v143, 0x1c0, v20
	v_lshl_add_u64 v[20:21], v[12:13], 0, s[2:3]
	v_exp_f32_e32 v12, v0
	v_mul_f32_e32 v0, 0xbfb8aa3b, v5
	v_cmp_lt_i32_e32 vcc, v11, v18
	v_exp_f32_e32 v13, v0
	v_mul_f32_e32 v0, 0xbfb8aa3b, v6
	v_cndmask_b32_e32 v11, v220, v11, vcc
	v_exp_f32_e32 v14, v0
	v_mul_f32_e32 v0, 0xbfb8aa3b, v7
	v_lshlrev_b32_e32 v31, 2, v11
	v_xor_b32_e32 v11, 2, v220
	v_exp_f32_e32 v15, v0
	v_mul_f32_e32 v0, 0xbfb8aa3b, v8
	v_cmp_lt_i32_e32 vcc, v11, v18
	v_exp_f32_e32 v16, v0
	v_mul_f32_e32 v0, 0xbfb8aa3b, v9
	v_cndmask_b32_e32 v11, v220, v11, vcc
	v_exp_f32_e32 v17, v0
	v_mul_f32_e32 v0, 0xbfb8aa3b, v10
	v_lshlrev_b32_e32 v32, 2, v11
	v_xor_b32_e32 v11, 4, v220
	v_exp_f32_e32 v0, v0
	v_cmp_lt_i32_e32 vcc, v11, v18
	v_pk_add_f32 v[16:17], v[16:17], 1.0 op_sel_hi:[1,0]
	v_pk_add_f32 v[14:15], v[14:15], 1.0 op_sel_hi:[1,0]
	v_cndmask_b32_e32 v11, v220, v11, vcc
	v_lshlrev_b32_e32 v33, 2, v11
	v_xor_b32_e32 v11, 8, v220
	v_cmp_lt_i32_e32 vcc, v11, v18
	v_pk_add_f32 v[0:1], v[0:1], 1.0 op_sel_hi:[1,0]
	v_pk_add_f32 v[12:13], v[12:13], 1.0 op_sel_hi:[1,0]
	v_cndmask_b32_e32 v11, v220, v11, vcc
	v_lshlrev_b32_e32 v34, 2, v11
	v_rcp_f32_e32 v18, v1
	s_nop 0
	v_lshl_add_u32 v141, v28, 4, v132
	v_lshl_add_u32 v139, v24, 2, v35
	v_mul_f32_e32 v27, v2, v18
	v_fma_f32 v29, -v1, v27, v2
	v_fmac_f32_e32 v27, v29, v18
	v_div_fixup_f32 v1, v27, v1, v2
	v_rcp_f32_e32 v11, v0
	s_nop 0
	v_mul_f32_e32 v19, v10, v11
	v_fma_f32 v27, -v0, v19, v10
	v_fmac_f32_e32 v19, v27, v11
	v_div_fixup_f32 v0, v19, v0, v10
	v_rcp_f32_e32 v18, v17
	s_nop 0
	v_pk_mul_f32 v[10:11], v[0:1], v[0:1]
	v_mul_f32_e32 v27, v9, v18
	v_fma_f32 v29, -v17, v27, v9
	v_fmac_f32_e32 v27, v29, v18
	v_div_fixup_f32 v9, v27, v17, v9
	v_rcp_f32_e32 v17, v16
	s_nop 0
	v_mul_f32_e32 v19, v8, v17
	v_fma_f32 v27, -v16, v19, v8
	v_fmac_f32_e32 v19, v27, v17
	v_div_fixup_f32 v8, v19, v16, v8
	v_rcp_f32_e32 v18, v15
	s_nop 0
	v_pk_mul_f32 v[16:17], v[8:9], v[8:9]
	v_mul_f32_e32 v27, v7, v18
	v_fma_f32 v29, -v15, v27, v7
	v_fmac_f32_e32 v27, v29, v18
	v_div_fixup_f32 v7, v27, v15, v7
	v_rcp_f32_e32 v15, v14
	s_nop 0
	v_mul_f32_e32 v19, v6, v15
	v_fma_f32 v27, -v14, v19, v6
	v_fmac_f32_e32 v19, v27, v15
	v_div_fixup_f32 v6, v19, v14, v6
	v_rcp_f32_e32 v18, v13
	s_nop 0
	v_pk_mul_f32 v[14:15], v[6:7], v[6:7]
	v_mul_f32_e32 v27, v5, v18
	v_fma_f32 v29, -v13, v27, v5
	v_fmac_f32_e32 v27, v29, v18
	v_div_fixup_f32 v5, v27, v13, v5
	v_rcp_f32_e32 v13, v12
	s_nop 0
	s_movk_i32 s2, 0x110
	v_mul_f32_e32 v19, v4, v13
	v_fma_f32 v27, -v12, v19, v4
	v_fmac_f32_e32 v19, v27, v13
	v_div_fixup_f32 v4, v19, v12, v4
	v_pk_mul_f32 v[12:13], v[4:5], v[4:5]
	s_nop 0
	v_add_f32_e32 v2, v12, v13
	v_add_f32_e32 v2, v14, v2
	v_add_f32_e32 v2, v15, v2
	v_add_f32_e32 v2, v16, v2
	v_add_f32_e32 v2, v17, v2
	v_add_f32_e32 v2, v10, v2
	v_add_f32_e32 v2, v11, v2
	ds_bpermute_b32 v10, v31, v2
	s_waitcnt lgkmcnt(0)
	v_add_f32_e32 v2, v2, v10
	ds_bpermute_b32 v10, v32, v2
	s_waitcnt lgkmcnt(0)
	v_add_f32_e32 v2, v2, v10
	ds_bpermute_b32 v10, v33, v2
	s_waitcnt lgkmcnt(0)
	v_add_f32_e32 v2, v2, v10
	ds_bpermute_b32 v10, v34, v2
	s_waitcnt lgkmcnt(0)
	v_add_f32_e32 v2, v2, v10
	v_add_f32_e32 v2, 0x358637bd, v2
	v_cmp_gt_f32_e32 vcc, s10, v2
	v_mul_f32_e32 v10, 0x4b800000, v2
	s_nop 0
	v_cndmask_b32_e32 v2, v2, v10, vcc
	v_rsq_f32_e32 v2, v2
	s_nop 0
	v_mul_f32_e32 v10, 0x45800000, v2
	v_cndmask_b32_e32 v2, v2, v10, vcc
	v_mul_f32_e32 v2, 0x3db504f3, v2
	v_pk_mul_f32 v[10:11], v[4:5], v[2:3] op_sel_hi:[1,0]
	v_pk_mul_f32 v[12:13], v[6:7], v[2:3] op_sel_hi:[1,0]
	v_pk_mul_f32 v[8:9], v[8:9], v[2:3] op_sel_hi:[1,0]
	v_pk_mul_f32 v[0:1], v[0:1], v[2:3] op_sel_hi:[1,0]
	v_mul_lo_u32 v2, v24, s2
	v_cvt_pk_bf16_f32 v4, v10, v11
	v_cvt_pk_bf16_f32 v5, v12, v13
	v_cvt_pk_bf16_f32 v6, v8, v9
	v_cvt_pk_bf16_f32 v7, v0, v1
	v_add_u32_e32 v140, v141, v2
	ds_write_b128 v140, v[4:7]
	ds_read_b32 v2, v139
	v_and_b32_e32 v4, 0xfffffe00, v138
	v_bfe_u32 v5, v138, 4, 5
	v_or3_b32 v4, v5, v4, v143
	v_ashrrev_i32_e32 v5, 31, v4
	s_waitcnt lgkmcnt(0)
	v_pk_mul_f32 v[6:7], v[2:3], v[10:11] op_sel_hi:[0,1]
	v_pk_mul_f32 v[10:11], v[2:3], v[12:13] op_sel_hi:[0,1]
	v_pk_mul_f32 v[8:9], v[2:3], v[8:9] op_sel_hi:[0,1]
	v_lshl_add_u64 v[4:5], v[4:5], 4, v[20:21]
	v_cvt_pk_bf16_f32 v6, v6, v7
	v_cvt_pk_bf16_f32 v7, v10, v11
	v_cvt_pk_bf16_f32 v8, v8, v9
	v_pk_mul_f32 v[0:1], v[2:3], v[0:1] op_sel_hi:[0,1]
	v_cvt_pk_bf16_f32 v9, v0, v1
	global_store_dwordx2 v[4:5], v[6:7], off
	global_store_dwordx2 v[4:5], v[8:9], off offset:512
	ds_read_b128 v[12:15], v26
	ds_read_b128 v[16:19], v26 offset:16
	v_add_u32_e32 v29, 0x200, v138
	v_ashrrev_i32_e32 v27, 4, v29
	v_add_u32_e32 v142, s20, v27
	v_lshlrev_b32_e32 v0, 16, v62
	v_lshlrev_b32_e32 v4, 16, v60
	v_and_b32_e32 v2, 0xffff0000, v62
	s_waitcnt lgkmcnt(1)
	v_fma_f32 v4, v12, v4, 0
	s_waitcnt lgkmcnt(0)
	v_mul_f32_e32 v5, v16, v0
	v_cmp_lt_i32_e64 s[44:45], 2, v142
	v_and_b32_e32 v1, 0xffff0000, v60
	v_fma_f32 v1, v13, v1, 0
	v_cndmask_b32_e64 v0, 0, v4, s[44:45]
	v_cndmask_b32_e64 v4, 0, v5, s[44:45]
	v_mul_f32_e32 v5, v17, v2
	v_cndmask_b32_e64 v5, 0, v5, s[44:45]
	v_cmp_gt_i32_e64 s[42:43], 3, v142
	v_add_f32_e32 v4, 0, v4
	v_cndmask_b32_e64 v1, 0, v1, s[44:45]
	v_mov_b32_e32 v2, v3
	v_mov_b32_e32 v6, v3
	v_mov_b32_e32 v7, v3
	v_add_f32_e32 v5, 0, v5
	s_and_saveexec_b64 s[2:3], s[42:43]
	s_xor_b64 s[2:3], exec, s[2:3]
	s_or_saveexec_b64 s[2:3], s[2:3]
	v_mov_b32_e32 v8, 0
	s_xor_b64 exec, exec, s[2:3]
	v_lshlrev_b32_e32 v8, 16, v63
	v_lshlrev_b32_e32 v2, 16, v61
	v_fma_f32 v2, v14, v2, 0
	v_mul_f32_e32 v8, v18, v8
	s_or_b64 exec, exec, s[2:3]
	v_add_f32_e32 v12, v6, v8
	v_mov_b64_e32 v[10:11], v[6:7]
	v_mov_b64_e32 v[8:9], v[4:5]
	v_mov_b64_e32 v[6:7], v[2:3]
	v_mov_b64_e32 v[4:5], v[0:1]
	v_mov_b32_e32 v10, v12
	s_and_saveexec_b64 s[2:3], s[42:43]
	s_xor_b64 s[2:3], exec, s[2:3]
	v_add_f32_e32 v7, 0, v3
	s_or_saveexec_b64 s[2:3], s[2:3]
	v_mov_b32_e32 v0, 0
	s_xor_b64 exec, exec, s[2:3]
	v_and_b32_e32 v0, 0xffff0000, v61
	v_and_b32_e32 v1, 0xffff0000, v63
	v_mov_b32_e32 v7, v3
	v_fmac_f32_e32 v7, v15, v0
	v_mul_f32_e32 v0, v19, v1
	s_or_b64 exec, exec, s[2:3]
	ds_read_b128 v[12:15], v26 offset:1536
	ds_read_b128 v[16:19], v26 offset:1552
	v_add_f32_e32 v11, v11, v0
	v_cmp_gt_i32_e64 s[34:35], 2, v142
	s_and_saveexec_b64 s[2:3], s[34:35]
	s_xor_b64 s[2:3], exec, s[2:3]
	v_add_f32_e32 v4, 0, v4
	s_or_saveexec_b64 s[2:3], s[2:3]
	v_mov_b32_e32 v0, 0
	s_xor_b64 exec, exec, s[2:3]
	s_cbranch_execz .LBB0_494
; #define LAS __attribute__((address_space(3)))
; DI void unpack8(u32x4 w, float* f) { f[0] = bflo(w.x); f[1] = bfhi(w.x); f[2] = bflo(w.y); f[3] = bfhi(w.y); f[4] = bflo(w.z); f[5] = bfhi(w.z); f[6] = bflo(w.w); f[7] = bfhi(w.w); }
; DI void gdn_intra(LAS unsigned char* lds, PP p, int l, int first, int stride) {
;     ...
;             for (int kk = 0; kk < 4; ++kk) { const bool ok = tok0 + j - 3 + kk >= 0;
;                 float x[8]; unpack8(R[(mat * 2 + it) * 4 + kk], x);
;                 const f32x4 w0 = *(const LAS f32x4*)(CW + kk * 384 + mat * 128 + o * 8), w1 = *(const LAS f32x4*)(CW + kk * 384 + mat * 128 + o * 8 + 4);
;                 for (int i = 0; i < 4; ++i) { a[i] += ok ? w0[i] * x[i] : 0.f; a[4 + i] += ok ? w1[i] * x[4 + i] : 0.f; } }
	v_lshlrev_b32_e32 v0, 16, v74
	v_lshlrev_b32_e32 v1, 16, v72
	s_waitcnt lgkmcnt(1)
	v_fmac_f32_e32 v4, v12, v1
	s_waitcnt lgkmcnt(0)
	v_mul_f32_e32 v0, v16, v0

; #define LAS __attribute__((address_space(3)))
; DI unsigned pk2(float lo, float hi) { f32x2 v = {lo, hi}; bf2_t b = __builtin_convertvector(v, bf2_t); return __builtin_bit_cast(unsigned, b); }
; DI void unpack8(u32x4 w, float* f) { f[0] = bflo(w.x); f[1] = bfhi(w.x); f[2] = bflo(w.y); f[3] = bfhi(w.y); f[4] = bflo(w.z); f[5] = bfhi(w.z); f[6] = bflo(w.w); f[7] = bfhi(w.w); }
; DI u32x4 pack8(const float* f) { u32x4 w; w.x = pk2(f[0], f[1]); w.y = pk2(f[2], f[3]); w.z = pk2(f[4], f[5]); w.w = pk2(f[6], f[7]); return w; }
; DI void gdn_intra(LAS unsigned char* lds, PP p, int l, int first, int stride) {
;     ...
;             for (int kk = 0; kk < 4; ++kk) { const bool ok = tok0 + j - 3 + kk >= 0;
;                 float x[8]; unpack8(R[(mat * 2 + it) * 4 + kk], x);
;                 const f32x4 w0 = *(const LAS f32x4*)(CW + kk * 384 + mat * 128 + o * 8), w1 = *(const LAS f32x4*)(CW + kk * 384 + mat * 128 + o * 8 + 4);
;                 for (int i = 0; i < 4; ++i) { a[i] += ok ? w0[i] * x[i] : 0.f; a[4 + i] += ok ? w1[i] * x[4 + i] : 0.f; } }
; #pragma unroll
;             for (int i = 0; i < 8; ++i) a[i] = a[i] / (1.f + __expf(-a[i]));
;             if (mat < 2) {
;                 float ss = 0.f;
; #pragma unroll
;                 for (int i = 0; i < 8; ++i) ss += a[i] * a[i];
;                 ss += __shfl_xor(ss, 1); ss += __shfl_xor(ss, 2); ss += __shfl_xor(ss, 4); ss += __shfl_xor(ss, 8);
;                 const float sc = rsqrtf(ss + 1e-6f) * (mat == 0 ? 0.08838834764831845f : 1.f);
; #pragma unroll
;                 for (int i = 0; i < 8; ++i) a[i] *= sc;
;             }
;             if (mat == 0) {
;                 *(LAS u32x4*)(Qn + j * 136 + o * 8) = pack8(a);
;                 const float eg = sce[j]; const int ct = j >> 5, s = o >> 1, part = o & 1;
;                 unsigned char* q0 = fb + 16384 + ((size_t)((ct * 8 + s) * 64 + (j & 31))) * 16 + 8 * part;
;                 u32x2 lo, hi2; lo.x = pk2(a[0] * eg, a[1] * eg); lo.y = pk2(a[2] * eg, a[3] * eg); hi2.x = pk2(a[4] * eg, a[5] * eg); hi2.y = pk2(a[6] * eg, a[7] * eg);
;                 *(u32x2*)q0 = lo; *(u32x2*)(q0 + 32 * 16) = hi2;
.LBB0_538:
	s_or_b64 exec, exec, s[2:3]
	v_add_f32_e32 v2, v0, v11
	v_mul_f32_e32 v0, 0xbfb8aa3b, v2
	v_exp_f32_e32 v1, v0
	v_mul_f32_e32 v0, 0xbfb8aa3b, v4
	s_waitcnt lgkmcnt(1)
	v_exp_f32_e32 v12, v0
	v_mul_f32_e32 v0, 0xbfb8aa3b, v5
	v_exp_f32_e32 v13, v0
	v_mul_f32_e32 v0, 0xbfb8aa3b, v6
	v_exp_f32_e32 v14, v0
	v_mul_f32_e32 v0, 0xbfb8aa3b, v7
	v_exp_f32_e32 v15, v0
	v_mul_f32_e32 v0, 0xbfb8aa3b, v8
	s_waitcnt lgkmcnt(0)
	v_exp_f32_e32 v16, v0
	v_mul_f32_e32 v0, 0xbfb8aa3b, v9
	v_exp_f32_e32 v17, v0
	v_mul_f32_e32 v0, 0xbfb8aa3b, v10
	v_exp_f32_e32 v0, v0
	v_pk_add_f32 v[14:15], v[14:15], 1.0 op_sel_hi:[1,0]
	v_pk_add_f32 v[16:17], v[16:17], 1.0 op_sel_hi:[1,0]
	v_pk_add_f32 v[12:13], v[12:13], 1.0 op_sel_hi:[1,0]
	v_pk_add_f32 v[0:1], v[0:1], 1.0 op_sel_hi:[1,0]
	s_nop 0
	v_rcp_f32_e32 v18, v1
	s_nop 0
	v_mul_f32_e32 v142, v2, v18
	v_fma_f32 v144, -v1, v142, v2
	v_fmac_f32_e32 v142, v144, v18
	v_div_fixup_f32 v1, v142, v1, v2
	v_rcp_f32_e32 v11, v0
	s_nop 0
	v_mul_f32_e32 v19, v10, v11
	v_fma_f32 v142, -v0, v19, v10
	v_fmac_f32_e32 v19, v142, v11
	v_div_fixup_f32 v0, v19, v0, v10
	v_rcp_f32_e32 v18, v17
	s_nop 0
	v_pk_mul_f32 v[10:11], v[0:1], v[0:1]
	v_mul_f32_e32 v142, v9, v18
	v_fma_f32 v144, -v17, v142, v9
	v_fmac_f32_e32 v142, v144, v18
	v_div_fixup_f32 v9, v142, v17, v9
	v_rcp_f32_e32 v17, v16
	s_nop 0
	v_mul_f32_e32 v19, v8, v17
	v_fma_f32 v142, -v16, v19, v8
	v_fmac_f32_e32 v19, v142, v17
	v_div_fixup_f32 v8, v19, v16, v8
	v_rcp_f32_e32 v18, v15
	s_nop 0
	v_pk_mul_f32 v[16:17], v[8:9], v[8:9]
	v_mul_f32_e32 v142, v7, v18
	v_fma_f32 v144, -v15, v142, v7
	v_fmac_f32_e32 v142, v144, v18
	v_div_fixup_f32 v7, v142, v15, v7
	v_rcp_f32_e32 v15, v14
	s_nop 0
	v_mul_f32_e32 v19, v6, v15
	v_fma_f32 v142, -v14, v19, v6
	v_fmac_f32_e32 v19, v142, v15
	v_div_fixup_f32 v6, v19, v14, v6
	v_rcp_f32_e32 v18, v13
	s_nop 0
	v_pk_mul_f32 v[14:15], v[6:7], v[6:7]
	v_mul_f32_e32 v142, v5, v18
	v_fma_f32 v144, -v13, v142, v5
	v_fmac_f32_e32 v142, v144, v18
	v_div_fixup_f32 v5, v142, v13, v5
	v_rcp_f32_e32 v13, v12
	s_nop 0
	s_movk_i32 s2, 0x110
	v_mul_f32_e32 v19, v4, v13
	v_fma_f32 v142, -v12, v19, v4
	v_fmac_f32_e32 v19, v142, v13
	v_div_fixup_f32 v4, v19, v12, v4
	v_pk_mul_f32 v[12:13], v[4:5], v[4:5]
	s_nop 0
	v_add_f32_e32 v2, v12, v13
	v_add_f32_e32 v2, v14, v2
	v_add_f32_e32 v2, v15, v2
	v_add_f32_e32 v2, v16, v2
	v_add_f32_e32 v2, v17, v2
	v_add_f32_e32 v2, v10, v2
	v_add_f32_e32 v2, v11, v2
	ds_bpermute_b32 v10, v31, v2
	s_waitcnt lgkmcnt(0)
	v_add_f32_e32 v2, v2, v10
	ds_bpermute_b32 v10, v32, v2
	s_waitcnt lgkmcnt(0)
	v_add_f32_e32 v2, v2, v10
	ds_bpermute_b32 v10, v33, v2
	s_waitcnt lgkmcnt(0)
	v_add_f32_e32 v2, v2, v10
	ds_bpermute_b32 v10, v34, v2
	s_waitcnt lgkmcnt(0)
	v_add_f32_e32 v2, v2, v10
	v_add_f32_e32 v2, 0x358637bd, v2
	v_cmp_gt_f32_e32 vcc, s10, v2
	v_mul_f32_e32 v10, 0x4b800000, v2
	s_nop 0
	v_cndmask_b32_e32 v2, v2, v10, vcc
	v_rsq_f32_e32 v2, v2
	s_nop 0
	v_mul_f32_e32 v10, 0x45800000, v2
	v_cndmask_b32_e32 v2, v2, v10, vcc
	v_mul_f32_e32 v2, 0x3db504f3, v2
	v_pk_mul_f32 v[10:11], v[4:5], v[2:3] op_sel_hi:[1,0]
	v_pk_mul_f32 v[12:13], v[6:7], v[2:3] op_sel_hi:[1,0]
	v_pk_mul_f32 v[8:9], v[8:9], v[2:3] op_sel_hi:[1,0]
	v_pk_mul_f32 v[0:1], v[0:1], v[2:3] op_sel_hi:[1,0]
	v_mul_lo_u32 v2, v27, s2
	v_cvt_pk_bf16_f32 v4, v10, v11
	v_cvt_pk_bf16_f32 v5, v12, v13
	v_cvt_pk_bf16_f32 v6, v8, v9
	v_cvt_pk_bf16_f32 v7, v0, v1
	v_add_u32_e32 v142, v141, v2
	ds_write_b128 v142, v[4:7]
	v_lshl_add_u32 v141, v27, 2, v35
	ds_read_b32 v2, v141
	v_and_b32_e32 v4, 0xfffffe00, v29
	v_bfe_u32 v5, v29, 4, 5
	v_or3_b32 v4, v5, v4, v143
	v_ashrrev_i32_e32 v5, 31, v4
	s_waitcnt lgkmcnt(0)
	v_pk_mul_f32 v[6:7], v[2:3], v[10:11] op_sel_hi:[0,1]
	v_pk_mul_f32 v[10:11], v[2:3], v[12:13] op_sel_hi:[0,1]
	v_pk_mul_f32 v[8:9], v[2:3], v[8:9] op_sel_hi:[0,1]
	v_lshl_add_u64 v[4:5], v[4:5], 4, v[20:21]
	v_cvt_pk_bf16_f32 v6, v6, v7
	v_cvt_pk_bf16_f32 v7, v10, v11
	v_cvt_pk_bf16_f32 v8, v8, v9
	v_pk_mul_f32 v[0:1], v[2:3], v[0:1] op_sel_hi:[0,1]
	v_cvt_pk_bf16_f32 v9, v0, v1
	global_store_dwordx2 v[4:5], v[6:7], off
	global_store_dwordx2 v[4:5], v[8:9], off offset:512
	ds_read_b128 v[12:15], v26 offset:512
	ds_read_b128 v[16:19], v26 offset:528
	v_lshlrev_b32_e32 v0, 16, v50
	v_lshlrev_b32_e32 v4, 16, v48
	v_and_b32_e32 v2, 0xffff0000, v50
	s_waitcnt lgkmcnt(1)
	v_fma_f32 v4, v12, v4, 0
	s_waitcnt lgkmcnt(0)
	v_mul_f32_e32 v5, v16, v0
	v_and_b32_e32 v1, 0xffff0000, v48
	v_cndmask_b32_e64 v0, 0, v4, s[40:41]
	v_cndmask_b32_e64 v4, 0, v5, s[40:41]
	v_mul_f32_e32 v5, v17, v2
	v_fma_f32 v1, v13, v1, 0
	v_cndmask_b32_e64 v5, 0, v5, s[40:41]
	v_add_f32_e32 v4, 0, v4
	v_cndmask_b32_e64 v1, 0, v1, s[40:41]
	v_mov_b32_e32 v2, v3
	v_mov_b32_e32 v6, v3
	v_mov_b32_e32 v7, v3
	v_add_f32_e32 v5, 0, v5
	s_and_saveexec_b64 s[2:3], s[30:31]
	s_xor_b64 s[2:3], exec, s[2:3]
	s_or_saveexec_b64 s[2:3], s[2:3]
	v_mov_b32_e32 v8, 0
	s_xor_b64 exec, exec, s[2:3]
	v_lshlrev_b32_e32 v8, 16, v51
	v_lshlrev_b32_e32 v2, 16, v49
	v_fma_f32 v2, v14, v2, 0
	v_mul_f32_e32 v8, v18, v8
	s_or_b64 exec, exec, s[2:3]
	v_add_f32_e32 v12, v6, v8
	v_mov_b64_e32 v[10:11], v[6:7]
	v_mov_b64_e32 v[8:9], v[4:5]
	v_mov_b64_e32 v[6:7], v[2:3]
	v_mov_b64_e32 v[4:5], v[0:1]
	v_mov_b32_e32 v10, v12
	s_and_saveexec_b64 s[2:3], s[30:31]
	s_xor_b64 s[2:3], exec, s[2:3]
	v_add_f32_e32 v7, 0, v3
	s_or_saveexec_b64 s[2:3], s[2:3]
	v_mov_b32_e32 v0, 0
	s_xor_b64 exec, exec, s[2:3]
	v_and_b32_e32 v0, 0xffff0000, v49
	v_and_b32_e32 v1, 0xffff0000, v51
	v_mov_b32_e32 v7, v3
	v_fmac_f32_e32 v7, v15, v0
	v_mul_f32_e32 v0, v19, v1
	s_or_b64 exec, exec, s[2:3]
	ds_read_b128 v[12:15], v26 offset:2048
	ds_read_b128 v[16:19], v26 offset:2064
	v_add_f32_e32 v11, v11, v0
	s_and_saveexec_b64 s[2:3], s[24:25]
	s_xor_b64 s[2:3], exec, s[2:3]
	v_add_f32_e32 v4, 0, v4
	s_or_saveexec_b64 s[2:3], s[2:3]
	v_mov_b32_e32 v0, 0
	s_xor_b64 exec, exec, s[2:3]
	s_cbranch_execz .LBB0_548
	v_lshlrev_b32_e32 v0, 16, v58
	v_lshlrev_b32_e32 v1, 16, v56
	s_waitcnt lgkmcnt(1)
	v_fmac_f32_e32 v4, v12, v1
	s_waitcnt lgkmcnt(0)
	v_mul_f32_e32 v0, v16, v0

; #define LAS __attribute__((address_space(3)))
; DI unsigned pk2(float lo, float hi) { f32x2 v = {lo, hi}; bf2_t b = __builtin_convertvector(v, bf2_t); return __builtin_bit_cast(unsigned, b); }
; DI bf16_t f2bf(float f) { return (bf16_t)(pk2(f, 0.f) & 0xffffu); }
; DI u32x4 pack8(const float* f) { u32x4 w; w.x = pk2(f[0], f[1]); w.y = pk2(f[2], f[3]); w.z = pk2(f[4], f[5]); w.w = pk2(f[6], f[7]); return w; }
; DI void gdn_intra(LAS unsigned char* lds, PP p, int l, int first, int stride) {
;     ...
;             for (int i = 0; i < 8; ++i) a[i] = a[i] / (1.f + __expf(-a[i]));
;             if (mat < 2) {
;                 float ss = 0.f;
; #pragma unroll
;                 for (int i = 0; i < 8; ++i) ss += a[i] * a[i];
;                 ss += __shfl_xor(ss, 1); ss += __shfl_xor(ss, 2); ss += __shfl_xor(ss, 4); ss += __shfl_xor(ss, 8);
;                 const float sc = rsqrtf(ss + 1e-6f) * (mat == 0 ? 0.08838834764831845f : 1.f);
; #pragma unroll
;                 for (int i = 0; i < 8; ++i) a[i] *= sc;
;             }
;             if (mat == 0) {
;                 *(LAS u32x4*)(Qn + j * 136 + o * 8) = pack8(a);
;                 const float eg = sce[j]; const int ct = j >> 5, s = o >> 1, part = o & 1;
;                 unsigned char* q0 = fb + 16384 + ((size_t)((ct * 8 + s) * 64 + (j & 31))) * 16 + 8 * part;
;                 u32x2 lo, hi2; lo.x = pk2(a[0] * eg, a[1] * eg); lo.y = pk2(a[2] * eg, a[3] * eg); hi2.x = pk2(a[4] * eg, a[5] * eg); hi2.y = pk2(a[6] * eg, a[7] * eg);
;                 *(u32x2*)q0 = lo; *(u32x2*)(q0 + 32 * 16) = hi2;
;             } else if (mat == 1) {
;                 *(LAS u32x4*)(Kn + j * 136 + o * 8) = pack8(a);
;                 const float f1 = scb[j] * sce[j], f2 = scl[j];
; #pragma unroll
;                 for (int i = 0; i < 8; ++i) { XTk[xsw(o * 8 + i, j)] = f2bf(a[i] * f1); KT2[xsw(o * 8 + i, j)] = f2bf(a[i] * f2); }
.LBB0_592:
	s_or_b64 exec, exec, s[2:3]
	v_add_f32_e32 v2, v0, v11
	v_mul_f32_e32 v0, 0xbfb8aa3b, v2
	v_exp_f32_e32 v1, v0
	v_mul_f32_e32 v0, 0xbfb8aa3b, v4
	s_waitcnt lgkmcnt(1)
	v_exp_f32_e32 v12, v0
	v_mul_f32_e32 v0, 0xbfb8aa3b, v5
	v_exp_f32_e32 v13, v0
	v_mul_f32_e32 v0, 0xbfb8aa3b, v6
	v_exp_f32_e32 v14, v0
	v_mul_f32_e32 v0, 0xbfb8aa3b, v7
	v_exp_f32_e32 v15, v0
	v_mul_f32_e32 v0, 0xbfb8aa3b, v8
	s_waitcnt lgkmcnt(0)
	v_exp_f32_e32 v16, v0
	v_mul_f32_e32 v0, 0xbfb8aa3b, v9
	v_exp_f32_e32 v17, v0
	v_mul_f32_e32 v0, 0xbfb8aa3b, v10
	v_exp_f32_e32 v0, v0
	v_pk_add_f32 v[14:15], v[14:15], 1.0 op_sel_hi:[1,0]
	v_pk_add_f32 v[16:17], v[16:17], 1.0 op_sel_hi:[1,0]
	v_pk_add_f32 v[12:13], v[12:13], 1.0 op_sel_hi:[1,0]
	v_pk_add_f32 v[0:1], v[0:1], 1.0 op_sel_hi:[1,0]
	v_lshlrev_b32_e32 v143, 3, v28
	v_rcp_f32_e32 v18, v1
	s_nop 0
	v_mul_u32_u24_e32 v144, 0x240, v28
	v_add_u32_e32 v20, 0x11800, v132
	v_mul_f32_e32 v21, v2, v18
	v_fma_f32 v35, -v1, v21, v2
	v_fmac_f32_e32 v21, v35, v18
	v_div_fixup_f32 v1, v21, v1, v2
	v_rcp_f32_e32 v11, v0
	s_nop 0
	v_mul_f32_e32 v19, v10, v11
	v_fma_f32 v21, -v0, v19, v10
	v_fmac_f32_e32 v19, v21, v11
	v_div_fixup_f32 v0, v19, v0, v10
	v_rcp_f32_e32 v18, v17
	s_nop 0
	v_pk_mul_f32 v[10:11], v[0:1], v[0:1]
	v_mul_f32_e32 v21, v9, v18
	v_fma_f32 v35, -v17, v21, v9
	v_fmac_f32_e32 v21, v35, v18
	v_div_fixup_f32 v9, v21, v17, v9
	v_rcp_f32_e32 v17, v16
	s_nop 0
	v_mul_f32_e32 v19, v8, v17
	v_fma_f32 v21, -v16, v19, v8
	v_fmac_f32_e32 v19, v21, v17
	v_div_fixup_f32 v8, v19, v16, v8
	v_rcp_f32_e32 v18, v15
	s_nop 0
	v_pk_mul_f32 v[16:17], v[8:9], v[8:9]
	v_mul_f32_e32 v21, v7, v18
	v_fma_f32 v35, -v15, v21, v7
	v_fmac_f32_e32 v21, v35, v18
	v_div_fixup_f32 v7, v21, v15, v7
	v_rcp_f32_e32 v15, v14
	s_nop 0
	v_mul_f32_e32 v19, v6, v15
	v_fma_f32 v21, -v14, v19, v6
	v_fmac_f32_e32 v19, v21, v15
	v_div_fixup_f32 v6, v19, v14, v6
	v_rcp_f32_e32 v18, v13
	s_nop 0
	v_pk_mul_f32 v[14:15], v[6:7], v[6:7]
	v_mul_f32_e32 v21, v5, v18
	v_fma_f32 v35, -v13, v21, v5
	v_fmac_f32_e32 v21, v35, v18
	v_div_fixup_f32 v5, v21, v13, v5
	v_rcp_f32_e32 v13, v12
	s_nop 0
	s_movk_i32 s2, 0x240
	v_mad_u32_u24 v151, v28, s2, v227
	v_mul_f32_e32 v19, v4, v13
	v_fma_f32 v21, -v12, v19, v4
	v_fmac_f32_e32 v19, v21, v13
	v_div_fixup_f32 v4, v19, v12, v4
	v_pk_mul_f32 v[12:13], v[4:5], v[4:5]
	s_nop 0
	v_add_f32_e32 v2, v12, v13
	v_add_f32_e32 v2, v14, v2
	v_add_f32_e32 v2, v15, v2
	v_add_f32_e32 v2, v16, v2
	v_add_f32_e32 v2, v17, v2
	v_add_f32_e32 v2, v10, v2
	v_add_f32_e32 v2, v11, v2
	ds_bpermute_b32 v10, v31, v2
	s_waitcnt lgkmcnt(0)
	v_add_f32_e32 v2, v2, v10
	ds_bpermute_b32 v10, v32, v2
	s_waitcnt lgkmcnt(0)
	v_add_f32_e32 v2, v2, v10
	ds_bpermute_b32 v10, v33, v2
	s_waitcnt lgkmcnt(0)
	v_add_f32_e32 v2, v2, v10
	ds_bpermute_b32 v10, v34, v2
	s_waitcnt lgkmcnt(0)
	v_add_f32_e32 v2, v2, v10
	v_add_f32_e32 v2, 0x358637bd, v2
	v_cmp_gt_f32_e32 vcc, s10, v2
	v_mul_f32_e32 v10, 0x4b800000, v2
	s_nop 0
	v_cndmask_b32_e32 v2, v2, v10, vcc
	v_rsq_f32_e32 v2, v2
	s_nop 0
	v_mul_f32_e32 v10, 0x45800000, v2
	v_cndmask_b32_e32 v2, v2, v10, vcc
	v_pk_mul_f32 v[10:11], v[4:5], v[2:3] op_sel_hi:[1,0]
	v_pk_mul_f32 v[12:13], v[6:7], v[2:3] op_sel_hi:[1,0]
	v_pk_mul_f32 v[8:9], v[8:9], v[2:3] op_sel_hi:[1,0]
	v_pk_mul_f32 v[0:1], v[0:1], v[2:3] op_sel_hi:[1,0]
	v_cvt_pk_bf16_f32 v4, v10, v11
	v_cvt_pk_bf16_f32 v5, v12, v13
	v_cvt_pk_bf16_f32 v6, v8, v9
	v_cvt_pk_bf16_f32 v7, v0, v1
	v_lshlrev_b32_e32 v2, 2, v24
	ds_write_b128 v140, v[4:7] offset:17408
	v_add_u32_e32 v35, v23, v2
	ds_read_b32 v4, v35
	ds_read_b32 v5, v139
	v_add_u32_e32 v2, v30, v2
	ds_read_b32 v2, v2
	v_bitop3_b32 v139, v143, 56, v24 bitop3:0x48
	v_bfe_u32 v140, v138, 4, 3
	s_waitcnt lgkmcnt(1)
	v_mul_f32_e32 v4, v4, v5
	v_or_b32_e32 v5, v139, v140
	v_or_b32_e32 v7, v5, v144
	v_mul_f32_e32 v6, v4, v10
	v_lshlrev_b32_e32 v7, 1, v7
	v_cvt_pk_bf16_f32 v6, v6, s0
	v_add_u32_e32 v14, v132, v7
	ds_write_b16 v14, v6 offset:34816
	s_waitcnt lgkmcnt(1)
; #define LAS __attribute__((address_space(3)))
; DI bf16_t f2bf(float f) { return (bf16_t)(pk2(f, 0.f) & 0xffffu); }
; DI void unpack8(u32x4 w, float* f) { f[0] = bflo(w.x); f[1] = bfhi(w.x); f[2] = bflo(w.y); f[3] = bfhi(w.y); f[4] = bflo(w.z); f[5] = bfhi(w.z); f[6] = bflo(w.w); f[7] = bfhi(w.w); }
; DI void gdn_intra(LAS unsigned char* lds, PP p, int l, int first, int stride) {
;     ...
;             for (int kk = 0; kk < 4; ++kk) { const bool ok = tok0 + j - 3 + kk >= 0;
;                 float x[8]; unpack8(R[(mat * 2 + it) * 4 + kk], x);
;                 const f32x4 w0 = *(const LAS f32x4*)(CW + kk * 384 + mat * 128 + o * 8), w1 = *(const LAS f32x4*)(CW + kk * 384 + mat * 128 + o * 8 + 4);
;                 for (int i = 0; i < 4; ++i) { a[i] += ok ? w0[i] * x[i] : 0.f; a[4 + i] += ok ? w1[i] * x[4 + i] : 0.f; } }
;     ...
; #pragma unroll
;                 for (int i = 0; i < 8; ++i) { XTk[xsw(o * 8 + i, j)] = f2bf(a[i] * f1); KT2[xsw(o * 8 + i, j)] = f2bf(a[i] * f2); }
	v_mul_f32_e32 v6, v2, v10
	v_cvt_pk_bf16_f32 v6, v6, s0
	v_add_u32_e32 v7, v20, v7
	ds_write_b16 v7, v6
	v_mul_f32_e32 v6, v4, v11
	v_mov_b32_e32 v7, 0x48
	v_cvt_pk_bf16_f32 v6, v6, s0
	v_mad_u32_u24 v145, v28, s2, v7
	v_add_u32_e32 v7, v5, v145
	ds_write_b16 v14, v6 offset:34960
	v_mul_f32_e32 v6, v2, v11
	v_cvt_pk_bf16_f32 v6, v6, s0
	v_lshl_add_u32 v7, v7, 1, v20
	ds_write_b16 v7, v6
	v_mul_f32_e32 v6, v4, v12
	v_mov_b32_e32 v7, 0x90
	v_cvt_pk_bf16_f32 v6, v6, s0
	v_mad_u32_u24 v146, v28, s2, v7
	v_add_u32_e32 v7, v5, v146
	ds_write_b16 v14, v6 offset:35104
	v_mul_f32_e32 v6, v2, v12
	v_cvt_pk_bf16_f32 v6, v6, s0
	v_lshl_add_u32 v7, v7, 1, v20
	ds_write_b16 v7, v6
	v_mul_f32_e32 v6, v4, v13
	v_mov_b32_e32 v7, 0xd8
	v_cvt_pk_bf16_f32 v6, v6, s0
	v_mad_u32_u24 v147, v28, s2, v7
	v_add_u32_e32 v7, v5, v147
	ds_write_b16 v14, v6 offset:35248
	v_mul_f32_e32 v6, v2, v13
	v_cvt_pk_bf16_f32 v6, v6, s0
	v_lshl_add_u32 v7, v7, 1, v20
	ds_write_b16 v7, v6
	v_mul_f32_e32 v6, v4, v8
	v_mov_b32_e32 v7, 0x120
	v_cvt_pk_bf16_f32 v6, v6, s0
	v_mad_u32_u24 v148, v28, s2, v7
	v_add_u32_e32 v7, v5, v148
	ds_write_b16 v14, v6 offset:35392
	v_mul_f32_e32 v6, v2, v8
	v_cvt_pk_bf16_f32 v6, v6, s0
	v_lshl_add_u32 v7, v7, 1, v20
	ds_write_b16 v7, v6
	v_mul_f32_e32 v6, v4, v9
	v_mov_b32_e32 v7, 0x168
	v_cvt_pk_bf16_f32 v6, v6, s0
	v_mad_u32_u24 v149, v28, s2, v7
	v_add_u32_e32 v7, v5, v149
	ds_write_b16 v14, v6 offset:35536
	v_mul_f32_e32 v6, v2, v9
	v_cvt_pk_bf16_f32 v6, v6, s0
	v_lshl_add_u32 v7, v7, 1, v20
	ds_write_b16 v7, v6
	v_mov_b32_e32 v7, 0x1b0
	v_mul_f32_e32 v6, v4, v0
	v_mad_u32_u24 v150, v28, s2, v7
	v_cvt_pk_bf16_f32 v6, v6, s0
	v_add_u32_e32 v7, v5, v150
	v_mul_f32_e32 v0, v2, v0
	ds_write_b16 v14, v6 offset:35680
	v_cvt_pk_bf16_f32 v0, v0, s0
	v_lshl_add_u32 v6, v7, 1, v20
	ds_write_b16 v6, v0
	v_mul_f32_e32 v0, v4, v1
	v_cvt_pk_bf16_f32 v0, v0, s0
	v_add_u32_e32 v4, v5, v151
	ds_write_b16 v14, v0 offset:35824
	v_mul_f32_e32 v0, v2, v1
	v_cvt_pk_bf16_f32 v0, v0, s0
	v_lshl_add_u32 v1, v4, 1, v20
	ds_write_b16 v1, v0
	ds_read_b128 v[12:15], v26 offset:512
	ds_read_b128 v[16:19], v26 offset:528
	v_lshlrev_b32_e32 v0, 16, v82
	v_lshlrev_b32_e32 v4, 16, v80
	v_and_b32_e32 v2, 0xffff0000, v82
	s_waitcnt lgkmcnt(1)
	v_fma_f32 v4, v12, v4, 0
	s_waitcnt lgkmcnt(0)
	v_mul_f32_e32 v5, v16, v0
	v_and_b32_e32 v1, 0xffff0000, v80
	v_cndmask_b32_e64 v0, 0, v4, s[44:45]
	v_cndmask_b32_e64 v4, 0, v5, s[44:45]
	v_mul_f32_e32 v5, v17, v2
	v_fma_f32 v1, v13, v1, 0
	v_cndmask_b32_e64 v5, 0, v5, s[44:45]
	v_add_f32_e32 v4, 0, v4
	v_cndmask_b32_e64 v1, 0, v1, s[44:45]
	v_mov_b32_e32 v2, v3
	v_mov_b32_e32 v6, v3
	v_mov_b32_e32 v7, v3
	v_add_f32_e32 v5, 0, v5
	s_and_saveexec_b64 s[2:3], s[42:43]
	s_xor_b64 s[2:3], exec, s[2:3]
	s_or_saveexec_b64 s[2:3], s[2:3]
	v_mov_b32_e32 v8, 0
	s_xor_b64 exec, exec, s[2:3]
	v_lshlrev_b32_e32 v8, 16, v83
	v_lshlrev_b32_e32 v2, 16, v81
	v_fma_f32 v2, v14, v2, 0
	v_mul_f32_e32 v8, v18, v8
	s_or_b64 exec, exec, s[2:3]
	v_add_f32_e32 v12, v6, v8
	v_mov_b64_e32 v[10:11], v[6:7]
	v_mov_b64_e32 v[8:9], v[4:5]
	v_mov_b64_e32 v[6:7], v[2:3]
	v_mov_b64_e32 v[4:5], v[0:1]
	v_mov_b32_e32 v10, v12
	s_and_saveexec_b64 s[2:3], s[42:43]
	s_xor_b64 s[2:3], exec, s[2:3]
	v_add_f32_e32 v7, 0, v3
	s_or_saveexec_b64 s[2:3], s[2:3]
	v_mov_b32_e32 v0, 0
	s_xor_b64 exec, exec, s[2:3]
	v_and_b32_e32 v0, 0xffff0000, v81
	v_and_b32_e32 v1, 0xffff0000, v83
	v_mov_b32_e32 v7, v3
	v_fmac_f32_e32 v7, v15, v0
	v_mul_f32_e32 v0, v19, v1
	s_or_b64 exec, exec, s[2:3]
	ds_read_b128 v[12:15], v26 offset:2048
	ds_read_b128 v[16:19], v26 offset:2064
	v_add_f32_e32 v11, v11, v0
	s_and_saveexec_b64 s[2:3], s[34:35]
	s_xor_b64 s[2:3], exec, s[2:3]
	v_add_f32_e32 v4, 0, v4
	s_or_saveexec_b64 s[2:3], s[2:3]
	v_mov_b32_e32 v0, 0
	s_xor_b64 exec, exec, s[2:3]
	s_cbranch_execz .LBB0_602
	v_lshlrev_b32_e32 v0, 16, v90
	v_lshlrev_b32_e32 v1, 16, v88
	s_waitcnt lgkmcnt(1)
	v_fmac_f32_e32 v4, v12, v1
	s_waitcnt lgkmcnt(0)
	v_mul_f32_e32 v0, v16, v0

; #define LAS __attribute__((address_space(3)))
; DI unsigned pk2(float lo, float hi) { f32x2 v = {lo, hi}; bf2_t b = __builtin_convertvector(v, bf2_t); return __builtin_bit_cast(unsigned, b); }
; DI bf16_t f2bf(float f) { return (bf16_t)(pk2(f, 0.f) & 0xffffu); }
; DI u32x4 pack8(const float* f) { u32x4 w; w.x = pk2(f[0], f[1]); w.y = pk2(f[2], f[3]); w.z = pk2(f[4], f[5]); w.w = pk2(f[6], f[7]); return w; }
; DI void gdn_intra(LAS unsigned char* lds, PP p, int l, int first, int stride) {
;     ...
;             for (int i = 0; i < 8; ++i) a[i] = a[i] / (1.f + __expf(-a[i]));
;             if (mat < 2) {
;                 float ss = 0.f;
; #pragma unroll
;                 for (int i = 0; i < 8; ++i) ss += a[i] * a[i];
;                 ss += __shfl_xor(ss, 1); ss += __shfl_xor(ss, 2); ss += __shfl_xor(ss, 4); ss += __shfl_xor(ss, 8);
;                 const float sc = rsqrtf(ss + 1e-6f) * (mat == 0 ? 0.08838834764831845f : 1.f);
; #pragma unroll
;                 for (int i = 0; i < 8; ++i) a[i] *= sc;
;             }
;             if (mat == 0) {
;                 *(LAS u32x4*)(Qn + j * 136 + o * 8) = pack8(a);
;                 const float eg = sce[j]; const int ct = j >> 5, s = o >> 1, part = o & 1;
;                 unsigned char* q0 = fb + 16384 + ((size_t)((ct * 8 + s) * 64 + (j & 31))) * 16 + 8 * part;
;                 u32x2 lo, hi2; lo.x = pk2(a[0] * eg, a[1] * eg); lo.y = pk2(a[2] * eg, a[3] * eg); hi2.x = pk2(a[4] * eg, a[5] * eg); hi2.y = pk2(a[6] * eg, a[7] * eg);
;                 *(u32x2*)q0 = lo; *(u32x2*)(q0 + 32 * 16) = hi2;
;             } else if (mat == 1) {
;                 *(LAS u32x4*)(Kn + j * 136 + o * 8) = pack8(a);
;                 const float f1 = scb[j] * sce[j], f2 = scl[j];
; #pragma unroll
;                 for (int i = 0; i < 8; ++i) { XTk[xsw(o * 8 + i, j)] = f2bf(a[i] * f1); KT2[xsw(o * 8 + i, j)] = f2bf(a[i] * f2); }
.LBB0_646:
	s_or_b64 exec, exec, s[2:3]
	v_add_f32_e32 v2, v0, v11
	v_mul_f32_e32 v0, 0xbfb8aa3b, v2
	v_exp_f32_e32 v1, v0
	v_mul_f32_e32 v0, 0xbfb8aa3b, v4
	s_waitcnt lgkmcnt(1)
	v_exp_f32_e32 v12, v0
	v_mul_f32_e32 v0, 0xbfb8aa3b, v5
	v_exp_f32_e32 v13, v0
	v_mul_f32_e32 v0, 0xbfb8aa3b, v6
	v_exp_f32_e32 v14, v0
	v_mul_f32_e32 v0, 0xbfb8aa3b, v7
	v_exp_f32_e32 v15, v0
	v_mul_f32_e32 v0, 0xbfb8aa3b, v8
	s_waitcnt lgkmcnt(0)
	v_exp_f32_e32 v16, v0
	v_mul_f32_e32 v0, 0xbfb8aa3b, v9
	v_exp_f32_e32 v17, v0
	v_mul_f32_e32 v0, 0xbfb8aa3b, v10
	v_exp_f32_e32 v0, v0
	v_pk_add_f32 v[14:15], v[14:15], 1.0 op_sel_hi:[1,0]
	v_pk_add_f32 v[16:17], v[16:17], 1.0 op_sel_hi:[1,0]
	v_pk_add_f32 v[12:13], v[12:13], 1.0 op_sel_hi:[1,0]
	v_pk_add_f32 v[0:1], v[0:1], 1.0 op_sel_hi:[1,0]
	s_nop 0
	v_rcp_f32_e32 v18, v1
	s_nop 0
	v_mul_f32_e32 v21, v2, v18
	v_fma_f32 v152, -v1, v21, v2
	v_fmac_f32_e32 v21, v152, v18
	v_div_fixup_f32 v1, v21, v1, v2
	v_rcp_f32_e32 v11, v0
	s_nop 0
	v_mul_f32_e32 v19, v10, v11
	v_fma_f32 v21, -v0, v19, v10
	v_fmac_f32_e32 v19, v21, v11
	v_div_fixup_f32 v0, v19, v0, v10
	v_rcp_f32_e32 v18, v17
	s_nop 0
	v_pk_mul_f32 v[10:11], v[0:1], v[0:1]
	v_mul_f32_e32 v21, v9, v18
	v_fma_f32 v152, -v17, v21, v9
	v_fmac_f32_e32 v21, v152, v18
	v_div_fixup_f32 v9, v21, v17, v9
	v_rcp_f32_e32 v17, v16
	s_nop 0
	v_mul_f32_e32 v19, v8, v17
	v_fma_f32 v21, -v16, v19, v8
	v_fmac_f32_e32 v19, v21, v17
	v_div_fixup_f32 v8, v19, v16, v8
	v_rcp_f32_e32 v18, v15
	s_nop 0
	v_pk_mul_f32 v[16:17], v[8:9], v[8:9]
	v_mul_f32_e32 v21, v7, v18
	v_fma_f32 v152, -v15, v21, v7
	v_fmac_f32_e32 v21, v152, v18
	v_div_fixup_f32 v7, v21, v15, v7
	v_rcp_f32_e32 v15, v14
	s_nop 0
	v_mul_f32_e32 v19, v6, v15
	v_fma_f32 v21, -v14, v19, v6
	v_fmac_f32_e32 v19, v21, v15
	v_div_fixup_f32 v6, v19, v14, v6
	v_rcp_f32_e32 v18, v13
	s_nop 0
	v_pk_mul_f32 v[14:15], v[6:7], v[6:7]
	v_mul_f32_e32 v21, v5, v18
	v_fma_f32 v152, -v13, v21, v5
	v_fmac_f32_e32 v21, v152, v18
	v_div_fixup_f32 v5, v21, v13, v5
	v_rcp_f32_e32 v13, v12
	s_nop 0
	v_mul_f32_e32 v19, v4, v13
	v_fma_f32 v21, -v12, v19, v4
	v_fmac_f32_e32 v19, v21, v13
	v_div_fixup_f32 v4, v19, v12, v4
	v_pk_mul_f32 v[12:13], v[4:5], v[4:5]
	s_nop 0
	v_add_f32_e32 v2, v12, v13
	v_add_f32_e32 v2, v14, v2
	v_add_f32_e32 v2, v15, v2
	v_add_f32_e32 v2, v16, v2
	v_add_f32_e32 v2, v17, v2
	v_add_f32_e32 v2, v10, v2
	v_add_f32_e32 v2, v11, v2
	ds_bpermute_b32 v10, v31, v2
	v_bfe_u32 v31, v29, 4, 3
	s_waitcnt lgkmcnt(0)
	v_add_f32_e32 v2, v2, v10
	ds_bpermute_b32 v10, v32, v2
	s_waitcnt lgkmcnt(0)
	v_add_f32_e32 v2, v2, v10
	ds_bpermute_b32 v10, v33, v2
	s_waitcnt lgkmcnt(0)
	v_add_f32_e32 v2, v2, v10
	ds_bpermute_b32 v10, v34, v2
	s_waitcnt lgkmcnt(0)
	v_add_f32_e32 v2, v2, v10
	v_add_f32_e32 v2, 0x358637bd, v2
	v_cmp_gt_f32_e32 vcc, s10, v2
	v_mul_f32_e32 v10, 0x4b800000, v2
	s_nop 0
	v_cndmask_b32_e32 v2, v2, v10, vcc
	v_rsq_f32_e32 v2, v2
	s_nop 0
	v_mul_f32_e32 v10, 0x45800000, v2
	v_cndmask_b32_e32 v2, v2, v10, vcc
	v_pk_mul_f32 v[10:11], v[4:5], v[2:3] op_sel_hi:[1,0]
	v_pk_mul_f32 v[12:13], v[6:7], v[2:3] op_sel_hi:[1,0]
	v_pk_mul_f32 v[8:9], v[8:9], v[2:3] op_sel_hi:[1,0]
	v_pk_mul_f32 v[0:1], v[0:1], v[2:3] op_sel_hi:[1,0]
	v_cvt_pk_bf16_f32 v4, v10, v11
	v_cvt_pk_bf16_f32 v5, v12, v13
	v_cvt_pk_bf16_f32 v6, v8, v9
	v_cvt_pk_bf16_f32 v7, v0, v1
	v_lshlrev_b32_e32 v2, 2, v27
	ds_write_b128 v142, v[4:7] offset:17408
	v_add_u32_e32 v21, v23, v2
	ds_read_b32 v4, v21
	ds_read_b32 v5, v141
	v_add_u32_e32 v2, v30, v2
	ds_read_b32 v2, v2
	v_bitop3_b32 v30, v27, 56, v143 bitop3:0x48
	s_waitcnt lgkmcnt(1)
	v_mul_f32_e32 v4, v4, v5
	v_or_b32_e32 v5, v30, v31
	v_or_b32_e32 v7, v5, v144
	v_mul_f32_e32 v6, v4, v10
	v_lshlrev_b32_e32 v7, 1, v7
	v_cvt_pk_bf16_f32 v6, v6, s0
	v_add_u32_e32 v14, v132, v7
	ds_write_b16 v14, v6 offset:34816
	s_waitcnt lgkmcnt(1)
; #define LAS __attribute__((address_space(3)))
; DI bf16_t f2bf(float f) { return (bf16_t)(pk2(f, 0.f) & 0xffffu); }
; DI void unpack8(u32x4 w, float* f) { f[0] = bflo(w.x); f[1] = bfhi(w.x); f[2] = bflo(w.y); f[3] = bfhi(w.y); f[4] = bflo(w.z); f[5] = bfhi(w.z); f[6] = bflo(w.w); f[7] = bfhi(w.w); }
; DI void gdn_intra(LAS unsigned char* lds, PP p, int l, int first, int stride) {
;     ...
;             for (int kk = 0; kk < 4; ++kk) { const bool ok = tok0 + j - 3 + kk >= 0;
;                 float x[8]; unpack8(R[(mat * 2 + it) * 4 + kk], x);
;                 const f32x4 w0 = *(const LAS f32x4*)(CW + kk * 384 + mat * 128 + o * 8), w1 = *(const LAS f32x4*)(CW + kk * 384 + mat * 128 + o * 8 + 4);
;                 for (int i = 0; i < 4; ++i) { a[i] += ok ? w0[i] * x[i] : 0.f; a[4 + i] += ok ? w1[i] * x[4 + i] : 0.f; } }
;     ...
; #pragma unroll
;                 for (int i = 0; i < 8; ++i) { XTk[xsw(o * 8 + i, j)] = f2bf(a[i] * f1); KT2[xsw(o * 8 + i, j)] = f2bf(a[i] * f2); }
	v_mul_f32_e32 v6, v2, v10
	v_cvt_pk_bf16_f32 v6, v6, s0
	v_add_u32_e32 v7, v20, v7
	ds_write_b16 v7, v6
	v_mul_f32_e32 v6, v4, v11
	v_add_u32_e32 v10, v5, v144
	v_cvt_pk_bf16_f32 v6, v6, s0
	v_lshl_add_u32 v10, v10, 1, v132
	v_add_u32_e32 v7, v5, v145
	ds_write_b16 v10, v6 offset:34960
	v_mul_f32_e32 v6, v2, v11
	v_cvt_pk_bf16_f32 v6, v6, s0
	v_lshl_add_u32 v7, v7, 1, v20
	ds_write_b16 v7, v6
	v_mul_f32_e32 v6, v4, v12
	v_cvt_pk_bf16_f32 v6, v6, s0
	v_add_u32_e32 v7, v5, v146
	ds_write_b16 v10, v6 offset:35104
	v_mul_f32_e32 v6, v2, v12
	v_cvt_pk_bf16_f32 v6, v6, s0
	v_lshl_add_u32 v7, v7, 1, v20
	ds_write_b16 v7, v6
	v_mul_f32_e32 v6, v4, v13
	v_cvt_pk_bf16_f32 v6, v6, s0
	v_add_u32_e32 v7, v5, v147
	ds_write_b16 v10, v6 offset:35248
	v_mul_f32_e32 v6, v2, v13
	v_cvt_pk_bf16_f32 v6, v6, s0
	v_lshl_add_u32 v7, v7, 1, v20
	ds_write_b16 v7, v6
	v_mul_f32_e32 v6, v4, v8
	v_cvt_pk_bf16_f32 v6, v6, s0
	v_add_u32_e32 v7, v5, v148
	ds_write_b16 v10, v6 offset:35392
	v_mul_f32_e32 v6, v2, v8
	v_cvt_pk_bf16_f32 v6, v6, s0
	v_lshl_add_u32 v7, v7, 1, v20
	ds_write_b16 v7, v6
	v_mul_f32_e32 v6, v4, v9
	v_cvt_pk_bf16_f32 v6, v6, s0
	v_add_u32_e32 v7, v5, v149
	ds_write_b16 v10, v6 offset:35536
	v_mul_f32_e32 v6, v2, v9
	v_cvt_pk_bf16_f32 v6, v6, s0
	v_lshl_add_u32 v7, v7, 1, v20
	ds_write_b16 v7, v6
	v_mul_f32_e32 v6, v4, v0
	v_cvt_pk_bf16_f32 v6, v6, s0
	v_add_u32_e32 v7, v5, v150
	v_mul_f32_e32 v0, v2, v0
	ds_write_b16 v10, v6 offset:35680
	v_cvt_pk_bf16_f32 v0, v0, s0
	v_lshl_add_u32 v6, v7, 1, v20
	ds_write_b16 v6, v0
	v_mul_f32_e32 v0, v4, v1
	v_cvt_pk_bf16_f32 v0, v0, s0
	v_add_u32_e32 v4, v5, v151
	ds_write_b16 v10, v0 offset:35824
	v_mul_f32_e32 v0, v2, v1
	v_cvt_pk_bf16_f32 v0, v0, s0
	v_lshl_add_u32 v1, v4, 1, v20
	ds_write_b16 v1, v0
	ds_read_b128 v[12:15], v26 offset:1024
	ds_read_b128 v[16:19], v26 offset:1040
	v_lshlrev_b32_e32 v0, 16, v102
	v_lshlrev_b32_e32 v4, 16, v100
	v_and_b32_e32 v2, 0xffff0000, v102
	s_waitcnt lgkmcnt(1)
	v_fma_f32 v4, v12, v4, 0
	s_waitcnt lgkmcnt(0)
	v_mul_f32_e32 v5, v16, v0
	v_and_b32_e32 v1, 0xffff0000, v100
	v_cndmask_b32_e64 v0, 0, v4, s[40:41]
	v_cndmask_b32_e64 v4, 0, v5, s[40:41]
	v_mul_f32_e32 v5, v17, v2
	v_fma_f32 v1, v13, v1, 0
	v_cndmask_b32_e64 v5, 0, v5, s[40:41]
	v_add_f32_e32 v4, 0, v4
	v_cndmask_b32_e64 v1, 0, v1, s[40:41]
	v_mov_b32_e32 v2, v3
	v_mov_b32_e32 v6, v3
	v_mov_b32_e32 v7, v3
	v_add_f32_e32 v5, 0, v5
	s_and_saveexec_b64 s[2:3], s[30:31]
	s_xor_b64 s[2:3], exec, s[2:3]
	s_or_saveexec_b64 s[2:3], s[2:3]
	v_mov_b32_e32 v8, 0
	s_xor_b64 exec, exec, s[2:3]
	v_lshlrev_b32_e32 v8, 16, v103
	v_lshlrev_b32_e32 v2, 16, v101
	v_fma_f32 v2, v14, v2, 0
	v_mul_f32_e32 v8, v18, v8
	s_or_b64 exec, exec, s[2:3]
	v_add_f32_e32 v12, v6, v8
	v_mov_b64_e32 v[10:11], v[6:7]
	v_mov_b64_e32 v[8:9], v[4:5]
	v_mov_b64_e32 v[6:7], v[2:3]
	v_mov_b64_e32 v[4:5], v[0:1]
	v_mov_b32_e32 v10, v12
	s_and_saveexec_b64 s[2:3], s[30:31]
	s_xor_b64 s[2:3], exec, s[2:3]
	v_add_f32_e32 v7, 0, v3
	s_or_saveexec_b64 s[2:3], s[2:3]
	v_mov_b32_e32 v0, 0
	s_xor_b64 exec, exec, s[2:3]
	v_and_b32_e32 v0, 0xffff0000, v101
	v_and_b32_e32 v1, 0xffff0000, v103
	v_mov_b32_e32 v7, v3
	v_fmac_f32_e32 v7, v15, v0
	v_mul_f32_e32 v0, v19, v1
	s_or_b64 exec, exec, s[2:3]
	ds_read_b128 v[12:15], v26 offset:2560
	ds_read_b128 v[16:19], v26 offset:2576
	v_add_f32_e32 v11, v11, v0
	s_and_saveexec_b64 s[2:3], s[24:25]
	s_xor_b64 s[2:3], exec, s[2:3]
	v_add_f32_e32 v4, 0, v4
	s_or_saveexec_b64 s[2:3], s[2:3]
	v_mov_b32_e32 v0, 0
	s_xor_b64 exec, exec, s[2:3]
	s_cbranch_execz .LBB0_656
	v_lshlrev_b32_e32 v0, 16, v106
	v_lshlrev_b32_e32 v1, 16, v104
	s_waitcnt lgkmcnt(1)
	v_fmac_f32_e32 v4, v12, v1
	s_waitcnt lgkmcnt(0)
	v_mul_f32_e32 v0, v16, v0

; #define LAS __attribute__((address_space(3)))
; DI bf16_t f2bf(float f) { return (bf16_t)(pk2(f, 0.f) & 0xffffu); }
; DI void unpack8(u32x4 w, float* f) { f[0] = bflo(w.x); f[1] = bfhi(w.x); f[2] = bflo(w.y); f[3] = bfhi(w.y); f[4] = bflo(w.z); f[5] = bfhi(w.z); f[6] = bflo(w.w); f[7] = bfhi(w.w); }
; DI void gdn_intra(LAS unsigned char* lds, PP p, int l, int first, int stride) {
;     ...
;             for (int kk = 0; kk < 4; ++kk) { const bool ok = tok0 + j - 3 + kk >= 0;
;                 float x[8]; unpack8(R[(mat * 2 + it) * 4 + kk], x);
;                 const f32x4 w0 = *(const LAS f32x4*)(CW + kk * 384 + mat * 128 + o * 8), w1 = *(const LAS f32x4*)(CW + kk * 384 + mat * 128 + o * 8 + 4);
;                 for (int i = 0; i < 4; ++i) { a[i] += ok ? w0[i] * x[i] : 0.f; a[4 + i] += ok ? w1[i] * x[4 + i] : 0.f; } }
; #pragma unroll
;             for (int i = 0; i < 8; ++i) a[i] = a[i] / (1.f + __expf(-a[i]));
;     ...
;             } else {
;                 const float f1 = scb[j];
; #pragma unroll
;                 for (int i = 0; i < 8; ++i) XTv[xsw(o * 8 + i, j)] = f2bf(a[i] * f1);
.LBB0_700:
	s_or_b64 exec, exec, s[2:3]
	v_add_f32_e32 v0, v11, v0
	v_mul_f32_e32 v1, 0xbfb8aa3b, v0
	v_exp_f32_e32 v1, v1
	v_mul_u32_u24_e32 v28, 0x480, v28
	v_add_f32_e32 v1, 1.0, v1
	v_rcp_f32_e32 v11, v1
	s_nop 0
	s_waitcnt lgkmcnt(1)
	v_mul_f32_e32 v13, v0, v11
	v_fma_f32 v14, -v1, v13, v0
	v_fmac_f32_e32 v13, v14, v11
	v_div_fixup_f32 v0, v13, v1, v0
	v_mul_f32_e32 v1, 0xbfb8aa3b, v10
	v_exp_f32_e32 v1, v1
	s_nop 0
	v_add_f32_e32 v1, 1.0, v1
	v_rcp_f32_e32 v11, v1
	s_nop 0
	v_mul_f32_e32 v13, v10, v11
	v_fma_f32 v14, -v1, v13, v10
	v_fmac_f32_e32 v13, v14, v11
	v_div_fixup_f32 v1, v13, v1, v10
	v_mul_f32_e32 v2, 0xbfb8aa3b, v9
	v_exp_f32_e32 v2, v2
	s_nop 0
	v_add_f32_e32 v2, 1.0, v2
	v_rcp_f32_e32 v11, v2
	s_nop 0
	v_mul_f32_e32 v13, v9, v11
	v_fma_f32 v14, -v2, v13, v9
	v_fmac_f32_e32 v13, v14, v11
	v_div_fixup_f32 v2, v13, v2, v9
	v_mul_f32_e32 v9, 0xbfb8aa3b, v8
	v_exp_f32_e32 v9, v9
	s_nop 0
	v_add_f32_e32 v9, 1.0, v9
	v_rcp_f32_e32 v11, v9
	s_nop 0
	v_mul_f32_e32 v13, v8, v11
	v_fma_f32 v14, -v9, v13, v8
	v_fmac_f32_e32 v13, v14, v11
	v_div_fixup_f32 v8, v13, v9, v8
	v_mul_f32_e32 v9, 0xbfb8aa3b, v7
	v_exp_f32_e32 v9, v9
	s_nop 0
	v_add_f32_e32 v9, 1.0, v9
	v_rcp_f32_e32 v11, v9
	s_nop 0
	v_mul_f32_e32 v13, v7, v11
	v_fma_f32 v14, -v9, v13, v7
	v_fmac_f32_e32 v13, v14, v11
	v_div_fixup_f32 v7, v13, v9, v7
	v_mul_f32_e32 v9, 0xbfb8aa3b, v6
	v_exp_f32_e32 v9, v9
	s_nop 0
	v_add_f32_e32 v9, 1.0, v9
	v_rcp_f32_e32 v11, v9
	s_nop 0
	v_mul_f32_e32 v13, v6, v11
	v_fma_f32 v14, -v9, v13, v6
	v_fmac_f32_e32 v13, v14, v11
	v_div_fixup_f32 v6, v13, v9, v6
	v_mul_f32_e32 v9, 0xbfb8aa3b, v5
	v_exp_f32_e32 v9, v9
	s_nop 0
	v_add_f32_e32 v9, 1.0, v9
	v_rcp_f32_e32 v11, v9
	s_nop 0
	v_mul_f32_e32 v13, v5, v11
	v_fma_f32 v14, -v9, v13, v5
	v_fmac_f32_e32 v13, v14, v11
	v_div_fixup_f32 v5, v13, v9, v5
	v_mul_f32_e32 v9, 0xbfb8aa3b, v4
	v_exp_f32_e32 v9, v9
	s_nop 0
	v_add_f32_e32 v9, 1.0, v9
	v_rcp_f32_e32 v11, v9
	s_nop 0
	v_mul_f32_e32 v13, v4, v11
	v_fma_f32 v14, -v9, v13, v4
	v_fmac_f32_e32 v13, v14, v11
	v_div_fixup_f32 v4, v13, v9, v4
	ds_read_b32 v9, v35
	v_lshl_add_u32 v10, v139, 1, v132
	v_lshlrev_b32_e32 v11, 1, v140
	v_add3_u32 v10, v10, v11, v28
	s_waitcnt lgkmcnt(0)
	v_mul_f32_e32 v4, v9, v4
	v_cvt_pk_bf16_f32 v4, v4, s0
	ds_write_b16 v10, v4 offset:53248
	v_mul_f32_e32 v4, v9, v5
	v_cvt_pk_bf16_f32 v4, v4, s0
	ds_write_b16 v10, v4 offset:53392
	v_mul_f32_e32 v4, v9, v6
	v_cvt_pk_bf16_f32 v4, v4, s0
	ds_write_b16 v10, v4 offset:53536
	v_mul_f32_e32 v4, v9, v7
	v_cvt_pk_bf16_f32 v4, v4, s0
	ds_write_b16 v10, v4 offset:53680
	v_mul_f32_e32 v4, v9, v8
	v_mul_f32_e32 v2, v9, v2
	v_mul_f32_e32 v1, v9, v1
	v_mul_f32_e32 v0, v9, v0
	v_cvt_pk_bf16_f32 v4, v4, s0
	v_cvt_pk_bf16_f32 v2, v2, s0
	v_cvt_pk_bf16_f32 v1, v1, s0
	v_cvt_pk_bf16_f32 v0, v0, s0
	ds_write_b16 v10, v4 offset:53824
	ds_write_b16 v10, v2 offset:53968
	ds_write_b16 v10, v1 offset:54112
	ds_write_b16 v10, v0 offset:54256
	ds_read_b128 v[12:15], v26 offset:1024
	ds_read_b128 v[16:19], v26 offset:1040
	v_lshlrev_b32_e32 v0, 16, v118
	v_lshlrev_b32_e32 v4, 16, v116
	v_and_b32_e32 v2, 0xffff0000, v118
	s_waitcnt lgkmcnt(1)
	v_fma_f32 v4, v12, v4, 0
	s_waitcnt lgkmcnt(0)
	v_mul_f32_e32 v5, v16, v0
	v_and_b32_e32 v1, 0xffff0000, v116
	v_cndmask_b32_e64 v0, 0, v4, s[44:45]
	v_cndmask_b32_e64 v4, 0, v5, s[44:45]
	v_mul_f32_e32 v5, v17, v2
	v_fma_f32 v1, v13, v1, 0
	v_cndmask_b32_e64 v5, 0, v5, s[44:45]
	v_add_f32_e32 v4, 0, v4
	v_cndmask_b32_e64 v1, 0, v1, s[44:45]
	v_mov_b32_e32 v2, v3
	v_mov_b32_e32 v6, v3
	v_mov_b32_e32 v7, v3
	v_add_f32_e32 v5, 0, v5
	s_and_saveexec_b64 s[2:3], s[42:43]
	s_xor_b64 s[2:3], exec, s[2:3]
	s_or_saveexec_b64 s[2:3], s[2:3]
	v_mov_b32_e32 v8, 0
	s_xor_b64 exec, exec, s[2:3]
	v_lshlrev_b32_e32 v8, 16, v119
	v_lshlrev_b32_e32 v2, 16, v117
	v_fma_f32 v2, v14, v2, 0
	v_mul_f32_e32 v8, v18, v8
	s_or_b64 exec, exec, s[2:3]
	v_add_f32_e32 v12, v6, v8
	v_mov_b64_e32 v[10:11], v[6:7]
	v_mov_b64_e32 v[8:9], v[4:5]
	v_mov_b64_e32 v[6:7], v[2:3]
	v_mov_b64_e32 v[4:5], v[0:1]
	v_mov_b32_e32 v10, v12
	s_and_saveexec_b64 s[2:3], s[42:43]
	s_xor_b64 s[2:3], exec, s[2:3]
	v_add_f32_e32 v7, 0, v3
	s_or_saveexec_b64 s[2:3], s[2:3]
	v_mov_b32_e32 v0, 0
	s_xor_b64 exec, exec, s[2:3]
	v_and_b32_e32 v0, 0xffff0000, v117
	v_and_b32_e32 v1, 0xffff0000, v119
	v_mov_b32_e32 v7, v3
	v_fmac_f32_e32 v7, v15, v0
	v_mul_f32_e32 v0, v19, v1
	s_or_b64 exec, exec, s[2:3]
	ds_read_b128 v[12:15], v26 offset:2560
	ds_read_b128 v[16:19], v26 offset:2576
	v_add_f32_e32 v11, v11, v0
	s_and_saveexec_b64 s[2:3], s[34:35]
	s_xor_b64 s[2:3], exec, s[2:3]
	v_add_f32_e32 v4, 0, v4
	s_or_saveexec_b64 s[2:3], s[2:3]
	v_mov_b32_e32 v0, 0
	s_xor_b64 exec, exec, s[2:3]
	s_cbranch_execz .LBB0_710
	v_lshlrev_b32_e32 v0, 16, v122
	v_lshlrev_b32_e32 v1, 16, v120
	s_waitcnt lgkmcnt(1)
	v_fmac_f32_e32 v4, v12, v1
	s_waitcnt lgkmcnt(0)
	v_mul_f32_e32 v0, v16, v0

; DI bf16_t f2bf(float f) { return (bf16_t)(pk2(f, 0.f) & 0xffffu); }
; DI void gdn_intra(LAS unsigned char* lds, PP p, int l, int first, int stride) {
;     ...
;             } else {
;                 const float f1 = scb[j];
; #pragma unroll
;                 for (int i = 0; i < 8; ++i) XTv[xsw(o * 8 + i, j)] = f2bf(a[i] * f1);
;             }
;             __builtin_amdgcn_sched_barrier(0);
;         }
;     }
;     { const int nxt = item + stride; if (nxt < 2048) { INTRA_PREFETCH(nxt); INTRA_LOADRAW(nxt); } }
.LBB0_754:
	s_or_b64 exec, exec, s[2:3]
	v_add_f32_e32 v0, v11, v0
	v_mul_f32_e32 v1, 0xbfb8aa3b, v0
	v_exp_f32_e32 v1, v1
	s_nop 0
	v_add_f32_e32 v1, 1.0, v1
	v_rcp_f32_e32 v11, v1
	s_nop 0
	s_waitcnt lgkmcnt(1)
	v_mul_f32_e32 v13, v0, v11
	v_fma_f32 v14, -v1, v13, v0
	v_fmac_f32_e32 v13, v14, v11
	v_div_fixup_f32 v0, v13, v1, v0
	v_mul_f32_e32 v1, 0xbfb8aa3b, v10
	v_exp_f32_e32 v1, v1
	s_nop 0
	v_add_f32_e32 v1, 1.0, v1
	v_rcp_f32_e32 v11, v1
	s_nop 0
	v_mul_f32_e32 v13, v10, v11
	v_fma_f32 v14, -v1, v13, v10
	v_fmac_f32_e32 v13, v14, v11
	v_div_fixup_f32 v1, v13, v1, v10
	v_mul_f32_e32 v2, 0xbfb8aa3b, v4
	v_exp_f32_e32 v2, v2
	s_nop 0
	v_add_f32_e32 v2, 1.0, v2
	v_rcp_f32_e32 v11, v2
	s_nop 0
	v_mul_f32_e32 v13, v4, v11
	v_fma_f32 v14, -v2, v13, v4
	v_fmac_f32_e32 v13, v14, v11
	v_div_fixup_f32 v2, v13, v2, v4
	v_mul_f32_e32 v4, 0xbfb8aa3b, v5
	v_exp_f32_e32 v4, v4
	s_nop 0
	v_add_f32_e32 v4, 1.0, v4
	v_rcp_f32_e32 v11, v4
	s_nop 0
	v_mul_f32_e32 v13, v5, v11
	v_fma_f32 v14, -v4, v13, v5
	v_fmac_f32_e32 v13, v14, v11
	v_div_fixup_f32 v4, v13, v4, v5
	v_mul_f32_e32 v5, 0xbfb8aa3b, v6
	v_exp_f32_e32 v5, v5
	s_nop 0
	v_add_f32_e32 v5, 1.0, v5
	v_rcp_f32_e32 v11, v5
	s_nop 0
	v_mul_f32_e32 v13, v6, v11
	v_fma_f32 v14, -v5, v13, v6
	v_fmac_f32_e32 v13, v14, v11
	v_div_fixup_f32 v5, v13, v5, v6
	v_mul_f32_e32 v6, 0xbfb8aa3b, v7
	v_exp_f32_e32 v6, v6
	s_nop 0
	v_add_f32_e32 v6, 1.0, v6
	v_rcp_f32_e32 v11, v6
	s_nop 0
	v_mul_f32_e32 v13, v7, v11
	v_fma_f32 v14, -v6, v13, v7
	v_fmac_f32_e32 v13, v14, v11
	v_div_fixup_f32 v6, v13, v6, v7
	v_mul_f32_e32 v7, 0xbfb8aa3b, v8
	v_exp_f32_e32 v7, v7
	s_nop 0
	v_add_f32_e32 v7, 1.0, v7
	v_rcp_f32_e32 v11, v7
	s_nop 0
	v_mul_f32_e32 v13, v8, v11
	v_fma_f32 v14, -v7, v13, v8
	v_fmac_f32_e32 v13, v14, v11
	v_div_fixup_f32 v7, v13, v7, v8
	v_mul_f32_e32 v8, 0xbfb8aa3b, v9
	v_exp_f32_e32 v8, v8
	s_nop 0
	v_add_f32_e32 v8, 1.0, v8
	v_rcp_f32_e32 v11, v8
	s_nop 0
	v_mul_f32_e32 v13, v9, v11
	v_fma_f32 v14, -v8, v13, v9
	v_fmac_f32_e32 v13, v14, v11
	v_div_fixup_f32 v8, v13, v8, v9
	ds_read_b32 v9, v21
	v_lshl_add_u32 v10, v30, 1, v132
	v_lshlrev_b32_e32 v11, 1, v31
	v_add3_u32 v10, v10, v11, v28
	s_waitcnt lgkmcnt(0)
	v_mul_f32_e32 v2, v9, v2
	v_cvt_pk_bf16_f32 v2, v2, s0
	ds_write_b16 v10, v2 offset:53248
	v_mul_f32_e32 v2, v9, v4
	v_cvt_pk_bf16_f32 v2, v2, s0
	ds_write_b16 v10, v2 offset:53392
	v_mul_f32_e32 v2, v9, v5
	v_cvt_pk_bf16_f32 v2, v2, s0
	ds_write_b16 v10, v2 offset:53536
	v_mul_f32_e32 v2, v9, v6
	v_cvt_pk_bf16_f32 v2, v2, s0
	ds_write_b16 v10, v2 offset:53680
	v_mul_f32_e32 v2, v9, v7
	v_cvt_pk_bf16_f32 v2, v2, s0
	ds_write_b16 v10, v2 offset:53824
	v_mul_f32_e32 v2, v9, v8
	v_mul_f32_e32 v1, v9, v1
	v_mul_f32_e32 v0, v9, v0
	v_cvt_pk_bf16_f32 v2, v2, s0
	v_cvt_pk_bf16_f32 v1, v1, s0
	v_cvt_pk_bf16_f32 v0, v0, s0
	ds_write_b16 v10, v2 offset:53968
	ds_write_b16 v10, v1 offset:54112
	ds_write_b16 v10, v0 offset:54256
	v_readlane_b32 s2, v254, 11
	s_add_i32 s30, s2, s54
	s_cmpk_gt_i32 s30, 0x7ff
	s_cselect_b64 s[26:27], -1, 0
	s_and_b64 vcc, exec, s[26:27]
	s_cbranch_vccnz .LBB0_758
	s_ashr_i32 s3, s30, 8
	s_lshl_b32 s2, s3, 7
	v_and_b32_e32 v0, 0x7f, v138
	s_mov_b32 s21, 0x2aaaaaab
	v_or_b32_e32 v2, s2, v0
	v_mul_hi_i32 v0, v138, s21
	v_lshrrev_b32_e32 v1, 31, v0
	v_ashrrev_i32_e32 v0, 6, v0
	v_add_u32_e32 v0, v0, v1
	v_mul_i32_i24_e32 v1, 0xfffffe80, v0
	v_add_lshl_u32 v1, v1, v138, 3
	v_mul_i32_i24_e32 v0, 0xc00, v0
	v_and_b32_e32 v1, 0xfffffc00, v1
	v_add3_u32 v0, v2, v0, v1
	v_ashrrev_i32_e32 v1, 31, v0
	v_lshl_add_u64 v[0:1], v[0:1], 2, s[52:53]
	global_load_dword v133, v[0:1], off
	v_mul_hi_i32 v0, v29, s21
	v_lshrrev_b32_e32 v1, 31, v0
	v_ashrrev_i32_e32 v0, 6, v0
	v_add_u32_e32 v0, v0, v1
	v_mul_i32_i24_e32 v1, 0xfffffe80, v0
	v_add_lshl_u32 v1, v1, v29, 3
	v_mul_i32_i24_e32 v0, 0xc00, v0
	v_and_b32_e32 v1, 0xfffffc00, v1
	v_add3_u32 v0, v2, v0, v1
	v_ashrrev_i32_e32 v1, 31, v0
	v_lshl_add_u64 v[0:1], v[0:1], 2, s[52:53]
	global_load_dword v136, v[0:1], off
	v_add_u32_e32 v0, 0x400, v138
	v_mul_hi_i32 v1, v0, s21
	v_lshrrev_b32_e32 v4, 31, v1
	v_ashrrev_i32_e32 v1, 6, v1
	v_add_u32_e32 v1, v1, v4
	v_mul_i32_i24_e32 v4, 0xfffffe80, v1
	v_add_lshl_u32 v0, v4, v0, 3
	v_mul_i32_i24_e32 v1, 0xc00, v1
	v_and_b32_e32 v0, 0xfffffc00, v0
	v_add3_u32 v0, v2, v1, v0
	v_ashrrev_i32_e32 v1, 31, v0
	v_lshl_add_u64 v[0:1], v[0:1], 2, s[52:53]
	global_load_dword v137, v[0:1], off
	s_lshl_b32 s20, s30, 6
	s_and_b32 s24, s20, 0x3fc0
	s_and_saveexec_b64 s[20:21], s[22:23]
	s_cbranch_execz .LBB0_757
	v_add_u32_e32 v0, s24, v138
	s_ashr_i32 s22, s3, 31
	v_ashrrev_i32_e32 v1, 31, v0
	v_mov_b32_e32 v4, s3
	v_mov_b32_e32 v5, s22
	v_lshl_add_u64 v[0:1], v[0:1], 4, v[4:5]
	v_lshlrev_b64 v[0:1], 2, v[0:1]
	v_lshl_add_u64 v[4:5], s[48:49], 0, v[0:1]
	v_lshl_add_u64 v[0:1], s[50:51], 0, v[0:1]
	global_load_dword v7, v[4:5], off
	global_load_dword v9, v[0:1], off
	global_load_dword v8, v[0:1], off offset:32
	global_load_dword v6, v[4:5], off offset:32
	s_waitcnt vmcnt(0)
	v_pk_add_f32 v[134:135], v[6:7], v[8:9]

; DI u32x4 pack44(f32x4 a, f32x4 b) { u32x4 w; w.x = pk2(a[0], a[1]); w.y = pk2(a[2], a[3]); w.z = pk2(b[0], b[1]); w.w = pk2(b[2], b[3]); return w; }
; #define EPI_LOOP_PERM(...) _Pragma("unroll") for (int ai = 0; ai < 2; ++ai) _Pragma("unroll") for (int m = 0; m < 4; ++m) { const int row = u.pm * 256 + ai * 128 + wr * 64 + m * 16 + fr; \
;     _Pragma("unroll") for (int bj = 0; bj < 2; ++bj) { const int c8 = bj * 128 + wc * 32 + 8 * fq; f32x4 v0 = acc[ai][bj][m][0], v1 = acc[ai][bj][m][1]; __VA_ARGS__ } }
; DI float sigmoidf_(float x) { return 1.f / (1.f + __expf(-x)); }
;     DI void operator()(const Acc& acc, const Unit& u, int wr, int wc, int fr, int fq) const {
;     ...
;             bf16_t* dst = pn < 28 ? sgs + (pn - 20) * 256 : sgg + (pn - 28) * 256;
;             EPI_LOOP_PERM({ for (int j = 0; j < 4; ++j) { v0[j] = sigmoidf_(v0[j]); v1[j] = sigmoidf_(v1[j]); } *(u32x4*)(dst + (size_t)row * 2048 + c8) = pack44(v0, v1); })
.LBB0_1216:
	s_andn2_b64 vcc, exec, s[2:3]
	s_cbranch_vccnz .LBB0_1218
	v_mul_f32_e32 v2, 0xbfb8aa3b, v128
	v_exp_f32_e32 v160, v2
	v_mul_f32_e32 v2, 0xbfb8aa3b, v124
	s_cmp_lt_u32 s24, 28
	v_readlane_b32 s3, v254, 56
	v_readlane_b32 s20, v254, 49
	v_exp_f32_e32 v162, v2
	v_mul_f32_e32 v2, 0xbfb8aa3b, v129
	s_movk_i32 s2, 0xd800
	s_cselect_b32 s3, s3, s20
	v_readlane_b32 s20, v254, 55
	v_readlane_b32 s21, v254, 51
	v_exp_f32_e32 v161, v2
	s_cselect_b32 s2, s2, 0xffffc800
	s_cselect_b32 s20, s20, s21
	s_lshl_b32 s21, s24, 9
	s_add_u32 s20, s20, s21
	s_addc_u32 s3, s3, 0
	s_add_u32 s44, s20, s2
	v_pk_add_f32 v[160:161], v[160:161], 1.0 op_sel_hi:[1,0]
	s_addc_u32 s45, s3, -1
	v_div_scale_f32 v2, s[2:3], v161, v161, 1.0
	v_rcp_f32_e32 v151, v2
	v_lshl_add_u32 v152, s26, 8, v139
	v_ashrrev_i32_e32 v153, 31, v152
	v_lshlrev_b64 v[154:155], 12, v[152:153]
	v_fma_f32 v153, -v2, v151, 1.0
	v_fmac_f32_e32 v151, v153, v151
	v_div_scale_f32 v153, vcc, 1.0, v161, 1.0
	v_mul_f32_e32 v163, v153, v151
	v_fma_f32 v164, -v2, v163, v153
	v_fmac_f32_e32 v163, v164, v151
	v_fma_f32 v2, -v2, v163, v153
	v_div_fmas_f32 v2, v2, v151, v163
	v_div_scale_f32 v151, s[2:3], v160, v160, 1.0
	v_rcp_f32_e32 v153, v151
	v_div_fixup_f32 v2, v2, v161, 1.0
	v_lshl_add_u64 v[154:155], s[44:45], 0, v[154:155]
	v_fma_f32 v161, -v151, v153, 1.0
	v_fmac_f32_e32 v153, v161, v153
	v_div_scale_f32 v161, vcc, 1.0, v160, 1.0
	v_mul_f32_e32 v163, v161, v153
	v_fma_f32 v164, -v151, v163, v161
	v_fmac_f32_e32 v163, v164, v153
	v_fma_f32 v151, -v151, v163, v161
	v_div_fmas_f32 v151, v151, v153, v163
	v_mul_f32_e32 v153, 0xbfb8aa3b, v125
	v_exp_f32_e32 v163, v153
	v_div_fixup_f32 v151, v151, v160, 1.0
	v_pk_add_f32 v[160:161], v[162:163], 1.0 op_sel_hi:[1,0]
	s_nop 0
	v_rcp_f32_e32 v162, v161
	s_nop 0
	v_mul_f32_e32 v164, 1.0, v162
	v_fma_f32 v165, -v161, v164, 1.0
	v_fmac_f32_e32 v164, v165, v162
	v_div_fixup_f32 v153, v164, v161, 1.0
	v_rcp_f32_e32 v162, v160
	s_nop 0
	v_mul_f32_e32 v164, 1.0, v162
	v_fma_f32 v165, -v160, v164, 1.0
	v_fmac_f32_e32 v164, v165, v162
	v_div_fixup_f32 v164, v164, v160, 1.0
	v_mul_f32_e32 v161, 0xbfb8aa3b, v126
	v_mul_f32_e32 v160, 0xbfb8aa3b, v130
	v_exp_f32_e32 v162, v161
	v_mul_f32_e32 v161, 0xbfb8aa3b, v131
	v_exp_f32_e32 v160, v160
	v_exp_f32_e32 v161, v161
	s_nop 0
	v_pk_add_f32 v[160:161], v[160:161], 1.0 op_sel_hi:[1,0]
	s_nop 0
	v_rcp_f32_e32 v165, v161
	s_nop 0
	v_mul_f32_e32 v167, 1.0, v165
	v_fma_f32 v168, -v161, v167, 1.0
	v_fmac_f32_e32 v167, v168, v165
	v_div_fixup_f32 v165, v167, v161, 1.0
	v_rcp_f32_e32 v163, v160
	s_nop 0
	v_mul_f32_e32 v167, 1.0, v163
	v_fma_f32 v168, -v160, v167, 1.0
	v_fmac_f32_e32 v167, v168, v163
	v_div_fixup_f32 v166, v167, v160, 1.0
	v_mul_f32_e32 v160, 0xbfb8aa3b, v127
	v_exp_f32_e32 v163, v160
	s_nop 0
	v_pk_add_f32 v[160:161], v[162:163], 1.0 op_sel_hi:[1,0]
	s_nop 0
	v_rcp_f32_e32 v163, v161
	s_nop 0
	v_mul_f32_e32 v168, 1.0, v163
	v_fma_f32 v169, -v161, v168, 1.0
	v_fmac_f32_e32 v168, v169, v163
	v_div_fixup_f32 v163, v168, v161, 1.0
	v_rcp_f32_e32 v162, v160
	s_nop 0
	v_mul_f32_e32 v168, 1.0, v162
	v_fma_f32 v169, -v160, v168, 1.0
	v_fmac_f32_e32 v168, v169, v162
	v_div_fixup_f32 v167, v168, v160, 1.0
	v_cvt_pk_bf16_f32 v160, v151, v2
	v_lshlrev_b32_e32 v2, 1, v138
	v_cvt_pk_bf16_f32 v161, v166, v165
	v_cvt_pk_bf16_f32 v162, v164, v153
	v_cvt_pk_bf16_f32 v163, v167, v163
	v_lshl_add_u64 v[154:155], v[154:155], 0, v[2:3]
	v_mul_f32_e32 v151, 0xbfb8aa3b, v112
	global_store_dwordx4 v[154:155], v[160:163], off
	s_nop 1
	v_exp_f32_e32 v160, v151
	v_mul_f32_e32 v151, 0xbfb8aa3b, v108
	v_exp_f32_e32 v162, v151
	v_mul_f32_e32 v151, 0xbfb8aa3b, v113
	v_exp_f32_e32 v161, v151
	s_nop 0
	v_pk_add_f32 v[160:161], v[160:161], 1.0 op_sel_hi:[1,0]
	s_nop 0
	v_div_scale_f32 v151, s[2:3], v161, v161, 1.0
	v_rcp_f32_e32 v153, v151
	s_nop 0
	v_fma_f32 v163, -v151, v153, 1.0
	v_fmac_f32_e32 v153, v163, v153
	v_div_scale_f32 v163, vcc, 1.0, v161, 1.0
	v_mul_f32_e32 v164, v163, v153
	v_fma_f32 v165, -v151, v164, v163
	v_fmac_f32_e32 v164, v165, v153
	v_fma_f32 v151, -v151, v164, v163
	v_div_fmas_f32 v151, v151, v153, v164
	v_div_scale_f32 v153, s[2:3], v160, v160, 1.0
	v_div_fixup_f32 v151, v151, v161, 1.0
	v_rcp_f32_e32 v161, v153
	s_nop 0
	v_fma_f32 v163, -v153, v161, 1.0
	v_fmac_f32_e32 v161, v163, v161
	v_div_scale_f32 v163, vcc, 1.0, v160, 1.0
	v_mul_f32_e32 v164, v163, v161
	v_fma_f32 v165, -v153, v164, v163
	v_fmac_f32_e32 v164, v165, v161
	v_fma_f32 v153, -v153, v164, v163
	v_div_fmas_f32 v153, v153, v161, v164
	v_div_fixup_f32 v153, v153, v160, 1.0
	v_mul_f32_e32 v160, 0xbfb8aa3b, v109
	v_exp_f32_e32 v163, v160
	s_nop 0
	v_pk_add_f32 v[160:161], v[162:163], 1.0 op_sel_hi:[1,0]
	s_nop 0
	v_rcp_f32_e32 v163, v161
	s_nop 0
	v_mul_f32_e32 v165, 1.0, v163
	v_fma_f32 v166, -v161, v165, 1.0
	v_fmac_f32_e32 v165, v166, v163
	v_div_fixup_f32 v164, v165, v161, 1.0
	v_rcp_f32_e32 v162, v160
	s_nop 0
	v_mul_f32_e32 v165, 1.0, v162
	v_fma_f32 v166, -v160, v165, 1.0
	v_fmac_f32_e32 v165, v166, v162
	v_div_fixup_f32 v165, v165, v160, 1.0
	v_mul_f32_e32 v161, 0xbfb8aa3b, v110
	v_mul_f32_e32 v160, 0xbfb8aa3b, v114
	v_exp_f32_e32 v162, v161
	v_mul_f32_e32 v161, 0xbfb8aa3b, v115
	v_exp_f32_e32 v160, v160
	v_exp_f32_e32 v161, v161
	s_nop 0
	v_pk_add_f32 v[160:161], v[160:161], 1.0 op_sel_hi:[1,0]
	s_nop 0
	v_rcp_f32_e32 v166, v161
	s_nop 0
	v_mul_f32_e32 v168, 1.0, v166
	v_fma_f32 v169, -v161, v168, 1.0
	v_fmac_f32_e32 v168, v169, v166
	v_div_fixup_f32 v166, v168, v161, 1.0
	v_rcp_f32_e32 v163, v160
	s_nop 0
	v_mul_f32_e32 v168, 1.0, v163
	v_fma_f32 v169, -v160, v168, 1.0
	v_fmac_f32_e32 v168, v169, v163
	v_div_fixup_f32 v167, v168, v160, 1.0
; DI u32x4 pack44(f32x4 a, f32x4 b) { u32x4 w; w.x = pk2(a[0], a[1]); w.y = pk2(a[2], a[3]); w.z = pk2(b[0], b[1]); w.w = pk2(b[2], b[3]); return w; }
; #define EPI_LOOP_PERM(...) _Pragma("unroll") for (int ai = 0; ai < 2; ++ai) _Pragma("unroll") for (int m = 0; m < 4; ++m) { const int row = u.pm * 256 + ai * 128 + wr * 64 + m * 16 + fr; \
;     _Pragma("unroll") for (int bj = 0; bj < 2; ++bj) { const int c8 = bj * 128 + wc * 32 + 8 * fq; f32x4 v0 = acc[ai][bj][m][0], v1 = acc[ai][bj][m][1]; __VA_ARGS__ } }
; DI float sigmoidf_(float x) { return 1.f / (1.f + __expf(-x)); }
;     DI void operator()(const Acc& acc, const Unit& u, int wr, int wc, int fr, int fq) const {
;     ...
;             bf16_t* dst = pn < 28 ? sgs + (pn - 20) * 256 : sgg + (pn - 28) * 256;
;             EPI_LOOP_PERM({ for (int j = 0; j < 4; ++j) { v0[j] = sigmoidf_(v0[j]); v1[j] = sigmoidf_(v1[j]); } *(u32x4*)(dst + (size_t)row * 2048 + c8) = pack44(v0, v1); })
	v_mul_f32_e32 v160, 0xbfb8aa3b, v111
	v_exp_f32_e32 v163, v160
	s_nop 0
	v_pk_add_f32 v[160:161], v[162:163], 1.0 op_sel_hi:[1,0]
	s_nop 0
	v_rcp_f32_e32 v163, v161
	s_nop 0
	v_mul_f32_e32 v169, 1.0, v163
	v_fma_f32 v170, -v161, v169, 1.0
	v_fmac_f32_e32 v169, v170, v163
	v_div_fixup_f32 v163, v169, v161, 1.0
	v_rcp_f32_e32 v162, v160
	s_nop 0
	v_mul_f32_e32 v169, 1.0, v162
	v_fma_f32 v170, -v160, v169, 1.0
	v_fmac_f32_e32 v169, v170, v162
	v_div_fixup_f32 v168, v169, v160, 1.0
	v_cvt_pk_bf16_f32 v160, v153, v151
	v_cvt_pk_bf16_f32 v161, v167, v166
	v_cvt_pk_bf16_f32 v162, v165, v164
	v_cvt_pk_bf16_f32 v163, v168, v163
	v_mul_f32_e32 v151, 0xbfb8aa3b, v120
	global_store_dwordx4 v[154:155], v[160:163], off offset:256
	v_or_b32_e32 v154, 16, v152
	v_ashrrev_i32_e32 v155, 31, v154
	v_exp_f32_e32 v160, v151
	v_mul_f32_e32 v151, 0xbfb8aa3b, v116
	v_exp_f32_e32 v162, v151
	v_mul_f32_e32 v151, 0xbfb8aa3b, v121
	v_exp_f32_e32 v161, v151
	v_lshlrev_b64 v[154:155], 12, v[154:155]
	v_lshl_add_u64 v[154:155], s[44:45], 0, v[154:155]
	v_lshl_add_u64 v[154:155], v[154:155], 0, v[2:3]
	v_pk_add_f32 v[160:161], v[160:161], 1.0 op_sel_hi:[1,0]
	s_nop 0
	v_div_scale_f32 v151, s[2:3], v161, v161, 1.0
	v_rcp_f32_e32 v153, v151
	s_nop 0
	v_fma_f32 v163, -v151, v153, 1.0
	v_fmac_f32_e32 v153, v163, v153
	v_div_scale_f32 v163, vcc, 1.0, v161, 1.0
	v_mul_f32_e32 v164, v163, v153
	v_fma_f32 v165, -v151, v164, v163
	v_fmac_f32_e32 v164, v165, v153
	v_fma_f32 v151, -v151, v164, v163
	v_div_fmas_f32 v151, v151, v153, v164
	v_div_scale_f32 v153, s[2:3], v160, v160, 1.0
	v_div_fixup_f32 v151, v151, v161, 1.0
	v_rcp_f32_e32 v161, v153
	s_nop 0
	v_fma_f32 v163, -v153, v161, 1.0
	v_fmac_f32_e32 v161, v163, v161
	v_div_scale_f32 v163, vcc, 1.0, v160, 1.0
	v_mul_f32_e32 v164, v163, v161
	v_fma_f32 v165, -v153, v164, v163
	v_fmac_f32_e32 v164, v165, v161
	v_fma_f32 v153, -v153, v164, v163
	v_div_fmas_f32 v153, v153, v161, v164
	v_div_fixup_f32 v153, v153, v160, 1.0
	v_mul_f32_e32 v160, 0xbfb8aa3b, v117
	v_exp_f32_e32 v163, v160
	s_nop 0
	v_pk_add_f32 v[160:161], v[162:163], 1.0 op_sel_hi:[1,0]
	s_nop 0
	v_rcp_f32_e32 v163, v161
	s_nop 0
	v_mul_f32_e32 v165, 1.0, v163
	v_fma_f32 v166, -v161, v165, 1.0
	v_fmac_f32_e32 v165, v166, v163
	v_div_fixup_f32 v164, v165, v161, 1.0
	v_rcp_f32_e32 v162, v160
	s_nop 0
	v_mul_f32_e32 v165, 1.0, v162
	v_fma_f32 v166, -v160, v165, 1.0
	v_fmac_f32_e32 v165, v166, v162
	v_div_fixup_f32 v165, v165, v160, 1.0
	v_mul_f32_e32 v161, 0xbfb8aa3b, v118
	v_mul_f32_e32 v160, 0xbfb8aa3b, v122
	v_exp_f32_e32 v162, v161
	v_mul_f32_e32 v161, 0xbfb8aa3b, v123
	v_exp_f32_e32 v160, v160
	v_exp_f32_e32 v161, v161
	s_nop 0
	v_pk_add_f32 v[160:161], v[160:161], 1.0 op_sel_hi:[1,0]
	s_nop 0
	v_rcp_f32_e32 v166, v161
	s_nop 0
	v_mul_f32_e32 v168, 1.0, v166
	v_fma_f32 v169, -v161, v168, 1.0
	v_fmac_f32_e32 v168, v169, v166
	v_div_fixup_f32 v166, v168, v161, 1.0
	v_rcp_f32_e32 v163, v160
	s_nop 0
	v_mul_f32_e32 v168, 1.0, v163
	v_fma_f32 v169, -v160, v168, 1.0
	v_fmac_f32_e32 v168, v169, v163
	v_div_fixup_f32 v167, v168, v160, 1.0
	v_mul_f32_e32 v160, 0xbfb8aa3b, v119
	v_exp_f32_e32 v163, v160
	s_nop 0
	v_pk_add_f32 v[160:161], v[162:163], 1.0 op_sel_hi:[1,0]
	s_nop 0
	v_rcp_f32_e32 v163, v161
	s_nop 0
	v_mul_f32_e32 v169, 1.0, v163
	v_fma_f32 v170, -v161, v169, 1.0
	v_fmac_f32_e32 v169, v170, v163
	v_div_fixup_f32 v163, v169, v161, 1.0
	v_rcp_f32_e32 v162, v160
	s_nop 0
	v_mul_f32_e32 v169, 1.0, v162
	v_fma_f32 v170, -v160, v169, 1.0
	v_fmac_f32_e32 v169, v170, v162
	v_div_fixup_f32 v168, v169, v160, 1.0
	v_cvt_pk_bf16_f32 v160, v153, v151
	v_cvt_pk_bf16_f32 v161, v167, v166
	v_cvt_pk_bf16_f32 v162, v165, v164
	v_cvt_pk_bf16_f32 v163, v168, v163
	v_mul_f32_e32 v151, 0xbfb8aa3b, v96
	global_store_dwordx4 v[154:155], v[160:163], off
	s_nop 1
	v_exp_f32_e32 v160, v151
	v_mul_f32_e32 v151, 0xbfb8aa3b, v92
	v_exp_f32_e32 v162, v151
	v_mul_f32_e32 v151, 0xbfb8aa3b, v97
	v_exp_f32_e32 v161, v151
	s_nop 0
	v_pk_add_f32 v[160:161], v[160:161], 1.0 op_sel_hi:[1,0]
	s_nop 0
	v_div_scale_f32 v151, s[2:3], v161, v161, 1.0
	v_rcp_f32_e32 v153, v151
	s_nop 0
	v_fma_f32 v163, -v151, v153, 1.0
	v_fmac_f32_e32 v153, v163, v153
	v_div_scale_f32 v163, vcc, 1.0, v161, 1.0
	v_mul_f32_e32 v164, v163, v153
	v_fma_f32 v165, -v151, v164, v163
	v_fmac_f32_e32 v164, v165, v153
	v_fma_f32 v151, -v151, v164, v163
	v_div_fmas_f32 v151, v151, v153, v164
	v_div_scale_f32 v153, s[2:3], v160, v160, 1.0
	v_div_fixup_f32 v151, v151, v161, 1.0
	v_rcp_f32_e32 v161, v153
	s_nop 0
	v_fma_f32 v163, -v153, v161, 1.0
	v_fmac_f32_e32 v161, v163, v161
	v_div_scale_f32 v163, vcc, 1.0, v160, 1.0
	v_mul_f32_e32 v164, v163, v161
	v_fma_f32 v165, -v153, v164, v163
	v_fmac_f32_e32 v164, v165, v161
	v_fma_f32 v153, -v153, v164, v163
	v_div_fmas_f32 v153, v153, v161, v164
	v_div_fixup_f32 v153, v153, v160, 1.0
	v_mul_f32_e32 v160, 0xbfb8aa3b, v93
	v_exp_f32_e32 v163, v160
	s_nop 0
	v_pk_add_f32 v[160:161], v[162:163], 1.0 op_sel_hi:[1,0]
	s_nop 0
	v_rcp_f32_e32 v163, v161
	s_nop 0
	v_mul_f32_e32 v165, 1.0, v163
	v_fma_f32 v166, -v161, v165, 1.0
	v_fmac_f32_e32 v165, v166, v163
	v_div_fixup_f32 v164, v165, v161, 1.0
	v_rcp_f32_e32 v162, v160
	s_nop 0
	v_mul_f32_e32 v165, 1.0, v162
	v_fma_f32 v166, -v160, v165, 1.0
	v_fmac_f32_e32 v165, v166, v162
	v_div_fixup_f32 v165, v165, v160, 1.0
	v_mul_f32_e32 v161, 0xbfb8aa3b, v94
	v_mul_f32_e32 v160, 0xbfb8aa3b, v98
	v_exp_f32_e32 v162, v161
	v_mul_f32_e32 v161, 0xbfb8aa3b, v99
	v_exp_f32_e32 v160, v160
	v_exp_f32_e32 v161, v161
	s_nop 0
	v_pk_add_f32 v[160:161], v[160:161], 1.0 op_sel_hi:[1,0]
	s_nop 0
	v_rcp_f32_e32 v166, v161
	s_nop 0
	v_mul_f32_e32 v168, 1.0, v166
; DI u32x4 pack44(f32x4 a, f32x4 b) { u32x4 w; w.x = pk2(a[0], a[1]); w.y = pk2(a[2], a[3]); w.z = pk2(b[0], b[1]); w.w = pk2(b[2], b[3]); return w; }
; #define EPI_LOOP_PERM(...) _Pragma("unroll") for (int ai = 0; ai < 2; ++ai) _Pragma("unroll") for (int m = 0; m < 4; ++m) { const int row = u.pm * 256 + ai * 128 + wr * 64 + m * 16 + fr; \
;     _Pragma("unroll") for (int bj = 0; bj < 2; ++bj) { const int c8 = bj * 128 + wc * 32 + 8 * fq; f32x4 v0 = acc[ai][bj][m][0], v1 = acc[ai][bj][m][1]; __VA_ARGS__ } }
; DI float sigmoidf_(float x) { return 1.f / (1.f + __expf(-x)); }
;     DI void operator()(const Acc& acc, const Unit& u, int wr, int wc, int fr, int fq) const {
;     ...
;             bf16_t* dst = pn < 28 ? sgs + (pn - 20) * 256 : sgg + (pn - 28) * 256;
;             EPI_LOOP_PERM({ for (int j = 0; j < 4; ++j) { v0[j] = sigmoidf_(v0[j]); v1[j] = sigmoidf_(v1[j]); } *(u32x4*)(dst + (size_t)row * 2048 + c8) = pack44(v0, v1); })
	v_fma_f32 v169, -v161, v168, 1.0
	v_fmac_f32_e32 v168, v169, v166
	v_div_fixup_f32 v166, v168, v161, 1.0
	v_rcp_f32_e32 v163, v160
	s_nop 0
	v_mul_f32_e32 v168, 1.0, v163
	v_fma_f32 v169, -v160, v168, 1.0
	v_fmac_f32_e32 v168, v169, v163
	v_div_fixup_f32 v167, v168, v160, 1.0
	v_mul_f32_e32 v160, 0xbfb8aa3b, v95
	v_exp_f32_e32 v163, v160
	s_nop 0
	v_pk_add_f32 v[160:161], v[162:163], 1.0 op_sel_hi:[1,0]
	s_nop 0
	v_rcp_f32_e32 v163, v161
	s_nop 0
	v_mul_f32_e32 v169, 1.0, v163
	v_fma_f32 v170, -v161, v169, 1.0
	v_fmac_f32_e32 v169, v170, v163
	v_div_fixup_f32 v163, v169, v161, 1.0
	v_rcp_f32_e32 v162, v160
	s_nop 0
	v_mul_f32_e32 v169, 1.0, v162
	v_fma_f32 v170, -v160, v169, 1.0
	v_fmac_f32_e32 v169, v170, v162
	v_div_fixup_f32 v168, v169, v160, 1.0
	v_cvt_pk_bf16_f32 v160, v153, v151
	v_cvt_pk_bf16_f32 v161, v167, v166
	v_cvt_pk_bf16_f32 v162, v165, v164
	v_cvt_pk_bf16_f32 v163, v168, v163
	v_mul_f32_e32 v151, 0xbfb8aa3b, v104
	global_store_dwordx4 v[154:155], v[160:163], off offset:256
	v_or_b32_e32 v154, 32, v152
	v_ashrrev_i32_e32 v155, 31, v154
	v_exp_f32_e32 v160, v151
	v_mul_f32_e32 v151, 0xbfb8aa3b, v100
	v_exp_f32_e32 v162, v151
	v_mul_f32_e32 v151, 0xbfb8aa3b, v105
	v_exp_f32_e32 v161, v151
	v_lshlrev_b64 v[154:155], 12, v[154:155]
	v_lshl_add_u64 v[154:155], s[44:45], 0, v[154:155]
	v_lshl_add_u64 v[154:155], v[154:155], 0, v[2:3]
	v_pk_add_f32 v[160:161], v[160:161], 1.0 op_sel_hi:[1,0]
	s_nop 0
	v_div_scale_f32 v151, s[2:3], v161, v161, 1.0
	v_rcp_f32_e32 v153, v151
	s_nop 0
	v_fma_f32 v163, -v151, v153, 1.0
	v_fmac_f32_e32 v153, v163, v153
	v_div_scale_f32 v163, vcc, 1.0, v161, 1.0
	v_mul_f32_e32 v164, v163, v153
	v_fma_f32 v165, -v151, v164, v163
	v_fmac_f32_e32 v164, v165, v153
	v_fma_f32 v151, -v151, v164, v163
	v_div_fmas_f32 v151, v151, v153, v164
	v_div_scale_f32 v153, s[2:3], v160, v160, 1.0
	v_div_fixup_f32 v151, v151, v161, 1.0
	v_rcp_f32_e32 v161, v153
	s_nop 0
	v_fma_f32 v163, -v153, v161, 1.0
	v_fmac_f32_e32 v161, v163, v161
	v_div_scale_f32 v163, vcc, 1.0, v160, 1.0
	v_mul_f32_e32 v164, v163, v161
	v_fma_f32 v165, -v153, v164, v163
	v_fmac_f32_e32 v164, v165, v161
	v_fma_f32 v153, -v153, v164, v163
	v_div_fmas_f32 v153, v153, v161, v164
	v_div_fixup_f32 v153, v153, v160, 1.0
	v_mul_f32_e32 v160, 0xbfb8aa3b, v101
	v_exp_f32_e32 v163, v160
	s_nop 0
	v_pk_add_f32 v[160:161], v[162:163], 1.0 op_sel_hi:[1,0]
	s_nop 0
	v_rcp_f32_e32 v163, v161
	s_nop 0
	v_mul_f32_e32 v165, 1.0, v163
	v_fma_f32 v166, -v161, v165, 1.0
	v_fmac_f32_e32 v165, v166, v163
	v_div_fixup_f32 v164, v165, v161, 1.0
	v_rcp_f32_e32 v162, v160
	s_nop 0
	v_mul_f32_e32 v165, 1.0, v162
	v_fma_f32 v166, -v160, v165, 1.0
	v_fmac_f32_e32 v165, v166, v162
	v_div_fixup_f32 v165, v165, v160, 1.0
	v_mul_f32_e32 v161, 0xbfb8aa3b, v102
	v_mul_f32_e32 v160, 0xbfb8aa3b, v106
	v_exp_f32_e32 v162, v161
	v_mul_f32_e32 v161, 0xbfb8aa3b, v107
	v_exp_f32_e32 v160, v160
	v_exp_f32_e32 v161, v161
	s_nop 0
	v_pk_add_f32 v[160:161], v[160:161], 1.0 op_sel_hi:[1,0]
	s_nop 0
	v_rcp_f32_e32 v166, v161
	s_nop 0
	v_mul_f32_e32 v168, 1.0, v166
	v_fma_f32 v169, -v161, v168, 1.0
	v_fmac_f32_e32 v168, v169, v166
	v_div_fixup_f32 v166, v168, v161, 1.0
	v_rcp_f32_e32 v163, v160
	s_nop 0
	v_mul_f32_e32 v168, 1.0, v163
	v_fma_f32 v169, -v160, v168, 1.0
	v_fmac_f32_e32 v168, v169, v163
	v_div_fixup_f32 v167, v168, v160, 1.0
	v_mul_f32_e32 v160, 0xbfb8aa3b, v103
	v_exp_f32_e32 v163, v160
	s_nop 0
	v_pk_add_f32 v[160:161], v[162:163], 1.0 op_sel_hi:[1,0]
	s_nop 0
	v_rcp_f32_e32 v163, v161
	s_nop 0
	v_mul_f32_e32 v169, 1.0, v163
	v_fma_f32 v170, -v161, v169, 1.0
	v_fmac_f32_e32 v169, v170, v163
	v_div_fixup_f32 v163, v169, v161, 1.0
	v_rcp_f32_e32 v162, v160
	s_nop 0
	v_mul_f32_e32 v169, 1.0, v162
	v_fma_f32 v170, -v160, v169, 1.0
	v_fmac_f32_e32 v169, v170, v162
	v_div_fixup_f32 v168, v169, v160, 1.0
	v_cvt_pk_bf16_f32 v160, v153, v151
	v_cvt_pk_bf16_f32 v161, v167, v166
	v_cvt_pk_bf16_f32 v162, v165, v164
	v_cvt_pk_bf16_f32 v163, v168, v163
	v_mul_f32_e32 v151, 0xbfb8aa3b, v80
	global_store_dwordx4 v[154:155], v[160:163], off
	s_nop 1
	v_exp_f32_e32 v160, v151
	v_mul_f32_e32 v151, 0xbfb8aa3b, v76
	v_exp_f32_e32 v162, v151
	v_mul_f32_e32 v151, 0xbfb8aa3b, v81
	v_exp_f32_e32 v161, v151
	s_nop 0
	v_pk_add_f32 v[160:161], v[160:161], 1.0 op_sel_hi:[1,0]
	s_nop 0
	v_div_scale_f32 v151, s[2:3], v161, v161, 1.0
	v_rcp_f32_e32 v153, v151
	s_nop 0
	v_fma_f32 v163, -v151, v153, 1.0
	v_fmac_f32_e32 v153, v163, v153
	v_div_scale_f32 v163, vcc, 1.0, v161, 1.0
	v_mul_f32_e32 v164, v163, v153
	v_fma_f32 v165, -v151, v164, v163
	v_fmac_f32_e32 v164, v165, v153
	v_fma_f32 v151, -v151, v164, v163
	v_div_fmas_f32 v151, v151, v153, v164
	v_div_scale_f32 v153, s[2:3], v160, v160, 1.0
	v_div_fixup_f32 v151, v151, v161, 1.0
	v_rcp_f32_e32 v161, v153
	s_nop 0
	v_fma_f32 v163, -v153, v161, 1.0
	v_fmac_f32_e32 v161, v163, v161
	v_div_scale_f32 v163, vcc, 1.0, v160, 1.0
	v_mul_f32_e32 v164, v163, v161
	v_fma_f32 v165, -v153, v164, v163
	v_fmac_f32_e32 v164, v165, v161
	v_fma_f32 v153, -v153, v164, v163
	v_div_fmas_f32 v153, v153, v161, v164
	v_div_fixup_f32 v153, v153, v160, 1.0
	v_mul_f32_e32 v160, 0xbfb8aa3b, v77
	v_exp_f32_e32 v163, v160
	s_nop 0
	v_pk_add_f32 v[160:161], v[162:163], 1.0 op_sel_hi:[1,0]
	s_nop 0
	v_rcp_f32_e32 v163, v161
	s_nop 0
	v_mul_f32_e32 v165, 1.0, v163
	v_fma_f32 v166, -v161, v165, 1.0
	v_fmac_f32_e32 v165, v166, v163
	v_div_fixup_f32 v164, v165, v161, 1.0
	v_rcp_f32_e32 v162, v160
	s_nop 0
	v_mul_f32_e32 v165, 1.0, v162
	v_fma_f32 v166, -v160, v165, 1.0
	v_fmac_f32_e32 v165, v166, v162
	v_div_fixup_f32 v165, v165, v160, 1.0
	v_mul_f32_e32 v161, 0xbfb8aa3b, v78
	v_mul_f32_e32 v160, 0xbfb8aa3b, v82
; DI u32x4 pack44(f32x4 a, f32x4 b) { u32x4 w; w.x = pk2(a[0], a[1]); w.y = pk2(a[2], a[3]); w.z = pk2(b[0], b[1]); w.w = pk2(b[2], b[3]); return w; }
; #define EPI_LOOP_PERM(...) _Pragma("unroll") for (int ai = 0; ai < 2; ++ai) _Pragma("unroll") for (int m = 0; m < 4; ++m) { const int row = u.pm * 256 + ai * 128 + wr * 64 + m * 16 + fr; \
;     _Pragma("unroll") for (int bj = 0; bj < 2; ++bj) { const int c8 = bj * 128 + wc * 32 + 8 * fq; f32x4 v0 = acc[ai][bj][m][0], v1 = acc[ai][bj][m][1]; __VA_ARGS__ } }
; DI float sigmoidf_(float x) { return 1.f / (1.f + __expf(-x)); }
;     DI void operator()(const Acc& acc, const Unit& u, int wr, int wc, int fr, int fq) const {
;     ...
;             bf16_t* dst = pn < 28 ? sgs + (pn - 20) * 256 : sgg + (pn - 28) * 256;
;             EPI_LOOP_PERM({ for (int j = 0; j < 4; ++j) { v0[j] = sigmoidf_(v0[j]); v1[j] = sigmoidf_(v1[j]); } *(u32x4*)(dst + (size_t)row * 2048 + c8) = pack44(v0, v1); })
	v_exp_f32_e32 v162, v161
	v_mul_f32_e32 v161, 0xbfb8aa3b, v83
	v_exp_f32_e32 v160, v160
	v_exp_f32_e32 v161, v161
	s_nop 0
	v_pk_add_f32 v[160:161], v[160:161], 1.0 op_sel_hi:[1,0]
	s_nop 0
	v_rcp_f32_e32 v166, v161
	s_nop 0
	v_mul_f32_e32 v168, 1.0, v166
	v_fma_f32 v169, -v161, v168, 1.0
	v_fmac_f32_e32 v168, v169, v166
	v_div_fixup_f32 v166, v168, v161, 1.0
	v_rcp_f32_e32 v163, v160
	s_nop 0
	v_mul_f32_e32 v168, 1.0, v163
	v_fma_f32 v169, -v160, v168, 1.0
	v_fmac_f32_e32 v168, v169, v163
	v_div_fixup_f32 v167, v168, v160, 1.0
	v_mul_f32_e32 v160, 0xbfb8aa3b, v79
	v_exp_f32_e32 v163, v160
	s_nop 0
	v_pk_add_f32 v[160:161], v[162:163], 1.0 op_sel_hi:[1,0]
	s_nop 0
	v_rcp_f32_e32 v163, v161
	s_nop 0
	v_mul_f32_e32 v169, 1.0, v163
	v_fma_f32 v170, -v161, v169, 1.0
	v_fmac_f32_e32 v169, v170, v163
	v_div_fixup_f32 v163, v169, v161, 1.0
	v_rcp_f32_e32 v162, v160
	s_nop 0
	v_mul_f32_e32 v169, 1.0, v162
	v_fma_f32 v170, -v160, v169, 1.0
	v_fmac_f32_e32 v169, v170, v162
	v_div_fixup_f32 v168, v169, v160, 1.0
	v_cvt_pk_bf16_f32 v160, v153, v151
	v_cvt_pk_bf16_f32 v161, v167, v166
	v_cvt_pk_bf16_f32 v162, v165, v164
	v_cvt_pk_bf16_f32 v163, v168, v163
	v_mul_f32_e32 v151, 0xbfb8aa3b, v88
	global_store_dwordx4 v[154:155], v[160:163], off offset:256
	v_or_b32_e32 v154, 48, v152
	v_ashrrev_i32_e32 v155, 31, v154
	v_exp_f32_e32 v160, v151
	v_mul_f32_e32 v151, 0xbfb8aa3b, v84
	v_exp_f32_e32 v162, v151
	v_mul_f32_e32 v151, 0xbfb8aa3b, v89
	v_exp_f32_e32 v161, v151
	v_lshlrev_b64 v[154:155], 12, v[154:155]
	v_lshl_add_u64 v[154:155], s[44:45], 0, v[154:155]
	v_lshl_add_u64 v[154:155], v[154:155], 0, v[2:3]
	v_pk_add_f32 v[160:161], v[160:161], 1.0 op_sel_hi:[1,0]
	s_nop 0
	v_div_scale_f32 v151, s[2:3], v161, v161, 1.0
	v_rcp_f32_e32 v153, v151
	s_nop 0
	v_fma_f32 v163, -v151, v153, 1.0
	v_fmac_f32_e32 v153, v163, v153
	v_div_scale_f32 v163, vcc, 1.0, v161, 1.0
	v_mul_f32_e32 v164, v163, v153
	v_fma_f32 v165, -v151, v164, v163
	v_fmac_f32_e32 v164, v165, v153
	v_fma_f32 v151, -v151, v164, v163
	v_div_fmas_f32 v151, v151, v153, v164
	v_div_scale_f32 v153, s[2:3], v160, v160, 1.0
	v_div_fixup_f32 v151, v151, v161, 1.0
	v_rcp_f32_e32 v161, v153
	s_nop 0
	v_fma_f32 v163, -v153, v161, 1.0
	v_fmac_f32_e32 v161, v163, v161
	v_div_scale_f32 v163, vcc, 1.0, v160, 1.0
	v_mul_f32_e32 v164, v163, v161
	v_fma_f32 v165, -v153, v164, v163
	v_fmac_f32_e32 v164, v165, v161
	v_fma_f32 v153, -v153, v164, v163
	v_div_fmas_f32 v153, v153, v161, v164
	v_div_fixup_f32 v153, v153, v160, 1.0
	v_mul_f32_e32 v160, 0xbfb8aa3b, v85
	v_exp_f32_e32 v163, v160
	s_nop 0
	v_pk_add_f32 v[160:161], v[162:163], 1.0 op_sel_hi:[1,0]
	s_nop 0
	v_rcp_f32_e32 v163, v161
	s_nop 0
	v_mul_f32_e32 v165, 1.0, v163
	v_fma_f32 v166, -v161, v165, 1.0
	v_fmac_f32_e32 v165, v166, v163
	v_div_fixup_f32 v164, v165, v161, 1.0
	v_rcp_f32_e32 v162, v160
	s_nop 0
	v_mul_f32_e32 v165, 1.0, v162
	v_fma_f32 v166, -v160, v165, 1.0
	v_fmac_f32_e32 v165, v166, v162
	v_div_fixup_f32 v165, v165, v160, 1.0
	v_mul_f32_e32 v161, 0xbfb8aa3b, v86
	v_mul_f32_e32 v160, 0xbfb8aa3b, v90
	v_exp_f32_e32 v162, v161
	v_mul_f32_e32 v161, 0xbfb8aa3b, v91
	v_exp_f32_e32 v160, v160
	v_exp_f32_e32 v161, v161
	s_nop 0
	v_pk_add_f32 v[160:161], v[160:161], 1.0 op_sel_hi:[1,0]
	s_nop 0
	v_rcp_f32_e32 v166, v161
	s_nop 0
	v_mul_f32_e32 v168, 1.0, v166
	v_fma_f32 v169, -v161, v168, 1.0
	v_fmac_f32_e32 v168, v169, v166
	v_div_fixup_f32 v166, v168, v161, 1.0
	v_rcp_f32_e32 v163, v160
	s_nop 0
	v_mul_f32_e32 v168, 1.0, v163
	v_fma_f32 v169, -v160, v168, 1.0
	v_fmac_f32_e32 v168, v169, v163
	v_div_fixup_f32 v167, v168, v160, 1.0
	v_mul_f32_e32 v160, 0xbfb8aa3b, v87
	v_exp_f32_e32 v163, v160
	s_nop 0
	v_pk_add_f32 v[160:161], v[162:163], 1.0 op_sel_hi:[1,0]
	s_nop 0
	v_rcp_f32_e32 v163, v161
	s_nop 0
	v_mul_f32_e32 v169, 1.0, v163
	v_fma_f32 v170, -v161, v169, 1.0
	v_fmac_f32_e32 v169, v170, v163
	v_div_fixup_f32 v163, v169, v161, 1.0
	v_rcp_f32_e32 v162, v160
	s_nop 0
	v_mul_f32_e32 v169, 1.0, v162
	v_fma_f32 v170, -v160, v169, 1.0
	v_fmac_f32_e32 v169, v170, v162
	v_div_fixup_f32 v168, v169, v160, 1.0
	v_cvt_pk_bf16_f32 v160, v153, v151
	v_cvt_pk_bf16_f32 v161, v167, v166
	v_cvt_pk_bf16_f32 v162, v165, v164
	v_cvt_pk_bf16_f32 v163, v168, v163
	v_mul_f32_e32 v151, 0xbfb8aa3b, v72
	global_store_dwordx4 v[154:155], v[160:163], off
	s_nop 1
	v_exp_f32_e32 v160, v151
	v_mul_f32_e32 v151, 0xbfb8aa3b, v68
	v_exp_f32_e32 v162, v151
	v_mul_f32_e32 v151, 0xbfb8aa3b, v73
	v_exp_f32_e32 v161, v151
	s_nop 0
	v_pk_add_f32 v[160:161], v[160:161], 1.0 op_sel_hi:[1,0]
	s_nop 0
	v_div_scale_f32 v151, s[2:3], v161, v161, 1.0
	v_rcp_f32_e32 v153, v151
	s_nop 0
	v_fma_f32 v163, -v151, v153, 1.0
	v_fmac_f32_e32 v153, v163, v153
	v_div_scale_f32 v163, vcc, 1.0, v161, 1.0
	v_mul_f32_e32 v164, v163, v153
	v_fma_f32 v165, -v151, v164, v163
	v_fmac_f32_e32 v164, v165, v153
	v_fma_f32 v151, -v151, v164, v163
	v_div_fmas_f32 v151, v151, v153, v164
	v_div_scale_f32 v153, s[2:3], v160, v160, 1.0
	v_div_fixup_f32 v151, v151, v161, 1.0
	v_rcp_f32_e32 v161, v153
	s_nop 0
	v_fma_f32 v163, -v153, v161, 1.0
	v_fmac_f32_e32 v161, v163, v161
	v_div_scale_f32 v163, vcc, 1.0, v160, 1.0
	v_mul_f32_e32 v164, v163, v161
	v_fma_f32 v165, -v153, v164, v163
	v_fmac_f32_e32 v164, v165, v161
	v_fma_f32 v153, -v153, v164, v163
	v_div_fmas_f32 v153, v153, v161, v164
	v_div_fixup_f32 v153, v153, v160, 1.0
	v_mul_f32_e32 v160, 0xbfb8aa3b, v69
	v_exp_f32_e32 v163, v160
	s_nop 0
	v_pk_add_f32 v[160:161], v[162:163], 1.0 op_sel_hi:[1,0]
	s_nop 0
	v_rcp_f32_e32 v163, v161
	s_nop 0
	v_mul_f32_e32 v165, 1.0, v163
	v_fma_f32 v166, -v161, v165, 1.0
	v_fmac_f32_e32 v165, v166, v163
; DI u32x4 pack44(f32x4 a, f32x4 b) { u32x4 w; w.x = pk2(a[0], a[1]); w.y = pk2(a[2], a[3]); w.z = pk2(b[0], b[1]); w.w = pk2(b[2], b[3]); return w; }
; #define EPI_LOOP_PERM(...) _Pragma("unroll") for (int ai = 0; ai < 2; ++ai) _Pragma("unroll") for (int m = 0; m < 4; ++m) { const int row = u.pm * 256 + ai * 128 + wr * 64 + m * 16 + fr; \
;     _Pragma("unroll") for (int bj = 0; bj < 2; ++bj) { const int c8 = bj * 128 + wc * 32 + 8 * fq; f32x4 v0 = acc[ai][bj][m][0], v1 = acc[ai][bj][m][1]; __VA_ARGS__ } }
; DI float sigmoidf_(float x) { return 1.f / (1.f + __expf(-x)); }
;     DI void operator()(const Acc& acc, const Unit& u, int wr, int wc, int fr, int fq) const {
;     ...
;             bf16_t* dst = pn < 28 ? sgs + (pn - 20) * 256 : sgg + (pn - 28) * 256;
;             EPI_LOOP_PERM({ for (int j = 0; j < 4; ++j) { v0[j] = sigmoidf_(v0[j]); v1[j] = sigmoidf_(v1[j]); } *(u32x4*)(dst + (size_t)row * 2048 + c8) = pack44(v0, v1); })
	v_div_fixup_f32 v164, v165, v161, 1.0
	v_rcp_f32_e32 v162, v160
	s_nop 0
	v_mul_f32_e32 v165, 1.0, v162
	v_fma_f32 v166, -v160, v165, 1.0
	v_fmac_f32_e32 v165, v166, v162
	v_div_fixup_f32 v165, v165, v160, 1.0
	v_mul_f32_e32 v161, 0xbfb8aa3b, v70
	v_mul_f32_e32 v160, 0xbfb8aa3b, v74
	v_exp_f32_e32 v162, v161
	v_mul_f32_e32 v161, 0xbfb8aa3b, v75
	v_exp_f32_e32 v160, v160
	v_exp_f32_e32 v161, v161
	s_nop 0
	v_pk_add_f32 v[160:161], v[160:161], 1.0 op_sel_hi:[1,0]
	s_nop 0
	v_rcp_f32_e32 v166, v161
	s_nop 0
	v_mul_f32_e32 v168, 1.0, v166
	v_fma_f32 v169, -v161, v168, 1.0
	v_fmac_f32_e32 v168, v169, v166
	v_div_fixup_f32 v166, v168, v161, 1.0
	v_rcp_f32_e32 v163, v160
	s_nop 0
	v_mul_f32_e32 v168, 1.0, v163
	v_fma_f32 v169, -v160, v168, 1.0
	v_fmac_f32_e32 v168, v169, v163
	v_div_fixup_f32 v167, v168, v160, 1.0
	v_mul_f32_e32 v160, 0xbfb8aa3b, v71
	v_exp_f32_e32 v163, v160
	s_nop 0
	v_pk_add_f32 v[160:161], v[162:163], 1.0 op_sel_hi:[1,0]
	s_nop 0
	v_rcp_f32_e32 v163, v161
	s_nop 0
	v_mul_f32_e32 v169, 1.0, v163
	v_fma_f32 v170, -v161, v169, 1.0
	v_fmac_f32_e32 v169, v170, v163
	v_div_fixup_f32 v163, v169, v161, 1.0
	v_rcp_f32_e32 v162, v160
	s_nop 0
	v_mul_f32_e32 v169, 1.0, v162
	v_fma_f32 v170, -v160, v169, 1.0
	v_fmac_f32_e32 v169, v170, v162
	v_div_fixup_f32 v168, v169, v160, 1.0
	v_cvt_pk_bf16_f32 v160, v153, v151
	v_cvt_pk_bf16_f32 v161, v167, v166
	v_cvt_pk_bf16_f32 v162, v165, v164
	v_cvt_pk_bf16_f32 v163, v168, v163
	v_mul_f32_e32 v151, 0xbfb8aa3b, v64
	global_store_dwordx4 v[154:155], v[160:163], off offset:256
	v_add_u32_e32 v154, 0x80, v152
	v_ashrrev_i32_e32 v155, 31, v154
	v_exp_f32_e32 v160, v151
	v_mul_f32_e32 v151, 0xbfb8aa3b, v60
	v_exp_f32_e32 v162, v151
	v_mul_f32_e32 v151, 0xbfb8aa3b, v65
	v_exp_f32_e32 v161, v151
	v_lshlrev_b64 v[154:155], 12, v[154:155]
	v_lshl_add_u64 v[154:155], s[44:45], 0, v[154:155]
	v_lshl_add_u64 v[154:155], v[154:155], 0, v[2:3]
	v_pk_add_f32 v[160:161], v[160:161], 1.0 op_sel_hi:[1,0]
	s_nop 0
	v_div_scale_f32 v151, s[2:3], v161, v161, 1.0
	v_rcp_f32_e32 v153, v151
	s_nop 0
	v_fma_f32 v163, -v151, v153, 1.0
	v_fmac_f32_e32 v153, v163, v153
	v_div_scale_f32 v163, vcc, 1.0, v161, 1.0
	v_mul_f32_e32 v164, v163, v153
	v_fma_f32 v165, -v151, v164, v163
	v_fmac_f32_e32 v164, v165, v153
	v_fma_f32 v151, -v151, v164, v163
	v_div_fmas_f32 v151, v151, v153, v164
	v_div_scale_f32 v153, s[2:3], v160, v160, 1.0
	v_div_fixup_f32 v151, v151, v161, 1.0
	v_rcp_f32_e32 v161, v153
	s_nop 0
	v_fma_f32 v163, -v153, v161, 1.0
	v_fmac_f32_e32 v161, v163, v161
	v_div_scale_f32 v163, vcc, 1.0, v160, 1.0
	v_mul_f32_e32 v164, v163, v161
	v_fma_f32 v165, -v153, v164, v163
	v_fmac_f32_e32 v164, v165, v161
	v_fma_f32 v153, -v153, v164, v163
	v_div_fmas_f32 v153, v153, v161, v164
	v_div_fixup_f32 v153, v153, v160, 1.0
	v_mul_f32_e32 v160, 0xbfb8aa3b, v61
	v_exp_f32_e32 v163, v160
	s_nop 0
	v_pk_add_f32 v[160:161], v[162:163], 1.0 op_sel_hi:[1,0]
	s_nop 0
	v_rcp_f32_e32 v163, v161
	s_nop 0
	v_mul_f32_e32 v165, 1.0, v163
	v_fma_f32 v166, -v161, v165, 1.0
	v_fmac_f32_e32 v165, v166, v163
	v_div_fixup_f32 v164, v165, v161, 1.0
	v_rcp_f32_e32 v162, v160
	s_nop 0
	v_mul_f32_e32 v165, 1.0, v162
	v_fma_f32 v166, -v160, v165, 1.0
	v_fmac_f32_e32 v165, v166, v162
	v_div_fixup_f32 v165, v165, v160, 1.0
	v_mul_f32_e32 v161, 0xbfb8aa3b, v62
	v_mul_f32_e32 v160, 0xbfb8aa3b, v66
	v_exp_f32_e32 v162, v161
	v_mul_f32_e32 v161, 0xbfb8aa3b, v67
	v_exp_f32_e32 v160, v160
	v_exp_f32_e32 v161, v161
	s_nop 0
	v_pk_add_f32 v[160:161], v[160:161], 1.0 op_sel_hi:[1,0]
	s_nop 0
	v_rcp_f32_e32 v166, v161
	s_nop 0
	v_mul_f32_e32 v168, 1.0, v166
	v_fma_f32 v169, -v161, v168, 1.0
	v_fmac_f32_e32 v168, v169, v166
	v_div_fixup_f32 v166, v168, v161, 1.0
	v_rcp_f32_e32 v163, v160
	s_nop 0
	v_mul_f32_e32 v168, 1.0, v163
	v_fma_f32 v169, -v160, v168, 1.0
	v_fmac_f32_e32 v168, v169, v163
	v_div_fixup_f32 v167, v168, v160, 1.0
	v_mul_f32_e32 v160, 0xbfb8aa3b, v63
	v_exp_f32_e32 v163, v160
	s_nop 0
	v_pk_add_f32 v[160:161], v[162:163], 1.0 op_sel_hi:[1,0]
	s_nop 0
	v_rcp_f32_e32 v163, v161
	s_nop 0
	v_mul_f32_e32 v169, 1.0, v163
	v_fma_f32 v170, -v161, v169, 1.0
	v_fmac_f32_e32 v169, v170, v163
	v_div_fixup_f32 v163, v169, v161, 1.0
	v_rcp_f32_e32 v162, v160
	s_nop 0
	v_mul_f32_e32 v169, 1.0, v162
	v_fma_f32 v170, -v160, v169, 1.0
	v_fmac_f32_e32 v169, v170, v162
	v_div_fixup_f32 v168, v169, v160, 1.0
	v_cvt_pk_bf16_f32 v160, v153, v151
	v_cvt_pk_bf16_f32 v161, v167, v166
	v_cvt_pk_bf16_f32 v162, v165, v164
	v_cvt_pk_bf16_f32 v163, v168, v163
	v_mul_f32_e32 v151, 0xbfb8aa3b, v48
	global_store_dwordx4 v[154:155], v[160:163], off
	s_nop 1
	v_exp_f32_e32 v160, v151
	v_mul_f32_e32 v151, 0xbfb8aa3b, v44
	v_exp_f32_e32 v162, v151
	v_mul_f32_e32 v151, 0xbfb8aa3b, v49
	v_exp_f32_e32 v161, v151
	s_nop 0
	v_pk_add_f32 v[160:161], v[160:161], 1.0 op_sel_hi:[1,0]
	s_nop 0
	v_div_scale_f32 v151, s[2:3], v161, v161, 1.0
	v_rcp_f32_e32 v153, v151
	s_nop 0
	v_fma_f32 v163, -v151, v153, 1.0
	v_fmac_f32_e32 v153, v163, v153
	v_div_scale_f32 v163, vcc, 1.0, v161, 1.0
	v_mul_f32_e32 v164, v163, v153
	v_fma_f32 v165, -v151, v164, v163
	v_fmac_f32_e32 v164, v165, v153
	v_fma_f32 v151, -v151, v164, v163
	v_div_fmas_f32 v151, v151, v153, v164
	v_div_scale_f32 v153, s[2:3], v160, v160, 1.0
	v_div_fixup_f32 v151, v151, v161, 1.0
	v_rcp_f32_e32 v161, v153
	s_nop 0
	v_fma_f32 v163, -v153, v161, 1.0
	v_fmac_f32_e32 v161, v163, v161
	v_div_scale_f32 v163, vcc, 1.0, v160, 1.0
	v_mul_f32_e32 v164, v163, v161
	v_fma_f32 v165, -v153, v164, v163
	v_fmac_f32_e32 v164, v165, v161
	v_fma_f32 v153, -v153, v164, v163
	v_div_fmas_f32 v153, v153, v161, v164
	v_div_fixup_f32 v153, v153, v160, 1.0
; DI u32x4 pack44(f32x4 a, f32x4 b) { u32x4 w; w.x = pk2(a[0], a[1]); w.y = pk2(a[2], a[3]); w.z = pk2(b[0], b[1]); w.w = pk2(b[2], b[3]); return w; }
; #define EPI_LOOP_PERM(...) _Pragma("unroll") for (int ai = 0; ai < 2; ++ai) _Pragma("unroll") for (int m = 0; m < 4; ++m) { const int row = u.pm * 256 + ai * 128 + wr * 64 + m * 16 + fr; \
;     _Pragma("unroll") for (int bj = 0; bj < 2; ++bj) { const int c8 = bj * 128 + wc * 32 + 8 * fq; f32x4 v0 = acc[ai][bj][m][0], v1 = acc[ai][bj][m][1]; __VA_ARGS__ } }
; DI float sigmoidf_(float x) { return 1.f / (1.f + __expf(-x)); }
;     DI void operator()(const Acc& acc, const Unit& u, int wr, int wc, int fr, int fq) const {
;     ...
;             bf16_t* dst = pn < 28 ? sgs + (pn - 20) * 256 : sgg + (pn - 28) * 256;
;             EPI_LOOP_PERM({ for (int j = 0; j < 4; ++j) { v0[j] = sigmoidf_(v0[j]); v1[j] = sigmoidf_(v1[j]); } *(u32x4*)(dst + (size_t)row * 2048 + c8) = pack44(v0, v1); })
	v_mul_f32_e32 v160, 0xbfb8aa3b, v45
	v_exp_f32_e32 v163, v160
	s_nop 0
	v_pk_add_f32 v[160:161], v[162:163], 1.0 op_sel_hi:[1,0]
	s_nop 0
	v_rcp_f32_e32 v163, v161
	s_nop 0
	v_mul_f32_e32 v165, 1.0, v163
	v_fma_f32 v166, -v161, v165, 1.0
	v_fmac_f32_e32 v165, v166, v163
	v_div_fixup_f32 v164, v165, v161, 1.0
	v_rcp_f32_e32 v162, v160
	s_nop 0
	v_mul_f32_e32 v165, 1.0, v162
	v_fma_f32 v166, -v160, v165, 1.0
	v_fmac_f32_e32 v165, v166, v162
	v_div_fixup_f32 v165, v165, v160, 1.0
	v_mul_f32_e32 v161, 0xbfb8aa3b, v46
	v_mul_f32_e32 v160, 0xbfb8aa3b, v50
	v_exp_f32_e32 v162, v161
	v_mul_f32_e32 v161, 0xbfb8aa3b, v51
	v_exp_f32_e32 v160, v160
	v_exp_f32_e32 v161, v161
	s_nop 0
	v_pk_add_f32 v[160:161], v[160:161], 1.0 op_sel_hi:[1,0]
	s_nop 0
	v_rcp_f32_e32 v166, v161
	s_nop 0
	v_mul_f32_e32 v168, 1.0, v166
	v_fma_f32 v169, -v161, v168, 1.0
	v_fmac_f32_e32 v168, v169, v166
	v_div_fixup_f32 v166, v168, v161, 1.0
	v_rcp_f32_e32 v163, v160
	s_nop 0
	v_mul_f32_e32 v168, 1.0, v163
	v_fma_f32 v169, -v160, v168, 1.0
	v_fmac_f32_e32 v168, v169, v163
	v_div_fixup_f32 v167, v168, v160, 1.0
	v_mul_f32_e32 v160, 0xbfb8aa3b, v47
	v_exp_f32_e32 v163, v160
	s_nop 0
	v_pk_add_f32 v[160:161], v[162:163], 1.0 op_sel_hi:[1,0]
	s_nop 0
	v_rcp_f32_e32 v163, v161
	s_nop 0
	v_mul_f32_e32 v169, 1.0, v163
	v_fma_f32 v170, -v161, v169, 1.0
	v_fmac_f32_e32 v169, v170, v163
	v_div_fixup_f32 v163, v169, v161, 1.0
	v_rcp_f32_e32 v162, v160
	s_nop 0
	v_mul_f32_e32 v169, 1.0, v162
	v_fma_f32 v170, -v160, v169, 1.0
	v_fmac_f32_e32 v169, v170, v162
	v_div_fixup_f32 v168, v169, v160, 1.0
	v_cvt_pk_bf16_f32 v160, v153, v151
	v_cvt_pk_bf16_f32 v161, v167, v166
	v_cvt_pk_bf16_f32 v162, v165, v164
	v_cvt_pk_bf16_f32 v163, v168, v163
	v_mul_f32_e32 v151, 0xbfb8aa3b, v56
	global_store_dwordx4 v[154:155], v[160:163], off offset:256
	v_add_u32_e32 v154, 0x90, v152
	v_ashrrev_i32_e32 v155, 31, v154
	v_exp_f32_e32 v160, v151
	v_mul_f32_e32 v151, 0xbfb8aa3b, v52
	v_exp_f32_e32 v162, v151
	v_mul_f32_e32 v151, 0xbfb8aa3b, v57
	v_exp_f32_e32 v161, v151
	v_lshlrev_b64 v[154:155], 12, v[154:155]
	v_lshl_add_u64 v[154:155], s[44:45], 0, v[154:155]
	v_lshl_add_u64 v[154:155], v[154:155], 0, v[2:3]
	v_pk_add_f32 v[160:161], v[160:161], 1.0 op_sel_hi:[1,0]
	s_nop 0
	v_div_scale_f32 v151, s[2:3], v161, v161, 1.0
	v_rcp_f32_e32 v153, v151
	s_nop 0
	v_fma_f32 v163, -v151, v153, 1.0
	v_fmac_f32_e32 v153, v163, v153
	v_div_scale_f32 v163, vcc, 1.0, v161, 1.0
	v_mul_f32_e32 v164, v163, v153
	v_fma_f32 v165, -v151, v164, v163
	v_fmac_f32_e32 v164, v165, v153
	v_fma_f32 v151, -v151, v164, v163
	v_div_fmas_f32 v151, v151, v153, v164
	v_div_scale_f32 v153, s[2:3], v160, v160, 1.0
	v_div_fixup_f32 v151, v151, v161, 1.0
	v_rcp_f32_e32 v161, v153
	s_nop 0
	v_fma_f32 v163, -v153, v161, 1.0
	v_fmac_f32_e32 v161, v163, v161
	v_div_scale_f32 v163, vcc, 1.0, v160, 1.0
	v_mul_f32_e32 v164, v163, v161
	v_fma_f32 v165, -v153, v164, v163
	v_fmac_f32_e32 v164, v165, v161
	v_fma_f32 v153, -v153, v164, v163
	v_div_fmas_f32 v153, v153, v161, v164
	v_div_fixup_f32 v153, v153, v160, 1.0
	v_mul_f32_e32 v160, 0xbfb8aa3b, v53
	v_exp_f32_e32 v163, v160
	s_nop 0
	v_pk_add_f32 v[160:161], v[162:163], 1.0 op_sel_hi:[1,0]
	s_nop 0
	v_rcp_f32_e32 v163, v161
	s_nop 0
	v_mul_f32_e32 v165, 1.0, v163
	v_fma_f32 v166, -v161, v165, 1.0
	v_fmac_f32_e32 v165, v166, v163
	v_div_fixup_f32 v164, v165, v161, 1.0
	v_rcp_f32_e32 v162, v160
	s_nop 0
	v_mul_f32_e32 v165, 1.0, v162
	v_fma_f32 v166, -v160, v165, 1.0
	v_fmac_f32_e32 v165, v166, v162
	v_div_fixup_f32 v165, v165, v160, 1.0
	v_mul_f32_e32 v161, 0xbfb8aa3b, v54
	v_mul_f32_e32 v160, 0xbfb8aa3b, v58
	v_exp_f32_e32 v162, v161
	v_mul_f32_e32 v161, 0xbfb8aa3b, v59
	v_exp_f32_e32 v160, v160
	v_exp_f32_e32 v161, v161
	s_nop 0
	v_pk_add_f32 v[160:161], v[160:161], 1.0 op_sel_hi:[1,0]
	s_nop 0
	v_rcp_f32_e32 v166, v161
	s_nop 0
	v_mul_f32_e32 v168, 1.0, v166
	v_fma_f32 v169, -v161, v168, 1.0
	v_fmac_f32_e32 v168, v169, v166
	v_div_fixup_f32 v166, v168, v161, 1.0
	v_rcp_f32_e32 v163, v160
	s_nop 0
	v_mul_f32_e32 v168, 1.0, v163
	v_fma_f32 v169, -v160, v168, 1.0
	v_fmac_f32_e32 v168, v169, v163
	v_div_fixup_f32 v167, v168, v160, 1.0
	v_mul_f32_e32 v160, 0xbfb8aa3b, v55
	v_exp_f32_e32 v163, v160
	s_nop 0
	v_pk_add_f32 v[160:161], v[162:163], 1.0 op_sel_hi:[1,0]
	s_nop 0
	v_rcp_f32_e32 v163, v161
	s_nop 0
	v_mul_f32_e32 v169, 1.0, v163
	v_fma_f32 v170, -v161, v169, 1.0
	v_fmac_f32_e32 v169, v170, v163
	v_div_fixup_f32 v163, v169, v161, 1.0
	v_rcp_f32_e32 v162, v160
	s_nop 0
	v_mul_f32_e32 v169, 1.0, v162
	v_fma_f32 v170, -v160, v169, 1.0
	v_fmac_f32_e32 v169, v170, v162
	v_div_fixup_f32 v168, v169, v160, 1.0
	v_cvt_pk_bf16_f32 v160, v153, v151
	v_cvt_pk_bf16_f32 v161, v167, v166
	v_cvt_pk_bf16_f32 v162, v165, v164
	v_cvt_pk_bf16_f32 v163, v168, v163
	v_mul_f32_e32 v151, 0xbfb8aa3b, v32
	global_store_dwordx4 v[154:155], v[160:163], off
	s_nop 1
	v_exp_f32_e32 v160, v151
	v_mul_f32_e32 v151, 0xbfb8aa3b, v28
	v_exp_f32_e32 v162, v151
	v_mul_f32_e32 v151, 0xbfb8aa3b, v33
	v_exp_f32_e32 v161, v151
	s_nop 0
	v_pk_add_f32 v[160:161], v[160:161], 1.0 op_sel_hi:[1,0]
	s_nop 0
	v_div_scale_f32 v151, s[2:3], v161, v161, 1.0
	v_rcp_f32_e32 v153, v151
	s_nop 0
	v_fma_f32 v163, -v151, v153, 1.0
	v_fmac_f32_e32 v153, v163, v153
	v_div_scale_f32 v163, vcc, 1.0, v161, 1.0
	v_mul_f32_e32 v164, v163, v153
	v_fma_f32 v165, -v151, v164, v163
	v_fmac_f32_e32 v164, v165, v153
	v_fma_f32 v151, -v151, v164, v163
	v_div_fmas_f32 v151, v151, v153, v164
	v_div_scale_f32 v153, s[2:3], v160, v160, 1.0
	v_div_fixup_f32 v151, v151, v161, 1.0
	v_rcp_f32_e32 v161, v153
	s_nop 0
	v_fma_f32 v163, -v153, v161, 1.0
	v_fmac_f32_e32 v161, v163, v161
; DI u32x4 pack44(f32x4 a, f32x4 b) { u32x4 w; w.x = pk2(a[0], a[1]); w.y = pk2(a[2], a[3]); w.z = pk2(b[0], b[1]); w.w = pk2(b[2], b[3]); return w; }
; #define EPI_LOOP_PERM(...) _Pragma("unroll") for (int ai = 0; ai < 2; ++ai) _Pragma("unroll") for (int m = 0; m < 4; ++m) { const int row = u.pm * 256 + ai * 128 + wr * 64 + m * 16 + fr; \
;     _Pragma("unroll") for (int bj = 0; bj < 2; ++bj) { const int c8 = bj * 128 + wc * 32 + 8 * fq; f32x4 v0 = acc[ai][bj][m][0], v1 = acc[ai][bj][m][1]; __VA_ARGS__ } }
; DI float sigmoidf_(float x) { return 1.f / (1.f + __expf(-x)); }
;     DI void operator()(const Acc& acc, const Unit& u, int wr, int wc, int fr, int fq) const {
;     ...
;             bf16_t* dst = pn < 28 ? sgs + (pn - 20) * 256 : sgg + (pn - 28) * 256;
;             EPI_LOOP_PERM({ for (int j = 0; j < 4; ++j) { v0[j] = sigmoidf_(v0[j]); v1[j] = sigmoidf_(v1[j]); } *(u32x4*)(dst + (size_t)row * 2048 + c8) = pack44(v0, v1); })
	v_div_scale_f32 v163, vcc, 1.0, v160, 1.0
	v_mul_f32_e32 v164, v163, v161
	v_fma_f32 v165, -v153, v164, v163
	v_fmac_f32_e32 v164, v165, v161
	v_fma_f32 v153, -v153, v164, v163
	v_div_fmas_f32 v153, v153, v161, v164
	v_div_fixup_f32 v153, v153, v160, 1.0
	v_mul_f32_e32 v160, 0xbfb8aa3b, v29
	v_exp_f32_e32 v163, v160
	s_nop 0
	v_pk_add_f32 v[160:161], v[162:163], 1.0 op_sel_hi:[1,0]
	s_nop 0
	v_rcp_f32_e32 v163, v161
	s_nop 0
	v_mul_f32_e32 v165, 1.0, v163
	v_fma_f32 v166, -v161, v165, 1.0
	v_fmac_f32_e32 v165, v166, v163
	v_div_fixup_f32 v164, v165, v161, 1.0
	v_rcp_f32_e32 v162, v160
	s_nop 0
	v_mul_f32_e32 v165, 1.0, v162
	v_fma_f32 v166, -v160, v165, 1.0
	v_fmac_f32_e32 v165, v166, v162
	v_div_fixup_f32 v165, v165, v160, 1.0
	v_mul_f32_e32 v161, 0xbfb8aa3b, v30
	v_mul_f32_e32 v160, 0xbfb8aa3b, v34
	v_exp_f32_e32 v162, v161
	v_mul_f32_e32 v161, 0xbfb8aa3b, v35
	v_exp_f32_e32 v160, v160
	v_exp_f32_e32 v161, v161
	s_nop 0
	v_pk_add_f32 v[160:161], v[160:161], 1.0 op_sel_hi:[1,0]
	s_nop 0
	v_rcp_f32_e32 v166, v161
	s_nop 0
	v_mul_f32_e32 v168, 1.0, v166
	v_fma_f32 v169, -v161, v168, 1.0
	v_fmac_f32_e32 v168, v169, v166
	v_div_fixup_f32 v166, v168, v161, 1.0
	v_rcp_f32_e32 v163, v160
	s_nop 0
	v_mul_f32_e32 v168, 1.0, v163
	v_fma_f32 v169, -v160, v168, 1.0
	v_fmac_f32_e32 v168, v169, v163
	v_div_fixup_f32 v167, v168, v160, 1.0
	v_mul_f32_e32 v160, 0xbfb8aa3b, v31
	v_exp_f32_e32 v163, v160
	s_nop 0
	v_pk_add_f32 v[160:161], v[162:163], 1.0 op_sel_hi:[1,0]
	s_nop 0
	v_rcp_f32_e32 v163, v161
	s_nop 0
	v_mul_f32_e32 v169, 1.0, v163
	v_fma_f32 v170, -v161, v169, 1.0
	v_fmac_f32_e32 v169, v170, v163
	v_div_fixup_f32 v163, v169, v161, 1.0
	v_rcp_f32_e32 v162, v160
	s_nop 0
	v_mul_f32_e32 v169, 1.0, v162
	v_fma_f32 v170, -v160, v169, 1.0
	v_fmac_f32_e32 v169, v170, v162
	v_div_fixup_f32 v168, v169, v160, 1.0
	v_cvt_pk_bf16_f32 v160, v153, v151
	v_cvt_pk_bf16_f32 v161, v167, v166
	v_cvt_pk_bf16_f32 v162, v165, v164
	v_cvt_pk_bf16_f32 v163, v168, v163
	v_mul_f32_e32 v151, 0xbfb8aa3b, v40
	global_store_dwordx4 v[154:155], v[160:163], off offset:256
	v_add_u32_e32 v154, 0xa0, v152
	v_ashrrev_i32_e32 v155, 31, v154
	v_exp_f32_e32 v160, v151
	v_mul_f32_e32 v151, 0xbfb8aa3b, v36
	v_exp_f32_e32 v162, v151
	v_mul_f32_e32 v151, 0xbfb8aa3b, v41
	v_exp_f32_e32 v161, v151
	v_lshlrev_b64 v[154:155], 12, v[154:155]
	v_lshl_add_u64 v[154:155], s[44:45], 0, v[154:155]
	v_lshl_add_u64 v[154:155], v[154:155], 0, v[2:3]
	v_pk_add_f32 v[160:161], v[160:161], 1.0 op_sel_hi:[1,0]
	v_add_u32_e32 v152, 0xb0, v152
	v_div_scale_f32 v151, s[2:3], v161, v161, 1.0
	v_rcp_f32_e32 v153, v151
	s_nop 0
	v_fma_f32 v163, -v151, v153, 1.0
	v_fmac_f32_e32 v153, v163, v153
	v_div_scale_f32 v163, vcc, 1.0, v161, 1.0
	v_mul_f32_e32 v164, v163, v153
	v_fma_f32 v165, -v151, v164, v163
	v_fmac_f32_e32 v164, v165, v153
	v_fma_f32 v151, -v151, v164, v163
	v_div_fmas_f32 v151, v151, v153, v164
	v_div_scale_f32 v153, s[2:3], v160, v160, 1.0
	v_div_fixup_f32 v151, v151, v161, 1.0
	v_rcp_f32_e32 v161, v153
	s_nop 0
	v_fma_f32 v163, -v153, v161, 1.0
	v_fmac_f32_e32 v161, v163, v161
	v_div_scale_f32 v163, vcc, 1.0, v160, 1.0
	v_mul_f32_e32 v164, v163, v161
	v_fma_f32 v165, -v153, v164, v163
	v_fmac_f32_e32 v164, v165, v161
	v_fma_f32 v153, -v153, v164, v163
	v_div_fmas_f32 v153, v153, v161, v164
	v_div_fixup_f32 v153, v153, v160, 1.0
	v_mul_f32_e32 v160, 0xbfb8aa3b, v37
	v_exp_f32_e32 v163, v160
	s_nop 0
	v_pk_add_f32 v[160:161], v[162:163], 1.0 op_sel_hi:[1,0]
	s_nop 0
	v_rcp_f32_e32 v163, v161
	s_nop 0
	v_mul_f32_e32 v165, 1.0, v163
	v_fma_f32 v166, -v161, v165, 1.0
	v_fmac_f32_e32 v165, v166, v163
	v_div_fixup_f32 v164, v165, v161, 1.0
	v_rcp_f32_e32 v162, v160
	s_nop 0
	v_mul_f32_e32 v165, 1.0, v162
	v_fma_f32 v166, -v160, v165, 1.0
	v_fmac_f32_e32 v165, v166, v162
	v_div_fixup_f32 v165, v165, v160, 1.0
	v_mul_f32_e32 v161, 0xbfb8aa3b, v38
	v_mul_f32_e32 v160, 0xbfb8aa3b, v42
	v_exp_f32_e32 v162, v161
	v_mul_f32_e32 v161, 0xbfb8aa3b, v43
	v_exp_f32_e32 v160, v160
	v_exp_f32_e32 v161, v161
	s_nop 0
	v_pk_add_f32 v[160:161], v[160:161], 1.0 op_sel_hi:[1,0]
	s_nop 0
	v_rcp_f32_e32 v166, v161
	s_nop 0
	v_mul_f32_e32 v168, 1.0, v166
	v_fma_f32 v169, -v161, v168, 1.0
	v_fmac_f32_e32 v168, v169, v166
	v_div_fixup_f32 v166, v168, v161, 1.0
	v_rcp_f32_e32 v163, v160
	s_nop 0
	v_mul_f32_e32 v168, 1.0, v163
	v_fma_f32 v169, -v160, v168, 1.0
	v_fmac_f32_e32 v168, v169, v163
	v_div_fixup_f32 v167, v168, v160, 1.0
	v_mul_f32_e32 v160, 0xbfb8aa3b, v39
	v_exp_f32_e32 v163, v160
	s_nop 0
	v_pk_add_f32 v[160:161], v[162:163], 1.0 op_sel_hi:[1,0]
	s_nop 0
	v_rcp_f32_e32 v163, v161
	s_nop 0
	v_mul_f32_e32 v169, 1.0, v163
	v_fma_f32 v170, -v161, v169, 1.0
	v_fmac_f32_e32 v169, v170, v163
	v_div_fixup_f32 v163, v169, v161, 1.0
	v_rcp_f32_e32 v162, v160
	s_nop 0
	v_mul_f32_e32 v169, 1.0, v162
	v_fma_f32 v170, -v160, v169, 1.0
	v_fmac_f32_e32 v169, v170, v162
	v_div_fixup_f32 v168, v169, v160, 1.0
	v_cvt_pk_bf16_f32 v160, v153, v151
	v_cvt_pk_bf16_f32 v161, v167, v166
	v_cvt_pk_bf16_f32 v162, v165, v164
	v_cvt_pk_bf16_f32 v163, v168, v163
	v_mul_f32_e32 v151, 0xbfb8aa3b, v16
	global_store_dwordx4 v[154:155], v[160:163], off
	s_nop 1
	v_exp_f32_e32 v160, v151
	v_mul_f32_e32 v151, 0xbfb8aa3b, v12
	v_exp_f32_e32 v162, v151
	v_mul_f32_e32 v151, 0xbfb8aa3b, v17
	v_exp_f32_e32 v161, v151
	s_nop 0
	v_pk_add_f32 v[160:161], v[160:161], 1.0 op_sel_hi:[1,0]
	s_nop 0
	v_div_scale_f32 v151, s[2:3], v161, v161, 1.0
	v_rcp_f32_e32 v153, v151
	s_nop 0
	v_fma_f32 v163, -v151, v153, 1.0
	v_fmac_f32_e32 v153, v163, v153
	v_div_scale_f32 v163, vcc, 1.0, v161, 1.0
	v_mul_f32_e32 v164, v163, v153
	v_fma_f32 v165, -v151, v164, v163
; DI u32x4 pack44(f32x4 a, f32x4 b) { u32x4 w; w.x = pk2(a[0], a[1]); w.y = pk2(a[2], a[3]); w.z = pk2(b[0], b[1]); w.w = pk2(b[2], b[3]); return w; }
; #define EPI_LOOP_PERM(...) _Pragma("unroll") for (int ai = 0; ai < 2; ++ai) _Pragma("unroll") for (int m = 0; m < 4; ++m) { const int row = u.pm * 256 + ai * 128 + wr * 64 + m * 16 + fr; \
;     _Pragma("unroll") for (int bj = 0; bj < 2; ++bj) { const int c8 = bj * 128 + wc * 32 + 8 * fq; f32x4 v0 = acc[ai][bj][m][0], v1 = acc[ai][bj][m][1]; __VA_ARGS__ } }
; DI float sigmoidf_(float x) { return 1.f / (1.f + __expf(-x)); }
;     DI void operator()(const Acc& acc, const Unit& u, int wr, int wc, int fr, int fq) const {
;     ...
;         } else if (pn < 36) {
;             bf16_t* dst = pn < 28 ? sgs + (pn - 20) * 256 : sgg + (pn - 28) * 256;
;             EPI_LOOP_PERM({ for (int j = 0; j < 4; ++j) { v0[j] = sigmoidf_(v0[j]); v1[j] = sigmoidf_(v1[j]); } *(u32x4*)(dst + (size_t)row * 2048 + c8) = pack44(v0, v1); })
	v_fmac_f32_e32 v164, v165, v153
	v_fma_f32 v151, -v151, v164, v163
	v_div_fmas_f32 v151, v151, v153, v164
	v_div_scale_f32 v153, s[2:3], v160, v160, 1.0
	v_div_fixup_f32 v151, v151, v161, 1.0
	v_rcp_f32_e32 v161, v153
	s_nop 0
	v_fma_f32 v163, -v153, v161, 1.0
	v_fmac_f32_e32 v161, v163, v161
	v_div_scale_f32 v163, vcc, 1.0, v160, 1.0
	v_mul_f32_e32 v164, v163, v161
	v_fma_f32 v165, -v153, v164, v163
	v_fmac_f32_e32 v164, v165, v161
	v_fma_f32 v153, -v153, v164, v163
	v_div_fmas_f32 v153, v153, v161, v164
	v_div_fixup_f32 v153, v153, v160, 1.0
	v_mul_f32_e32 v160, 0xbfb8aa3b, v13
	v_exp_f32_e32 v163, v160
	s_nop 0
	v_pk_add_f32 v[160:161], v[162:163], 1.0 op_sel_hi:[1,0]
	s_nop 0
	v_rcp_f32_e32 v163, v161
	s_nop 0
	v_mul_f32_e32 v165, 1.0, v163
	v_fma_f32 v166, -v161, v165, 1.0
	v_fmac_f32_e32 v165, v166, v163
	v_div_fixup_f32 v164, v165, v161, 1.0
	v_rcp_f32_e32 v162, v160
	s_nop 0
	v_mul_f32_e32 v165, 1.0, v162
	v_fma_f32 v166, -v160, v165, 1.0
	v_fmac_f32_e32 v165, v166, v162
	v_div_fixup_f32 v165, v165, v160, 1.0
	v_mul_f32_e32 v161, 0xbfb8aa3b, v14
	v_mul_f32_e32 v160, 0xbfb8aa3b, v18
	v_exp_f32_e32 v162, v161
	v_mul_f32_e32 v161, 0xbfb8aa3b, v19
	v_exp_f32_e32 v160, v160
	v_exp_f32_e32 v161, v161
	s_nop 0
	v_pk_add_f32 v[160:161], v[160:161], 1.0 op_sel_hi:[1,0]
	s_nop 0
	v_rcp_f32_e32 v166, v161
	s_nop 0
	v_mul_f32_e32 v168, 1.0, v166
	v_fma_f32 v169, -v161, v168, 1.0
	v_fmac_f32_e32 v168, v169, v166
	v_div_fixup_f32 v166, v168, v161, 1.0
	v_rcp_f32_e32 v163, v160
	s_nop 0
	v_mul_f32_e32 v168, 1.0, v163
	v_fma_f32 v169, -v160, v168, 1.0
	v_fmac_f32_e32 v168, v169, v163
	v_div_fixup_f32 v167, v168, v160, 1.0
	v_mul_f32_e32 v160, 0xbfb8aa3b, v15
	v_exp_f32_e32 v163, v160
	s_nop 0
	v_pk_add_f32 v[160:161], v[162:163], 1.0 op_sel_hi:[1,0]
	s_nop 0
	v_rcp_f32_e32 v163, v161
	s_nop 0
	v_mul_f32_e32 v169, 1.0, v163
	v_fma_f32 v170, -v161, v169, 1.0
	v_fmac_f32_e32 v169, v170, v163
	v_div_fixup_f32 v163, v169, v161, 1.0
	v_rcp_f32_e32 v162, v160
	s_nop 0
	v_mul_f32_e32 v169, 1.0, v162
	v_fma_f32 v170, -v160, v169, 1.0
	v_fmac_f32_e32 v169, v170, v162
	v_div_fixup_f32 v168, v169, v160, 1.0
	v_cvt_pk_bf16_f32 v160, v153, v151
	v_cvt_pk_bf16_f32 v161, v167, v166
	v_cvt_pk_bf16_f32 v162, v165, v164
	v_cvt_pk_bf16_f32 v163, v168, v163
	v_mul_f32_e32 v151, 0xbfb8aa3b, v24
	global_store_dwordx4 v[154:155], v[160:163], off offset:256
	v_exp_f32_e32 v154, v151
	v_mul_f32_e32 v151, 0xbfb8aa3b, v20
	v_exp_f32_e32 v160, v151
	v_mul_f32_e32 v151, 0xbfb8aa3b, v25
	v_exp_f32_e32 v155, v151
	v_ashrrev_i32_e32 v153, 31, v152
	v_lshlrev_b64 v[152:153], 12, v[152:153]
	v_lshl_add_u64 v[152:153], s[44:45], 0, v[152:153]
	v_pk_add_f32 v[154:155], v[154:155], 1.0 op_sel_hi:[1,0]
	v_lshl_add_u64 v[152:153], v[152:153], 0, v[2:3]
	v_rcp_f32_e32 v161, v155
	s_nop 0
	v_mul_f32_e32 v2, 0xbfb8aa3b, v8
	v_mul_f32_e32 v163, 1.0, v161
	v_fma_f32 v164, -v155, v163, 1.0
	v_fmac_f32_e32 v163, v164, v161
	v_div_fixup_f32 v151, v163, v155, 1.0
	v_rcp_f32_e32 v161, v154
	s_nop 0
	v_mul_f32_e32 v163, 1.0, v161
	v_fma_f32 v164, -v154, v163, 1.0
	v_fmac_f32_e32 v163, v164, v161
	v_div_fixup_f32 v162, v163, v154, 1.0
	v_mul_f32_e32 v154, 0xbfb8aa3b, v21
	v_exp_f32_e32 v161, v154
	s_nop 0
	v_pk_add_f32 v[154:155], v[160:161], 1.0 op_sel_hi:[1,0]
	s_nop 0
	v_rcp_f32_e32 v161, v155
	s_nop 0
	v_mul_f32_e32 v164, 1.0, v161
	v_fma_f32 v165, -v155, v164, 1.0
	v_fmac_f32_e32 v164, v165, v161
	v_div_fixup_f32 v163, v164, v155, 1.0
	v_rcp_f32_e32 v160, v154
	s_nop 0
	v_mul_f32_e32 v164, 1.0, v160
	v_fma_f32 v165, -v154, v164, 1.0
	v_fmac_f32_e32 v164, v165, v160
	v_div_fixup_f32 v164, v164, v154, 1.0
	v_mul_f32_e32 v155, 0xbfb8aa3b, v22
	v_mul_f32_e32 v154, 0xbfb8aa3b, v26
	v_exp_f32_e32 v160, v155
	v_mul_f32_e32 v155, 0xbfb8aa3b, v27
	v_exp_f32_e32 v154, v154
	v_exp_f32_e32 v155, v155
	s_nop 0
; DI u32x4 pack44(f32x4 a, f32x4 b) { u32x4 w; w.x = pk2(a[0], a[1]); w.y = pk2(a[2], a[3]); w.z = pk2(b[0], b[1]); w.w = pk2(b[2], b[3]); return w; }
; #define EPI_LOOP_PERM(...) _Pragma("unroll") for (int ai = 0; ai < 2; ++ai) _Pragma("unroll") for (int m = 0; m < 4; ++m) { const int row = u.pm * 256 + ai * 128 + wr * 64 + m * 16 + fr; \
;     _Pragma("unroll") for (int bj = 0; bj < 2; ++bj) { const int c8 = bj * 128 + wc * 32 + 8 * fq; f32x4 v0 = acc[ai][bj][m][0], v1 = acc[ai][bj][m][1]; __VA_ARGS__ } }
; DI float sigmoidf_(float x) { return 1.f / (1.f + __expf(-x)); }
;     DI void operator()(const Acc& acc, const Unit& u, int wr, int wc, int fr, int fq) const {
;     ...
;         } else if (pn < 36) {
;             bf16_t* dst = pn < 28 ? sgs + (pn - 20) * 256 : sgg + (pn - 28) * 256;
;             EPI_LOOP_PERM({ for (int j = 0; j < 4; ++j) { v0[j] = sigmoidf_(v0[j]); v1[j] = sigmoidf_(v1[j]); } *(u32x4*)(dst + (size_t)row * 2048 + c8) = pack44(v0, v1); })
	v_pk_add_f32 v[154:155], v[154:155], 1.0 op_sel_hi:[1,0]
	s_nop 0
	v_rcp_f32_e32 v165, v155
	s_nop 0
	v_mul_f32_e32 v167, 1.0, v165
	v_fma_f32 v168, -v155, v167, 1.0
	v_fmac_f32_e32 v167, v168, v165
	v_div_fixup_f32 v165, v167, v155, 1.0
	v_rcp_f32_e32 v161, v154
	s_nop 0
	v_mul_f32_e32 v167, 1.0, v161
	v_fma_f32 v168, -v154, v167, 1.0
	v_fmac_f32_e32 v167, v168, v161
	v_div_fixup_f32 v166, v167, v154, 1.0
	v_mul_f32_e32 v154, 0xbfb8aa3b, v23
	v_exp_f32_e32 v161, v154
	s_nop 0
	v_pk_add_f32 v[154:155], v[160:161], 1.0 op_sel_hi:[1,0]
	s_nop 0
	v_rcp_f32_e32 v161, v155
	s_nop 0
	v_mul_f32_e32 v168, 1.0, v161
	v_fma_f32 v169, -v155, v168, 1.0
	v_fmac_f32_e32 v168, v169, v161
	v_div_fixup_f32 v155, v168, v155, 1.0
	v_rcp_f32_e32 v161, v154
	s_nop 0
	v_mul_f32_e32 v168, 1.0, v161
	v_fma_f32 v169, -v154, v168, 1.0
	v_fmac_f32_e32 v168, v169, v161
	v_div_fixup_f32 v154, v168, v154, 1.0
	v_cvt_pk_bf16_f32 v160, v162, v151
	v_cvt_pk_bf16_f32 v161, v166, v165
	v_cvt_pk_bf16_f32 v162, v164, v163
	v_cvt_pk_bf16_f32 v163, v154, v155
	v_exp_f32_e32 v154, v2
	v_mul_f32_e32 v2, 0xbfb8aa3b, v4
	global_store_dwordx4 v[152:153], v[160:163], off
	s_nop 1
	v_exp_f32_e32 v160, v2
	v_mul_f32_e32 v2, 0xbfb8aa3b, v9
	v_exp_f32_e32 v155, v2
	s_nop 0
	v_pk_add_f32 v[154:155], v[154:155], 1.0 op_sel_hi:[1,0]
	s_nop 0
	v_div_scale_f32 v2, s[2:3], v155, v155, 1.0
	v_rcp_f32_e32 v151, v2
	s_nop 0
	v_fma_f32 v161, -v2, v151, 1.0
	v_fmac_f32_e32 v151, v161, v151
	v_div_scale_f32 v161, vcc, 1.0, v155, 1.0
	v_mul_f32_e32 v162, v161, v151
	v_fma_f32 v163, -v2, v162, v161
	v_fmac_f32_e32 v162, v163, v151
	v_fma_f32 v2, -v2, v162, v161
	v_div_fmas_f32 v2, v2, v151, v162
	v_div_scale_f32 v151, s[2:3], v154, v154, 1.0
	v_div_fixup_f32 v2, v2, v155, 1.0
	v_rcp_f32_e32 v155, v151
	s_nop 0
	v_fma_f32 v161, -v151, v155, 1.0
	v_fmac_f32_e32 v155, v161, v155
	v_div_scale_f32 v161, vcc, 1.0, v154, 1.0
	v_mul_f32_e32 v162, v161, v155
	v_fma_f32 v163, -v151, v162, v161
	v_fmac_f32_e32 v162, v163, v155
	v_fma_f32 v151, -v151, v162, v161
	v_div_fmas_f32 v151, v151, v155, v162
	v_div_fixup_f32 v151, v151, v154, 1.0
	v_mul_f32_e32 v154, 0xbfb8aa3b, v5
	v_exp_f32_e32 v161, v154
	s_nop 0
	v_pk_add_f32 v[154:155], v[160:161], 1.0 op_sel_hi:[1,0]
	s_nop 0
	v_rcp_f32_e32 v161, v155
	s_nop 0
	v_mul_f32_e32 v163, 1.0, v161
	v_fma_f32 v164, -v155, v163, 1.0
	v_fmac_f32_e32 v163, v164, v161
	v_div_fixup_f32 v162, v163, v155, 1.0
	v_rcp_f32_e32 v160, v154
	s_nop 0
	v_mul_f32_e32 v163, 1.0, v160
	v_fma_f32 v164, -v154, v163, 1.0
	v_fmac_f32_e32 v163, v164, v160
	v_div_fixup_f32 v163, v163, v154, 1.0
	v_mul_f32_e32 v155, 0xbfb8aa3b, v6
	v_mul_f32_e32 v154, 0xbfb8aa3b, v10
	v_exp_f32_e32 v160, v155
	v_mul_f32_e32 v155, 0xbfb8aa3b, v11
	v_exp_f32_e32 v154, v154
	v_exp_f32_e32 v155, v155
	v_cvt_pk_bf16_f32 v162, v163, v162
	v_pk_add_f32 v[154:155], v[154:155], 1.0 op_sel_hi:[1,0]
	s_nop 0
	v_rcp_f32_e32 v164, v155
	s_nop 0
	v_mul_f32_e32 v166, 1.0, v164
	v_fma_f32 v167, -v155, v166, 1.0
	v_fmac_f32_e32 v166, v167, v164
	v_div_fixup_f32 v164, v166, v155, 1.0
	v_rcp_f32_e32 v161, v154
	s_nop 0
	v_mul_f32_e32 v166, 1.0, v161
	v_fma_f32 v167, -v154, v166, 1.0
	v_fmac_f32_e32 v166, v167, v161
	v_div_fixup_f32 v165, v166, v154, 1.0
	v_mul_f32_e32 v154, 0xbfb8aa3b, v7
	v_exp_f32_e32 v161, v154
	s_nop 0
	v_pk_add_f32 v[154:155], v[160:161], 1.0 op_sel_hi:[1,0]
	s_nop 0
	v_rcp_f32_e32 v161, v155
	s_nop 0
	v_mul_f32_e32 v167, 1.0, v161
	v_fma_f32 v168, -v155, v167, 1.0
	v_fmac_f32_e32 v167, v168, v161
	v_div_fixup_f32 v155, v167, v155, 1.0
	v_rcp_f32_e32 v161, v154
	s_nop 0
	v_mul_f32_e32 v167, 1.0, v161
	v_fma_f32 v168, -v154, v167, 1.0
	v_fmac_f32_e32 v167, v168, v161
	v_div_fixup_f32 v154, v167, v154, 1.0
	v_cvt_pk_bf16_f32 v160, v151, v2
	v_cvt_pk_bf16_f32 v161, v165, v164
	v_cvt_pk_bf16_f32 v163, v154, v155
	global_store_dwordx4 v[152:153], v[160:163], off offset:256

; #define LAS __attribute__((address_space(3)))
; DI int TID() { int t = __builtin_amdgcn_workitem_id_x(); asm volatile("" : "+v"(t)); return t; }
; DI int GDIM() { return (int)__ockl_get_num_groups(0); }
; DI int BID() { int t = __builtin_amdgcn_workgroup_id_x(); asm volatile("" : "+s"(t)); return t; }
; DI void phase_mod(LAS unsigned char* lds, PP p) {
;     LAS float* red = (LAS float*)lds;
;     const int tid = TID(), col = tid & 31, kp = tid >> 5;
;     const float* c = p->in[1];
;     float* mod = (float*)(p->ws + O_MOD);
;     for (int u = BID(); u < 768; u += GDIM()) {
;         const int l = u / 384, c0 = (u % 384) * 32;
;         const float* w = p->in[2] + (size_t)l * 2048 * 12288 + c0 + col;
;         float s = 0.f;
;         for (int k = kp * 128; k < kp * 128 + 128; ++k) { const float cv = c[k]; s += (cv / (1.f + __expf(-cv))) * w[(size_t)k * 12288]; }
.LBB0_1262:
	s_andn2_b64 vcc, exec, s[28:29]
	s_cbranch_vccnz .LBB0_1386
	v_mov_b32_e32 v2, v201
	s_mov_b32 s20, s64
	s_cmpk_gt_i32 s20, 0x2ff
	s_cbranch_scc1 .LBB0_1270
	s_waitcnt lgkmcnt(0)
	s_load_dwordx4 s[24:27], s[0:1], 0x8
	v_lshlrev_b32_e32 v0, 2, v2
	s_waitcnt vmcnt(0)
	v_and_b32_e32 v4, 0xffffff80, v0
	s_mov_b32 s2, 0xc000
	v_and_b32_e32 v6, 31, v2
	v_add_u32_e32 v10, 0, v0
	v_mad_i64_i32 v[0:1], s[2:3], v4, s2, 0
	v_lshl_or_b32 v0, v6, 2, v0
	v_cmp_gt_i32_e64 s[22:23], 32, v2
	v_lshlrev_b32_e32 v32, 4, v2
	s_waitcnt lgkmcnt(0)
	v_lshl_add_u64 v[0:1], s[26:27], 0, v[0:1]
	global_load_dwordx4 v[28:31], v32, s[24:25]
	v_and_b32_e32 v33, 0xfffffe00, v32
	s_mov_b64 s[26:27], 0xc000
	s_waitcnt vmcnt(0)
	v_mul_f32_e32 v17, 0xbfb8aa3b, v28
	v_exp_f32_e32 v17, v17
	s_nop 0
	v_add_f32_e32 v17, 1.0, v17
	v_rcp_f32_e32 v19, v17
	s_nop 0
	v_mul_f32_e32 v21, v28, v19
	v_fma_f32 v22, -v17, v21, v28
	v_fmac_f32_e32 v21, v22, v19
	v_div_fixup_f32 v28, v21, v17, v28
	v_mul_f32_e32 v17, 0xbfb8aa3b, v29
	v_exp_f32_e32 v17, v17
	s_nop 0
	v_add_f32_e32 v17, 1.0, v17
	v_rcp_f32_e32 v19, v17
	s_nop 0
	v_mul_f32_e32 v21, v29, v19
	v_fma_f32 v22, -v17, v21, v29
	v_fmac_f32_e32 v21, v22, v19
	v_div_fixup_f32 v29, v21, v17, v29
	v_mul_f32_e32 v17, 0xbfb8aa3b, v30
	v_exp_f32_e32 v17, v17
	s_nop 0
	v_add_f32_e32 v17, 1.0, v17
	v_rcp_f32_e32 v19, v17
	s_nop 0
	v_mul_f32_e32 v21, v30, v19
	v_fma_f32 v22, -v17, v21, v30
	v_fmac_f32_e32 v21, v22, v19
	v_div_fixup_f32 v30, v21, v17, v30
	v_mul_f32_e32 v17, 0xbfb8aa3b, v31
	v_exp_f32_e32 v17, v17
	s_nop 0
	v_add_f32_e32 v17, 1.0, v17
	v_rcp_f32_e32 v19, v17
	s_nop 0
	v_mul_f32_e32 v21, v31, v19
	v_fma_f32 v22, -v17, v21, v31
	v_fmac_f32_e32 v21, v22, v19
	v_div_fixup_f32 v31, v21, v17, v31
	ds_write_b128 v32, v[28:31] offset:4096
	s_waitcnt lgkmcnt(0)
	s_barrier
	s_branch .LBB0_1266
